# 8-phase loops: fragment read addresses precomputed per tile (buffer 0 reads need no address arithmetic, buffer 1 one add per address)
# baseline (speedup 1.0000x reference)
; template <bool SWAP>
; DI void gemm_mainloop(f32x16 (&acc)[4][2], const u16* __restrict__ A, int lda, int rlo, int rhi,
;                       const u16* __restrict__ B, int ldb, int K, char* lds, const u16* zero_line) {
;   const int tid = opaque_tid(), lane = tid & 63, w = tid >> 6;
;   const int wm = w >> 2, wn = w & 3;
;   const int h = lane >> 5, r = lane & 31;
;   const int lr = tid >> 3, lc = tid & 7;
; #pragma unroll
;   for (int mi = 0; mi < 4; ++mi)
; #pragma unroll
;     for (int ni = 0; ni < 2; ++ni)
; #pragma unroll
;       for (int i = 0; i < 16; ++i) acc[mi][ni][i] = 0.f;
;   const int gch = (lc ^ ((lr >> 1) & 7)) * 8;
;   const u16* ap = A + (ptrdiff_t)lr * lda + gch;
;   const u16* bp = B + (ptrdiff_t)lr * ldb + gch;
;   const int nk = K >> 6;
;   typedef __attribute__((address_space(3))) unsigned lds_u32;
;   auto glds = [&](int kt, int st) {
;     char* as_ = lds + st * 65536 + tid * 16;
; #pragma unroll
;     for (int i = 0; i < 4; ++i) {
;       const int rr = lr + 64 * i;
;       const u16* srca = (rr >= rlo && rr < rhi) ? (ap + (ptrdiff_t)(64 * i) * lda + kt * 64) : (zero_line + lc * 8);
;       __builtin_amdgcn_global_load_lds((const unsigned*)srca, (lds_u32*)(as_ + i * 8192), 16, 0, 0);
;       __builtin_amdgcn_global_load_lds((const unsigned*)(bp + (ptrdiff_t)(64 * i) * ldb + kt * 64), (lds_u32*)(as_ + 32768 + i * 8192), 16, 0, 0);
;     }
;   };
;   const int sw = (r >> 1) & 7;
;   const int arow_off = (wm * 128 + r) * 128;
;   const int brow_off = 32768 + (wn * 64 + r) * 128;
;   __syncthreads();
;   glds(0, 0);
;   asm volatile("s_waitcnt vmcnt(0)" ::: "memory");
;   __syncthreads();
; template <int EPI>
; DI void phase_gemm(const Params& p, const GemmArgs& ga, char* lds) {
;     ...
;   for (int it = 0; it * (int)gridDim.x < total; ++it) {
;     const int lt = logical_index(it);
;     if (lt >= total) continue;
;     int mt, nt;
;     tile_mn(lt, Mt, ga.Nt, mt, nt);
;     int bb, tokbase, S, pos0, rlo = 0, rhi = 256;
;     if (EPI == EPI_UP) {
;       bb = 0; tokbase = 0; S = NTOK;
;       pos0 = 254 * mt - 1;
;       rlo = (mt == 0) ? 1 : 0;
;       rhi = NTOK - pos0; if (rhi > 256) rhi = 256;
;     } else {
;       seq_of_token(mt * 256, bb, tokbase, S);
;       pos0 = mt * 256 - tokbase;
;     }
;     const u16* A = ga.A + (ptrdiff_t)(tokbase + pos0) * ga.lda;
;     const u16* B = ga.Bt + (size_t)(nt * 256) * ga.K;
.LBB0_56:
	s_add_i32 s30, s10, s25
	s_cmpk_gt_i32 s30, 0x10ab
	s_cbranch_scc1 .LBB0_55
	s_mul_hi_i32 s10, s30, 0x2e8ba2e9
	s_lshr_b32 s11, s10, 31
	s_ashr_i32 s10, s10, 5
	s_add_i32 s31, s10, s11
	s_lshl_b32 s10, s31, 3
	s_sub_i32 s11, 0xc2, s10
	s_min_u32 s11, s11, 8
	v_cvt_f32_ubyte0_e32 v0, s11
	v_rcp_iflag_f32_e32 v0, v0
	s_sub_i32 s15, 0, s11
	s_mul_i32 s12, s31, 0xffffff50
	s_add_i32 s12, s12, s30
	v_mul_f32_e32 v0, 0x4f7ffffe, v0
	v_cvt_u32_f32_e32 v0, v0
	s_abs_i32 s14, s12
	s_ashr_i32 s13, s12, 31
	s_waitcnt vmcnt(5)
	v_mov_b32_e32 v13, v204
	v_readfirstlane_b32 s16, v0
	s_mul_i32 s15, s15, s16
	s_mul_hi_u32 s15, s16, s15
	s_add_i32 s16, s16, s15
	s_mul_hi_u32 s15, s14, s16
	s_mul_i32 s16, s15, s11
	s_sub_i32 s14, s14, s16
	s_add_i32 s16, s15, 1
	s_sub_i32 s17, s14, s11
	s_cmp_ge_u32 s14, s11
	s_cselect_b32 s15, s16, s15
	s_cselect_b32 s14, s17, s14
	s_add_i32 s16, s15, 1
	s_cmp_ge_u32 s14, s11
	s_cselect_b32 s14, s16, s15
	s_xor_b32 s14, s14, s13
	s_sub_i32 s28, s14, s13
	s_mul_i32 s34, s28, s11
	s_add_i32 s14, s12, s10
	s_sub_i32 s27, s14, s34
	s_mulk_i32 s27, 0xfe
	s_lshl_b32 s10, s28, 8
	s_add_i32 s20, s27, -1
	s_ashr_i32 s11, s10, 31
	s_ashr_i32 s21, s20, 31
	s_lshl_b64 s[22:23], s[10:11], 11
	v_readlane_b32 s10, v253, 17
	v_readlane_b32 s11, v253, 18
	s_add_u32 s10, s10, s22
	s_addc_u32 s11, s11, s23
	s_lshl_b64 s[12:13], s[20:21], 11
	s_add_u32 s12, s90, s12
	v_ashrrev_i32_e32 v2, 3, v13
	s_waitcnt vmcnt(4)
	v_lshrrev_b32_e32 v15, 1, v2
	s_addc_u32 s13, s91, s13
	s_sub_i32 s15, 0xc001, s27
	v_xor_b32_e32 v0, v15, v13
	v_ashrrev_i32_e32 v3, 31, v2
	s_min_i32 s18, s15, 0x100
	v_lshlrev_b64 v[4:5], 11, v[2:3]
	v_lshlrev_b32_e32 v0, 4, v0
	s_cmp_eq_u32 s14, s34
	v_and_b32_e32 v10, 31, v13
	v_lshl_add_u64 v[6:7], s[12:13], 0, v[4:5]
	v_and_b32_e32 v0, 0x70, v0
	v_lshl_add_u64 v[8:9], s[10:11], 0, v[4:5]
	v_lshrrev_b32_e32 v16, 1, v13
	s_cselect_b64 s[14:15], -1, 0
	v_lshl_add_u64 v[6:7], v[6:7], 0, v[0:1]
	v_lshl_add_u64 v[8:9], v[8:9], 0, v[0:1]
	v_and_or_b32 v0, v16, s51, v10
	v_cndmask_b32_e64 v12, 0, 1, s[14:15]
	v_lshlrev_b32_e32 v175, 7, v0
	v_lshlrev_b32_e32 v0, 7, v13
	v_lshlrev_b32_e32 v177, 4, v13
	v_and_b32_e32 v176, 0x6f80, v0
	v_cmp_ge_i32_e64 s[10:11], v2, v12
	v_cmp_gt_i32_e64 s[12:13], s18, v2
	v_and_b32_e32 v0, 0x70, v177
	v_add_u32_e32 v178, 0x8000, v177
	v_lshl_add_u64 v[158:159], s[80:81], 0, v[0:1]
	s_and_b64 s[10:11], s[10:11], s[12:13]
	v_readfirstlane_b32 s12, v177
	v_cndmask_b32_e64 v11, v159, v7, s[10:11]
	v_cndmask_b32_e64 v10, v158, v6, s[10:11]
	s_mov_b32 m0, s12
	v_readfirstlane_b32 s12, v178
	v_add_u32_e32 v0, 64, v2
	s_barrier
	s_mov_b32 m0, s12
	v_cmp_ge_i32_e64 s[12:13], v0, v12
	v_cmp_gt_i32_e64 s[14:15], s18, v0
	s_mov_b64 s[16:17], 0x20000
	v_add_u32_e32 v0, 0x2000, v177
	v_lshl_add_u64 v[10:11], v[6:7], 0, s[16:17]
	s_and_b64 s[12:13], s[12:13], s[14:15]
	v_readfirstlane_b32 s14, v0
	v_add_u32_e32 v179, 0xa000, v177
	v_cndmask_b32_e64 v11, v159, v11, s[12:13]
	v_cndmask_b32_e64 v10, v158, v10, s[12:13]
	s_mov_b32 m0, s14
	v_readfirstlane_b32 s14, v179
	v_add_u32_e32 v3, 0x80, v2
	v_lshl_add_u64 v[10:11], v[8:9], 0, s[16:17]
	s_mov_b32 m0, s14
	v_cmp_ge_i32_e64 s[14:15], v3, v12
	v_cmp_gt_i32_e64 s[16:17], s18, v3
	s_mov_b64 s[38:39], 0x40000
	v_add_u32_e32 v180, 0x4000, v177
	v_lshl_add_u64 v[10:11], v[6:7], 0, s[38:39]
	s_and_b64 s[14:15], s[14:15], s[16:17]
	v_readfirstlane_b32 s16, v180
	v_add_u32_e32 v181, 0xc000, v177
	v_cndmask_b32_e64 v11, v159, v11, s[14:15]
	v_cndmask_b32_e64 v10, v158, v10, s[14:15]
	s_mov_b32 m0, s16
	v_readfirstlane_b32 s16, v181
	v_add_u32_e32 v2, 0xc0, v2
	v_lshl_add_u64 v[10:11], v[8:9], 0, s[38:39]
	s_mov_b32 m0, s16
	v_cmp_ge_i32_e64 s[16:17], v2, v12
	v_cmp_gt_i32_e64 s[18:19], s18, v2
	s_mov_b64 s[38:39], 0x60000
	v_add_u32_e32 v182, 0x6000, v177
	v_lshl_add_u64 v[2:3], v[6:7], 0, s[38:39]
	s_and_b64 s[16:17], s[16:17], s[18:19]
	v_readfirstlane_b32 s18, v182
	v_add_u32_e32 v183, 0xe000, v177
	v_cndmask_b32_e64 v3, v159, v3, s[16:17]
	v_cndmask_b32_e64 v2, v158, v2, s[16:17]
	s_mov_b32 m0, s18
	v_readfirstlane_b32 s18, v183
	v_lshl_add_u64 v[2:3], v[8:9], 0, s[38:39]
	s_mov_b32 m0, s18
	s_sub_i32 s18, s30, s34
	s_mulk_i32 s31, 0xa8
	v_bfe_u32 v14, v13, 5, 1
	s_sub_i32 s18, s18, s31
	v_bfe_u32 v17, v13, 1, 3
	v_bitop3_b32 v2, v16, v14, 7 bitop3:0x6c
	s_mulk_i32 s18, 0xfe
	v_lshlrev_b32_e32 v185, 4, v2
	v_bitop3_b32 v2, v14, v17, 2 bitop3:0x36
	s_add_i32 s18, s18, -2
	v_lshlrev_b32_e32 v186, 4, v2
	v_bitop3_b32 v2, v14, v17, 4 bitop3:0x36
	s_ashr_i32 s19, s18, 31
	v_lshlrev_b32_e32 v187, 4, v2
	v_bitop3_b32 v2, v14, v17, 6 bitop3:0x36
	s_lshl_b64 s[18:19], s[18:19], 11
	v_bitop3_b32 v6, v15, 7, v13 bitop3:0x48
	v_lshlrev_b32_e32 v188, 4, v2
	v_lshl_add_u64 v[2:3], v[4:5], 0, s[18:19]
	v_lshlrev_b32_e32 v6, 4, v6
	v_or_b32_e32 v2, v2, v6
	v_lshl_add_u64 v[160:161], s[70:71], 0, v[2:3]
	v_lshl_add_u64 v[2:3], v[4:5], 0, s[22:23]
	s_waitcnt vmcnt(0)
	v_or_b32_e32 v2, v2, v6
	v_lshl_add_u64 v[162:163], s[70:71], 0, v[2:3]
	v_mov_b32_e32 v130, 0
	v_mov_b32_e32 v2, 0
	s_mov_b32 s29, 1
	s_mov_b64 s[38:39], 0x3858900
	v_add_u32_e32 v189, 0x10000, v177
	v_add_u32_e32 v190, 0x18000, v177
	v_add_u32_e32 v191, 0x12000, v177
	v_add_u32_e32 v192, 0x1a000, v177
	v_add_u32_e32 v193, 0x14000, v177
	v_add_u32_e32 v194, 0x1c000, v177
	v_add_u32_e32 v195, 0x16000, v177
	v_add_u32_e32 v196, 0x1e000, v177
	v_add_u32_e32 v197, 0x10000, v175
	v_or_b32_e32 v198, 0x10000, v176
	s_mov_b64 s[18:19], 0
	v_mov_b32_e32 v3, v2
	v_mov_b32_e32 v4, v2
	v_mov_b32_e32 v5, v2
	v_mov_b32_e32 v6, v2
	v_mov_b32_e32 v7, v2
	v_mov_b32_e32 v8, v2
	v_mov_b32_e32 v9, v2
	v_mov_b32_e32 v10, v2
	v_mov_b32_e32 v11, v2
	v_mov_b32_e32 v12, v2
	v_mov_b32_e32 v13, v2
	v_mov_b32_e32 v14, v2
	v_mov_b32_e32 v15, v2
	v_mov_b32_e32 v16, v2
	v_mov_b32_e32 v17, v2
	s_waitcnt vmcnt(0)
; DI int opaque_tid() { int t = threadIdx.x; asm volatile("" : "+v"(t)); return t; }
; template <bool SWAP>
; DI void gemm_mainloop(f32x16 (&acc)[4][2], const u16* __restrict__ A, int lda, int rlo, int rhi,
;                       const u16* __restrict__ B, int ldb, int K, char* lds, const u16* zero_line) {
;   const int tid = opaque_tid(), lane = tid & 63, w = tid >> 6;
;   const int wm = w >> 2, wn = w & 3;
;   const int h = lane >> 5, r = lane & 31;
;   const int lr = tid >> 3, lc = tid & 7;
; #pragma unroll
;   for (int mi = 0; mi < 4; ++mi)
; #pragma unroll
;     for (int ni = 0; ni < 2; ++ni)
; #pragma unroll
;       for (int i = 0; i < 16; ++i) acc[mi][ni][i] = 0.f;
;   const int gch = (lc ^ ((lr >> 1) & 7)) * 8;
;   const u16* ap = A + (ptrdiff_t)lr * lda + gch;
;   const u16* bp = B + (ptrdiff_t)lr * ldb + gch;
;   const int nk = K >> 6;
;   typedef __attribute__((address_space(3))) unsigned lds_u32;
;   auto glds = [&](int kt, int st) {
;     char* as_ = lds + st * 65536 + tid * 16;
; #pragma unroll
;     for (int i = 0; i < 4; ++i) {
;       const int rr = lr + 64 * i;
;       const u16* srca = (rr >= rlo && rr < rhi) ? (ap + (ptrdiff_t)(64 * i) * lda + kt * 64) : (zero_line + lc * 8);
;       __builtin_amdgcn_global_load_lds((const unsigned*)srca, (lds_u32*)(as_ + i * 8192), 16, 0, 0);
;       __builtin_amdgcn_global_load_lds((const unsigned*)(bp + (ptrdiff_t)(64 * i) * ldb + kt * 64), (lds_u32*)(as_ + 32768 + i * 8192), 16, 0, 0);
;     }
;   };
;   const int sw = (r >> 1) & 7;
;   const int arow_off = (wm * 128 + r) * 128;
;   const int brow_off = 32768 + (wn * 64 + r) * 128;
;   __syncthreads();
;   glds(0, 0);
;   asm volatile("s_waitcnt vmcnt(0)" ::: "memory");
;   __syncthreads();
	v_mov_b32_e32 v18, v2
	v_mov_b32_e32 v19, v2
	v_mov_b32_e32 v20, v2
	v_mov_b32_e32 v21, v2
	v_mov_b32_e32 v22, v2
	v_mov_b32_e32 v23, v2
	v_mov_b32_e32 v24, v2
	v_mov_b32_e32 v25, v2
	v_mov_b32_e32 v26, v2
	v_mov_b32_e32 v27, v2
	v_mov_b32_e32 v28, v2
	v_mov_b32_e32 v29, v2
	v_mov_b32_e32 v30, v2
	v_mov_b32_e32 v31, v2
	v_mov_b32_e32 v32, v2
	v_mov_b32_e32 v33, v2
	v_mov_b32_e32 v34, v2
	v_mov_b32_e32 v35, v2
	v_mov_b32_e32 v36, v2
	v_mov_b32_e32 v37, v2
	v_mov_b32_e32 v38, v2
	v_mov_b32_e32 v39, v2
	v_mov_b32_e32 v40, v2
	v_mov_b32_e32 v41, v2
	v_mov_b32_e32 v42, v2
	v_mov_b32_e32 v43, v2
	v_mov_b32_e32 v44, v2
	v_mov_b32_e32 v45, v2
	v_mov_b32_e32 v46, v2
	v_mov_b32_e32 v47, v2
	v_mov_b32_e32 v48, v2
	v_mov_b32_e32 v49, v2
	v_mov_b32_e32 v50, v2
	v_mov_b32_e32 v51, v2
	v_mov_b32_e32 v52, v2
	v_mov_b32_e32 v53, v2
	v_mov_b32_e32 v54, v2
	v_mov_b32_e32 v55, v2
	v_mov_b32_e32 v56, v2
	v_mov_b32_e32 v57, v2
	v_mov_b32_e32 v58, v2
	v_mov_b32_e32 v59, v2
	v_mov_b32_e32 v60, v2
	v_mov_b32_e32 v61, v2
	v_mov_b32_e32 v62, v2
	v_mov_b32_e32 v63, v2
	v_mov_b32_e32 v64, v2
	v_mov_b32_e32 v65, v2
	v_mov_b32_e32 v66, v2
	v_mov_b32_e32 v67, v2
	v_mov_b32_e32 v68, v2
	v_mov_b32_e32 v69, v2
	v_mov_b32_e32 v70, v2
	v_mov_b32_e32 v71, v2
	v_mov_b32_e32 v72, v2
	v_mov_b32_e32 v73, v2
	v_mov_b32_e32 v74, v2
	v_mov_b32_e32 v75, v2
	v_mov_b32_e32 v76, v2
	v_mov_b32_e32 v77, v2
	v_mov_b32_e32 v78, v2
	v_mov_b32_e32 v79, v2
	v_mov_b32_e32 v80, v2
	v_mov_b32_e32 v81, v2
	v_mov_b32_e32 v82, v2
	v_mov_b32_e32 v83, v2
	v_mov_b32_e32 v84, v2
	v_mov_b32_e32 v85, v2
	v_mov_b32_e32 v86, v2
	v_mov_b32_e32 v87, v2
	v_mov_b32_e32 v88, v2
	v_mov_b32_e32 v89, v2
	v_mov_b32_e32 v90, v2
	v_mov_b32_e32 v91, v2
	v_mov_b32_e32 v92, v2
	v_mov_b32_e32 v93, v2
	v_mov_b32_e32 v94, v2
	v_mov_b32_e32 v95, v2
	v_mov_b32_e32 v96, v2
	v_mov_b32_e32 v97, v2
	v_mov_b32_e32 v98, v2
	v_mov_b32_e32 v99, v2
	v_mov_b32_e32 v100, v2
	v_mov_b32_e32 v101, v2
	v_mov_b32_e32 v102, v2
	v_mov_b32_e32 v103, v2
	v_mov_b32_e32 v104, v2
	v_mov_b32_e32 v105, v2
	v_mov_b32_e32 v106, v2
	v_mov_b32_e32 v107, v2
	v_mov_b32_e32 v108, v2
	v_mov_b32_e32 v109, v2
	v_mov_b32_e32 v110, v2
	v_mov_b32_e32 v111, v2
	v_mov_b32_e32 v112, v2
	v_mov_b32_e32 v113, v2
	v_mov_b32_e32 v114, v2
	v_mov_b32_e32 v115, v2
	v_mov_b32_e32 v116, v2
	v_mov_b32_e32 v117, v2
	v_mov_b32_e32 v118, v2
	v_mov_b32_e32 v119, v2
	v_mov_b32_e32 v120, v2
	v_mov_b32_e32 v121, v2
	v_mov_b32_e32 v122, v2
	v_mov_b32_e32 v123, v2
	v_mov_b32_e32 v124, v2
	v_mov_b32_e32 v125, v2
	v_mov_b32_e32 v126, v2
	v_mov_b32_e32 v127, v2
	v_mov_b32_e32 v128, v2
	v_mov_b32_e32 v129, v2
	v_mov_b32_e32 v131, v130
	v_mov_b32_e32 v132, v130
	v_mov_b32_e32 v133, v130
	v_mov_b32_e32 v134, v130
	v_mov_b32_e32 v135, v130
	v_mov_b32_e32 v136, v130
	v_mov_b32_e32 v137, v130
	v_mov_b32_e32 v138, v130
	v_mov_b32_e32 v139, v130
	v_mov_b32_e32 v140, v130
	v_mov_b32_e32 v141, v130
	v_mov_b32_e32 v142, v130
	v_mov_b32_e32 v143, v130
	v_mov_b32_e32 v144, v130
	v_mov_b32_e32 v145, v130
	v_mov_b32_e32 v146, v130
	v_mov_b32_e32 v147, v130
	v_mov_b32_e32 v148, v130
	v_mov_b32_e32 v149, v130
	v_mov_b32_e32 v150, v130
	v_mov_b32_e32 v151, v130
	v_mov_b32_e32 v152, v130
	v_mov_b32_e32 v153, v130
	s_mov_b64 s[30:31], 0x37f8900
	s_waitcnt vmcnt(0) lgkmcnt(0)
	s_barrier
	s_add_i32 s18, s27, -1
	s_ashr_i32 s19, s18, 31
	s_lshl_b64 s[18:19], s[18:19], 11
	s_add_u32 s18, s90, s18
	s_addc_u32 s19, s91, s19
	v_readlane_b32 s22, v253, 17
	v_readlane_b32 s23, v253, 18
	s_lshl_b32 s21, s28, 19
	s_add_u32 s22, s22, s21
	s_addc_u32 s23, s23, 0
	v_and_b32_e32 v130, 63, v204
	v_lshrrev_b32_e32 v131, 6, v204
	v_lshrrev_b32_e32 v132, 3, v204
	v_lshrrev_b32_e32 v0, 4, v130
	v_lshl_add_u32 v0, v131, 2, v0
	v_xor_b32_e32 v0, v0, v130
	v_and_b32_e32 v0, 7, v0
	v_lshlrev_b32_e32 v133, 4, v0
	v_lshl_add_u32 v236, v132, 11, v133
	v_add_u32_e32 v237, 0x20000, v236
	v_add_u32_e32 v238, 0x40000, v236
	v_add_u32_e32 v239, 0x60000, v236
	v_and_b32_e32 v0, 31, v132
	v_lshrrev_b32_e32 v130, 5, v132
	v_lshl_add_u32 v0, v130, 6, v0
	v_lshl_add_u32 v240, v0, 11, v133
	v_add_u32_e32 v241, 0x10000, v240
	v_add_u32_e32 v242, 0x40000, v240
	v_add_u32_e32 v243, 0x50000, v240
	v_and_b32_e32 v132, 31, v204
	v_lshrrev_b32_e32 v0, 2, v131
	v_lshl_add_u32 v0, v0, 6, v132
	v_lshlrev_b32_e32 v248, 7, v0
	v_and_b32_e32 v0, 3, v131
	v_lshl_add_u32 v0, v0, 5, v132
	v_lshlrev_b32_e32 v249, 7, v0
	v_bfe_u32 v0, v204, 5, 1
	v_bfe_u32 v130, v132, 1, 3
	v_or_b32_e32 v133, 0, v0
	v_xor_b32_e32 v133, v133, v130
	v_lshlrev_b32_e32 v244, 4, v133
	v_or_b32_e32 v133, 2, v0
	v_xor_b32_e32 v133, v133, v130
	v_lshlrev_b32_e32 v245, 4, v133
	v_or_b32_e32 v133, 4, v0
	v_xor_b32_e32 v133, v133, v130
	v_lshlrev_b32_e32 v246, 4, v133
	v_or_b32_e32 v133, 6, v0
	v_xor_b32_e32 v133, v133, v130
	v_lshlrev_b32_e32 v247, 4, v133
	v_add_u32_e32 v202, v249, v244
	v_add_u32_e32 v203, v249, v245
	v_add_u32_e32 v175, v249, v246
	v_add_u32_e32 v185, v249, v247
	v_add_u32_e32 v244, v248, v244
	v_add_u32_e32 v245, v248, v245
	v_add_u32_e32 v246, v248, v246
	v_add_u32_e32 v247, v248, v247
	v_lshlrev_b32_e32 v131, 10, v131
	s_nop 0
	v_readfirstlane_b32 s100, v131
	v_mov_b32_e32 v146, 0
	v_mov_b32_e32 v147, 0
	v_mov_b32_e32 v148, 0
	v_mov_b32_e32 v149, 0
	v_lshlrev_b32_e32 v130, 4, v204
	v_add_u32_e32 v132, 0x10000, v130
	s_not_b64 exec, s[10:11]
	ds_write_b128 v130, v[146:149]
	ds_write_b128 v132, v[146:149]
	s_not_b64 exec, s[12:13]
	ds_write_b128 v130, v[146:149] offset:16384
	ds_write_b128 v132, v[146:149] offset:16384
	s_not_b64 exec, s[14:15]
	ds_write_b128 v130, v[146:149] offset:8192
	ds_write_b128 v132, v[146:149] offset:8192
	s_not_b64 exec, s[16:17]
	ds_write_b128 v130, v[146:149] offset:24576
	ds_write_b128 v132, v[146:149] offset:24576
	s_mov_b64 exec, -1
	s_mov_b32 s29, 0
	s_mov_b32 s21, 0x10000
	s_waitcnt lgkmcnt(0)
	s_cmp_eq_u32 s27, 0
	s_cbranch_scc1 .Lg8_u0_msk
	s_cmp_gt_i32 s20, 0xbf00
	s_cbranch_scc1 .Lg8_u0_msk
	s_add_u32 m0, s100, 0x8000
	s_nop 0
	global_load_lds_dwordx4 v240, s[22:23]
	v_add_u32_e32 v240, 0x80, v240
	s_add_u32 m0, s100, 0xa000
	s_nop 0
	global_load_lds_dwordx4 v242, s[22:23]
	v_add_u32_e32 v242, 0x80, v242
	s_add_u32 m0, s100, 0x0
	s_nop 0
	global_load_lds_dwordx4 v236, s[18:19]
	v_add_u32_e32 v236, 0x80, v236
	s_add_u32 m0, s100, 0x2000
	s_nop 0
	global_load_lds_dwordx4 v238, s[18:19]
	v_add_u32_e32 v238, 0x80, v238
	s_add_u32 m0, s100, 0xc000
	s_nop 0
	global_load_lds_dwordx4 v241, s[22:23]
	v_add_u32_e32 v241, 0x80, v241
	s_add_u32 m0, s100, 0xe000
	s_nop 0
	global_load_lds_dwordx4 v243, s[22:23]
	v_add_u32_e32 v243, 0x80, v243
	s_add_u32 m0, s100, 0x4000
	s_nop 0
	global_load_lds_dwordx4 v237, s[18:19]
	v_add_u32_e32 v237, 0x80, v237
	s_add_u32 m0, s100, 0x6000
	s_nop 0
	global_load_lds_dwordx4 v239, s[18:19]
	v_add_u32_e32 v239, 0x80, v239
	s_cmp_eq_u32 s101, 1
	s_cbranch_scc0 .Lg8_u0u_p0
	s_barrier
; #define MFMA(a, b, c) __builtin_amdgcn_mfma_f32_32x32x16_bf16((a), (b), (c), 0, 0, 0)
; template <bool SWAP>
; DI void gemm_mainloop(f32x16 (&acc)[4][2], const u16* __restrict__ A, int lda, int rlo, int rhi,
;                       const u16* __restrict__ B, int ldb, int K, char* lds, const u16* zero_line) {
;     ...
;   auto ldfrag = [&](const char* st, int ks, int buf) {
;     const int co = ((2 * ks + h) ^ sw) << 4;
; #pragma unroll
;     for (int mi = 0; mi < 4; ++mi) fa[buf][mi] = *(const bf16x8*)(st + arow_off + mi * 4096 + co);
; #pragma unroll
;     for (int ni = 0; ni < 2; ++ni) fb[buf][ni] = *(const bf16x8*)(st + brow_off + ni * 4096 + co);
;   };
;   auto mma = [&](int buf) {
; #pragma unroll
;     for (int mi = 0; mi < 4; ++mi)
; #pragma unroll
;       for (int ni = 0; ni < 2; ++ni)
;         acc[mi][ni] = SWAP ? MFMA(fb[buf][ni], fa[buf][mi], acc[mi][ni]) : MFMA(fa[buf][mi], fb[buf][ni], acc[mi][ni]);
;   };
;   auto pat_rd = [&]() {
; #pragma unroll
;     for (int g = 0; g < 6; ++g) {
;       __builtin_amdgcn_sched_group_barrier(0x100, 1, 0);
;       __builtin_amdgcn_sched_group_barrier(0x008, 1, 0);
;     }
;     __builtin_amdgcn_sched_group_barrier(0x008, 2, 0);
;   };
; #pragma unroll 2
;   for (int kt = 0; kt < nk; ++kt) {
;     const char* st = lds + (kt & 1) * 65536;
;     ldfrag(st, 0, 0);
;     mma(1);
;     pat_rd();
;     if (kt + 1 < nk) glds(kt + 1, (kt + 1) & 1);
;     ldfrag(st, 1, 1);
;     mma(0);
;     pat_rd();
;     ldfrag(st, 2, 0);
;     mma(1);
;     pat_rd();
;     ldfrag(st, 3, 1);
;     mma(0);
;     pat_rd();
;     asm volatile("s_waitcnt vmcnt(0)" ::: "memory");
;     __syncthreads();
;   }
.Lg8_u0u_p0:
	s_waitcnt vmcnt(4)
	s_barrier
	s_add_u32 m0, s100, 0x18000
	s_nop 0
	global_load_lds_dwordx4 v240, s[22:23]
	v_add_u32_e32 v240, 0x80, v240
	s_add_u32 m0, s100, 0x1a000
	s_nop 0
	global_load_lds_dwordx4 v242, s[22:23]
	v_add_u32_e32 v242, 0x80, v242
	s_add_u32 m0, s100, 0x10000
	s_nop 0
	global_load_lds_dwordx4 v236, s[18:19]
	v_add_u32_e32 v236, 0x80, v236
	s_add_u32 m0, s100, 0x12000
	s_nop 0
	global_load_lds_dwordx4 v238, s[18:19]
	v_add_u32_e32 v238, 0x80, v238
	s_add_u32 m0, s100, 0x1c000
	s_nop 0
	global_load_lds_dwordx4 v241, s[22:23]
	v_add_u32_e32 v241, 0x80, v241
	s_add_u32 m0, s100, 0x1e000
	s_nop 0
	global_load_lds_dwordx4 v243, s[22:23]
	v_add_u32_e32 v243, 0x80, v243
	s_waitcnt vmcnt(6)
	s_barrier
	ds_read_b128 v[176:179], v202 offset:32768
	ds_read_b128 v[180:183], v203 offset:32768
	ds_read_b128 v[186:189], v175 offset:32768
	ds_read_b128 v[190:193], v185 offset:32768
.Lg8_u0u:
	ds_read_b128 v[130:133], v244
	ds_read_b128 v[134:137], v245
	ds_read_b128 v[138:141], v246
	ds_read_b128 v[142:145], v247
	ds_read_b128 v[146:149], v244 offset:4096
	ds_read_b128 v[150:153], v245 offset:4096
	ds_read_b128 v[158:161], v246 offset:4096
	ds_read_b128 v[162:165], v247 offset:4096
	s_add_u32 m0, s100, 0x14000
	s_nop 0
	global_load_lds_dwordx4 v237, s[18:19]
	v_add_u32_e32 v237, 0x80, v237
	s_add_u32 m0, s100, 0x16000
	s_nop 0
	global_load_lds_dwordx4 v239, s[18:19]
	v_add_u32_e32 v239, 0x80, v239
	s_barrier
	s_waitcnt lgkmcnt(0)
	v_mfma_f32_32x32x16_bf16 v[114:129], v[176:179], v[130:133], v[114:129]
	v_mfma_f32_32x32x16_bf16 v[82:97], v[176:179], v[146:149], v[82:97]
	v_mfma_f32_32x32x16_bf16 v[114:129], v[180:183], v[134:137], v[114:129]
	v_mfma_f32_32x32x16_bf16 v[82:97], v[180:183], v[150:153], v[82:97]
	v_mfma_f32_32x32x16_bf16 v[114:129], v[186:189], v[138:141], v[114:129]
	v_mfma_f32_32x32x16_bf16 v[82:97], v[186:189], v[158:161], v[82:97]
	v_mfma_f32_32x32x16_bf16 v[114:129], v[190:193], v[142:145], v[114:129]
	v_mfma_f32_32x32x16_bf16 v[82:97], v[190:193], v[162:165], v[82:97]
	s_barrier
	ds_read_b128 v[194:197], v202 offset:49152
	ds_read_b128 v[198:201], v203 offset:49152
	ds_read_b128 v[228:231], v175 offset:49152
	ds_read_b128 v[232:235], v185 offset:49152
	s_add_u32 m0, s100, 0x8000
	s_nop 0
	global_load_lds_dwordx4 v240, s[22:23]
	v_add_u32_e32 v240, 0x80, v240
	s_add_u32 m0, s100, 0xa000
	s_nop 0
	global_load_lds_dwordx4 v242, s[22:23]
	v_add_u32_e32 v242, 0x80, v242
	s_barrier
	s_waitcnt lgkmcnt(0)
	v_mfma_f32_32x32x16_bf16 v[98:113], v[194:197], v[130:133], v[98:113]
	v_mfma_f32_32x32x16_bf16 v[66:81], v[194:197], v[146:149], v[66:81]
	v_mfma_f32_32x32x16_bf16 v[98:113], v[198:201], v[134:137], v[98:113]
	v_mfma_f32_32x32x16_bf16 v[66:81], v[198:201], v[150:153], v[66:81]
	v_mfma_f32_32x32x16_bf16 v[98:113], v[228:231], v[138:141], v[98:113]
	v_mfma_f32_32x32x16_bf16 v[66:81], v[228:231], v[158:161], v[66:81]
	v_mfma_f32_32x32x16_bf16 v[98:113], v[232:235], v[142:145], v[98:113]
	v_mfma_f32_32x32x16_bf16 v[66:81], v[232:235], v[162:165], v[66:81]
	s_barrier
	ds_read_b128 v[130:133], v244 offset:16384
	ds_read_b128 v[134:137], v245 offset:16384
	ds_read_b128 v[138:141], v246 offset:16384
	ds_read_b128 v[142:145], v247 offset:16384
	ds_read_b128 v[146:149], v244 offset:20480
	ds_read_b128 v[150:153], v245 offset:20480
	ds_read_b128 v[158:161], v246 offset:20480
	ds_read_b128 v[162:165], v247 offset:20480
	s_add_u32 m0, s100, 0x0
	s_nop 0
	global_load_lds_dwordx4 v236, s[18:19]
	v_add_u32_e32 v236, 0x80, v236
	s_add_u32 m0, s100, 0x2000
	s_nop 0
	global_load_lds_dwordx4 v238, s[18:19]
	v_add_u32_e32 v238, 0x80, v238
	s_waitcnt vmcnt(10)
	s_barrier
	s_waitcnt lgkmcnt(0)
	v_mfma_f32_32x32x16_bf16 v[50:65], v[176:179], v[130:133], v[50:65]
	v_mfma_f32_32x32x16_bf16 v[18:33], v[176:179], v[146:149], v[18:33]
	v_mfma_f32_32x32x16_bf16 v[50:65], v[180:183], v[134:137], v[50:65]
	v_mfma_f32_32x32x16_bf16 v[18:33], v[180:183], v[150:153], v[18:33]
	v_mfma_f32_32x32x16_bf16 v[50:65], v[186:189], v[138:141], v[50:65]
	v_mfma_f32_32x32x16_bf16 v[18:33], v[186:189], v[158:161], v[18:33]
	v_mfma_f32_32x32x16_bf16 v[50:65], v[190:193], v[142:145], v[50:65]
	v_mfma_f32_32x32x16_bf16 v[18:33], v[190:193], v[162:165], v[18:33]
	s_barrier
	v_add_u32_e32 v166, s21, v202
	v_add_u32_e32 v167, s21, v203
	ds_read_b128 v[176:179], v166 offset:32768
	ds_read_b128 v[180:183], v167 offset:32768
	v_add_u32_e32 v166, s21, v175
	v_add_u32_e32 v167, s21, v185
	ds_read_b128 v[186:189], v166 offset:32768
	ds_read_b128 v[190:193], v167 offset:32768
	s_add_u32 m0, s100, 0xc000
	s_nop 0
	global_load_lds_dwordx4 v241, s[22:23]
	v_add_u32_e32 v241, 0x80, v241
	s_add_u32 m0, s100, 0xe000
	s_nop 0
	global_load_lds_dwordx4 v243, s[22:23]
	v_add_u32_e32 v243, 0x80, v243
	s_waitcnt vmcnt(6)
	s_barrier
	s_waitcnt lgkmcnt(0)
	v_mfma_f32_32x32x16_bf16 v[34:49], v[194:197], v[130:133], v[34:49]
	v_mfma_f32_32x32x16_bf16 v[2:17], v[194:197], v[146:149], v[2:17]
	v_mfma_f32_32x32x16_bf16 v[34:49], v[198:201], v[134:137], v[34:49]
	v_mfma_f32_32x32x16_bf16 v[2:17], v[198:201], v[150:153], v[2:17]
	v_mfma_f32_32x32x16_bf16 v[34:49], v[228:231], v[138:141], v[34:49]
	v_mfma_f32_32x32x16_bf16 v[2:17], v[228:231], v[158:161], v[2:17]
	v_mfma_f32_32x32x16_bf16 v[34:49], v[232:235], v[142:145], v[34:49]
	v_mfma_f32_32x32x16_bf16 v[2:17], v[232:235], v[162:165], v[2:17]
	s_barrier
; #define MFMA(a, b, c) __builtin_amdgcn_mfma_f32_32x32x16_bf16((a), (b), (c), 0, 0, 0)
; template <bool SWAP>
; DI void gemm_mainloop(f32x16 (&acc)[4][2], const u16* __restrict__ A, int lda, int rlo, int rhi,
;                       const u16* __restrict__ B, int ldb, int K, char* lds, const u16* zero_line) {
;     ...
;   auto ldfrag = [&](const char* st, int ks, int buf) {
;     const int co = ((2 * ks + h) ^ sw) << 4;
; #pragma unroll
;     for (int mi = 0; mi < 4; ++mi) fa[buf][mi] = *(const bf16x8*)(st + arow_off + mi * 4096 + co);
; #pragma unroll
;     for (int ni = 0; ni < 2; ++ni) fb[buf][ni] = *(const bf16x8*)(st + brow_off + ni * 4096 + co);
;   };
;   auto mma = [&](int buf) {
; #pragma unroll
;     for (int mi = 0; mi < 4; ++mi)
; #pragma unroll
;       for (int ni = 0; ni < 2; ++ni)
;         acc[mi][ni] = SWAP ? MFMA(fb[buf][ni], fa[buf][mi], acc[mi][ni]) : MFMA(fa[buf][mi], fb[buf][ni], acc[mi][ni]);
;   };
;   auto pat_rd = [&]() {
; #pragma unroll
;     for (int g = 0; g < 6; ++g) {
;       __builtin_amdgcn_sched_group_barrier(0x100, 1, 0);
;       __builtin_amdgcn_sched_group_barrier(0x008, 1, 0);
;     }
;     __builtin_amdgcn_sched_group_barrier(0x008, 2, 0);
;   };
; #pragma unroll 2
;   for (int kt = 0; kt < nk; ++kt) {
;     const char* st = lds + (kt & 1) * 65536;
;     ldfrag(st, 0, 0);
;     mma(1);
;     pat_rd();
;     if (kt + 1 < nk) glds(kt + 1, (kt + 1) & 1);
;     ldfrag(st, 1, 1);
;     mma(0);
;     pat_rd();
;     ldfrag(st, 2, 0);
;     mma(1);
;     pat_rd();
;     ldfrag(st, 3, 1);
;     mma(0);
;     pat_rd();
;     asm volatile("s_waitcnt vmcnt(0)" ::: "memory");
;     __syncthreads();
;   }
	v_add_u32_e32 v166, s21, v244
	v_add_u32_e32 v167, s21, v245
	ds_read_b128 v[130:133], v166
	ds_read_b128 v[134:137], v167
	ds_read_b128 v[146:149], v166 offset:4096
	ds_read_b128 v[150:153], v167 offset:4096
	v_add_u32_e32 v166, s21, v246
	v_add_u32_e32 v167, s21, v247
	ds_read_b128 v[138:141], v166
	ds_read_b128 v[142:145], v167
	ds_read_b128 v[158:161], v166 offset:4096
	ds_read_b128 v[162:165], v167 offset:4096
	s_add_u32 m0, s100, 0x4000
	s_nop 0
	global_load_lds_dwordx4 v237, s[18:19]
	v_add_u32_e32 v237, 0x80, v237
	s_add_u32 m0, s100, 0x6000
	s_nop 0
	global_load_lds_dwordx4 v239, s[18:19]
	v_add_u32_e32 v239, 0x80, v239
	s_barrier
	s_waitcnt lgkmcnt(0)
	v_mfma_f32_32x32x16_bf16 v[114:129], v[176:179], v[130:133], v[114:129]
	v_mfma_f32_32x32x16_bf16 v[82:97], v[176:179], v[146:149], v[82:97]
	v_mfma_f32_32x32x16_bf16 v[114:129], v[180:183], v[134:137], v[114:129]
	v_mfma_f32_32x32x16_bf16 v[82:97], v[180:183], v[150:153], v[82:97]
	v_mfma_f32_32x32x16_bf16 v[114:129], v[186:189], v[138:141], v[114:129]
	v_mfma_f32_32x32x16_bf16 v[82:97], v[186:189], v[158:161], v[82:97]
	v_mfma_f32_32x32x16_bf16 v[114:129], v[190:193], v[142:145], v[114:129]
	v_mfma_f32_32x32x16_bf16 v[82:97], v[190:193], v[162:165], v[82:97]
	s_barrier
	v_add_u32_e32 v166, s21, v202
	v_add_u32_e32 v167, s21, v203
	ds_read_b128 v[194:197], v166 offset:49152
	ds_read_b128 v[198:201], v167 offset:49152
	v_add_u32_e32 v166, s21, v175
	v_add_u32_e32 v167, s21, v185
	ds_read_b128 v[228:231], v166 offset:49152
	ds_read_b128 v[232:235], v167 offset:49152
	s_add_u32 m0, s100, 0x18000
	s_nop 0
	global_load_lds_dwordx4 v240, s[22:23]
	v_add_u32_e32 v240, 0x80, v240
	s_add_u32 m0, s100, 0x1a000
	s_nop 0
	global_load_lds_dwordx4 v242, s[22:23]
	v_add_u32_e32 v242, 0x80, v242
	s_barrier
	s_waitcnt lgkmcnt(0)
	v_mfma_f32_32x32x16_bf16 v[98:113], v[194:197], v[130:133], v[98:113]
	v_mfma_f32_32x32x16_bf16 v[66:81], v[194:197], v[146:149], v[66:81]
	v_mfma_f32_32x32x16_bf16 v[98:113], v[198:201], v[134:137], v[98:113]
	v_mfma_f32_32x32x16_bf16 v[66:81], v[198:201], v[150:153], v[66:81]
	v_mfma_f32_32x32x16_bf16 v[98:113], v[228:231], v[138:141], v[98:113]
	v_mfma_f32_32x32x16_bf16 v[66:81], v[228:231], v[158:161], v[66:81]
	v_mfma_f32_32x32x16_bf16 v[98:113], v[232:235], v[142:145], v[98:113]
	v_mfma_f32_32x32x16_bf16 v[66:81], v[232:235], v[162:165], v[66:81]
	s_barrier
	v_add_u32_e32 v166, s21, v244
	v_add_u32_e32 v167, s21, v245
	ds_read_b128 v[130:133], v166 offset:16384
	ds_read_b128 v[134:137], v167 offset:16384
	ds_read_b128 v[146:149], v166 offset:20480
	ds_read_b128 v[150:153], v167 offset:20480
	v_add_u32_e32 v166, s21, v246
	v_add_u32_e32 v167, s21, v247
	ds_read_b128 v[138:141], v166 offset:16384
	ds_read_b128 v[142:145], v167 offset:16384
	ds_read_b128 v[158:161], v166 offset:20480
	ds_read_b128 v[162:165], v167 offset:20480
	s_add_u32 m0, s100, 0x10000
	s_nop 0
	global_load_lds_dwordx4 v236, s[18:19]
	v_add_u32_e32 v236, 0x80, v236
	s_add_u32 m0, s100, 0x12000
	s_nop 0
	global_load_lds_dwordx4 v238, s[18:19]
	v_add_u32_e32 v238, 0x80, v238
	s_waitcnt vmcnt(10)
	s_barrier
	s_waitcnt lgkmcnt(0)
	v_mfma_f32_32x32x16_bf16 v[50:65], v[176:179], v[130:133], v[50:65]
	v_mfma_f32_32x32x16_bf16 v[18:33], v[176:179], v[146:149], v[18:33]
	v_mfma_f32_32x32x16_bf16 v[50:65], v[180:183], v[134:137], v[50:65]
	v_mfma_f32_32x32x16_bf16 v[18:33], v[180:183], v[150:153], v[18:33]
	v_mfma_f32_32x32x16_bf16 v[50:65], v[186:189], v[138:141], v[50:65]
	v_mfma_f32_32x32x16_bf16 v[18:33], v[186:189], v[158:161], v[18:33]
	v_mfma_f32_32x32x16_bf16 v[50:65], v[190:193], v[142:145], v[50:65]
	v_mfma_f32_32x32x16_bf16 v[18:33], v[190:193], v[162:165], v[18:33]
	s_barrier
	ds_read_b128 v[176:179], v202 offset:32768
	ds_read_b128 v[180:183], v203 offset:32768
	ds_read_b128 v[186:189], v175 offset:32768
	ds_read_b128 v[190:193], v185 offset:32768
	s_add_u32 m0, s100, 0x1c000
	s_nop 0
	global_load_lds_dwordx4 v241, s[22:23]
	v_add_u32_e32 v241, 0x80, v241
	s_add_u32 m0, s100, 0x1e000
	s_nop 0
	global_load_lds_dwordx4 v243, s[22:23]
	v_add_u32_e32 v243, 0x80, v243
	s_waitcnt vmcnt(6)
	s_barrier
	s_waitcnt lgkmcnt(0)
	v_mfma_f32_32x32x16_bf16 v[34:49], v[194:197], v[130:133], v[34:49]
	v_mfma_f32_32x32x16_bf16 v[2:17], v[194:197], v[146:149], v[2:17]
	v_mfma_f32_32x32x16_bf16 v[34:49], v[198:201], v[134:137], v[34:49]
	v_mfma_f32_32x32x16_bf16 v[2:17], v[198:201], v[150:153], v[2:17]
	v_mfma_f32_32x32x16_bf16 v[34:49], v[228:231], v[138:141], v[34:49]
	v_mfma_f32_32x32x16_bf16 v[2:17], v[228:231], v[158:161], v[2:17]
	v_mfma_f32_32x32x16_bf16 v[34:49], v[232:235], v[142:145], v[34:49]
	v_mfma_f32_32x32x16_bf16 v[2:17], v[232:235], v[162:165], v[2:17]
	s_barrier
	s_add_i32 s29, s29, 2
	s_cmp_lt_u32 s29, 14
	s_cbranch_scc1 .Lg8_u0u
	ds_read_b128 v[130:133], v244
	ds_read_b128 v[134:137], v245
	ds_read_b128 v[138:141], v246
	ds_read_b128 v[142:145], v247
	ds_read_b128 v[146:149], v244 offset:4096
	ds_read_b128 v[150:153], v245 offset:4096
	ds_read_b128 v[158:161], v246 offset:4096
	ds_read_b128 v[162:165], v247 offset:4096
	s_add_u32 m0, s100, 0x14000
	s_nop 0
	global_load_lds_dwordx4 v237, s[18:19]
	v_add_u32_e32 v237, 0x80, v237
	s_add_u32 m0, s100, 0x16000
	s_nop 0
	global_load_lds_dwordx4 v239, s[18:19]
	v_add_u32_e32 v239, 0x80, v239
	s_barrier
	s_waitcnt lgkmcnt(0)
	v_mfma_f32_32x32x16_bf16 v[114:129], v[176:179], v[130:133], v[114:129]
	v_mfma_f32_32x32x16_bf16 v[82:97], v[176:179], v[146:149], v[82:97]
	v_mfma_f32_32x32x16_bf16 v[114:129], v[180:183], v[134:137], v[114:129]
	v_mfma_f32_32x32x16_bf16 v[82:97], v[180:183], v[150:153], v[82:97]
	v_mfma_f32_32x32x16_bf16 v[114:129], v[186:189], v[138:141], v[114:129]
	v_mfma_f32_32x32x16_bf16 v[82:97], v[186:189], v[158:161], v[82:97]
	v_mfma_f32_32x32x16_bf16 v[114:129], v[190:193], v[142:145], v[114:129]
	v_mfma_f32_32x32x16_bf16 v[82:97], v[190:193], v[162:165], v[82:97]
	s_barrier
; #define MFMA(a, b, c) __builtin_amdgcn_mfma_f32_32x32x16_bf16((a), (b), (c), 0, 0, 0)
; template <bool SWAP>
; DI void gemm_mainloop(f32x16 (&acc)[4][2], const u16* __restrict__ A, int lda, int rlo, int rhi,
;                       const u16* __restrict__ B, int ldb, int K, char* lds, const u16* zero_line) {
;     ...
;   auto ldfrag = [&](const char* st, int ks, int buf) {
;     const int co = ((2 * ks + h) ^ sw) << 4;
; #pragma unroll
;     for (int mi = 0; mi < 4; ++mi) fa[buf][mi] = *(const bf16x8*)(st + arow_off + mi * 4096 + co);
; #pragma unroll
;     for (int ni = 0; ni < 2; ++ni) fb[buf][ni] = *(const bf16x8*)(st + brow_off + ni * 4096 + co);
;   };
;   auto mma = [&](int buf) {
; #pragma unroll
;     for (int mi = 0; mi < 4; ++mi)
; #pragma unroll
;       for (int ni = 0; ni < 2; ++ni)
;         acc[mi][ni] = SWAP ? MFMA(fb[buf][ni], fa[buf][mi], acc[mi][ni]) : MFMA(fa[buf][mi], fb[buf][ni], acc[mi][ni]);
;   };
;   auto pat_rd = [&]() {
; #pragma unroll
;     for (int g = 0; g < 6; ++g) {
;       __builtin_amdgcn_sched_group_barrier(0x100, 1, 0);
;       __builtin_amdgcn_sched_group_barrier(0x008, 1, 0);
;     }
;     __builtin_amdgcn_sched_group_barrier(0x008, 2, 0);
;   };
; #pragma unroll 2
;   for (int kt = 0; kt < nk; ++kt) {
;     const char* st = lds + (kt & 1) * 65536;
;     ldfrag(st, 0, 0);
;     mma(1);
;     pat_rd();
;     if (kt + 1 < nk) glds(kt + 1, (kt + 1) & 1);
;     ldfrag(st, 1, 1);
;     mma(0);
;     pat_rd();
;     ldfrag(st, 2, 0);
;     mma(1);
;     pat_rd();
;     ldfrag(st, 3, 1);
;     mma(0);
;     pat_rd();
;     asm volatile("s_waitcnt vmcnt(0)" ::: "memory");
;     __syncthreads();
;   }
;   mma(1);
	ds_read_b128 v[194:197], v202 offset:49152
	ds_read_b128 v[198:201], v203 offset:49152
	ds_read_b128 v[228:231], v175 offset:49152
	ds_read_b128 v[232:235], v185 offset:49152
	s_barrier
	s_waitcnt lgkmcnt(0)
	v_mfma_f32_32x32x16_bf16 v[98:113], v[194:197], v[130:133], v[98:113]
	v_mfma_f32_32x32x16_bf16 v[66:81], v[194:197], v[146:149], v[66:81]
	v_mfma_f32_32x32x16_bf16 v[98:113], v[198:201], v[134:137], v[98:113]
	v_mfma_f32_32x32x16_bf16 v[66:81], v[198:201], v[150:153], v[66:81]
	v_mfma_f32_32x32x16_bf16 v[98:113], v[228:231], v[138:141], v[98:113]
	v_mfma_f32_32x32x16_bf16 v[66:81], v[228:231], v[158:161], v[66:81]
	v_mfma_f32_32x32x16_bf16 v[98:113], v[232:235], v[142:145], v[98:113]
	v_mfma_f32_32x32x16_bf16 v[66:81], v[232:235], v[162:165], v[66:81]
	s_barrier
	ds_read_b128 v[130:133], v244 offset:16384
	ds_read_b128 v[134:137], v245 offset:16384
	ds_read_b128 v[138:141], v246 offset:16384
	ds_read_b128 v[142:145], v247 offset:16384
	ds_read_b128 v[146:149], v244 offset:20480
	ds_read_b128 v[150:153], v245 offset:20480
	ds_read_b128 v[158:161], v246 offset:20480
	ds_read_b128 v[162:165], v247 offset:20480
	s_waitcnt vmcnt(4)
	s_barrier
	s_waitcnt lgkmcnt(0)
	v_mfma_f32_32x32x16_bf16 v[50:65], v[176:179], v[130:133], v[50:65]
	v_mfma_f32_32x32x16_bf16 v[18:33], v[176:179], v[146:149], v[18:33]
	v_mfma_f32_32x32x16_bf16 v[50:65], v[180:183], v[134:137], v[50:65]
	v_mfma_f32_32x32x16_bf16 v[18:33], v[180:183], v[150:153], v[18:33]
	v_mfma_f32_32x32x16_bf16 v[50:65], v[186:189], v[138:141], v[50:65]
	v_mfma_f32_32x32x16_bf16 v[18:33], v[186:189], v[158:161], v[18:33]
	v_mfma_f32_32x32x16_bf16 v[50:65], v[190:193], v[142:145], v[50:65]
	v_mfma_f32_32x32x16_bf16 v[18:33], v[190:193], v[162:165], v[18:33]
	v_mfma_f32_32x32x16_bf16 v[34:49], v[194:197], v[130:133], v[34:49]
	v_mfma_f32_32x32x16_bf16 v[2:17], v[194:197], v[146:149], v[2:17]
	v_mfma_f32_32x32x16_bf16 v[34:49], v[198:201], v[134:137], v[34:49]
	v_mfma_f32_32x32x16_bf16 v[2:17], v[198:201], v[150:153], v[2:17]
	v_mfma_f32_32x32x16_bf16 v[34:49], v[228:231], v[138:141], v[34:49]
	v_mfma_f32_32x32x16_bf16 v[2:17], v[228:231], v[158:161], v[2:17]
	v_mfma_f32_32x32x16_bf16 v[34:49], v[232:235], v[142:145], v[34:49]
	v_mfma_f32_32x32x16_bf16 v[2:17], v[232:235], v[162:165], v[2:17]
	s_barrier
	v_add_u32_e32 v166, s21, v202
	v_add_u32_e32 v167, s21, v203
	ds_read_b128 v[176:179], v166 offset:32768
	ds_read_b128 v[180:183], v167 offset:32768
	v_add_u32_e32 v166, s21, v175
	v_add_u32_e32 v167, s21, v185
	ds_read_b128 v[186:189], v166 offset:32768
	ds_read_b128 v[190:193], v167 offset:32768
	v_add_u32_e32 v166, s21, v244
	v_add_u32_e32 v167, s21, v245
	ds_read_b128 v[130:133], v166
	ds_read_b128 v[134:137], v167
	ds_read_b128 v[146:149], v166 offset:4096
	ds_read_b128 v[150:153], v167 offset:4096
	v_add_u32_e32 v166, s21, v246
	v_add_u32_e32 v167, s21, v247
	ds_read_b128 v[138:141], v166
	ds_read_b128 v[142:145], v167
	ds_read_b128 v[158:161], v166 offset:4096
	ds_read_b128 v[162:165], v167 offset:4096
	s_waitcnt vmcnt(2)
	s_barrier
	s_waitcnt lgkmcnt(0)
	v_mfma_f32_32x32x16_bf16 v[114:129], v[176:179], v[130:133], v[114:129]
	v_mfma_f32_32x32x16_bf16 v[82:97], v[176:179], v[146:149], v[82:97]
	v_mfma_f32_32x32x16_bf16 v[114:129], v[180:183], v[134:137], v[114:129]
	v_mfma_f32_32x32x16_bf16 v[82:97], v[180:183], v[150:153], v[82:97]
	v_mfma_f32_32x32x16_bf16 v[114:129], v[186:189], v[138:141], v[114:129]
	v_mfma_f32_32x32x16_bf16 v[82:97], v[186:189], v[158:161], v[82:97]
	v_mfma_f32_32x32x16_bf16 v[114:129], v[190:193], v[142:145], v[114:129]
	v_mfma_f32_32x32x16_bf16 v[82:97], v[190:193], v[162:165], v[82:97]
	s_barrier
	v_add_u32_e32 v166, s21, v202
	v_add_u32_e32 v167, s21, v203
	ds_read_b128 v[194:197], v166 offset:49152
	ds_read_b128 v[198:201], v167 offset:49152
	v_add_u32_e32 v166, s21, v175
	v_add_u32_e32 v167, s21, v185
	ds_read_b128 v[228:231], v166 offset:49152
	ds_read_b128 v[232:235], v167 offset:49152
	s_waitcnt vmcnt(0)
	s_barrier
	s_waitcnt lgkmcnt(0)
	v_mfma_f32_32x32x16_bf16 v[98:113], v[194:197], v[130:133], v[98:113]
	v_mfma_f32_32x32x16_bf16 v[66:81], v[194:197], v[146:149], v[66:81]
	v_mfma_f32_32x32x16_bf16 v[98:113], v[198:201], v[134:137], v[98:113]
	v_mfma_f32_32x32x16_bf16 v[66:81], v[198:201], v[150:153], v[66:81]
	v_mfma_f32_32x32x16_bf16 v[98:113], v[228:231], v[138:141], v[98:113]
	v_mfma_f32_32x32x16_bf16 v[66:81], v[228:231], v[158:161], v[66:81]
	v_mfma_f32_32x32x16_bf16 v[98:113], v[232:235], v[142:145], v[98:113]
	v_mfma_f32_32x32x16_bf16 v[66:81], v[232:235], v[162:165], v[66:81]
	s_barrier
	v_add_u32_e32 v166, s21, v244
	v_add_u32_e32 v167, s21, v245
	ds_read_b128 v[130:133], v166 offset:16384
	ds_read_b128 v[134:137], v167 offset:16384
	ds_read_b128 v[146:149], v166 offset:20480
	ds_read_b128 v[150:153], v167 offset:20480
	v_add_u32_e32 v166, s21, v246
	v_add_u32_e32 v167, s21, v247
	ds_read_b128 v[138:141], v166 offset:16384
	ds_read_b128 v[142:145], v167 offset:16384
	ds_read_b128 v[158:161], v166 offset:20480
	ds_read_b128 v[162:165], v167 offset:20480
	s_barrier
	s_waitcnt lgkmcnt(0)
	v_mfma_f32_32x32x16_bf16 v[50:65], v[176:179], v[130:133], v[50:65]
	v_mfma_f32_32x32x16_bf16 v[18:33], v[176:179], v[146:149], v[18:33]
	v_mfma_f32_32x32x16_bf16 v[50:65], v[180:183], v[134:137], v[50:65]
	v_mfma_f32_32x32x16_bf16 v[18:33], v[180:183], v[150:153], v[18:33]
	v_mfma_f32_32x32x16_bf16 v[50:65], v[186:189], v[138:141], v[50:65]
	v_mfma_f32_32x32x16_bf16 v[18:33], v[186:189], v[158:161], v[18:33]
	v_mfma_f32_32x32x16_bf16 v[50:65], v[190:193], v[142:145], v[50:65]
	v_mfma_f32_32x32x16_bf16 v[18:33], v[190:193], v[162:165], v[18:33]
	v_mfma_f32_32x32x16_bf16 v[34:49], v[194:197], v[130:133], v[34:49]
	v_mfma_f32_32x32x16_bf16 v[2:17], v[194:197], v[146:149], v[2:17]
	v_mfma_f32_32x32x16_bf16 v[34:49], v[198:201], v[134:137], v[34:49]
	v_mfma_f32_32x32x16_bf16 v[2:17], v[198:201], v[150:153], v[2:17]
	v_mfma_f32_32x32x16_bf16 v[34:49], v[228:231], v[138:141], v[34:49]
	v_mfma_f32_32x32x16_bf16 v[2:17], v[228:231], v[158:161], v[2:17]
	v_mfma_f32_32x32x16_bf16 v[34:49], v[232:235], v[142:145], v[34:49]
	v_mfma_f32_32x32x16_bf16 v[2:17], v[232:235], v[162:165], v[2:17]
	s_barrier
	s_cmp_eq_u32 s101, 0
	s_cbranch_scc0 .Lg8_u0u_p1
	s_barrier

; #define MFMA(a, b, c) __builtin_amdgcn_mfma_f32_32x32x16_bf16((a), (b), (c), 0, 0, 0)
; template <bool SWAP>
; DI void gemm_mainloop(f32x16 (&acc)[4][2], const u16* __restrict__ A, int lda, int rlo, int rhi,
;                       const u16* __restrict__ B, int ldb, int K, char* lds, const u16* zero_line) {
;     ...
;   auto glds = [&](int kt, int st) {
;     char* as_ = lds + st * 65536 + tid * 16;
; #pragma unroll
;     for (int i = 0; i < 4; ++i) {
;       const int rr = lr + 64 * i;
;       const u16* srca = (rr >= rlo && rr < rhi) ? (ap + (ptrdiff_t)(64 * i) * lda + kt * 64) : (zero_line + lc * 8);
;       __builtin_amdgcn_global_load_lds((const unsigned*)srca, (lds_u32*)(as_ + i * 8192), 16, 0, 0);
;       __builtin_amdgcn_global_load_lds((const unsigned*)(bp + (ptrdiff_t)(64 * i) * ldb + kt * 64), (lds_u32*)(as_ + 32768 + i * 8192), 16, 0, 0);
;     }
;   };
;     ...
;   auto ldfrag = [&](const char* st, int ks, int buf) {
;     const int co = ((2 * ks + h) ^ sw) << 4;
; #pragma unroll
;     for (int mi = 0; mi < 4; ++mi) fa[buf][mi] = *(const bf16x8*)(st + arow_off + mi * 4096 + co);
; #pragma unroll
;     for (int ni = 0; ni < 2; ++ni) fb[buf][ni] = *(const bf16x8*)(st + brow_off + ni * 4096 + co);
;   };
;   auto mma = [&](int buf) {
; #pragma unroll
;     for (int mi = 0; mi < 4; ++mi)
; #pragma unroll
;       for (int ni = 0; ni < 2; ++ni)
;         acc[mi][ni] = SWAP ? MFMA(fb[buf][ni], fa[buf][mi], acc[mi][ni]) : MFMA(fa[buf][mi], fb[buf][ni], acc[mi][ni]);
;   };
;   auto pat_rd = [&]() {
; #pragma unroll
;     for (int g = 0; g < 6; ++g) {
;       __builtin_amdgcn_sched_group_barrier(0x100, 1, 0);
;       __builtin_amdgcn_sched_group_barrier(0x008, 1, 0);
;     }
;     __builtin_amdgcn_sched_group_barrier(0x008, 2, 0);
;   };
; #pragma unroll 2
;   for (int kt = 0; kt < nk; ++kt) {
;     const char* st = lds + (kt & 1) * 65536;
;     ldfrag(st, 0, 0);
;     mma(1);
;     pat_rd();
;     if (kt + 1 < nk) glds(kt + 1, (kt + 1) & 1);
;     ldfrag(st, 1, 1);
;     mma(0);
;     pat_rd();
;     ldfrag(st, 2, 0);
;     mma(1);
;     pat_rd();
;     ldfrag(st, 3, 1);
;     mma(0);
;     pat_rd();
;     asm volatile("s_waitcnt vmcnt(0)" ::: "memory");
;     __syncthreads();
;   }
.Lg8_u0m_p0:
	s_waitcnt vmcnt(4)
	s_barrier
	s_add_u32 m0, s100, 0x18000
	s_nop 0
	global_load_lds_dwordx4 v240, s[22:23]
	v_add_u32_e32 v240, 0x80, v240
	s_add_u32 m0, s100, 0x1a000
	s_nop 0
	global_load_lds_dwordx4 v242, s[22:23]
	v_add_u32_e32 v242, 0x80, v242
	s_add_u32 m0, s100, 0x10000
	s_mov_b64 exec, s[10:11]
	global_load_lds_dwordx4 v236, s[18:19]
	s_mov_b64 exec, -1
	v_add_u32_e32 v236, 0x80, v236
	s_add_u32 m0, s100, 0x12000
	s_mov_b64 exec, s[14:15]
	global_load_lds_dwordx4 v238, s[18:19]
	s_mov_b64 exec, -1
	v_add_u32_e32 v238, 0x80, v238
	s_add_u32 m0, s100, 0x1c000
	s_nop 0
	global_load_lds_dwordx4 v241, s[22:23]
	v_add_u32_e32 v241, 0x80, v241
	s_add_u32 m0, s100, 0x1e000
	s_nop 0
	global_load_lds_dwordx4 v243, s[22:23]
	v_add_u32_e32 v243, 0x80, v243
	s_waitcnt vmcnt(6)
	s_barrier
	ds_read_b128 v[176:179], v202 offset:32768
	ds_read_b128 v[180:183], v203 offset:32768
	ds_read_b128 v[186:189], v175 offset:32768
	ds_read_b128 v[190:193], v185 offset:32768
.Lg8_u0m:
	ds_read_b128 v[130:133], v244
	ds_read_b128 v[134:137], v245
	ds_read_b128 v[138:141], v246
	ds_read_b128 v[142:145], v247
	ds_read_b128 v[146:149], v244 offset:4096
	ds_read_b128 v[150:153], v245 offset:4096
	ds_read_b128 v[158:161], v246 offset:4096
	ds_read_b128 v[162:165], v247 offset:4096
	s_add_u32 m0, s100, 0x14000
	s_mov_b64 exec, s[12:13]
	global_load_lds_dwordx4 v237, s[18:19]
	s_mov_b64 exec, -1
	v_add_u32_e32 v237, 0x80, v237
	s_add_u32 m0, s100, 0x16000
	s_mov_b64 exec, s[16:17]
	global_load_lds_dwordx4 v239, s[18:19]
	s_mov_b64 exec, -1
	v_add_u32_e32 v239, 0x80, v239
	s_barrier
	s_waitcnt lgkmcnt(0)
	v_mfma_f32_32x32x16_bf16 v[114:129], v[176:179], v[130:133], v[114:129]
	v_mfma_f32_32x32x16_bf16 v[82:97], v[176:179], v[146:149], v[82:97]
	v_mfma_f32_32x32x16_bf16 v[114:129], v[180:183], v[134:137], v[114:129]
	v_mfma_f32_32x32x16_bf16 v[82:97], v[180:183], v[150:153], v[82:97]
	v_mfma_f32_32x32x16_bf16 v[114:129], v[186:189], v[138:141], v[114:129]
	v_mfma_f32_32x32x16_bf16 v[82:97], v[186:189], v[158:161], v[82:97]
	v_mfma_f32_32x32x16_bf16 v[114:129], v[190:193], v[142:145], v[114:129]
	v_mfma_f32_32x32x16_bf16 v[82:97], v[190:193], v[162:165], v[82:97]
	s_barrier
	ds_read_b128 v[194:197], v202 offset:49152
	ds_read_b128 v[198:201], v203 offset:49152
	ds_read_b128 v[228:231], v175 offset:49152
	ds_read_b128 v[232:235], v185 offset:49152
	s_add_u32 m0, s100, 0x8000
	s_nop 0
	global_load_lds_dwordx4 v240, s[22:23]
	v_add_u32_e32 v240, 0x80, v240
	s_add_u32 m0, s100, 0xa000
	s_nop 0
	global_load_lds_dwordx4 v242, s[22:23]
	v_add_u32_e32 v242, 0x80, v242
	s_barrier
	s_waitcnt lgkmcnt(0)
	v_mfma_f32_32x32x16_bf16 v[98:113], v[194:197], v[130:133], v[98:113]
	v_mfma_f32_32x32x16_bf16 v[66:81], v[194:197], v[146:149], v[66:81]
	v_mfma_f32_32x32x16_bf16 v[98:113], v[198:201], v[134:137], v[98:113]
	v_mfma_f32_32x32x16_bf16 v[66:81], v[198:201], v[150:153], v[66:81]
	v_mfma_f32_32x32x16_bf16 v[98:113], v[228:231], v[138:141], v[98:113]
	v_mfma_f32_32x32x16_bf16 v[66:81], v[228:231], v[158:161], v[66:81]
	v_mfma_f32_32x32x16_bf16 v[98:113], v[232:235], v[142:145], v[98:113]
	v_mfma_f32_32x32x16_bf16 v[66:81], v[232:235], v[162:165], v[66:81]
	s_barrier
	ds_read_b128 v[130:133], v244 offset:16384
	ds_read_b128 v[134:137], v245 offset:16384
	ds_read_b128 v[138:141], v246 offset:16384
	ds_read_b128 v[142:145], v247 offset:16384
	ds_read_b128 v[146:149], v244 offset:20480
	ds_read_b128 v[150:153], v245 offset:20480
	ds_read_b128 v[158:161], v246 offset:20480
	ds_read_b128 v[162:165], v247 offset:20480
	s_add_u32 m0, s100, 0x0
	s_mov_b64 exec, s[10:11]
	global_load_lds_dwordx4 v236, s[18:19]
	s_mov_b64 exec, -1
	v_add_u32_e32 v236, 0x80, v236
	s_add_u32 m0, s100, 0x2000
	s_mov_b64 exec, s[14:15]
	global_load_lds_dwordx4 v238, s[18:19]
	s_mov_b64 exec, -1
	v_add_u32_e32 v238, 0x80, v238
	s_waitcnt vmcnt(10)
	s_barrier
	s_waitcnt lgkmcnt(0)
	v_mfma_f32_32x32x16_bf16 v[50:65], v[176:179], v[130:133], v[50:65]
	v_mfma_f32_32x32x16_bf16 v[18:33], v[176:179], v[146:149], v[18:33]
	v_mfma_f32_32x32x16_bf16 v[50:65], v[180:183], v[134:137], v[50:65]
	v_mfma_f32_32x32x16_bf16 v[18:33], v[180:183], v[150:153], v[18:33]
	v_mfma_f32_32x32x16_bf16 v[50:65], v[186:189], v[138:141], v[50:65]
	v_mfma_f32_32x32x16_bf16 v[18:33], v[186:189], v[158:161], v[18:33]
	v_mfma_f32_32x32x16_bf16 v[50:65], v[190:193], v[142:145], v[50:65]
	v_mfma_f32_32x32x16_bf16 v[18:33], v[190:193], v[162:165], v[18:33]
	s_barrier
	v_add_u32_e32 v166, s21, v202
	v_add_u32_e32 v167, s21, v203
	ds_read_b128 v[176:179], v166 offset:32768
	ds_read_b128 v[180:183], v167 offset:32768
	v_add_u32_e32 v166, s21, v175
	v_add_u32_e32 v167, s21, v185
	ds_read_b128 v[186:189], v166 offset:32768
	ds_read_b128 v[190:193], v167 offset:32768
	s_add_u32 m0, s100, 0xc000
	s_nop 0
	global_load_lds_dwordx4 v241, s[22:23]
	v_add_u32_e32 v241, 0x80, v241
	s_add_u32 m0, s100, 0xe000
	s_nop 0
	global_load_lds_dwordx4 v243, s[22:23]
	v_add_u32_e32 v243, 0x80, v243
	s_waitcnt vmcnt(6)
	s_barrier
	s_waitcnt lgkmcnt(0)
	v_mfma_f32_32x32x16_bf16 v[34:49], v[194:197], v[130:133], v[34:49]
	v_mfma_f32_32x32x16_bf16 v[2:17], v[194:197], v[146:149], v[2:17]
	v_mfma_f32_32x32x16_bf16 v[34:49], v[198:201], v[134:137], v[34:49]
	v_mfma_f32_32x32x16_bf16 v[2:17], v[198:201], v[150:153], v[2:17]
	v_mfma_f32_32x32x16_bf16 v[34:49], v[228:231], v[138:141], v[34:49]
	v_mfma_f32_32x32x16_bf16 v[2:17], v[228:231], v[158:161], v[2:17]
	v_mfma_f32_32x32x16_bf16 v[34:49], v[232:235], v[142:145], v[34:49]
	v_mfma_f32_32x32x16_bf16 v[2:17], v[232:235], v[162:165], v[2:17]
	s_barrier
; #define MFMA(a, b, c) __builtin_amdgcn_mfma_f32_32x32x16_bf16((a), (b), (c), 0, 0, 0)
; template <bool SWAP>
; DI void gemm_mainloop(f32x16 (&acc)[4][2], const u16* __restrict__ A, int lda, int rlo, int rhi,
;                       const u16* __restrict__ B, int ldb, int K, char* lds, const u16* zero_line) {
;     ...
;   auto glds = [&](int kt, int st) {
;     char* as_ = lds + st * 65536 + tid * 16;
; #pragma unroll
;     for (int i = 0; i < 4; ++i) {
;       const int rr = lr + 64 * i;
;       const u16* srca = (rr >= rlo && rr < rhi) ? (ap + (ptrdiff_t)(64 * i) * lda + kt * 64) : (zero_line + lc * 8);
;       __builtin_amdgcn_global_load_lds((const unsigned*)srca, (lds_u32*)(as_ + i * 8192), 16, 0, 0);
;       __builtin_amdgcn_global_load_lds((const unsigned*)(bp + (ptrdiff_t)(64 * i) * ldb + kt * 64), (lds_u32*)(as_ + 32768 + i * 8192), 16, 0, 0);
;     }
;   };
;     ...
;   auto ldfrag = [&](const char* st, int ks, int buf) {
;     const int co = ((2 * ks + h) ^ sw) << 4;
; #pragma unroll
;     for (int mi = 0; mi < 4; ++mi) fa[buf][mi] = *(const bf16x8*)(st + arow_off + mi * 4096 + co);
; #pragma unroll
;     for (int ni = 0; ni < 2; ++ni) fb[buf][ni] = *(const bf16x8*)(st + brow_off + ni * 4096 + co);
;   };
;   auto mma = [&](int buf) {
; #pragma unroll
;     for (int mi = 0; mi < 4; ++mi)
; #pragma unroll
;       for (int ni = 0; ni < 2; ++ni)
;         acc[mi][ni] = SWAP ? MFMA(fb[buf][ni], fa[buf][mi], acc[mi][ni]) : MFMA(fa[buf][mi], fb[buf][ni], acc[mi][ni]);
;   };
;   auto pat_rd = [&]() {
; #pragma unroll
;     for (int g = 0; g < 6; ++g) {
;       __builtin_amdgcn_sched_group_barrier(0x100, 1, 0);
;       __builtin_amdgcn_sched_group_barrier(0x008, 1, 0);
;     }
;     __builtin_amdgcn_sched_group_barrier(0x008, 2, 0);
;   };
; #pragma unroll 2
;   for (int kt = 0; kt < nk; ++kt) {
;     const char* st = lds + (kt & 1) * 65536;
;     ldfrag(st, 0, 0);
;     mma(1);
;     pat_rd();
;     if (kt + 1 < nk) glds(kt + 1, (kt + 1) & 1);
;     ldfrag(st, 1, 1);
;     mma(0);
;     pat_rd();
;     ldfrag(st, 2, 0);
;     mma(1);
;     pat_rd();
;     ldfrag(st, 3, 1);
;     mma(0);
;     pat_rd();
;     asm volatile("s_waitcnt vmcnt(0)" ::: "memory");
;     __syncthreads();
;   }
	v_add_u32_e32 v166, s21, v244
	v_add_u32_e32 v167, s21, v245
	ds_read_b128 v[130:133], v166
	ds_read_b128 v[134:137], v167
	ds_read_b128 v[146:149], v166 offset:4096
	ds_read_b128 v[150:153], v167 offset:4096
	v_add_u32_e32 v166, s21, v246
	v_add_u32_e32 v167, s21, v247
	ds_read_b128 v[138:141], v166
	ds_read_b128 v[142:145], v167
	ds_read_b128 v[158:161], v166 offset:4096
	ds_read_b128 v[162:165], v167 offset:4096
	s_add_u32 m0, s100, 0x4000
	s_mov_b64 exec, s[12:13]
	global_load_lds_dwordx4 v237, s[18:19]
	s_mov_b64 exec, -1
	v_add_u32_e32 v237, 0x80, v237
	s_add_u32 m0, s100, 0x6000
	s_mov_b64 exec, s[16:17]
	global_load_lds_dwordx4 v239, s[18:19]
	s_mov_b64 exec, -1
	v_add_u32_e32 v239, 0x80, v239
	s_barrier
	s_waitcnt lgkmcnt(0)
	v_mfma_f32_32x32x16_bf16 v[114:129], v[176:179], v[130:133], v[114:129]
	v_mfma_f32_32x32x16_bf16 v[82:97], v[176:179], v[146:149], v[82:97]
	v_mfma_f32_32x32x16_bf16 v[114:129], v[180:183], v[134:137], v[114:129]
	v_mfma_f32_32x32x16_bf16 v[82:97], v[180:183], v[150:153], v[82:97]
	v_mfma_f32_32x32x16_bf16 v[114:129], v[186:189], v[138:141], v[114:129]
	v_mfma_f32_32x32x16_bf16 v[82:97], v[186:189], v[158:161], v[82:97]
	v_mfma_f32_32x32x16_bf16 v[114:129], v[190:193], v[142:145], v[114:129]
	v_mfma_f32_32x32x16_bf16 v[82:97], v[190:193], v[162:165], v[82:97]
	s_barrier
	v_add_u32_e32 v166, s21, v202
	v_add_u32_e32 v167, s21, v203
	ds_read_b128 v[194:197], v166 offset:49152
	ds_read_b128 v[198:201], v167 offset:49152
	v_add_u32_e32 v166, s21, v175
	v_add_u32_e32 v167, s21, v185
	ds_read_b128 v[228:231], v166 offset:49152
	ds_read_b128 v[232:235], v167 offset:49152
	s_add_u32 m0, s100, 0x18000
	s_nop 0
	global_load_lds_dwordx4 v240, s[22:23]
	v_add_u32_e32 v240, 0x80, v240
	s_add_u32 m0, s100, 0x1a000
	s_nop 0
	global_load_lds_dwordx4 v242, s[22:23]
	v_add_u32_e32 v242, 0x80, v242
	s_barrier
	s_waitcnt lgkmcnt(0)
	v_mfma_f32_32x32x16_bf16 v[98:113], v[194:197], v[130:133], v[98:113]
	v_mfma_f32_32x32x16_bf16 v[66:81], v[194:197], v[146:149], v[66:81]
	v_mfma_f32_32x32x16_bf16 v[98:113], v[198:201], v[134:137], v[98:113]
	v_mfma_f32_32x32x16_bf16 v[66:81], v[198:201], v[150:153], v[66:81]
	v_mfma_f32_32x32x16_bf16 v[98:113], v[228:231], v[138:141], v[98:113]
	v_mfma_f32_32x32x16_bf16 v[66:81], v[228:231], v[158:161], v[66:81]
	v_mfma_f32_32x32x16_bf16 v[98:113], v[232:235], v[142:145], v[98:113]
	v_mfma_f32_32x32x16_bf16 v[66:81], v[232:235], v[162:165], v[66:81]
	s_barrier
	v_add_u32_e32 v166, s21, v244
	v_add_u32_e32 v167, s21, v245
	ds_read_b128 v[130:133], v166 offset:16384
	ds_read_b128 v[134:137], v167 offset:16384
	ds_read_b128 v[146:149], v166 offset:20480
	ds_read_b128 v[150:153], v167 offset:20480
	v_add_u32_e32 v166, s21, v246
	v_add_u32_e32 v167, s21, v247
	ds_read_b128 v[138:141], v166 offset:16384
	ds_read_b128 v[142:145], v167 offset:16384
	ds_read_b128 v[158:161], v166 offset:20480
	ds_read_b128 v[162:165], v167 offset:20480
	s_add_u32 m0, s100, 0x10000
	s_mov_b64 exec, s[10:11]
	global_load_lds_dwordx4 v236, s[18:19]
	s_mov_b64 exec, -1
	v_add_u32_e32 v236, 0x80, v236
	s_add_u32 m0, s100, 0x12000
	s_mov_b64 exec, s[14:15]
	global_load_lds_dwordx4 v238, s[18:19]
	s_mov_b64 exec, -1
	v_add_u32_e32 v238, 0x80, v238
	s_waitcnt vmcnt(10)
	s_barrier
	s_waitcnt lgkmcnt(0)
	v_mfma_f32_32x32x16_bf16 v[50:65], v[176:179], v[130:133], v[50:65]
	v_mfma_f32_32x32x16_bf16 v[18:33], v[176:179], v[146:149], v[18:33]
	v_mfma_f32_32x32x16_bf16 v[50:65], v[180:183], v[134:137], v[50:65]
	v_mfma_f32_32x32x16_bf16 v[18:33], v[180:183], v[150:153], v[18:33]
	v_mfma_f32_32x32x16_bf16 v[50:65], v[186:189], v[138:141], v[50:65]
	v_mfma_f32_32x32x16_bf16 v[18:33], v[186:189], v[158:161], v[18:33]
	v_mfma_f32_32x32x16_bf16 v[50:65], v[190:193], v[142:145], v[50:65]
	v_mfma_f32_32x32x16_bf16 v[18:33], v[190:193], v[162:165], v[18:33]
	s_barrier
	ds_read_b128 v[176:179], v202 offset:32768
	ds_read_b128 v[180:183], v203 offset:32768
	ds_read_b128 v[186:189], v175 offset:32768
	ds_read_b128 v[190:193], v185 offset:32768
	s_add_u32 m0, s100, 0x1c000
	s_nop 0
	global_load_lds_dwordx4 v241, s[22:23]
	v_add_u32_e32 v241, 0x80, v241
	s_add_u32 m0, s100, 0x1e000
	s_nop 0
	global_load_lds_dwordx4 v243, s[22:23]
	v_add_u32_e32 v243, 0x80, v243
	s_waitcnt vmcnt(6)
	s_barrier
	s_waitcnt lgkmcnt(0)
	v_mfma_f32_32x32x16_bf16 v[34:49], v[194:197], v[130:133], v[34:49]
	v_mfma_f32_32x32x16_bf16 v[2:17], v[194:197], v[146:149], v[2:17]
	v_mfma_f32_32x32x16_bf16 v[34:49], v[198:201], v[134:137], v[34:49]
	v_mfma_f32_32x32x16_bf16 v[2:17], v[198:201], v[150:153], v[2:17]
	v_mfma_f32_32x32x16_bf16 v[34:49], v[228:231], v[138:141], v[34:49]
	v_mfma_f32_32x32x16_bf16 v[2:17], v[228:231], v[158:161], v[2:17]
	v_mfma_f32_32x32x16_bf16 v[34:49], v[232:235], v[142:145], v[34:49]
	v_mfma_f32_32x32x16_bf16 v[2:17], v[232:235], v[162:165], v[2:17]
	s_barrier
	s_add_i32 s29, s29, 2
	s_cmp_lt_u32 s29, 14
	s_cbranch_scc1 .Lg8_u0m
	ds_read_b128 v[130:133], v244
	ds_read_b128 v[134:137], v245
	ds_read_b128 v[138:141], v246
	ds_read_b128 v[142:145], v247
	ds_read_b128 v[146:149], v244 offset:4096
	ds_read_b128 v[150:153], v245 offset:4096
	ds_read_b128 v[158:161], v246 offset:4096
	ds_read_b128 v[162:165], v247 offset:4096
	s_add_u32 m0, s100, 0x14000
	s_mov_b64 exec, s[12:13]
	global_load_lds_dwordx4 v237, s[18:19]
	s_mov_b64 exec, -1
	v_add_u32_e32 v237, 0x80, v237
	s_add_u32 m0, s100, 0x16000
	s_mov_b64 exec, s[16:17]
	global_load_lds_dwordx4 v239, s[18:19]
	s_mov_b64 exec, -1
	v_add_u32_e32 v239, 0x80, v239
	s_barrier
; #define MFMA(a, b, c) __builtin_amdgcn_mfma_f32_32x32x16_bf16((a), (b), (c), 0, 0, 0)
; template <bool SWAP>
; DI void gemm_mainloop(f32x16 (&acc)[4][2], const u16* __restrict__ A, int lda, int rlo, int rhi,
;                       const u16* __restrict__ B, int ldb, int K, char* lds, const u16* zero_line) {
;     ...
;   auto ldfrag = [&](const char* st, int ks, int buf) {
;     const int co = ((2 * ks + h) ^ sw) << 4;
; #pragma unroll
;     for (int mi = 0; mi < 4; ++mi) fa[buf][mi] = *(const bf16x8*)(st + arow_off + mi * 4096 + co);
; #pragma unroll
;     for (int ni = 0; ni < 2; ++ni) fb[buf][ni] = *(const bf16x8*)(st + brow_off + ni * 4096 + co);
;   };
;   auto mma = [&](int buf) {
; #pragma unroll
;     for (int mi = 0; mi < 4; ++mi)
; #pragma unroll
;       for (int ni = 0; ni < 2; ++ni)
;         acc[mi][ni] = SWAP ? MFMA(fb[buf][ni], fa[buf][mi], acc[mi][ni]) : MFMA(fa[buf][mi], fb[buf][ni], acc[mi][ni]);
;   };
;   auto pat_rd = [&]() {
; #pragma unroll
;     for (int g = 0; g < 6; ++g) {
;       __builtin_amdgcn_sched_group_barrier(0x100, 1, 0);
;       __builtin_amdgcn_sched_group_barrier(0x008, 1, 0);
;     }
;     __builtin_amdgcn_sched_group_barrier(0x008, 2, 0);
;   };
; #pragma unroll 2
;   for (int kt = 0; kt < nk; ++kt) {
;     const char* st = lds + (kt & 1) * 65536;
;     ldfrag(st, 0, 0);
;     mma(1);
;     pat_rd();
;     if (kt + 1 < nk) glds(kt + 1, (kt + 1) & 1);
;     ldfrag(st, 1, 1);
;     mma(0);
;     pat_rd();
;     ldfrag(st, 2, 0);
;     mma(1);
;     pat_rd();
;     ldfrag(st, 3, 1);
;     mma(0);
;     pat_rd();
;     asm volatile("s_waitcnt vmcnt(0)" ::: "memory");
;     __syncthreads();
;   }
;   mma(1);
	s_waitcnt lgkmcnt(0)
	v_mfma_f32_32x32x16_bf16 v[114:129], v[176:179], v[130:133], v[114:129]
	v_mfma_f32_32x32x16_bf16 v[82:97], v[176:179], v[146:149], v[82:97]
	v_mfma_f32_32x32x16_bf16 v[114:129], v[180:183], v[134:137], v[114:129]
	v_mfma_f32_32x32x16_bf16 v[82:97], v[180:183], v[150:153], v[82:97]
	v_mfma_f32_32x32x16_bf16 v[114:129], v[186:189], v[138:141], v[114:129]
	v_mfma_f32_32x32x16_bf16 v[82:97], v[186:189], v[158:161], v[82:97]
	v_mfma_f32_32x32x16_bf16 v[114:129], v[190:193], v[142:145], v[114:129]
	v_mfma_f32_32x32x16_bf16 v[82:97], v[190:193], v[162:165], v[82:97]
	s_barrier
	ds_read_b128 v[194:197], v202 offset:49152
	ds_read_b128 v[198:201], v203 offset:49152
	ds_read_b128 v[228:231], v175 offset:49152
	ds_read_b128 v[232:235], v185 offset:49152
	s_barrier
	s_waitcnt lgkmcnt(0)
	v_mfma_f32_32x32x16_bf16 v[98:113], v[194:197], v[130:133], v[98:113]
	v_mfma_f32_32x32x16_bf16 v[66:81], v[194:197], v[146:149], v[66:81]
	v_mfma_f32_32x32x16_bf16 v[98:113], v[198:201], v[134:137], v[98:113]
	v_mfma_f32_32x32x16_bf16 v[66:81], v[198:201], v[150:153], v[66:81]
	v_mfma_f32_32x32x16_bf16 v[98:113], v[228:231], v[138:141], v[98:113]
	v_mfma_f32_32x32x16_bf16 v[66:81], v[228:231], v[158:161], v[66:81]
	v_mfma_f32_32x32x16_bf16 v[98:113], v[232:235], v[142:145], v[98:113]
	v_mfma_f32_32x32x16_bf16 v[66:81], v[232:235], v[162:165], v[66:81]
	s_barrier
	ds_read_b128 v[130:133], v244 offset:16384
	ds_read_b128 v[134:137], v245 offset:16384
	ds_read_b128 v[138:141], v246 offset:16384
	ds_read_b128 v[142:145], v247 offset:16384
	ds_read_b128 v[146:149], v244 offset:20480
	ds_read_b128 v[150:153], v245 offset:20480
	ds_read_b128 v[158:161], v246 offset:20480
	ds_read_b128 v[162:165], v247 offset:20480
	s_waitcnt vmcnt(4)
	s_barrier
	s_waitcnt lgkmcnt(0)
	v_mfma_f32_32x32x16_bf16 v[50:65], v[176:179], v[130:133], v[50:65]
	v_mfma_f32_32x32x16_bf16 v[18:33], v[176:179], v[146:149], v[18:33]
	v_mfma_f32_32x32x16_bf16 v[50:65], v[180:183], v[134:137], v[50:65]
	v_mfma_f32_32x32x16_bf16 v[18:33], v[180:183], v[150:153], v[18:33]
	v_mfma_f32_32x32x16_bf16 v[50:65], v[186:189], v[138:141], v[50:65]
	v_mfma_f32_32x32x16_bf16 v[18:33], v[186:189], v[158:161], v[18:33]
	v_mfma_f32_32x32x16_bf16 v[50:65], v[190:193], v[142:145], v[50:65]
	v_mfma_f32_32x32x16_bf16 v[18:33], v[190:193], v[162:165], v[18:33]
	v_mfma_f32_32x32x16_bf16 v[34:49], v[194:197], v[130:133], v[34:49]
	v_mfma_f32_32x32x16_bf16 v[2:17], v[194:197], v[146:149], v[2:17]
	v_mfma_f32_32x32x16_bf16 v[34:49], v[198:201], v[134:137], v[34:49]
	v_mfma_f32_32x32x16_bf16 v[2:17], v[198:201], v[150:153], v[2:17]
	v_mfma_f32_32x32x16_bf16 v[34:49], v[228:231], v[138:141], v[34:49]
	v_mfma_f32_32x32x16_bf16 v[2:17], v[228:231], v[158:161], v[2:17]
	v_mfma_f32_32x32x16_bf16 v[34:49], v[232:235], v[142:145], v[34:49]
	v_mfma_f32_32x32x16_bf16 v[2:17], v[232:235], v[162:165], v[2:17]
	s_barrier
	v_add_u32_e32 v166, s21, v202
	v_add_u32_e32 v167, s21, v203
	ds_read_b128 v[176:179], v166 offset:32768
	ds_read_b128 v[180:183], v167 offset:32768
	v_add_u32_e32 v166, s21, v175
	v_add_u32_e32 v167, s21, v185
	ds_read_b128 v[186:189], v166 offset:32768
	ds_read_b128 v[190:193], v167 offset:32768
	v_add_u32_e32 v166, s21, v244
	v_add_u32_e32 v167, s21, v245
	ds_read_b128 v[130:133], v166
	ds_read_b128 v[134:137], v167
	ds_read_b128 v[146:149], v166 offset:4096
	ds_read_b128 v[150:153], v167 offset:4096
	v_add_u32_e32 v166, s21, v246
	v_add_u32_e32 v167, s21, v247
	ds_read_b128 v[138:141], v166
	ds_read_b128 v[142:145], v167
	ds_read_b128 v[158:161], v166 offset:4096
	ds_read_b128 v[162:165], v167 offset:4096
	s_waitcnt vmcnt(2)
	s_barrier
	s_waitcnt lgkmcnt(0)
	v_mfma_f32_32x32x16_bf16 v[114:129], v[176:179], v[130:133], v[114:129]
	v_mfma_f32_32x32x16_bf16 v[82:97], v[176:179], v[146:149], v[82:97]
	v_mfma_f32_32x32x16_bf16 v[114:129], v[180:183], v[134:137], v[114:129]
	v_mfma_f32_32x32x16_bf16 v[82:97], v[180:183], v[150:153], v[82:97]
	v_mfma_f32_32x32x16_bf16 v[114:129], v[186:189], v[138:141], v[114:129]
	v_mfma_f32_32x32x16_bf16 v[82:97], v[186:189], v[158:161], v[82:97]
	v_mfma_f32_32x32x16_bf16 v[114:129], v[190:193], v[142:145], v[114:129]
	v_mfma_f32_32x32x16_bf16 v[82:97], v[190:193], v[162:165], v[82:97]
	s_barrier
	v_add_u32_e32 v166, s21, v202
	v_add_u32_e32 v167, s21, v203
	ds_read_b128 v[194:197], v166 offset:49152
	ds_read_b128 v[198:201], v167 offset:49152
	v_add_u32_e32 v166, s21, v175
	v_add_u32_e32 v167, s21, v185
	ds_read_b128 v[228:231], v166 offset:49152
	ds_read_b128 v[232:235], v167 offset:49152
	s_waitcnt vmcnt(0)
	s_barrier
	s_waitcnt lgkmcnt(0)
	v_mfma_f32_32x32x16_bf16 v[98:113], v[194:197], v[130:133], v[98:113]
	v_mfma_f32_32x32x16_bf16 v[66:81], v[194:197], v[146:149], v[66:81]
	v_mfma_f32_32x32x16_bf16 v[98:113], v[198:201], v[134:137], v[98:113]
	v_mfma_f32_32x32x16_bf16 v[66:81], v[198:201], v[150:153], v[66:81]
	v_mfma_f32_32x32x16_bf16 v[98:113], v[228:231], v[138:141], v[98:113]
	v_mfma_f32_32x32x16_bf16 v[66:81], v[228:231], v[158:161], v[66:81]
	v_mfma_f32_32x32x16_bf16 v[98:113], v[232:235], v[142:145], v[98:113]
	v_mfma_f32_32x32x16_bf16 v[66:81], v[232:235], v[162:165], v[66:81]
	s_barrier
	v_add_u32_e32 v166, s21, v244
	v_add_u32_e32 v167, s21, v245
	ds_read_b128 v[130:133], v166 offset:16384
	ds_read_b128 v[134:137], v167 offset:16384
	ds_read_b128 v[146:149], v166 offset:20480
	ds_read_b128 v[150:153], v167 offset:20480
	v_add_u32_e32 v166, s21, v246
	v_add_u32_e32 v167, s21, v247
	ds_read_b128 v[138:141], v166 offset:16384
	ds_read_b128 v[142:145], v167 offset:16384
	ds_read_b128 v[158:161], v166 offset:20480
	ds_read_b128 v[162:165], v167 offset:20480
	s_barrier
	s_waitcnt lgkmcnt(0)
	v_mfma_f32_32x32x16_bf16 v[50:65], v[176:179], v[130:133], v[50:65]
	v_mfma_f32_32x32x16_bf16 v[18:33], v[176:179], v[146:149], v[18:33]
	v_mfma_f32_32x32x16_bf16 v[50:65], v[180:183], v[134:137], v[50:65]
	v_mfma_f32_32x32x16_bf16 v[18:33], v[180:183], v[150:153], v[18:33]
	v_mfma_f32_32x32x16_bf16 v[50:65], v[186:189], v[138:141], v[50:65]
	v_mfma_f32_32x32x16_bf16 v[18:33], v[186:189], v[158:161], v[18:33]
	v_mfma_f32_32x32x16_bf16 v[50:65], v[190:193], v[142:145], v[50:65]
	v_mfma_f32_32x32x16_bf16 v[18:33], v[190:193], v[162:165], v[18:33]
	v_mfma_f32_32x32x16_bf16 v[34:49], v[194:197], v[130:133], v[34:49]
	v_mfma_f32_32x32x16_bf16 v[2:17], v[194:197], v[146:149], v[2:17]
	v_mfma_f32_32x32x16_bf16 v[34:49], v[198:201], v[134:137], v[34:49]
	v_mfma_f32_32x32x16_bf16 v[2:17], v[198:201], v[150:153], v[2:17]
	v_mfma_f32_32x32x16_bf16 v[34:49], v[228:231], v[138:141], v[34:49]
	v_mfma_f32_32x32x16_bf16 v[2:17], v[228:231], v[158:161], v[2:17]
	v_mfma_f32_32x32x16_bf16 v[34:49], v[232:235], v[142:145], v[34:49]
	v_mfma_f32_32x32x16_bf16 v[2:17], v[232:235], v[162:165], v[2:17]
	s_barrier
	s_cmp_eq_u32 s101, 0
	s_cbranch_scc0 .Lg8_u0m_p1
	s_barrier

; template <bool SWAP>
; DI void gemm_mainloop(f32x16 (&acc)[4][2], const u16* __restrict__ A, int lda, int rlo, int rhi,
;                       const u16* __restrict__ B, int ldb, int K, char* lds, const u16* zero_line) {
;   const int tid = opaque_tid(), lane = tid & 63, w = tid >> 6;
;   const int wm = w >> 2, wn = w & 3;
;   const int h = lane >> 5, r = lane & 31;
;   const int lr = tid >> 3, lc = tid & 7;
; #pragma unroll
;   for (int mi = 0; mi < 4; ++mi)
; #pragma unroll
;     for (int ni = 0; ni < 2; ++ni)
; #pragma unroll
;       for (int i = 0; i < 16; ++i) acc[mi][ni][i] = 0.f;
;   const int gch = (lc ^ ((lr >> 1) & 7)) * 8;
;   const u16* ap = A + (ptrdiff_t)lr * lda + gch;
;   const u16* bp = B + (ptrdiff_t)lr * ldb + gch;
;   const int nk = K >> 6;
;   typedef __attribute__((address_space(3))) unsigned lds_u32;
;   auto glds = [&](int kt, int st) {
;     char* as_ = lds + st * 65536 + tid * 16;
; #pragma unroll
;     for (int i = 0; i < 4; ++i) {
;       const int rr = lr + 64 * i;
;       const u16* srca = (rr >= rlo && rr < rhi) ? (ap + (ptrdiff_t)(64 * i) * lda + kt * 64) : (zero_line + lc * 8);
;       __builtin_amdgcn_global_load_lds((const unsigned*)srca, (lds_u32*)(as_ + i * 8192), 16, 0, 0);
;       __builtin_amdgcn_global_load_lds((const unsigned*)(bp + (ptrdiff_t)(64 * i) * ldb + kt * 64), (lds_u32*)(as_ + 32768 + i * 8192), 16, 0, 0);
;     }
;   };
;   const int sw = (r >> 1) & 7;
;   const int arow_off = (wm * 128 + r) * 128;
;   const int brow_off = 32768 + (wn * 64 + r) * 128;
;   __syncthreads();
;   glds(0, 0);
;   asm volatile("s_waitcnt vmcnt(0)" ::: "memory");
;   __syncthreads();
; template <int EPI>
; DI void phase_gemm(const Params& p, const GemmArgs& ga, char* lds) {
;     ...
;   for (int it = 0; it * (int)gridDim.x < total; ++it) {
;     const int lt = logical_index(it);
;     if (lt >= total) continue;
;     int mt, nt;
;     tile_mn(lt, Mt, ga.Nt, mt, nt);
;     int bb, tokbase, S, pos0, rlo = 0, rhi = 256;
;     if (EPI == EPI_UP) {
;       bb = 0; tokbase = 0; S = NTOK;
;       pos0 = 254 * mt - 1;
;       rlo = (mt == 0) ? 1 : 0;
;       rhi = NTOK - pos0; if (rhi > 256) rhi = 256;
;     } else {
;       seq_of_token(mt * 256, bb, tokbase, S);
;       pos0 = mt * 256 - tokbase;
;     }
;     const u16* A = ga.A + (ptrdiff_t)(tokbase + pos0) * ga.lda;
;     const u16* B = ga.Bt + (size_t)(nt * 256) * ga.K;
.LBB0_167:
	s_add_i32 s30, s10, s25
	s_cmpk_gt_i32 s30, 0x10ab
	s_cbranch_scc1 .LBB0_166
	s_mul_hi_i32 s10, s30, 0x2e8ba2e9
	s_lshr_b32 s11, s10, 31
	s_ashr_i32 s10, s10, 5
	s_add_i32 s31, s10, s11
	s_lshl_b32 s10, s31, 3
	s_sub_i32 s11, 0xc2, s10
	s_min_u32 s11, s11, 8
	v_cvt_f32_ubyte0_e32 v0, s11
	v_rcp_iflag_f32_e32 v0, v0
	s_sub_i32 s15, 0, s11
	s_mul_i32 s12, s31, 0xffffff50
	s_add_i32 s12, s12, s30
	v_mul_f32_e32 v0, 0x4f7ffffe, v0
	v_cvt_u32_f32_e32 v0, v0
	s_abs_i32 s14, s12
	s_ashr_i32 s13, s12, 31
	s_waitcnt vmcnt(5)
	v_mov_b32_e32 v13, v204
	v_readfirstlane_b32 s16, v0
	s_mul_i32 s15, s15, s16
	s_mul_hi_u32 s15, s16, s15
	s_add_i32 s16, s16, s15
	s_mul_hi_u32 s15, s14, s16
	s_mul_i32 s16, s15, s11
	s_sub_i32 s14, s14, s16
	s_add_i32 s16, s15, 1
	s_sub_i32 s17, s14, s11
	s_cmp_ge_u32 s14, s11
	s_cselect_b32 s15, s16, s15
	s_cselect_b32 s14, s17, s14
	s_add_i32 s16, s15, 1
	s_cmp_ge_u32 s14, s11
	s_cselect_b32 s14, s16, s15
	s_xor_b32 s14, s14, s13
	s_sub_i32 s28, s14, s13
	s_mul_i32 s34, s28, s11
	s_add_i32 s14, s12, s10
	s_sub_i32 s27, s14, s34
	s_mulk_i32 s27, 0xfe
	s_lshl_b32 s10, s28, 8
	s_add_i32 s20, s27, -1
	s_ashr_i32 s11, s10, 31
	s_ashr_i32 s21, s20, 31
	s_lshl_b64 s[22:23], s[10:11], 11
	v_readlane_b32 s10, v253, 47
	v_readlane_b32 s11, v253, 48
	s_add_u32 s10, s10, s22
	s_addc_u32 s11, s11, s23
	s_lshl_b64 s[12:13], s[20:21], 11
	s_add_u32 s12, s90, s12
	v_ashrrev_i32_e32 v2, 3, v13
	s_waitcnt vmcnt(4)
	v_lshrrev_b32_e32 v15, 1, v2
	s_addc_u32 s13, s91, s13
	s_sub_i32 s15, 0xc001, s27
	v_xor_b32_e32 v0, v15, v13
	v_ashrrev_i32_e32 v3, 31, v2
	s_min_i32 s18, s15, 0x100
	v_lshlrev_b64 v[4:5], 11, v[2:3]
	v_lshlrev_b32_e32 v0, 4, v0
	s_cmp_eq_u32 s14, s34
	v_and_b32_e32 v10, 31, v13
	v_lshl_add_u64 v[6:7], s[12:13], 0, v[4:5]
	v_and_b32_e32 v0, 0x70, v0
	v_lshl_add_u64 v[8:9], s[10:11], 0, v[4:5]
	v_lshrrev_b32_e32 v16, 1, v13
	s_cselect_b64 s[14:15], -1, 0
	v_lshl_add_u64 v[6:7], v[6:7], 0, v[0:1]
	v_lshl_add_u64 v[8:9], v[8:9], 0, v[0:1]
	v_and_or_b32 v0, v16, s51, v10
	v_cndmask_b32_e64 v12, 0, 1, s[14:15]
	v_lshlrev_b32_e32 v175, 7, v0
	v_lshlrev_b32_e32 v0, 7, v13
	v_lshlrev_b32_e32 v177, 4, v13
	v_and_b32_e32 v176, 0x6f80, v0
	v_cmp_ge_i32_e64 s[10:11], v2, v12
	v_cmp_gt_i32_e64 s[12:13], s18, v2
	v_and_b32_e32 v0, 0x70, v177
	v_add_u32_e32 v178, 0x8000, v177
	v_lshl_add_u64 v[158:159], s[80:81], 0, v[0:1]
	s_and_b64 s[10:11], s[10:11], s[12:13]
	v_readfirstlane_b32 s12, v177
	v_cndmask_b32_e64 v11, v159, v7, s[10:11]
	v_cndmask_b32_e64 v10, v158, v6, s[10:11]
	s_mov_b32 m0, s12
	v_readfirstlane_b32 s12, v178
	v_add_u32_e32 v0, 64, v2
	s_barrier
	s_mov_b32 m0, s12
	v_cmp_ge_i32_e64 s[12:13], v0, v12
	v_cmp_gt_i32_e64 s[14:15], s18, v0
	s_mov_b64 s[16:17], 0x20000
	v_add_u32_e32 v0, 0x2000, v177
	v_lshl_add_u64 v[10:11], v[6:7], 0, s[16:17]
	s_and_b64 s[12:13], s[12:13], s[14:15]
	v_readfirstlane_b32 s14, v0
	v_add_u32_e32 v179, 0xa000, v177
	v_cndmask_b32_e64 v11, v159, v11, s[12:13]
	v_cndmask_b32_e64 v10, v158, v10, s[12:13]
	s_mov_b32 m0, s14
	v_readfirstlane_b32 s14, v179
	v_add_u32_e32 v3, 0x80, v2
	v_lshl_add_u64 v[10:11], v[8:9], 0, s[16:17]
	s_mov_b32 m0, s14
	v_cmp_ge_i32_e64 s[14:15], v3, v12
	v_cmp_gt_i32_e64 s[16:17], s18, v3
	s_mov_b64 s[36:37], 0x40000
	v_add_u32_e32 v180, 0x4000, v177
	v_lshl_add_u64 v[10:11], v[6:7], 0, s[36:37]
	s_and_b64 s[14:15], s[14:15], s[16:17]
	v_readfirstlane_b32 s16, v180
	v_add_u32_e32 v181, 0xc000, v177
	v_cndmask_b32_e64 v11, v159, v11, s[14:15]
	v_cndmask_b32_e64 v10, v158, v10, s[14:15]
	s_mov_b32 m0, s16
	v_readfirstlane_b32 s16, v181
	v_add_u32_e32 v2, 0xc0, v2
	v_lshl_add_u64 v[10:11], v[8:9], 0, s[36:37]
	s_mov_b32 m0, s16
	v_cmp_ge_i32_e64 s[16:17], v2, v12
	v_cmp_gt_i32_e64 s[18:19], s18, v2
	s_mov_b64 s[36:37], 0x60000
	v_add_u32_e32 v182, 0x6000, v177
	v_lshl_add_u64 v[2:3], v[6:7], 0, s[36:37]
	s_and_b64 s[16:17], s[16:17], s[18:19]
	v_readfirstlane_b32 s18, v182
	v_add_u32_e32 v183, 0xe000, v177
	v_cndmask_b32_e64 v3, v159, v3, s[16:17]
	v_cndmask_b32_e64 v2, v158, v2, s[16:17]
	s_mov_b32 m0, s18
	v_readfirstlane_b32 s18, v183
	v_lshl_add_u64 v[2:3], v[8:9], 0, s[36:37]
	s_mov_b32 m0, s18
	s_sub_i32 s18, s30, s34
	s_mulk_i32 s31, 0xa8
	v_bfe_u32 v14, v13, 5, 1
	s_sub_i32 s18, s18, s31
	v_bfe_u32 v17, v13, 1, 3
	v_bitop3_b32 v2, v16, v14, 7 bitop3:0x6c
	s_mulk_i32 s18, 0xfe
	v_lshlrev_b32_e32 v185, 4, v2
	v_bitop3_b32 v2, v14, v17, 2 bitop3:0x36
	s_add_i32 s18, s18, -2
	v_lshlrev_b32_e32 v186, 4, v2
	v_bitop3_b32 v2, v14, v17, 4 bitop3:0x36
	s_ashr_i32 s19, s18, 31
	v_lshlrev_b32_e32 v187, 4, v2
	v_bitop3_b32 v2, v14, v17, 6 bitop3:0x36
	s_lshl_b64 s[18:19], s[18:19], 11
	v_bitop3_b32 v6, v15, 7, v13 bitop3:0x48
	v_lshlrev_b32_e32 v188, 4, v2
	v_lshl_add_u64 v[2:3], v[4:5], 0, s[18:19]
	v_lshlrev_b32_e32 v6, 4, v6
	v_or_b32_e32 v2, v2, v6
	v_lshl_add_u64 v[160:161], s[70:71], 0, v[2:3]
	v_lshl_add_u64 v[2:3], v[4:5], 0, s[22:23]
	s_waitcnt vmcnt(0)
	v_or_b32_e32 v2, v2, v6
	v_lshl_add_u64 v[162:163], s[70:71], 0, v[2:3]
	v_mov_b32_e32 v130, 0
	v_mov_b32_e32 v2, 0
	s_mov_b32 s29, 1
	v_add_u32_e32 v189, 0x10000, v177
	v_add_u32_e32 v190, 0x18000, v177
	v_add_u32_e32 v191, 0x12000, v177
	v_add_u32_e32 v192, 0x1a000, v177
	v_add_u32_e32 v193, 0x14000, v177
	v_add_u32_e32 v194, 0x1c000, v177
	v_add_u32_e32 v195, 0x16000, v177
	v_add_u32_e32 v196, 0x1e000, v177
	v_add_u32_e32 v197, 0x10000, v175
	v_or_b32_e32 v198, 0x10000, v176
	s_mov_b64 s[18:19], 0
	v_mov_b32_e32 v3, v2
	v_mov_b32_e32 v4, v2
	v_mov_b32_e32 v5, v2
	v_mov_b32_e32 v6, v2
	v_mov_b32_e32 v7, v2
	v_mov_b32_e32 v8, v2
	v_mov_b32_e32 v9, v2
	v_mov_b32_e32 v10, v2
	v_mov_b32_e32 v11, v2
	v_mov_b32_e32 v12, v2
	v_mov_b32_e32 v13, v2
	v_mov_b32_e32 v14, v2
	v_mov_b32_e32 v15, v2
	v_mov_b32_e32 v16, v2
	v_mov_b32_e32 v17, v2
	s_waitcnt vmcnt(0)
; DI int opaque_tid() { int t = threadIdx.x; asm volatile("" : "+v"(t)); return t; }
; template <bool SWAP>
; DI void gemm_mainloop(f32x16 (&acc)[4][2], const u16* __restrict__ A, int lda, int rlo, int rhi,
;                       const u16* __restrict__ B, int ldb, int K, char* lds, const u16* zero_line) {
;   const int tid = opaque_tid(), lane = tid & 63, w = tid >> 6;
;   const int wm = w >> 2, wn = w & 3;
;   const int h = lane >> 5, r = lane & 31;
;   const int lr = tid >> 3, lc = tid & 7;
; #pragma unroll
;   for (int mi = 0; mi < 4; ++mi)
; #pragma unroll
;     for (int ni = 0; ni < 2; ++ni)
; #pragma unroll
;       for (int i = 0; i < 16; ++i) acc[mi][ni][i] = 0.f;
;   const int gch = (lc ^ ((lr >> 1) & 7)) * 8;
;   const u16* ap = A + (ptrdiff_t)lr * lda + gch;
;   const u16* bp = B + (ptrdiff_t)lr * ldb + gch;
;   const int nk = K >> 6;
;   typedef __attribute__((address_space(3))) unsigned lds_u32;
;   auto glds = [&](int kt, int st) {
;     char* as_ = lds + st * 65536 + tid * 16;
; #pragma unroll
;     for (int i = 0; i < 4; ++i) {
;       const int rr = lr + 64 * i;
;       const u16* srca = (rr >= rlo && rr < rhi) ? (ap + (ptrdiff_t)(64 * i) * lda + kt * 64) : (zero_line + lc * 8);
;       __builtin_amdgcn_global_load_lds((const unsigned*)srca, (lds_u32*)(as_ + i * 8192), 16, 0, 0);
;       __builtin_amdgcn_global_load_lds((const unsigned*)(bp + (ptrdiff_t)(64 * i) * ldb + kt * 64), (lds_u32*)(as_ + 32768 + i * 8192), 16, 0, 0);
;     }
;   };
;   const int sw = (r >> 1) & 7;
;   const int arow_off = (wm * 128 + r) * 128;
;   const int brow_off = 32768 + (wn * 64 + r) * 128;
;   __syncthreads();
;   glds(0, 0);
;   asm volatile("s_waitcnt vmcnt(0)" ::: "memory");
;   __syncthreads();
	v_mov_b32_e32 v18, v2
	v_mov_b32_e32 v19, v2
	v_mov_b32_e32 v20, v2
	v_mov_b32_e32 v21, v2
	v_mov_b32_e32 v22, v2
	v_mov_b32_e32 v23, v2
	v_mov_b32_e32 v24, v2
	v_mov_b32_e32 v25, v2
	v_mov_b32_e32 v26, v2
	v_mov_b32_e32 v27, v2
	v_mov_b32_e32 v28, v2
	v_mov_b32_e32 v29, v2
	v_mov_b32_e32 v30, v2
	v_mov_b32_e32 v31, v2
	v_mov_b32_e32 v32, v2
	v_mov_b32_e32 v33, v2
	v_mov_b32_e32 v34, v2
	v_mov_b32_e32 v35, v2
	v_mov_b32_e32 v36, v2
	v_mov_b32_e32 v37, v2
	v_mov_b32_e32 v38, v2
	v_mov_b32_e32 v39, v2
	v_mov_b32_e32 v40, v2
	v_mov_b32_e32 v41, v2
	v_mov_b32_e32 v42, v2
	v_mov_b32_e32 v43, v2
	v_mov_b32_e32 v44, v2
	v_mov_b32_e32 v45, v2
	v_mov_b32_e32 v46, v2
	v_mov_b32_e32 v47, v2
	v_mov_b32_e32 v48, v2
	v_mov_b32_e32 v49, v2
	v_mov_b32_e32 v50, v2
	v_mov_b32_e32 v51, v2
	v_mov_b32_e32 v52, v2
	v_mov_b32_e32 v53, v2
	v_mov_b32_e32 v54, v2
	v_mov_b32_e32 v55, v2
	v_mov_b32_e32 v56, v2
	v_mov_b32_e32 v57, v2
	v_mov_b32_e32 v58, v2
	v_mov_b32_e32 v59, v2
	v_mov_b32_e32 v60, v2
	v_mov_b32_e32 v61, v2
	v_mov_b32_e32 v62, v2
	v_mov_b32_e32 v63, v2
	v_mov_b32_e32 v64, v2
	v_mov_b32_e32 v65, v2
	v_mov_b32_e32 v66, v2
	v_mov_b32_e32 v67, v2
	v_mov_b32_e32 v68, v2
	v_mov_b32_e32 v69, v2
	v_mov_b32_e32 v70, v2
	v_mov_b32_e32 v71, v2
	v_mov_b32_e32 v72, v2
	v_mov_b32_e32 v73, v2
	v_mov_b32_e32 v74, v2
	v_mov_b32_e32 v75, v2
	v_mov_b32_e32 v76, v2
	v_mov_b32_e32 v77, v2
	v_mov_b32_e32 v78, v2
	v_mov_b32_e32 v79, v2
	v_mov_b32_e32 v80, v2
	v_mov_b32_e32 v81, v2
	v_mov_b32_e32 v82, v2
	v_mov_b32_e32 v83, v2
	v_mov_b32_e32 v84, v2
	v_mov_b32_e32 v85, v2
	v_mov_b32_e32 v86, v2
	v_mov_b32_e32 v87, v2
	v_mov_b32_e32 v88, v2
	v_mov_b32_e32 v89, v2
	v_mov_b32_e32 v90, v2
	v_mov_b32_e32 v91, v2
	v_mov_b32_e32 v92, v2
	v_mov_b32_e32 v93, v2
	v_mov_b32_e32 v94, v2
	v_mov_b32_e32 v95, v2
	v_mov_b32_e32 v96, v2
	v_mov_b32_e32 v97, v2
	v_mov_b32_e32 v98, v2
	v_mov_b32_e32 v99, v2
	v_mov_b32_e32 v100, v2
	v_mov_b32_e32 v101, v2
	v_mov_b32_e32 v102, v2
	v_mov_b32_e32 v103, v2
	v_mov_b32_e32 v104, v2
	v_mov_b32_e32 v105, v2
	v_mov_b32_e32 v106, v2
	v_mov_b32_e32 v107, v2
	v_mov_b32_e32 v108, v2
	v_mov_b32_e32 v109, v2
	v_mov_b32_e32 v110, v2
	v_mov_b32_e32 v111, v2
	v_mov_b32_e32 v112, v2
	v_mov_b32_e32 v113, v2
	v_mov_b32_e32 v114, v2
	v_mov_b32_e32 v115, v2
	v_mov_b32_e32 v116, v2
	v_mov_b32_e32 v117, v2
	v_mov_b32_e32 v118, v2
	v_mov_b32_e32 v119, v2
	v_mov_b32_e32 v120, v2
	v_mov_b32_e32 v121, v2
	v_mov_b32_e32 v122, v2
	v_mov_b32_e32 v123, v2
	v_mov_b32_e32 v124, v2
	v_mov_b32_e32 v125, v2
	v_mov_b32_e32 v126, v2
	v_mov_b32_e32 v127, v2
	v_mov_b32_e32 v128, v2
	v_mov_b32_e32 v129, v2
	v_mov_b32_e32 v131, v130
	v_mov_b32_e32 v132, v130
	v_mov_b32_e32 v133, v130
	v_mov_b32_e32 v134, v130
	v_mov_b32_e32 v135, v130
	v_mov_b32_e32 v136, v130
	v_mov_b32_e32 v137, v130
	v_mov_b32_e32 v138, v130
	v_mov_b32_e32 v139, v130
	v_mov_b32_e32 v140, v130
	v_mov_b32_e32 v141, v130
	v_mov_b32_e32 v142, v130
	v_mov_b32_e32 v143, v130
	v_mov_b32_e32 v144, v130
	v_mov_b32_e32 v145, v130
	v_mov_b32_e32 v146, v130
	v_mov_b32_e32 v147, v130
	v_mov_b32_e32 v148, v130
	v_mov_b32_e32 v149, v130
	v_mov_b32_e32 v150, v130
	v_mov_b32_e32 v151, v130
	v_mov_b32_e32 v152, v130
	v_mov_b32_e32 v153, v130
	s_mov_b64 s[30:31], 0x37f8900
	s_waitcnt lgkmcnt(0)
	s_barrier
	s_add_i32 s18, s27, -1
	s_ashr_i32 s19, s18, 31
	s_lshl_b64 s[18:19], s[18:19], 11
	s_add_u32 s18, s90, s18
	s_addc_u32 s19, s91, s19
	v_readlane_b32 s22, v253, 47
	v_readlane_b32 s23, v253, 48
	s_lshl_b32 s21, s28, 19
	s_add_u32 s22, s22, s21
	s_addc_u32 s23, s23, 0
	v_and_b32_e32 v130, 63, v204
	v_lshrrev_b32_e32 v131, 6, v204
	v_lshrrev_b32_e32 v132, 3, v204
	v_lshrrev_b32_e32 v0, 4, v130
	v_lshl_add_u32 v0, v131, 2, v0
	v_xor_b32_e32 v0, v0, v130
	v_and_b32_e32 v0, 7, v0
	v_lshlrev_b32_e32 v133, 4, v0
	v_lshl_add_u32 v236, v132, 11, v133
	v_add_u32_e32 v237, 0x20000, v236
	v_add_u32_e32 v238, 0x40000, v236
	v_add_u32_e32 v239, 0x60000, v236
	v_and_b32_e32 v0, 31, v132
	v_lshrrev_b32_e32 v130, 5, v132
	v_lshl_add_u32 v0, v130, 6, v0
	v_lshl_add_u32 v240, v0, 11, v133
	v_add_u32_e32 v241, 0x10000, v240
	v_add_u32_e32 v242, 0x40000, v240
	v_add_u32_e32 v243, 0x50000, v240
	v_and_b32_e32 v132, 31, v204
	v_lshrrev_b32_e32 v0, 2, v131
	v_lshl_add_u32 v0, v0, 6, v132
	v_lshlrev_b32_e32 v248, 7, v0
	v_and_b32_e32 v0, 3, v131
	v_lshl_add_u32 v0, v0, 5, v132
	v_lshlrev_b32_e32 v249, 7, v0
	v_bfe_u32 v0, v204, 5, 1
	v_bfe_u32 v130, v132, 1, 3
	v_or_b32_e32 v133, 0, v0
	v_xor_b32_e32 v133, v133, v130
	v_lshlrev_b32_e32 v244, 4, v133
	v_or_b32_e32 v133, 2, v0
	v_xor_b32_e32 v133, v133, v130
	v_lshlrev_b32_e32 v245, 4, v133
	v_or_b32_e32 v133, 4, v0
	v_xor_b32_e32 v133, v133, v130
	v_lshlrev_b32_e32 v246, 4, v133
	v_or_b32_e32 v133, 6, v0
	v_xor_b32_e32 v133, v133, v130
	v_lshlrev_b32_e32 v247, 4, v133
	v_add_u32_e32 v202, v249, v244
	v_add_u32_e32 v203, v249, v245
	v_add_u32_e32 v175, v249, v246
	v_add_u32_e32 v185, v249, v247
	v_add_u32_e32 v244, v248, v244
	v_add_u32_e32 v245, v248, v245
	v_add_u32_e32 v246, v248, v246
	v_add_u32_e32 v247, v248, v247
	v_lshlrev_b32_e32 v131, 10, v131
	s_nop 0
	v_readfirstlane_b32 s100, v131
	v_mov_b32_e32 v146, 0
	v_mov_b32_e32 v147, 0
	v_mov_b32_e32 v148, 0
	v_mov_b32_e32 v149, 0
	v_lshlrev_b32_e32 v130, 4, v204
	v_add_u32_e32 v132, 0x10000, v130
	s_not_b64 exec, s[10:11]
	ds_write_b128 v130, v[146:149]
	ds_write_b128 v132, v[146:149]
	s_not_b64 exec, s[12:13]
	ds_write_b128 v130, v[146:149] offset:16384
	ds_write_b128 v132, v[146:149] offset:16384
	s_not_b64 exec, s[14:15]
	ds_write_b128 v130, v[146:149] offset:8192
	ds_write_b128 v132, v[146:149] offset:8192
	s_not_b64 exec, s[16:17]
	ds_write_b128 v130, v[146:149] offset:24576
	ds_write_b128 v132, v[146:149] offset:24576
	s_mov_b64 exec, -1
	s_mov_b32 s29, 0
	s_mov_b32 s21, 0x10000
	s_waitcnt lgkmcnt(0)
	s_cmp_eq_u32 s27, 0
	s_cbranch_scc1 .Lg8_u1_msk
	s_cmp_gt_i32 s20, 0xbf00
	s_cbranch_scc1 .Lg8_u1_msk
	s_add_u32 m0, s100, 0x8000
	s_nop 0
	global_load_lds_dwordx4 v240, s[22:23]
	v_add_u32_e32 v240, 0x80, v240
	s_add_u32 m0, s100, 0xa000
	s_nop 0
	global_load_lds_dwordx4 v242, s[22:23]
	v_add_u32_e32 v242, 0x80, v242
	s_add_u32 m0, s100, 0x0
	s_nop 0
	global_load_lds_dwordx4 v236, s[18:19]
	v_add_u32_e32 v236, 0x80, v236
	s_add_u32 m0, s100, 0x2000
	s_nop 0
	global_load_lds_dwordx4 v238, s[18:19]
	v_add_u32_e32 v238, 0x80, v238
	s_add_u32 m0, s100, 0xc000
	s_nop 0
	global_load_lds_dwordx4 v241, s[22:23]
	v_add_u32_e32 v241, 0x80, v241
	s_add_u32 m0, s100, 0xe000
	s_nop 0
	global_load_lds_dwordx4 v243, s[22:23]
	v_add_u32_e32 v243, 0x80, v243
	s_add_u32 m0, s100, 0x4000
	s_nop 0
	global_load_lds_dwordx4 v237, s[18:19]
	v_add_u32_e32 v237, 0x80, v237
	s_add_u32 m0, s100, 0x6000
	s_nop 0
	global_load_lds_dwordx4 v239, s[18:19]
	v_add_u32_e32 v239, 0x80, v239
	s_cmp_eq_u32 s101, 1
	s_cbranch_scc0 .Lg8_u1u_p0
	s_barrier

; DI int opaque_tid() { int t = threadIdx.x; asm volatile("" : "+v"(t)); return t; }
; template <bool SWAP>
; DI void gemm_mainloop(f32x16 (&acc)[4][2], const u16* __restrict__ A, int lda, int rlo, int rhi,
;                       const u16* __restrict__ B, int ldb, int K, char* lds, const u16* zero_line) {
;   const int tid = opaque_tid(), lane = tid & 63, w = tid >> 6;
;   const int wm = w >> 2, wn = w & 3;
;   const int h = lane >> 5, r = lane & 31;
;   const int lr = tid >> 3, lc = tid & 7;
; #pragma unroll
;   for (int mi = 0; mi < 4; ++mi)
; #pragma unroll
;     for (int ni = 0; ni < 2; ++ni)
; #pragma unroll
;       for (int i = 0; i < 16; ++i) acc[mi][ni][i] = 0.f;
;   const int gch = (lc ^ ((lr >> 1) & 7)) * 8;
;   const u16* ap = A + (ptrdiff_t)lr * lda + gch;
;   const u16* bp = B + (ptrdiff_t)lr * ldb + gch;
;   const int nk = K >> 6;
;   typedef __attribute__((address_space(3))) unsigned lds_u32;
;   auto glds = [&](int kt, int st) {
;     char* as_ = lds + st * 65536 + tid * 16;
; #pragma unroll
;     for (int i = 0; i < 4; ++i) {
;       const int rr = lr + 64 * i;
;       const u16* srca = (rr >= rlo && rr < rhi) ? (ap + (ptrdiff_t)(64 * i) * lda + kt * 64) : (zero_line + lc * 8);
;       __builtin_amdgcn_global_load_lds((const unsigned*)srca, (lds_u32*)(as_ + i * 8192), 16, 0, 0);
; template <int EPI>
; DI void phase_gemm(const Params& p, const GemmArgs& ga, char* lds) {
;     ...
;   for (int it = 0; it * (int)gridDim.x < total; ++it) {
;     const int lt = logical_index(it);
;     if (lt >= total) continue;
;     int mt, nt;
;     tile_mn(lt, Mt, ga.Nt, mt, nt);
;     int bb, tokbase, S, pos0, rlo = 0, rhi = 256;
;     if (EPI == EPI_UP) {
;       bb = 0; tokbase = 0; S = NTOK;
;       pos0 = 254 * mt - 1;
;       rlo = (mt == 0) ? 1 : 0;
;       rhi = NTOK - pos0; if (rhi > 256) rhi = 256;
;     } else {
;       seq_of_token(mt * 256, bb, tokbase, S);
;       pos0 = mt * 256 - tokbase;
;     }
;     const u16* A = ga.A + (ptrdiff_t)(tokbase + pos0) * ga.lda;
;     const u16* B = ga.Bt + (size_t)(nt * 256) * ga.K;
;     f32x16 acc[4][2];
;     bool swap;
;     if (EPI == EPI_M) swap = true;
;     else if (EPI == EPI_UP) swap = true;
;     else if (EPI == EPI_QKV1) swap = (nt < 8);
;     else swap = !(nt == 4 || nt == 5);
;     if (swap) gemm_mainloop<true>(acc, A, ga.lda, rlo, rhi, B, ga.K, ga.K, lds, (const u16*)(p.ws + OFF_ZERO));
.LBB0_196:
	s_add_i32 s6, s6, s27
	s_cmpk_gt_i32 s6, 0x8ff
	s_cbranch_scc1 .LBB0_195
	s_mul_hi_i32 s7, s6, 0x2aaaaaab
	s_lshr_b32 s8, s7, 31
	s_ashr_i32 s7, s7, 4
	s_add_i32 s8, s7, s8
	s_mul_i32 s7, s8, 0xffffffa0
	s_add_i32 s9, s7, s6
	s_ashr_i32 s7, s9, 31
	s_lshr_b32 s7, s7, 29
	s_lshl_b32 s6, s8, 3
	s_add_i32 s10, s9, s7
	s_add_i32 s6, s9, s6
	s_and_b32 s31, s10, -8
	s_sub_i32 s30, s6, s31
	s_lshl_b32 s12, s30, 8
	s_ashr_i32 s13, s12, 31
	s_lshl_b64 s[6:7], s[12:13], 11
	s_add_u32 s20, s90, s6
	s_addc_u32 s21, s91, s7
	s_lshl_b32 s6, s10, 5
	s_and_b32 s14, s6, 0xffffff00
	s_ashr_i32 s15, s14, 31
	s_lshl_b64 s[18:19], s[14:15], 11
	v_readlane_b32 s6, v253, 43
	v_readlane_b32 s7, v253, 44
	s_add_u32 s22, s6, s18
	s_addc_u32 s23, s7, s19
	s_cmp_gt_i32 s9, 63
	s_cselect_b64 s[16:17], -1, 0
	s_mov_b64 s[6:7], -1
	s_and_b64 vcc, exec, s[16:17]
	s_mul_i32 s13, s8, 0x58
	s_cbranch_vccz .LBB0_203
	v_mov_b32_e32 v12, v204
	s_mov_b64 s[10:11], 0x20000
	v_ashrrev_i32_e32 v2, 3, v12
	v_lshrrev_b32_e32 v14, 1, v2
	v_xor_b32_e32 v0, v14, v12
	v_ashrrev_i32_e32 v3, 31, v2
	v_lshlrev_b64 v[4:5], 11, v[2:3]
	v_lshlrev_b32_e32 v0, 4, v0
	v_and_b32_e32 v10, 31, v12
	v_lshl_add_u64 v[6:7], s[20:21], 0, v[4:5]
	v_and_b32_e32 v0, 0x70, v0
	v_lshl_add_u64 v[8:9], s[22:23], 0, v[4:5]
	v_lshrrev_b32_e32 v15, 1, v12
	v_lshl_add_u64 v[6:7], v[6:7], 0, v[0:1]
	v_lshl_add_u64 v[8:9], v[8:9], 0, v[0:1]
	v_and_or_b32 v0, v15, s51, v10
	v_lshlrev_b32_e32 v169, 7, v0
	v_lshlrev_b32_e32 v0, 7, v12
	v_lshlrev_b32_e32 v171, 4, v12
	v_and_b32_e32 v170, 0x6f80, v0
	v_and_b32_e32 v0, 0x70, v171
	v_add_u32_e32 v172, 0x8000, v171
	v_lshl_add_u64 v[156:157], s[80:81], 0, v[0:1]
	v_cmp_gt_u32_e32 vcc, s50, v2
	v_readfirstlane_b32 s6, v171
	s_mov_b32 m0, s6
	v_cndmask_b32_e32 v11, v157, v7, vcc
	v_cndmask_b32_e32 v10, v156, v6, vcc
	v_readfirstlane_b32 s6, v172
	v_add_u32_e32 v0, 64, v2
	v_add_u32_e32 v173, 0x2000, v171
	s_barrier
	s_mov_b32 m0, s6
	v_lshl_add_u64 v[10:11], v[6:7], 0, s[10:11]
	v_cmp_gt_u32_e64 s[6:7], s50, v0
	v_readfirstlane_b32 s8, v173
	v_add_u32_e32 v174, 0xa000, v171
	v_cndmask_b32_e64 v11, v157, v11, s[6:7]
	v_cndmask_b32_e64 v10, v156, v10, s[6:7]
	s_mov_b32 m0, s8
	v_readfirstlane_b32 s8, v174
	v_lshl_add_u64 v[10:11], v[8:9], 0, s[10:11]
	s_mov_b32 m0, s8
	v_add_u32_e32 v0, 0x80, v2
	s_mov_b64 s[24:25], 0x40000
	v_add_u32_e32 v175, 0x4000, v171
	v_lshl_add_u64 v[10:11], v[6:7], 0, s[24:25]
	v_cmp_gt_u32_e64 s[8:9], s50, v0
	v_readfirstlane_b32 s10, v175
	v_add_u32_e32 v176, 0xc000, v171
	v_cndmask_b32_e64 v11, v157, v11, s[8:9]
	v_cndmask_b32_e64 v10, v156, v10, s[8:9]
	s_mov_b32 m0, s10
	v_readfirstlane_b32 s10, v176
	v_add_u32_e32 v0, 0xc0, v2
	s_mov_b64 s[34:35], 0x60000
	v_add_u32_e32 v177, 0x6000, v171
	v_lshl_add_u64 v[10:11], v[8:9], 0, s[24:25]
	s_mov_b32 m0, s10
	v_lshl_add_u64 v[2:3], v[6:7], 0, s[34:35]
	v_cmp_gt_u32_e64 s[10:11], s50, v0
	v_readfirstlane_b32 s24, v177
	v_add_u32_e32 v178, 0xe000, v171
	v_cndmask_b32_e64 v3, v157, v3, s[10:11]
	v_cndmask_b32_e64 v2, v156, v2, s[10:11]
	s_mov_b32 m0, s24
	v_readfirstlane_b32 s24, v178
	v_lshl_add_u64 v[2:3], v[8:9], 0, s[34:35]
	s_mov_b32 m0, s24
	v_bfe_u32 v13, v12, 5, 1
	v_bfe_u32 v16, v12, 1, 3
	v_bitop3_b32 v0, v15, v13, 7 bitop3:0x6c
	s_sub_i32 s24, s28, s31
	v_lshlrev_b32_e32 v179, 4, v0
	v_bitop3_b32 v0, v13, v16, 2 bitop3:0x36
	s_sub_i32 s24, s24, s13
	v_lshlrev_b32_e32 v180, 4, v0
	v_bitop3_b32 v0, v13, v16, 4 bitop3:0x36
	s_lshl_b32 s24, s24, 8
	v_lshlrev_b32_e32 v181, 4, v0
	v_bitop3_b32 v0, v13, v16, 6 bitop3:0x36
	s_ashr_i32 s25, s24, 31
	v_lshlrev_b32_e32 v182, 4, v0
	s_lshl_b64 s[24:25], s[24:25], 11
	v_bitop3_b32 v0, v14, 7, v12 bitop3:0x48
	v_lshl_add_u64 v[2:3], v[4:5], 0, s[24:25]
	v_lshlrev_b32_e32 v0, 4, v0
	v_or_b32_e32 v2, v2, v0
	v_lshl_add_u64 v[158:159], s[70:71], 0, v[2:3]
	v_lshl_add_u64 v[2:3], v[4:5], 0, s[18:19]
	s_waitcnt vmcnt(0)
	v_lshl_add_u64 v[2:3], v[2:3], 0, v[0:1]
	v_lshl_add_u64 v[160:161], s[70:71], 0, v[2:3]
	v_mov_b32_e32 v130, 0
	v_mov_b32_e32 v2, 0
	s_mov_b32 s15, 1
	v_add_u32_e32 v183, 0x10000, v171
	v_add_u32_e32 v185, 0x18000, v171
	v_add_u32_e32 v186, 0x12000, v171
	v_add_u32_e32 v187, 0x1a000, v171
	v_add_u32_e32 v188, 0x14000, v171
	v_add_u32_e32 v189, 0x1c000, v171
	v_add_u32_e32 v190, 0x16000, v171
	v_add_u32_e32 v191, 0x1e000, v171
	v_add_u32_e32 v192, 0x10000, v169
	v_or_b32_e32 v193, 0x10000, v170
	s_mov_b64 s[24:25], 0
	v_mov_b32_e32 v3, v2
	v_mov_b32_e32 v4, v2
	v_mov_b32_e32 v5, v2
	v_mov_b32_e32 v6, v2
	v_mov_b32_e32 v7, v2
	v_mov_b32_e32 v8, v2
	v_mov_b32_e32 v9, v2
	v_mov_b32_e32 v10, v2
	v_mov_b32_e32 v11, v2
	v_mov_b32_e32 v12, v2
	v_mov_b32_e32 v13, v2
	v_mov_b32_e32 v14, v2
	v_mov_b32_e32 v15, v2
	v_mov_b32_e32 v16, v2
	v_mov_b32_e32 v17, v2
	v_mov_b32_e32 v18, v2
	v_mov_b32_e32 v19, v2
	v_mov_b32_e32 v20, v2
	v_mov_b32_e32 v21, v2
	v_mov_b32_e32 v22, v2
	v_mov_b32_e32 v23, v2
	v_mov_b32_e32 v24, v2
	v_mov_b32_e32 v25, v2
	v_mov_b32_e32 v26, v2
	v_mov_b32_e32 v27, v2
	v_mov_b32_e32 v28, v2
	v_mov_b32_e32 v29, v2
	v_mov_b32_e32 v30, v2
	v_mov_b32_e32 v31, v2
	v_mov_b32_e32 v32, v2
	v_mov_b32_e32 v33, v2
	v_mov_b32_e32 v34, v2
	v_mov_b32_e32 v35, v2
	v_mov_b32_e32 v36, v2
	v_mov_b32_e32 v37, v2
	v_mov_b32_e32 v38, v2
	v_mov_b32_e32 v39, v2
	v_mov_b32_e32 v40, v2
	v_mov_b32_e32 v41, v2
	v_mov_b32_e32 v42, v2
	v_mov_b32_e32 v43, v2
	v_mov_b32_e32 v44, v2
	v_mov_b32_e32 v45, v2
	v_mov_b32_e32 v46, v2
	v_mov_b32_e32 v47, v2
	v_mov_b32_e32 v48, v2
	v_mov_b32_e32 v49, v2
	v_mov_b32_e32 v50, v2
	v_mov_b32_e32 v51, v2
	v_mov_b32_e32 v52, v2
	v_mov_b32_e32 v53, v2
	v_mov_b32_e32 v54, v2
	v_mov_b32_e32 v55, v2
	v_mov_b32_e32 v56, v2
; DI int opaque_tid() { int t = threadIdx.x; asm volatile("" : "+v"(t)); return t; }
; template <bool SWAP>
; DI void gemm_mainloop(f32x16 (&acc)[4][2], const u16* __restrict__ A, int lda, int rlo, int rhi,
;                       const u16* __restrict__ B, int ldb, int K, char* lds, const u16* zero_line) {
;   const int tid = opaque_tid(), lane = tid & 63, w = tid >> 6;
;   const int wm = w >> 2, wn = w & 3;
;   const int h = lane >> 5, r = lane & 31;
;   const int lr = tid >> 3, lc = tid & 7;
; #pragma unroll
;   for (int mi = 0; mi < 4; ++mi)
; #pragma unroll
;     for (int ni = 0; ni < 2; ++ni)
; #pragma unroll
;       for (int i = 0; i < 16; ++i) acc[mi][ni][i] = 0.f;
;   const int gch = (lc ^ ((lr >> 1) & 7)) * 8;
;   const u16* ap = A + (ptrdiff_t)lr * lda + gch;
;   const u16* bp = B + (ptrdiff_t)lr * ldb + gch;
;   const int nk = K >> 6;
;   typedef __attribute__((address_space(3))) unsigned lds_u32;
;   auto glds = [&](int kt, int st) {
;     char* as_ = lds + st * 65536 + tid * 16;
; #pragma unroll
;     for (int i = 0; i < 4; ++i) {
;       const int rr = lr + 64 * i;
;       const u16* srca = (rr >= rlo && rr < rhi) ? (ap + (ptrdiff_t)(64 * i) * lda + kt * 64) : (zero_line + lc * 8);
;       __builtin_amdgcn_global_load_lds((const unsigned*)srca, (lds_u32*)(as_ + i * 8192), 16, 0, 0);
;       __builtin_amdgcn_global_load_lds((const unsigned*)(bp + (ptrdiff_t)(64 * i) * ldb + kt * 64), (lds_u32*)(as_ + 32768 + i * 8192), 16, 0, 0);
;     }
;   };
;   const int sw = (r >> 1) & 7;
;   const int arow_off = (wm * 128 + r) * 128;
;   const int brow_off = 32768 + (wn * 64 + r) * 128;
;   __syncthreads();
;   glds(0, 0);
;   asm volatile("s_waitcnt vmcnt(0)" ::: "memory");
;   __syncthreads();
	v_mov_b32_e32 v57, v2
	v_mov_b32_e32 v58, v2
	v_mov_b32_e32 v59, v2
	v_mov_b32_e32 v60, v2
	v_mov_b32_e32 v61, v2
	v_mov_b32_e32 v62, v2
	v_mov_b32_e32 v63, v2
	v_mov_b32_e32 v64, v2
	v_mov_b32_e32 v65, v2
	v_mov_b32_e32 v66, v2
	v_mov_b32_e32 v67, v2
	v_mov_b32_e32 v68, v2
	v_mov_b32_e32 v69, v2
	v_mov_b32_e32 v70, v2
	v_mov_b32_e32 v71, v2
	v_mov_b32_e32 v72, v2
	v_mov_b32_e32 v73, v2
	v_mov_b32_e32 v74, v2
	v_mov_b32_e32 v75, v2
	v_mov_b32_e32 v76, v2
	v_mov_b32_e32 v77, v2
	v_mov_b32_e32 v78, v2
	v_mov_b32_e32 v79, v2
	v_mov_b32_e32 v80, v2
	v_mov_b32_e32 v81, v2
	v_mov_b32_e32 v82, v2
	v_mov_b32_e32 v83, v2
	v_mov_b32_e32 v84, v2
	v_mov_b32_e32 v85, v2
	v_mov_b32_e32 v86, v2
	v_mov_b32_e32 v87, v2
	v_mov_b32_e32 v88, v2
	v_mov_b32_e32 v89, v2
	v_mov_b32_e32 v90, v2
	v_mov_b32_e32 v91, v2
	v_mov_b32_e32 v92, v2
	v_mov_b32_e32 v93, v2
	v_mov_b32_e32 v94, v2
	v_mov_b32_e32 v95, v2
	v_mov_b32_e32 v96, v2
	v_mov_b32_e32 v97, v2
	v_mov_b32_e32 v98, v2
	v_mov_b32_e32 v99, v2
	v_mov_b32_e32 v100, v2
	v_mov_b32_e32 v101, v2
	v_mov_b32_e32 v102, v2
	v_mov_b32_e32 v103, v2
	v_mov_b32_e32 v104, v2
	v_mov_b32_e32 v105, v2
	v_mov_b32_e32 v106, v2
	v_mov_b32_e32 v107, v2
	v_mov_b32_e32 v108, v2
	v_mov_b32_e32 v109, v2
	v_mov_b32_e32 v110, v2
	v_mov_b32_e32 v111, v2
	v_mov_b32_e32 v112, v2
	v_mov_b32_e32 v113, v2
	v_mov_b32_e32 v114, v2
	v_mov_b32_e32 v115, v2
	v_mov_b32_e32 v116, v2
	v_mov_b32_e32 v117, v2
	v_mov_b32_e32 v118, v2
	v_mov_b32_e32 v119, v2
	v_mov_b32_e32 v120, v2
	v_mov_b32_e32 v121, v2
	v_mov_b32_e32 v122, v2
	v_mov_b32_e32 v123, v2
	v_mov_b32_e32 v124, v2
	v_mov_b32_e32 v125, v2
	v_mov_b32_e32 v126, v2
	v_mov_b32_e32 v127, v2
	v_mov_b32_e32 v128, v2
	v_mov_b32_e32 v129, v2
	v_mov_b32_e32 v131, v130
	v_mov_b32_e32 v132, v130
	v_mov_b32_e32 v133, v130
	v_mov_b32_e32 v134, v130
	v_mov_b32_e32 v135, v130
	v_mov_b32_e32 v136, v130
	v_mov_b32_e32 v137, v130
	v_mov_b32_e32 v138, v130
	v_mov_b32_e32 v139, v130
	v_mov_b32_e32 v140, v130
	v_mov_b32_e32 v141, v130
	v_mov_b32_e32 v146, v130
	v_mov_b32_e32 v147, v130
	v_mov_b32_e32 v148, v130
	v_mov_b32_e32 v149, v130
	v_mov_b32_e32 v142, v130
	v_mov_b32_e32 v143, v130
	v_mov_b32_e32 v144, v130
	v_mov_b32_e32 v145, v130
	v_mov_b32_e32 v150, v130
	v_mov_b32_e32 v151, v130
	v_mov_b32_e32 v152, v130
	v_mov_b32_e32 v153, v130
	s_waitcnt vmcnt(0) lgkmcnt(0)
	s_barrier
	s_ashr_i32 s7, s12, 31
	s_mov_b32 s6, s12
	s_lshl_b64 s[6:7], s[6:7], 11
	s_add_u32 s6, s90, s6
	s_addc_u32 s7, s91, s7
	s_ashr_i32 s9, s14, 31
	s_mov_b32 s8, s14
	s_lshl_b64 s[8:9], s[8:9], 11
	v_readlane_b32 s10, v253, 43
	v_readlane_b32 s11, v253, 44
	s_add_u32 s8, s10, s8
	s_addc_u32 s9, s11, s9
	v_and_b32_e32 v130, 63, v204
	v_lshrrev_b32_e32 v131, 6, v204
	v_lshrrev_b32_e32 v132, 3, v204
	v_lshrrev_b32_e32 v0, 4, v130
	v_lshl_add_u32 v0, v131, 2, v0
	v_xor_b32_e32 v0, v0, v130
	v_and_b32_e32 v0, 7, v0
	v_lshlrev_b32_e32 v133, 4, v0
	v_lshl_add_u32 v232, v132, 11, v133
	v_add_u32_e32 v233, 0x20000, v232
	v_add_u32_e32 v234, 0x40000, v232
	v_add_u32_e32 v235, 0x60000, v232
	v_and_b32_e32 v0, 31, v132
	v_lshrrev_b32_e32 v130, 5, v132
	v_lshl_add_u32 v0, v130, 6, v0
	v_lshl_add_u32 v236, v0, 11, v133
	v_add_u32_e32 v237, 0x10000, v236
	v_add_u32_e32 v238, 0x40000, v236
	v_add_u32_e32 v239, 0x50000, v236
	v_and_b32_e32 v132, 31, v204
	v_lshrrev_b32_e32 v0, 2, v131
	v_lshl_add_u32 v0, v0, 6, v132
	v_lshlrev_b32_e32 v244, 7, v0
	v_and_b32_e32 v0, 3, v131
	v_lshl_add_u32 v0, v0, 5, v132
	v_lshlrev_b32_e32 v245, 7, v0
	v_bfe_u32 v0, v204, 5, 1
	v_bfe_u32 v130, v132, 1, 3
	v_or_b32_e32 v133, 0, v0
	v_xor_b32_e32 v133, v133, v130
	v_lshlrev_b32_e32 v240, 4, v133
	v_or_b32_e32 v133, 2, v0
	v_xor_b32_e32 v133, v133, v130
	v_lshlrev_b32_e32 v241, 4, v133
	v_or_b32_e32 v133, 4, v0
	v_xor_b32_e32 v133, v133, v130
	v_lshlrev_b32_e32 v242, 4, v133
	v_or_b32_e32 v133, 6, v0
	v_xor_b32_e32 v133, v133, v130
	v_lshlrev_b32_e32 v243, 4, v133
	v_add_u32_e32 v164, v245, v240
	v_add_u32_e32 v165, v245, v241
	v_add_u32_e32 v202, v245, v242
	v_add_u32_e32 v203, v245, v243
	v_add_u32_e32 v240, v244, v240
	v_add_u32_e32 v241, v244, v241
	v_add_u32_e32 v242, v244, v242
	v_add_u32_e32 v243, v244, v243
	v_lshlrev_b32_e32 v131, 10, v131
	s_nop 0
	v_readfirstlane_b32 s100, v131
	v_mov_b32_e32 v146, 0
	v_mov_b32_e32 v147, 0
	v_mov_b32_e32 v148, 0
	v_mov_b32_e32 v149, 0
	v_lshlrev_b32_e32 v130, 4, v204
	v_add_u32_e32 v132, 0x10000, v130
	s_mov_b64 exec, -1
	s_mov_b32 s11, 0
	s_mov_b32 s10, 0x10000
	s_waitcnt lgkmcnt(0)
	s_add_u32 m0, s100, 0x8000
	s_nop 0
	global_load_lds_dwordx4 v236, s[8:9]
	v_add_u32_e32 v236, 0x80, v236
	s_add_u32 m0, s100, 0xa000
	s_nop 0
	global_load_lds_dwordx4 v238, s[8:9]
	v_add_u32_e32 v238, 0x80, v238
	s_add_u32 m0, s100, 0x0
	s_nop 0
	global_load_lds_dwordx4 v232, s[6:7]
	v_add_u32_e32 v232, 0x80, v232
	s_add_u32 m0, s100, 0x2000
	s_nop 0
	global_load_lds_dwordx4 v234, s[6:7]
	v_add_u32_e32 v234, 0x80, v234
	s_add_u32 m0, s100, 0xc000
	s_nop 0
	global_load_lds_dwordx4 v237, s[8:9]
	v_add_u32_e32 v237, 0x80, v237
	s_add_u32 m0, s100, 0xe000
	s_nop 0
	global_load_lds_dwordx4 v239, s[8:9]
	v_add_u32_e32 v239, 0x80, v239
	s_add_u32 m0, s100, 0x4000
	s_nop 0
	global_load_lds_dwordx4 v233, s[6:7]
	v_add_u32_e32 v233, 0x80, v233
	s_add_u32 m0, s100, 0x6000
	s_nop 0
	global_load_lds_dwordx4 v235, s[6:7]
	v_add_u32_e32 v235, 0x80, v235
	s_cmp_eq_u32 s101, 1
	s_cbranch_scc0 .Lg8_qa_p0
	s_barrier
; #define MFMA(a, b, c) __builtin_amdgcn_mfma_f32_32x32x16_bf16((a), (b), (c), 0, 0, 0)
; template <bool SWAP>
; DI void gemm_mainloop(f32x16 (&acc)[4][2], const u16* __restrict__ A, int lda, int rlo, int rhi,
;                       const u16* __restrict__ B, int ldb, int K, char* lds, const u16* zero_line) {
;     ...
;   auto ldfrag = [&](const char* st, int ks, int buf) {
;     const int co = ((2 * ks + h) ^ sw) << 4;
; #pragma unroll
;     for (int mi = 0; mi < 4; ++mi) fa[buf][mi] = *(const bf16x8*)(st + arow_off + mi * 4096 + co);
; #pragma unroll
;     for (int ni = 0; ni < 2; ++ni) fb[buf][ni] = *(const bf16x8*)(st + brow_off + ni * 4096 + co);
;   };
;   auto mma = [&](int buf) {
; #pragma unroll
;     for (int mi = 0; mi < 4; ++mi)
; #pragma unroll
;       for (int ni = 0; ni < 2; ++ni)
;         acc[mi][ni] = SWAP ? MFMA(fb[buf][ni], fa[buf][mi], acc[mi][ni]) : MFMA(fa[buf][mi], fb[buf][ni], acc[mi][ni]);
;   };
;   auto pat_rd = [&]() {
; #pragma unroll
;     for (int g = 0; g < 6; ++g) {
;       __builtin_amdgcn_sched_group_barrier(0x100, 1, 0);
;       __builtin_amdgcn_sched_group_barrier(0x008, 1, 0);
;     }
;     __builtin_amdgcn_sched_group_barrier(0x008, 2, 0);
;   };
; #pragma unroll 2
;   for (int kt = 0; kt < nk; ++kt) {
;     const char* st = lds + (kt & 1) * 65536;
;     ldfrag(st, 0, 0);
;     mma(1);
;     pat_rd();
;     if (kt + 1 < nk) glds(kt + 1, (kt + 1) & 1);
;     ldfrag(st, 1, 1);
;     mma(0);
;     pat_rd();
;     ldfrag(st, 2, 0);
;     mma(1);
;     pat_rd();
;     ldfrag(st, 3, 1);
;     mma(0);
;     pat_rd();
;     asm volatile("s_waitcnt vmcnt(0)" ::: "memory");
;     __syncthreads();
;   }
.Lg8_qa_p0:
	s_waitcnt vmcnt(4)
	s_barrier
	s_add_u32 m0, s100, 0x18000
	s_nop 0
	global_load_lds_dwordx4 v236, s[8:9]
	v_add_u32_e32 v236, 0x80, v236
	s_add_u32 m0, s100, 0x1a000
	s_nop 0
	global_load_lds_dwordx4 v238, s[8:9]
	v_add_u32_e32 v238, 0x80, v238
	s_add_u32 m0, s100, 0x10000
	s_nop 0
	global_load_lds_dwordx4 v232, s[6:7]
	v_add_u32_e32 v232, 0x80, v232
	s_add_u32 m0, s100, 0x12000
	s_nop 0
	global_load_lds_dwordx4 v234, s[6:7]
	v_add_u32_e32 v234, 0x80, v234
	s_add_u32 m0, s100, 0x1c000
	s_nop 0
	global_load_lds_dwordx4 v237, s[8:9]
	v_add_u32_e32 v237, 0x80, v237
	s_add_u32 m0, s100, 0x1e000
	s_nop 0
	global_load_lds_dwordx4 v239, s[8:9]
	v_add_u32_e32 v239, 0x80, v239
	s_waitcnt vmcnt(6)
	s_barrier
	ds_read_b128 v[170:173], v164 offset:32768
	ds_read_b128 v[174:177], v165 offset:32768
	ds_read_b128 v[178:181], v202 offset:32768
	ds_read_b128 v[186:189], v203 offset:32768
.Lg8_qa:
	ds_read_b128 v[130:133], v240
	ds_read_b128 v[134:137], v241
	ds_read_b128 v[138:141], v242
	ds_read_b128 v[142:145], v243
	ds_read_b128 v[146:149], v240 offset:4096
	ds_read_b128 v[150:153], v241 offset:4096
	ds_read_b128 v[156:159], v242 offset:4096
	ds_read_b128 v[160:163], v243 offset:4096
	s_add_u32 m0, s100, 0x14000
	s_nop 0
	global_load_lds_dwordx4 v233, s[6:7]
	v_add_u32_e32 v233, 0x80, v233
	s_add_u32 m0, s100, 0x16000
	s_nop 0
	global_load_lds_dwordx4 v235, s[6:7]
	v_add_u32_e32 v235, 0x80, v235
	s_barrier
	s_waitcnt lgkmcnt(0)
	v_mfma_f32_32x32x16_bf16 v[114:129], v[130:133], v[170:173], v[114:129]
	v_mfma_f32_32x32x16_bf16 v[82:97], v[146:149], v[170:173], v[82:97]
	v_mfma_f32_32x32x16_bf16 v[114:129], v[134:137], v[174:177], v[114:129]
	v_mfma_f32_32x32x16_bf16 v[82:97], v[150:153], v[174:177], v[82:97]
	v_mfma_f32_32x32x16_bf16 v[114:129], v[138:141], v[178:181], v[114:129]
	v_mfma_f32_32x32x16_bf16 v[82:97], v[156:159], v[178:181], v[82:97]
	v_mfma_f32_32x32x16_bf16 v[114:129], v[142:145], v[186:189], v[114:129]
	v_mfma_f32_32x32x16_bf16 v[82:97], v[160:163], v[186:189], v[82:97]
	s_barrier
	ds_read_b128 v[190:193], v164 offset:49152
	ds_read_b128 v[194:197], v165 offset:49152
	ds_read_b128 v[198:201], v202 offset:49152
	ds_read_b128 v[228:231], v203 offset:49152
	s_add_u32 m0, s100, 0x8000
	s_nop 0
	global_load_lds_dwordx4 v236, s[8:9]
	v_add_u32_e32 v236, 0x80, v236
	s_add_u32 m0, s100, 0xa000
	s_nop 0
	global_load_lds_dwordx4 v238, s[8:9]
	v_add_u32_e32 v238, 0x80, v238
	s_barrier
	s_waitcnt lgkmcnt(0)
	v_mfma_f32_32x32x16_bf16 v[98:113], v[130:133], v[190:193], v[98:113]
	v_mfma_f32_32x32x16_bf16 v[66:81], v[146:149], v[190:193], v[66:81]
	v_mfma_f32_32x32x16_bf16 v[98:113], v[134:137], v[194:197], v[98:113]
	v_mfma_f32_32x32x16_bf16 v[66:81], v[150:153], v[194:197], v[66:81]
	v_mfma_f32_32x32x16_bf16 v[98:113], v[138:141], v[198:201], v[98:113]
	v_mfma_f32_32x32x16_bf16 v[66:81], v[156:159], v[198:201], v[66:81]
	v_mfma_f32_32x32x16_bf16 v[98:113], v[142:145], v[228:231], v[98:113]
	v_mfma_f32_32x32x16_bf16 v[66:81], v[160:163], v[228:231], v[66:81]
	s_barrier
	ds_read_b128 v[130:133], v240 offset:16384
	ds_read_b128 v[134:137], v241 offset:16384
	ds_read_b128 v[138:141], v242 offset:16384
	ds_read_b128 v[142:145], v243 offset:16384
	ds_read_b128 v[146:149], v240 offset:20480
	ds_read_b128 v[150:153], v241 offset:20480
	ds_read_b128 v[156:159], v242 offset:20480
	ds_read_b128 v[160:163], v243 offset:20480
	s_add_u32 m0, s100, 0x0
	s_nop 0
	global_load_lds_dwordx4 v232, s[6:7]
	v_add_u32_e32 v232, 0x80, v232
	s_add_u32 m0, s100, 0x2000
	s_nop 0
	global_load_lds_dwordx4 v234, s[6:7]
	v_add_u32_e32 v234, 0x80, v234
	s_waitcnt vmcnt(10)
	s_barrier
	s_waitcnt lgkmcnt(0)
	v_mfma_f32_32x32x16_bf16 v[50:65], v[130:133], v[170:173], v[50:65]
	v_mfma_f32_32x32x16_bf16 v[18:33], v[146:149], v[170:173], v[18:33]
	v_mfma_f32_32x32x16_bf16 v[50:65], v[134:137], v[174:177], v[50:65]
	v_mfma_f32_32x32x16_bf16 v[18:33], v[150:153], v[174:177], v[18:33]
	v_mfma_f32_32x32x16_bf16 v[50:65], v[138:141], v[178:181], v[50:65]
	v_mfma_f32_32x32x16_bf16 v[18:33], v[156:159], v[178:181], v[18:33]
	v_mfma_f32_32x32x16_bf16 v[50:65], v[142:145], v[186:189], v[50:65]
	v_mfma_f32_32x32x16_bf16 v[18:33], v[160:163], v[186:189], v[18:33]
	s_barrier
	v_add_u32_e32 v246, s10, v164
	v_add_u32_e32 v247, s10, v165
	v_add_u32_e32 v248, s10, v202
	v_add_u32_e32 v249, s10, v203
	ds_read_b128 v[170:173], v246 offset:32768
	ds_read_b128 v[174:177], v247 offset:32768
	ds_read_b128 v[178:181], v248 offset:32768
	ds_read_b128 v[186:189], v249 offset:32768
	s_add_u32 m0, s100, 0xc000
	s_nop 0
	global_load_lds_dwordx4 v237, s[8:9]
	v_add_u32_e32 v237, 0x80, v237
	s_add_u32 m0, s100, 0xe000
	s_nop 0
	global_load_lds_dwordx4 v239, s[8:9]
	v_add_u32_e32 v239, 0x80, v239
	s_waitcnt vmcnt(6)
	s_barrier
	s_waitcnt lgkmcnt(0)
	v_mfma_f32_32x32x16_bf16 v[34:49], v[130:133], v[190:193], v[34:49]
	v_mfma_f32_32x32x16_bf16 v[2:17], v[146:149], v[190:193], v[2:17]
	v_mfma_f32_32x32x16_bf16 v[34:49], v[134:137], v[194:197], v[34:49]
	v_mfma_f32_32x32x16_bf16 v[2:17], v[150:153], v[194:197], v[2:17]
	v_mfma_f32_32x32x16_bf16 v[34:49], v[138:141], v[198:201], v[34:49]
	v_mfma_f32_32x32x16_bf16 v[2:17], v[156:159], v[198:201], v[2:17]
	v_mfma_f32_32x32x16_bf16 v[34:49], v[142:145], v[228:231], v[34:49]
	v_mfma_f32_32x32x16_bf16 v[2:17], v[160:163], v[228:231], v[2:17]
	s_barrier
; #define MFMA(a, b, c) __builtin_amdgcn_mfma_f32_32x32x16_bf16((a), (b), (c), 0, 0, 0)
; template <bool SWAP>
; DI void gemm_mainloop(f32x16 (&acc)[4][2], const u16* __restrict__ A, int lda, int rlo, int rhi,
;                       const u16* __restrict__ B, int ldb, int K, char* lds, const u16* zero_line) {
;     ...
;   auto ldfrag = [&](const char* st, int ks, int buf) {
;     const int co = ((2 * ks + h) ^ sw) << 4;
; #pragma unroll
;     for (int mi = 0; mi < 4; ++mi) fa[buf][mi] = *(const bf16x8*)(st + arow_off + mi * 4096 + co);
; #pragma unroll
;     for (int ni = 0; ni < 2; ++ni) fb[buf][ni] = *(const bf16x8*)(st + brow_off + ni * 4096 + co);
;   };
;   auto mma = [&](int buf) {
; #pragma unroll
;     for (int mi = 0; mi < 4; ++mi)
; #pragma unroll
;       for (int ni = 0; ni < 2; ++ni)
;         acc[mi][ni] = SWAP ? MFMA(fb[buf][ni], fa[buf][mi], acc[mi][ni]) : MFMA(fa[buf][mi], fb[buf][ni], acc[mi][ni]);
;   };
;   auto pat_rd = [&]() {
; #pragma unroll
;     for (int g = 0; g < 6; ++g) {
;       __builtin_amdgcn_sched_group_barrier(0x100, 1, 0);
;       __builtin_amdgcn_sched_group_barrier(0x008, 1, 0);
;     }
;     __builtin_amdgcn_sched_group_barrier(0x008, 2, 0);
;   };
; #pragma unroll 2
;   for (int kt = 0; kt < nk; ++kt) {
;     const char* st = lds + (kt & 1) * 65536;
;     ldfrag(st, 0, 0);
;     mma(1);
;     pat_rd();
;     if (kt + 1 < nk) glds(kt + 1, (kt + 1) & 1);
;     ldfrag(st, 1, 1);
;     mma(0);
;     pat_rd();
;     ldfrag(st, 2, 0);
;     mma(1);
;     pat_rd();
;     ldfrag(st, 3, 1);
;     mma(0);
;     pat_rd();
;     asm volatile("s_waitcnt vmcnt(0)" ::: "memory");
;     __syncthreads();
;   }
	v_add_u32_e32 v246, s10, v240
	v_add_u32_e32 v247, s10, v241
	v_add_u32_e32 v248, s10, v242
	v_add_u32_e32 v249, s10, v243
	ds_read_b128 v[130:133], v246
	ds_read_b128 v[134:137], v247
	ds_read_b128 v[138:141], v248
	ds_read_b128 v[142:145], v249
	ds_read_b128 v[146:149], v246 offset:4096
	ds_read_b128 v[150:153], v247 offset:4096
	ds_read_b128 v[156:159], v248 offset:4096
	ds_read_b128 v[160:163], v249 offset:4096
	s_add_u32 m0, s100, 0x4000
	s_nop 0
	global_load_lds_dwordx4 v233, s[6:7]
	v_add_u32_e32 v233, 0x80, v233
	s_add_u32 m0, s100, 0x6000
	s_nop 0
	global_load_lds_dwordx4 v235, s[6:7]
	v_add_u32_e32 v235, 0x80, v235
	s_barrier
	s_waitcnt lgkmcnt(0)
	v_mfma_f32_32x32x16_bf16 v[114:129], v[130:133], v[170:173], v[114:129]
	v_mfma_f32_32x32x16_bf16 v[82:97], v[146:149], v[170:173], v[82:97]
	v_mfma_f32_32x32x16_bf16 v[114:129], v[134:137], v[174:177], v[114:129]
	v_mfma_f32_32x32x16_bf16 v[82:97], v[150:153], v[174:177], v[82:97]
	v_mfma_f32_32x32x16_bf16 v[114:129], v[138:141], v[178:181], v[114:129]
	v_mfma_f32_32x32x16_bf16 v[82:97], v[156:159], v[178:181], v[82:97]
	v_mfma_f32_32x32x16_bf16 v[114:129], v[142:145], v[186:189], v[114:129]
	v_mfma_f32_32x32x16_bf16 v[82:97], v[160:163], v[186:189], v[82:97]
	s_barrier
	v_add_u32_e32 v246, s10, v164
	v_add_u32_e32 v247, s10, v165
	v_add_u32_e32 v248, s10, v202
	v_add_u32_e32 v249, s10, v203
	ds_read_b128 v[190:193], v246 offset:49152
	ds_read_b128 v[194:197], v247 offset:49152
	ds_read_b128 v[198:201], v248 offset:49152
	ds_read_b128 v[228:231], v249 offset:49152
	s_add_u32 m0, s100, 0x18000
	s_nop 0
	global_load_lds_dwordx4 v236, s[8:9]
	v_add_u32_e32 v236, 0x80, v236
	s_add_u32 m0, s100, 0x1a000
	s_nop 0
	global_load_lds_dwordx4 v238, s[8:9]
	v_add_u32_e32 v238, 0x80, v238
	s_barrier
	s_waitcnt lgkmcnt(0)
	v_mfma_f32_32x32x16_bf16 v[98:113], v[130:133], v[190:193], v[98:113]
	v_mfma_f32_32x32x16_bf16 v[66:81], v[146:149], v[190:193], v[66:81]
	v_mfma_f32_32x32x16_bf16 v[98:113], v[134:137], v[194:197], v[98:113]
	v_mfma_f32_32x32x16_bf16 v[66:81], v[150:153], v[194:197], v[66:81]
	v_mfma_f32_32x32x16_bf16 v[98:113], v[138:141], v[198:201], v[98:113]
	v_mfma_f32_32x32x16_bf16 v[66:81], v[156:159], v[198:201], v[66:81]
	v_mfma_f32_32x32x16_bf16 v[98:113], v[142:145], v[228:231], v[98:113]
	v_mfma_f32_32x32x16_bf16 v[66:81], v[160:163], v[228:231], v[66:81]
	s_barrier
	v_add_u32_e32 v246, s10, v240
	v_add_u32_e32 v247, s10, v241
	v_add_u32_e32 v248, s10, v242
	v_add_u32_e32 v249, s10, v243
	ds_read_b128 v[130:133], v246 offset:16384
	ds_read_b128 v[134:137], v247 offset:16384
	ds_read_b128 v[138:141], v248 offset:16384
	ds_read_b128 v[142:145], v249 offset:16384
	ds_read_b128 v[146:149], v246 offset:20480
	ds_read_b128 v[150:153], v247 offset:20480
	ds_read_b128 v[156:159], v248 offset:20480
	ds_read_b128 v[160:163], v249 offset:20480
	s_add_u32 m0, s100, 0x10000
	s_nop 0
	global_load_lds_dwordx4 v232, s[6:7]
	v_add_u32_e32 v232, 0x80, v232
	s_add_u32 m0, s100, 0x12000
	s_nop 0
	global_load_lds_dwordx4 v234, s[6:7]
	v_add_u32_e32 v234, 0x80, v234
	s_waitcnt vmcnt(10)
	s_barrier
	s_waitcnt lgkmcnt(0)
	v_mfma_f32_32x32x16_bf16 v[50:65], v[130:133], v[170:173], v[50:65]
	v_mfma_f32_32x32x16_bf16 v[18:33], v[146:149], v[170:173], v[18:33]
	v_mfma_f32_32x32x16_bf16 v[50:65], v[134:137], v[174:177], v[50:65]
	v_mfma_f32_32x32x16_bf16 v[18:33], v[150:153], v[174:177], v[18:33]
	v_mfma_f32_32x32x16_bf16 v[50:65], v[138:141], v[178:181], v[50:65]
	v_mfma_f32_32x32x16_bf16 v[18:33], v[156:159], v[178:181], v[18:33]
	v_mfma_f32_32x32x16_bf16 v[50:65], v[142:145], v[186:189], v[50:65]
	v_mfma_f32_32x32x16_bf16 v[18:33], v[160:163], v[186:189], v[18:33]
	s_barrier
	ds_read_b128 v[170:173], v164 offset:32768
	ds_read_b128 v[174:177], v165 offset:32768
	ds_read_b128 v[178:181], v202 offset:32768
	ds_read_b128 v[186:189], v203 offset:32768
	s_add_u32 m0, s100, 0x1c000
	s_nop 0
	global_load_lds_dwordx4 v237, s[8:9]
	v_add_u32_e32 v237, 0x80, v237
	s_add_u32 m0, s100, 0x1e000
	s_nop 0
	global_load_lds_dwordx4 v239, s[8:9]
	v_add_u32_e32 v239, 0x80, v239
	s_waitcnt vmcnt(6)
	s_barrier
	s_waitcnt lgkmcnt(0)
	v_mfma_f32_32x32x16_bf16 v[34:49], v[130:133], v[190:193], v[34:49]
	v_mfma_f32_32x32x16_bf16 v[2:17], v[146:149], v[190:193], v[2:17]
	v_mfma_f32_32x32x16_bf16 v[34:49], v[134:137], v[194:197], v[34:49]
	v_mfma_f32_32x32x16_bf16 v[2:17], v[150:153], v[194:197], v[2:17]
	v_mfma_f32_32x32x16_bf16 v[34:49], v[138:141], v[198:201], v[34:49]
	v_mfma_f32_32x32x16_bf16 v[2:17], v[156:159], v[198:201], v[2:17]
	v_mfma_f32_32x32x16_bf16 v[34:49], v[142:145], v[228:231], v[34:49]
	v_mfma_f32_32x32x16_bf16 v[2:17], v[160:163], v[228:231], v[2:17]
	s_barrier
	s_add_i32 s11, s11, 2
	s_cmp_lt_u32 s11, 14
	s_cbranch_scc1 .Lg8_qa
	ds_read_b128 v[130:133], v240
	ds_read_b128 v[134:137], v241
	ds_read_b128 v[138:141], v242
	ds_read_b128 v[142:145], v243
	ds_read_b128 v[146:149], v240 offset:4096
	ds_read_b128 v[150:153], v241 offset:4096
	ds_read_b128 v[156:159], v242 offset:4096
	ds_read_b128 v[160:163], v243 offset:4096
	s_add_u32 m0, s100, 0x14000
	s_nop 0
	global_load_lds_dwordx4 v233, s[6:7]
	v_add_u32_e32 v233, 0x80, v233
	s_add_u32 m0, s100, 0x16000
	s_nop 0
	global_load_lds_dwordx4 v235, s[6:7]
	v_add_u32_e32 v235, 0x80, v235
	s_barrier
	s_waitcnt lgkmcnt(0)
	v_mfma_f32_32x32x16_bf16 v[114:129], v[130:133], v[170:173], v[114:129]
	v_mfma_f32_32x32x16_bf16 v[82:97], v[146:149], v[170:173], v[82:97]
	v_mfma_f32_32x32x16_bf16 v[114:129], v[134:137], v[174:177], v[114:129]
	v_mfma_f32_32x32x16_bf16 v[82:97], v[150:153], v[174:177], v[82:97]
	v_mfma_f32_32x32x16_bf16 v[114:129], v[138:141], v[178:181], v[114:129]
	v_mfma_f32_32x32x16_bf16 v[82:97], v[156:159], v[178:181], v[82:97]
	v_mfma_f32_32x32x16_bf16 v[114:129], v[142:145], v[186:189], v[114:129]
	v_mfma_f32_32x32x16_bf16 v[82:97], v[160:163], v[186:189], v[82:97]
	s_barrier
; #define MFMA(a, b, c) __builtin_amdgcn_mfma_f32_32x32x16_bf16((a), (b), (c), 0, 0, 0)
; template <bool SWAP>
; DI void gemm_mainloop(f32x16 (&acc)[4][2], const u16* __restrict__ A, int lda, int rlo, int rhi,
;                       const u16* __restrict__ B, int ldb, int K, char* lds, const u16* zero_line) {
;     ...
;   auto ldfrag = [&](const char* st, int ks, int buf) {
;     const int co = ((2 * ks + h) ^ sw) << 4;
; #pragma unroll
;     for (int mi = 0; mi < 4; ++mi) fa[buf][mi] = *(const bf16x8*)(st + arow_off + mi * 4096 + co);
; #pragma unroll
;     for (int ni = 0; ni < 2; ++ni) fb[buf][ni] = *(const bf16x8*)(st + brow_off + ni * 4096 + co);
;   };
;   auto mma = [&](int buf) {
; #pragma unroll
;     for (int mi = 0; mi < 4; ++mi)
; #pragma unroll
;       for (int ni = 0; ni < 2; ++ni)
;         acc[mi][ni] = SWAP ? MFMA(fb[buf][ni], fa[buf][mi], acc[mi][ni]) : MFMA(fa[buf][mi], fb[buf][ni], acc[mi][ni]);
;   };
;   auto pat_rd = [&]() {
; #pragma unroll
;     for (int g = 0; g < 6; ++g) {
;       __builtin_amdgcn_sched_group_barrier(0x100, 1, 0);
;       __builtin_amdgcn_sched_group_barrier(0x008, 1, 0);
;     }
;     __builtin_amdgcn_sched_group_barrier(0x008, 2, 0);
;   };
; #pragma unroll 2
;   for (int kt = 0; kt < nk; ++kt) {
;     const char* st = lds + (kt & 1) * 65536;
;     ldfrag(st, 0, 0);
;     mma(1);
;     pat_rd();
;     if (kt + 1 < nk) glds(kt + 1, (kt + 1) & 1);
;     ldfrag(st, 1, 1);
;     mma(0);
;     pat_rd();
;     ldfrag(st, 2, 0);
;     mma(1);
;     pat_rd();
;     ldfrag(st, 3, 1);
;     mma(0);
;     pat_rd();
;     asm volatile("s_waitcnt vmcnt(0)" ::: "memory");
;     __syncthreads();
;   }
;   mma(1);
	ds_read_b128 v[190:193], v164 offset:49152
	ds_read_b128 v[194:197], v165 offset:49152
	ds_read_b128 v[198:201], v202 offset:49152
	ds_read_b128 v[228:231], v203 offset:49152
	s_barrier
	s_waitcnt lgkmcnt(0)
	v_mfma_f32_32x32x16_bf16 v[98:113], v[130:133], v[190:193], v[98:113]
	v_mfma_f32_32x32x16_bf16 v[66:81], v[146:149], v[190:193], v[66:81]
	v_mfma_f32_32x32x16_bf16 v[98:113], v[134:137], v[194:197], v[98:113]
	v_mfma_f32_32x32x16_bf16 v[66:81], v[150:153], v[194:197], v[66:81]
	v_mfma_f32_32x32x16_bf16 v[98:113], v[138:141], v[198:201], v[98:113]
	v_mfma_f32_32x32x16_bf16 v[66:81], v[156:159], v[198:201], v[66:81]
	v_mfma_f32_32x32x16_bf16 v[98:113], v[142:145], v[228:231], v[98:113]
	v_mfma_f32_32x32x16_bf16 v[66:81], v[160:163], v[228:231], v[66:81]
	s_barrier
	ds_read_b128 v[130:133], v240 offset:16384
	ds_read_b128 v[134:137], v241 offset:16384
	ds_read_b128 v[138:141], v242 offset:16384
	ds_read_b128 v[142:145], v243 offset:16384
	ds_read_b128 v[146:149], v240 offset:20480
	ds_read_b128 v[150:153], v241 offset:20480
	ds_read_b128 v[156:159], v242 offset:20480
	ds_read_b128 v[160:163], v243 offset:20480
	s_waitcnt vmcnt(4)
	s_barrier
	s_waitcnt lgkmcnt(0)
	v_mfma_f32_32x32x16_bf16 v[50:65], v[130:133], v[170:173], v[50:65]
	v_mfma_f32_32x32x16_bf16 v[18:33], v[146:149], v[170:173], v[18:33]
	v_mfma_f32_32x32x16_bf16 v[50:65], v[134:137], v[174:177], v[50:65]
	v_mfma_f32_32x32x16_bf16 v[18:33], v[150:153], v[174:177], v[18:33]
	v_mfma_f32_32x32x16_bf16 v[50:65], v[138:141], v[178:181], v[50:65]
	v_mfma_f32_32x32x16_bf16 v[18:33], v[156:159], v[178:181], v[18:33]
	v_mfma_f32_32x32x16_bf16 v[50:65], v[142:145], v[186:189], v[50:65]
	v_mfma_f32_32x32x16_bf16 v[18:33], v[160:163], v[186:189], v[18:33]
	v_mfma_f32_32x32x16_bf16 v[34:49], v[130:133], v[190:193], v[34:49]
	v_mfma_f32_32x32x16_bf16 v[2:17], v[146:149], v[190:193], v[2:17]
	v_mfma_f32_32x32x16_bf16 v[34:49], v[134:137], v[194:197], v[34:49]
	v_mfma_f32_32x32x16_bf16 v[2:17], v[150:153], v[194:197], v[2:17]
	v_mfma_f32_32x32x16_bf16 v[34:49], v[138:141], v[198:201], v[34:49]
	v_mfma_f32_32x32x16_bf16 v[2:17], v[156:159], v[198:201], v[2:17]
	v_mfma_f32_32x32x16_bf16 v[34:49], v[142:145], v[228:231], v[34:49]
	v_mfma_f32_32x32x16_bf16 v[2:17], v[160:163], v[228:231], v[2:17]
	s_barrier
	v_add_u32_e32 v246, s10, v164
	v_add_u32_e32 v247, s10, v165
	v_add_u32_e32 v248, s10, v202
	v_add_u32_e32 v249, s10, v203
	ds_read_b128 v[170:173], v246 offset:32768
	ds_read_b128 v[174:177], v247 offset:32768
	ds_read_b128 v[178:181], v248 offset:32768
	ds_read_b128 v[186:189], v249 offset:32768
	v_add_u32_e32 v246, s10, v240
	v_add_u32_e32 v247, s10, v241
	v_add_u32_e32 v248, s10, v242
	v_add_u32_e32 v249, s10, v243
	ds_read_b128 v[130:133], v246
	ds_read_b128 v[134:137], v247
	ds_read_b128 v[138:141], v248
	ds_read_b128 v[142:145], v249
	ds_read_b128 v[146:149], v246 offset:4096
	ds_read_b128 v[150:153], v247 offset:4096
	ds_read_b128 v[156:159], v248 offset:4096
	ds_read_b128 v[160:163], v249 offset:4096
	s_waitcnt vmcnt(2)
	s_barrier
	s_waitcnt lgkmcnt(0)
	v_mfma_f32_32x32x16_bf16 v[114:129], v[130:133], v[170:173], v[114:129]
	v_mfma_f32_32x32x16_bf16 v[82:97], v[146:149], v[170:173], v[82:97]
	v_mfma_f32_32x32x16_bf16 v[114:129], v[134:137], v[174:177], v[114:129]
	v_mfma_f32_32x32x16_bf16 v[82:97], v[150:153], v[174:177], v[82:97]
	v_mfma_f32_32x32x16_bf16 v[114:129], v[138:141], v[178:181], v[114:129]
	v_mfma_f32_32x32x16_bf16 v[82:97], v[156:159], v[178:181], v[82:97]
	v_mfma_f32_32x32x16_bf16 v[114:129], v[142:145], v[186:189], v[114:129]
	v_mfma_f32_32x32x16_bf16 v[82:97], v[160:163], v[186:189], v[82:97]
	s_barrier
	v_add_u32_e32 v246, s10, v164
	v_add_u32_e32 v247, s10, v165
	v_add_u32_e32 v248, s10, v202
	v_add_u32_e32 v249, s10, v203
	ds_read_b128 v[190:193], v246 offset:49152
	ds_read_b128 v[194:197], v247 offset:49152
	ds_read_b128 v[198:201], v248 offset:49152
	ds_read_b128 v[228:231], v249 offset:49152
	s_waitcnt vmcnt(0)
	s_barrier
	s_waitcnt lgkmcnt(0)
	v_mfma_f32_32x32x16_bf16 v[98:113], v[130:133], v[190:193], v[98:113]
	v_mfma_f32_32x32x16_bf16 v[66:81], v[146:149], v[190:193], v[66:81]
	v_mfma_f32_32x32x16_bf16 v[98:113], v[134:137], v[194:197], v[98:113]
	v_mfma_f32_32x32x16_bf16 v[66:81], v[150:153], v[194:197], v[66:81]
	v_mfma_f32_32x32x16_bf16 v[98:113], v[138:141], v[198:201], v[98:113]
	v_mfma_f32_32x32x16_bf16 v[66:81], v[156:159], v[198:201], v[66:81]
	v_mfma_f32_32x32x16_bf16 v[98:113], v[142:145], v[228:231], v[98:113]
	v_mfma_f32_32x32x16_bf16 v[66:81], v[160:163], v[228:231], v[66:81]
	s_barrier
	v_add_u32_e32 v246, s10, v240
	v_add_u32_e32 v247, s10, v241
	v_add_u32_e32 v248, s10, v242
	v_add_u32_e32 v249, s10, v243
	ds_read_b128 v[130:133], v246 offset:16384
	ds_read_b128 v[134:137], v247 offset:16384
	ds_read_b128 v[138:141], v248 offset:16384
	ds_read_b128 v[142:145], v249 offset:16384
	ds_read_b128 v[146:149], v246 offset:20480
	ds_read_b128 v[150:153], v247 offset:20480
	ds_read_b128 v[156:159], v248 offset:20480
	ds_read_b128 v[160:163], v249 offset:20480
	s_barrier
	s_waitcnt lgkmcnt(0)
	v_mfma_f32_32x32x16_bf16 v[50:65], v[130:133], v[170:173], v[50:65]
	v_mfma_f32_32x32x16_bf16 v[18:33], v[146:149], v[170:173], v[18:33]
	v_mfma_f32_32x32x16_bf16 v[50:65], v[134:137], v[174:177], v[50:65]
	v_mfma_f32_32x32x16_bf16 v[18:33], v[150:153], v[174:177], v[18:33]
	v_mfma_f32_32x32x16_bf16 v[50:65], v[138:141], v[178:181], v[50:65]
	v_mfma_f32_32x32x16_bf16 v[18:33], v[156:159], v[178:181], v[18:33]
	v_mfma_f32_32x32x16_bf16 v[50:65], v[142:145], v[186:189], v[50:65]
	v_mfma_f32_32x32x16_bf16 v[18:33], v[160:163], v[186:189], v[18:33]
	v_mfma_f32_32x32x16_bf16 v[34:49], v[130:133], v[190:193], v[34:49]
	v_mfma_f32_32x32x16_bf16 v[2:17], v[146:149], v[190:193], v[2:17]
	v_mfma_f32_32x32x16_bf16 v[34:49], v[134:137], v[194:197], v[34:49]
	v_mfma_f32_32x32x16_bf16 v[2:17], v[150:153], v[194:197], v[2:17]
	v_mfma_f32_32x32x16_bf16 v[34:49], v[138:141], v[198:201], v[34:49]
	v_mfma_f32_32x32x16_bf16 v[2:17], v[156:159], v[198:201], v[2:17]
	v_mfma_f32_32x32x16_bf16 v[34:49], v[142:145], v[228:231], v[34:49]
	v_mfma_f32_32x32x16_bf16 v[2:17], v[160:163], v[228:231], v[2:17]
	s_barrier
	s_cmp_eq_u32 s101, 0
	s_cbranch_scc0 .Lg8_qa_p1
	s_barrier

; DI int opaque_tid() { int t = threadIdx.x; asm volatile("" : "+v"(t)); return t; }
; template <bool SWAP>
; DI void gemm_mainloop(f32x16 (&acc)[4][2], const u16* __restrict__ A, int lda, int rlo, int rhi,
;                       const u16* __restrict__ B, int ldb, int K, char* lds, const u16* zero_line) {
;   const int tid = opaque_tid(), lane = tid & 63, w = tid >> 6;
;   const int wm = w >> 2, wn = w & 3;
;   const int h = lane >> 5, r = lane & 31;
;   const int lr = tid >> 3, lc = tid & 7;
; #pragma unroll
;   for (int mi = 0; mi < 4; ++mi)
; #pragma unroll
;     for (int ni = 0; ni < 2; ++ni)
; #pragma unroll
;       for (int i = 0; i < 16; ++i) acc[mi][ni][i] = 0.f;
;   const int gch = (lc ^ ((lr >> 1) & 7)) * 8;
;   const u16* ap = A + (ptrdiff_t)lr * lda + gch;
;   const u16* bp = B + (ptrdiff_t)lr * ldb + gch;
;   const int nk = K >> 6;
;   typedef __attribute__((address_space(3))) unsigned lds_u32;
;   auto glds = [&](int kt, int st) {
;     char* as_ = lds + st * 65536 + tid * 16;
; #pragma unroll
;     for (int i = 0; i < 4; ++i) {
;       const int rr = lr + 64 * i;
;       const u16* srca = (rr >= rlo && rr < rhi) ? (ap + (ptrdiff_t)(64 * i) * lda + kt * 64) : (zero_line + lc * 8);
;       __builtin_amdgcn_global_load_lds((const unsigned*)srca, (lds_u32*)(as_ + i * 8192), 16, 0, 0);
;       __builtin_amdgcn_global_load_lds((const unsigned*)(bp + (ptrdiff_t)(64 * i) * ldb + kt * 64), (lds_u32*)(as_ + 32768 + i * 8192), 16, 0, 0);
;     }
;   };
;   const int sw = (r >> 1) & 7;
;   const int arow_off = (wm * 128 + r) * 128;
;   const int brow_off = 32768 + (wn * 64 + r) * 128;
;   __syncthreads();
;   glds(0, 0);
;   asm volatile("s_waitcnt vmcnt(0)" ::: "memory");
;   __syncthreads();
;   bf16x8 fa[2][4], fb[2][2];
; #pragma unroll
;   for (int mi = 0; mi < 4; ++mi)
; #pragma unroll
;     for (int e = 0; e < 8; ++e) fa[1][mi][e] = 0;
.LBB0_203:
	s_and_b64 vcc, exec, s[6:7]
	s_cbranch_vccz .LBB0_209
	s_nop 9
	v_mov_b32_e32 v12, v204
	s_mov_b64 s[10:11], 0x20000
	v_ashrrev_i32_e32 v2, 3, v12
	v_lshrrev_b32_e32 v14, 1, v2
	v_xor_b32_e32 v0, v14, v12
	v_ashrrev_i32_e32 v3, 31, v2
	v_lshlrev_b64 v[4:5], 11, v[2:3]
	v_lshlrev_b32_e32 v0, 4, v0
	v_and_b32_e32 v10, 31, v12
	v_lshl_add_u64 v[6:7], s[20:21], 0, v[4:5]
	v_and_b32_e32 v0, 0x70, v0
	v_lshl_add_u64 v[8:9], s[22:23], 0, v[4:5]
	v_lshrrev_b32_e32 v15, 1, v12
	v_lshl_add_u64 v[6:7], v[6:7], 0, v[0:1]
	v_lshl_add_u64 v[8:9], v[8:9], 0, v[0:1]
	v_and_or_b32 v0, v15, s51, v10
	v_lshlrev_b32_e32 v169, 7, v0
	v_lshlrev_b32_e32 v0, 7, v12
	v_lshlrev_b32_e32 v171, 4, v12
	v_and_b32_e32 v170, 0x6f80, v0
	v_and_b32_e32 v0, 0x70, v171
	v_add_u32_e32 v172, 0x8000, v171
	v_lshl_add_u64 v[156:157], s[80:81], 0, v[0:1]
	v_cmp_gt_u32_e32 vcc, s50, v2
	v_readfirstlane_b32 s6, v171
	s_mov_b32 m0, s6
	v_cndmask_b32_e32 v11, v157, v7, vcc
	v_cndmask_b32_e32 v10, v156, v6, vcc
	v_readfirstlane_b32 s6, v172
	v_add_u32_e32 v0, 64, v2
	v_add_u32_e32 v173, 0x2000, v171
	s_barrier
	s_mov_b32 m0, s6
	v_lshl_add_u64 v[10:11], v[6:7], 0, s[10:11]
	v_cmp_gt_u32_e64 s[6:7], s50, v0
	v_readfirstlane_b32 s8, v173
	v_add_u32_e32 v174, 0xa000, v171
	v_cndmask_b32_e64 v11, v157, v11, s[6:7]
	v_cndmask_b32_e64 v10, v156, v10, s[6:7]
	s_mov_b32 m0, s8
	v_readfirstlane_b32 s8, v174
	v_lshl_add_u64 v[10:11], v[8:9], 0, s[10:11]
	s_mov_b32 m0, s8
	v_add_u32_e32 v0, 0x80, v2
	s_mov_b64 s[20:21], 0x40000
	v_add_u32_e32 v175, 0x4000, v171
	v_lshl_add_u64 v[10:11], v[6:7], 0, s[20:21]
	v_cmp_gt_u32_e64 s[8:9], s50, v0
	v_readfirstlane_b32 s10, v175
	v_add_u32_e32 v176, 0xc000, v171
	v_cndmask_b32_e64 v11, v157, v11, s[8:9]
	v_cndmask_b32_e64 v10, v156, v10, s[8:9]
	s_mov_b32 m0, s10
	v_readfirstlane_b32 s10, v176
	v_add_u32_e32 v0, 0xc0, v2
	s_mov_b64 s[22:23], 0x60000
	v_add_u32_e32 v177, 0x6000, v171
	v_lshl_add_u64 v[10:11], v[8:9], 0, s[20:21]
	s_mov_b32 m0, s10
	v_lshl_add_u64 v[2:3], v[6:7], 0, s[22:23]
	v_cmp_gt_u32_e64 s[10:11], s50, v0
	v_readfirstlane_b32 s20, v177
	v_add_u32_e32 v178, 0xe000, v171
	v_cndmask_b32_e64 v3, v157, v3, s[10:11]
	v_cndmask_b32_e64 v2, v156, v2, s[10:11]
	s_mov_b32 m0, s20
	v_readfirstlane_b32 s20, v178
	v_lshl_add_u64 v[2:3], v[8:9], 0, s[22:23]
	s_mov_b32 m0, s20
	v_bfe_u32 v13, v12, 5, 1
	v_bfe_u32 v16, v12, 1, 3
	v_bitop3_b32 v0, v15, v13, 7 bitop3:0x6c
	s_sub_i32 s20, s28, s31
	v_lshlrev_b32_e32 v179, 4, v0
	v_bitop3_b32 v0, v13, v16, 2 bitop3:0x36
	s_sub_i32 s13, s20, s13
	v_lshlrev_b32_e32 v180, 4, v0
	v_bitop3_b32 v0, v13, v16, 4 bitop3:0x36
	s_lshl_b32 s20, s13, 8
	v_lshlrev_b32_e32 v181, 4, v0
	v_bitop3_b32 v0, v13, v16, 6 bitop3:0x36
	s_ashr_i32 s21, s20, 31
	v_lshlrev_b32_e32 v182, 4, v0
	s_lshl_b64 s[20:21], s[20:21], 11
	v_bitop3_b32 v0, v14, 7, v12 bitop3:0x48
	v_lshl_add_u64 v[2:3], v[4:5], 0, s[20:21]
	v_lshlrev_b32_e32 v0, 4, v0
	v_or_b32_e32 v2, v2, v0
	v_lshl_add_u64 v[158:159], s[70:71], 0, v[2:3]
	v_lshl_add_u64 v[2:3], v[4:5], 0, s[18:19]
	s_waitcnt vmcnt(0)
	v_lshl_add_u64 v[2:3], v[2:3], 0, v[0:1]
	v_lshl_add_u64 v[160:161], s[70:71], 0, v[2:3]
	v_mov_b32_e32 v130, 0
	v_mov_b32_e32 v2, 0
	s_mov_b32 s15, 1
	v_add_u32_e32 v183, 0x10000, v171
	v_add_u32_e32 v185, 0x18000, v171
	v_add_u32_e32 v186, 0x12000, v171
	v_add_u32_e32 v187, 0x1a000, v171
	v_add_u32_e32 v188, 0x14000, v171
	v_add_u32_e32 v189, 0x1c000, v171
	v_add_u32_e32 v190, 0x16000, v171
	v_add_u32_e32 v191, 0x1e000, v171
	v_add_u32_e32 v192, 0x10000, v169
	v_or_b32_e32 v193, 0x10000, v170
	s_mov_b64 s[18:19], 0
	v_mov_b32_e32 v3, v2
	v_mov_b32_e32 v4, v2
	v_mov_b32_e32 v5, v2
	v_mov_b32_e32 v6, v2
	v_mov_b32_e32 v7, v2
	v_mov_b32_e32 v8, v2
	v_mov_b32_e32 v9, v2
	v_mov_b32_e32 v10, v2
	v_mov_b32_e32 v11, v2
	v_mov_b32_e32 v12, v2
	v_mov_b32_e32 v13, v2
	v_mov_b32_e32 v14, v2
	v_mov_b32_e32 v15, v2
	v_mov_b32_e32 v16, v2
	v_mov_b32_e32 v17, v2
	v_mov_b32_e32 v18, v2
	v_mov_b32_e32 v19, v2
	v_mov_b32_e32 v20, v2
	v_mov_b32_e32 v21, v2
	v_mov_b32_e32 v22, v2
	v_mov_b32_e32 v23, v2
	v_mov_b32_e32 v24, v2
	v_mov_b32_e32 v25, v2
	v_mov_b32_e32 v26, v2
	v_mov_b32_e32 v27, v2
	v_mov_b32_e32 v28, v2
	v_mov_b32_e32 v29, v2
	v_mov_b32_e32 v30, v2
	v_mov_b32_e32 v31, v2
	v_mov_b32_e32 v32, v2
	v_mov_b32_e32 v33, v2
	v_mov_b32_e32 v34, v2
	v_mov_b32_e32 v35, v2
	v_mov_b32_e32 v36, v2
	v_mov_b32_e32 v37, v2
	v_mov_b32_e32 v38, v2
	v_mov_b32_e32 v39, v2
	v_mov_b32_e32 v40, v2
	v_mov_b32_e32 v41, v2
	v_mov_b32_e32 v42, v2
	v_mov_b32_e32 v43, v2
	v_mov_b32_e32 v44, v2
	v_mov_b32_e32 v45, v2
	v_mov_b32_e32 v46, v2
	v_mov_b32_e32 v47, v2
	v_mov_b32_e32 v48, v2
	v_mov_b32_e32 v49, v2
	v_mov_b32_e32 v50, v2
	v_mov_b32_e32 v51, v2
	v_mov_b32_e32 v52, v2
	v_mov_b32_e32 v53, v2
	v_mov_b32_e32 v54, v2
	v_mov_b32_e32 v55, v2
	v_mov_b32_e32 v56, v2
	v_mov_b32_e32 v57, v2
	v_mov_b32_e32 v58, v2
	v_mov_b32_e32 v59, v2
	v_mov_b32_e32 v60, v2
	v_mov_b32_e32 v61, v2
	v_mov_b32_e32 v62, v2
	v_mov_b32_e32 v63, v2
	v_mov_b32_e32 v64, v2
	v_mov_b32_e32 v65, v2
	v_mov_b32_e32 v66, v2
	v_mov_b32_e32 v67, v2
	v_mov_b32_e32 v68, v2
	v_mov_b32_e32 v69, v2
; template <bool SWAP>
; DI void gemm_mainloop(f32x16 (&acc)[4][2], const u16* __restrict__ A, int lda, int rlo, int rhi,
;                       const u16* __restrict__ B, int ldb, int K, char* lds, const u16* zero_line) {
;     ...
; #pragma unroll
;   for (int mi = 0; mi < 4; ++mi)
; #pragma unroll
;     for (int ni = 0; ni < 2; ++ni)
; #pragma unroll
;       for (int i = 0; i < 16; ++i) acc[mi][ni][i] = 0.f;
;   const int gch = (lc ^ ((lr >> 1) & 7)) * 8;
;   const u16* ap = A + (ptrdiff_t)lr * lda + gch;
;   const u16* bp = B + (ptrdiff_t)lr * ldb + gch;
;   const int nk = K >> 6;
;   typedef __attribute__((address_space(3))) unsigned lds_u32;
;   auto glds = [&](int kt, int st) {
;     char* as_ = lds + st * 65536 + tid * 16;
; #pragma unroll
;     for (int i = 0; i < 4; ++i) {
;       const int rr = lr + 64 * i;
;       const u16* srca = (rr >= rlo && rr < rhi) ? (ap + (ptrdiff_t)(64 * i) * lda + kt * 64) : (zero_line + lc * 8);
;       __builtin_amdgcn_global_load_lds((const unsigned*)srca, (lds_u32*)(as_ + i * 8192), 16, 0, 0);
;       __builtin_amdgcn_global_load_lds((const unsigned*)(bp + (ptrdiff_t)(64 * i) * ldb + kt * 64), (lds_u32*)(as_ + 32768 + i * 8192), 16, 0, 0);
;     }
;   };
;   const int sw = (r >> 1) & 7;
;   const int arow_off = (wm * 128 + r) * 128;
;   const int brow_off = 32768 + (wn * 64 + r) * 128;
;   __syncthreads();
;   glds(0, 0);
;   asm volatile("s_waitcnt vmcnt(0)" ::: "memory");
;   __syncthreads();
;   bf16x8 fa[2][4], fb[2][2];
; #pragma unroll
;   for (int mi = 0; mi < 4; ++mi)
; #pragma unroll
;     for (int e = 0; e < 8; ++e) fa[1][mi][e] = 0;
; #pragma unroll
;   for (int ni = 0; ni < 2; ++ni)
; #pragma unroll
;     for (int e = 0; e < 8; ++e) fb[1][ni][e] = 0;
;   auto ldfrag = [&](const char* st, int ks, int buf) {
;     const int co = ((2 * ks + h) ^ sw) << 4;
; #pragma unroll
;     for (int mi = 0; mi < 4; ++mi) fa[buf][mi] = *(const bf16x8*)(st + arow_off + mi * 4096 + co);
; #pragma unroll
;     for (int ni = 0; ni < 2; ++ni) fb[buf][ni] = *(const bf16x8*)(st + brow_off + ni * 4096 + co);
;   };
	v_mov_b32_e32 v70, v2
	v_mov_b32_e32 v71, v2
	v_mov_b32_e32 v72, v2
	v_mov_b32_e32 v73, v2
	v_mov_b32_e32 v74, v2
	v_mov_b32_e32 v75, v2
	v_mov_b32_e32 v76, v2
	v_mov_b32_e32 v77, v2
	v_mov_b32_e32 v78, v2
	v_mov_b32_e32 v79, v2
	v_mov_b32_e32 v80, v2
	v_mov_b32_e32 v81, v2
	v_mov_b32_e32 v82, v2
	v_mov_b32_e32 v83, v2
	v_mov_b32_e32 v84, v2
	v_mov_b32_e32 v85, v2
	v_mov_b32_e32 v86, v2
	v_mov_b32_e32 v87, v2
	v_mov_b32_e32 v88, v2
	v_mov_b32_e32 v89, v2
	v_mov_b32_e32 v90, v2
	v_mov_b32_e32 v91, v2
	v_mov_b32_e32 v92, v2
	v_mov_b32_e32 v93, v2
	v_mov_b32_e32 v94, v2
	v_mov_b32_e32 v95, v2
	v_mov_b32_e32 v96, v2
	v_mov_b32_e32 v97, v2
	v_mov_b32_e32 v98, v2
	v_mov_b32_e32 v99, v2
	v_mov_b32_e32 v100, v2
	v_mov_b32_e32 v101, v2
	v_mov_b32_e32 v102, v2
	v_mov_b32_e32 v103, v2
	v_mov_b32_e32 v104, v2
	v_mov_b32_e32 v105, v2
	v_mov_b32_e32 v106, v2
	v_mov_b32_e32 v107, v2
	v_mov_b32_e32 v108, v2
	v_mov_b32_e32 v109, v2
	v_mov_b32_e32 v110, v2
	v_mov_b32_e32 v111, v2
	v_mov_b32_e32 v112, v2
	v_mov_b32_e32 v113, v2
	v_mov_b32_e32 v114, v2
	v_mov_b32_e32 v115, v2
	v_mov_b32_e32 v116, v2
	v_mov_b32_e32 v117, v2
	v_mov_b32_e32 v118, v2
	v_mov_b32_e32 v119, v2
	v_mov_b32_e32 v120, v2
	v_mov_b32_e32 v121, v2
	v_mov_b32_e32 v122, v2
	v_mov_b32_e32 v123, v2
	v_mov_b32_e32 v124, v2
	v_mov_b32_e32 v125, v2
	v_mov_b32_e32 v126, v2
	v_mov_b32_e32 v127, v2
	v_mov_b32_e32 v128, v2
	v_mov_b32_e32 v129, v2
	v_mov_b32_e32 v131, v130
	v_mov_b32_e32 v132, v130
	v_mov_b32_e32 v133, v130
	v_mov_b32_e32 v134, v130
	v_mov_b32_e32 v135, v130
	v_mov_b32_e32 v136, v130
	v_mov_b32_e32 v137, v130
	v_mov_b32_e32 v138, v130
	v_mov_b32_e32 v139, v130
	v_mov_b32_e32 v140, v130
	v_mov_b32_e32 v141, v130
	v_mov_b32_e32 v146, v130
	v_mov_b32_e32 v147, v130
	v_mov_b32_e32 v148, v130
	v_mov_b32_e32 v149, v130
	v_mov_b32_e32 v142, v130
	v_mov_b32_e32 v143, v130
	v_mov_b32_e32 v144, v130
	v_mov_b32_e32 v145, v130
	v_mov_b32_e32 v150, v130
	v_mov_b32_e32 v151, v130
	v_mov_b32_e32 v152, v130
	v_mov_b32_e32 v153, v130
	s_waitcnt vmcnt(0) lgkmcnt(0)
	s_barrier
	s_ashr_i32 s7, s12, 31
	s_mov_b32 s6, s12
	s_lshl_b64 s[6:7], s[6:7], 11
	s_add_u32 s6, s90, s6
	s_addc_u32 s7, s91, s7
	s_ashr_i32 s9, s14, 31
	s_mov_b32 s8, s14
	s_lshl_b64 s[8:9], s[8:9], 11
	v_readlane_b32 s10, v253, 43
	v_readlane_b32 s11, v253, 44
	s_add_u32 s8, s10, s8
	s_addc_u32 s9, s11, s9
	v_and_b32_e32 v130, 63, v204
	v_lshrrev_b32_e32 v131, 6, v204
	v_lshrrev_b32_e32 v132, 3, v204
	v_lshrrev_b32_e32 v0, 4, v130
	v_lshl_add_u32 v0, v131, 2, v0
	v_xor_b32_e32 v0, v0, v130
	v_and_b32_e32 v0, 7, v0
	v_lshlrev_b32_e32 v133, 4, v0
	v_lshl_add_u32 v232, v132, 11, v133
	v_add_u32_e32 v233, 0x20000, v232
	v_add_u32_e32 v234, 0x40000, v232
	v_add_u32_e32 v235, 0x60000, v232
	v_and_b32_e32 v0, 31, v132
	v_lshrrev_b32_e32 v130, 5, v132
	v_lshl_add_u32 v0, v130, 6, v0
	v_lshl_add_u32 v236, v0, 11, v133
	v_add_u32_e32 v237, 0x10000, v236
	v_add_u32_e32 v238, 0x40000, v236
	v_add_u32_e32 v239, 0x50000, v236
	v_and_b32_e32 v132, 31, v204
	v_lshrrev_b32_e32 v0, 2, v131
	v_lshl_add_u32 v0, v0, 6, v132
	v_lshlrev_b32_e32 v244, 7, v0
	v_and_b32_e32 v0, 3, v131
	v_lshl_add_u32 v0, v0, 5, v132
	v_lshlrev_b32_e32 v245, 7, v0
	v_bfe_u32 v0, v204, 5, 1
	v_bfe_u32 v130, v132, 1, 3
	v_or_b32_e32 v133, 0, v0
	v_xor_b32_e32 v133, v133, v130
	v_lshlrev_b32_e32 v240, 4, v133
	v_or_b32_e32 v133, 2, v0
	v_xor_b32_e32 v133, v133, v130
	v_lshlrev_b32_e32 v241, 4, v133
	v_or_b32_e32 v133, 4, v0
	v_xor_b32_e32 v133, v133, v130
	v_lshlrev_b32_e32 v242, 4, v133
	v_or_b32_e32 v133, 6, v0
	v_xor_b32_e32 v133, v133, v130
	v_lshlrev_b32_e32 v243, 4, v133
	v_add_u32_e32 v164, v245, v240
	v_add_u32_e32 v165, v245, v241
	v_add_u32_e32 v202, v245, v242
	v_add_u32_e32 v203, v245, v243
	v_add_u32_e32 v240, v244, v240
	v_add_u32_e32 v241, v244, v241
	v_add_u32_e32 v242, v244, v242
	v_add_u32_e32 v243, v244, v243
	v_lshlrev_b32_e32 v131, 10, v131
	s_nop 0
	v_readfirstlane_b32 s100, v131
	v_mov_b32_e32 v146, 0
	v_mov_b32_e32 v147, 0
	v_mov_b32_e32 v148, 0
	v_mov_b32_e32 v149, 0
	v_lshlrev_b32_e32 v130, 4, v204
	v_add_u32_e32 v132, 0x10000, v130
	s_mov_b64 exec, -1
	s_mov_b32 s11, 0
	s_mov_b32 s10, 0x10000
	s_waitcnt lgkmcnt(0)
	s_add_u32 m0, s100, 0x8000
	s_nop 0
	global_load_lds_dwordx4 v236, s[8:9]
	v_add_u32_e32 v236, 0x80, v236
	s_add_u32 m0, s100, 0xa000
	s_nop 0
	global_load_lds_dwordx4 v238, s[8:9]
	v_add_u32_e32 v238, 0x80, v238
	s_add_u32 m0, s100, 0x0
	s_nop 0
	global_load_lds_dwordx4 v232, s[6:7]
	v_add_u32_e32 v232, 0x80, v232
	s_add_u32 m0, s100, 0x2000
	s_nop 0
	global_load_lds_dwordx4 v234, s[6:7]
	v_add_u32_e32 v234, 0x80, v234
	s_add_u32 m0, s100, 0xc000
	s_nop 0
	global_load_lds_dwordx4 v237, s[8:9]
	v_add_u32_e32 v237, 0x80, v237
	s_add_u32 m0, s100, 0xe000
	s_nop 0
	global_load_lds_dwordx4 v239, s[8:9]
	v_add_u32_e32 v239, 0x80, v239
	s_add_u32 m0, s100, 0x4000
	s_nop 0
	global_load_lds_dwordx4 v233, s[6:7]
	v_add_u32_e32 v233, 0x80, v233
	s_add_u32 m0, s100, 0x6000
	s_nop 0
	global_load_lds_dwordx4 v235, s[6:7]
	v_add_u32_e32 v235, 0x80, v235
	s_cmp_eq_u32 s101, 1
	s_cbranch_scc0 .Lg8_qb_p0
	s_barrier

; #define MFMA(a, b, c) __builtin_amdgcn_mfma_f32_32x32x16_bf16((a), (b), (c), 0, 0, 0)
; template <bool SWAP>
; DI void gemm_mainloop(f32x16 (&acc)[4][2], const u16* __restrict__ A, int lda, int rlo, int rhi,
;                       const u16* __restrict__ B, int ldb, int K, char* lds, const u16* zero_line) {
;     ...
;   auto ldfrag = [&](const char* st, int ks, int buf) {
;     const int co = ((2 * ks + h) ^ sw) << 4;
; #pragma unroll
;     for (int mi = 0; mi < 4; ++mi) fa[buf][mi] = *(const bf16x8*)(st + arow_off + mi * 4096 + co);
; #pragma unroll
;     for (int ni = 0; ni < 2; ++ni) fb[buf][ni] = *(const bf16x8*)(st + brow_off + ni * 4096 + co);
;   };
;   auto mma = [&](int buf) {
; #pragma unroll
;     for (int mi = 0; mi < 4; ++mi)
; #pragma unroll
;       for (int ni = 0; ni < 2; ++ni)
;         acc[mi][ni] = SWAP ? MFMA(fb[buf][ni], fa[buf][mi], acc[mi][ni]) : MFMA(fa[buf][mi], fb[buf][ni], acc[mi][ni]);
;   };
;   auto pat_rd = [&]() {
; #pragma unroll
;     for (int g = 0; g < 6; ++g) {
;       __builtin_amdgcn_sched_group_barrier(0x100, 1, 0);
;       __builtin_amdgcn_sched_group_barrier(0x008, 1, 0);
;     }
;     __builtin_amdgcn_sched_group_barrier(0x008, 2, 0);
;   };
; #pragma unroll 2
;   for (int kt = 0; kt < nk; ++kt) {
;     const char* st = lds + (kt & 1) * 65536;
;     ldfrag(st, 0, 0);
;     mma(1);
;     pat_rd();
;     if (kt + 1 < nk) glds(kt + 1, (kt + 1) & 1);
;     ldfrag(st, 1, 1);
;     mma(0);
;     pat_rd();
;     ldfrag(st, 2, 0);
;     mma(1);
;     pat_rd();
;     ldfrag(st, 3, 1);
;     mma(0);
;     pat_rd();
;     asm volatile("s_waitcnt vmcnt(0)" ::: "memory");
;     __syncthreads();
;   }
.Lg8_qb:
	ds_read_b128 v[130:133], v240
	ds_read_b128 v[134:137], v241
	ds_read_b128 v[138:141], v242
	ds_read_b128 v[142:145], v243
	ds_read_b128 v[146:149], v240 offset:4096
	ds_read_b128 v[150:153], v241 offset:4096
	ds_read_b128 v[156:159], v242 offset:4096
	ds_read_b128 v[160:163], v243 offset:4096
	s_add_u32 m0, s100, 0x14000
	s_nop 0
	global_load_lds_dwordx4 v233, s[6:7]
	v_add_u32_e32 v233, 0x80, v233
	s_add_u32 m0, s100, 0x16000
	s_nop 0
	global_load_lds_dwordx4 v235, s[6:7]
	v_add_u32_e32 v235, 0x80, v235
	s_barrier
	s_waitcnt lgkmcnt(0)
	v_mfma_f32_32x32x16_bf16 v[114:129], v[170:173], v[130:133], v[114:129]
	v_mfma_f32_32x32x16_bf16 v[82:97], v[170:173], v[146:149], v[82:97]
	v_mfma_f32_32x32x16_bf16 v[114:129], v[174:177], v[134:137], v[114:129]
	v_mfma_f32_32x32x16_bf16 v[82:97], v[174:177], v[150:153], v[82:97]
	v_mfma_f32_32x32x16_bf16 v[114:129], v[178:181], v[138:141], v[114:129]
	v_mfma_f32_32x32x16_bf16 v[82:97], v[178:181], v[156:159], v[82:97]
	v_mfma_f32_32x32x16_bf16 v[114:129], v[186:189], v[142:145], v[114:129]
	v_mfma_f32_32x32x16_bf16 v[82:97], v[186:189], v[160:163], v[82:97]
	s_barrier
	ds_read_b128 v[190:193], v164 offset:49152
	ds_read_b128 v[194:197], v165 offset:49152
	ds_read_b128 v[198:201], v202 offset:49152
	ds_read_b128 v[228:231], v203 offset:49152
	s_add_u32 m0, s100, 0x8000
	s_nop 0
	global_load_lds_dwordx4 v236, s[8:9]
	v_add_u32_e32 v236, 0x80, v236
	s_add_u32 m0, s100, 0xa000
	s_nop 0
	global_load_lds_dwordx4 v238, s[8:9]
	v_add_u32_e32 v238, 0x80, v238
	s_barrier
	s_waitcnt lgkmcnt(0)
	v_mfma_f32_32x32x16_bf16 v[98:113], v[190:193], v[130:133], v[98:113]
	v_mfma_f32_32x32x16_bf16 v[66:81], v[190:193], v[146:149], v[66:81]
	v_mfma_f32_32x32x16_bf16 v[98:113], v[194:197], v[134:137], v[98:113]
	v_mfma_f32_32x32x16_bf16 v[66:81], v[194:197], v[150:153], v[66:81]
	v_mfma_f32_32x32x16_bf16 v[98:113], v[198:201], v[138:141], v[98:113]
	v_mfma_f32_32x32x16_bf16 v[66:81], v[198:201], v[156:159], v[66:81]
	v_mfma_f32_32x32x16_bf16 v[98:113], v[228:231], v[142:145], v[98:113]
	v_mfma_f32_32x32x16_bf16 v[66:81], v[228:231], v[160:163], v[66:81]
	s_barrier
	ds_read_b128 v[130:133], v240 offset:16384
	ds_read_b128 v[134:137], v241 offset:16384
	ds_read_b128 v[138:141], v242 offset:16384
	ds_read_b128 v[142:145], v243 offset:16384
	ds_read_b128 v[146:149], v240 offset:20480
	ds_read_b128 v[150:153], v241 offset:20480
	ds_read_b128 v[156:159], v242 offset:20480
	ds_read_b128 v[160:163], v243 offset:20480
	s_add_u32 m0, s100, 0x0
	s_nop 0
	global_load_lds_dwordx4 v232, s[6:7]
	v_add_u32_e32 v232, 0x80, v232
	s_add_u32 m0, s100, 0x2000
	s_nop 0
	global_load_lds_dwordx4 v234, s[6:7]
	v_add_u32_e32 v234, 0x80, v234
	s_waitcnt vmcnt(10)
	s_barrier
	s_waitcnt lgkmcnt(0)
	v_mfma_f32_32x32x16_bf16 v[50:65], v[170:173], v[130:133], v[50:65]
	v_mfma_f32_32x32x16_bf16 v[18:33], v[170:173], v[146:149], v[18:33]
	v_mfma_f32_32x32x16_bf16 v[50:65], v[174:177], v[134:137], v[50:65]
	v_mfma_f32_32x32x16_bf16 v[18:33], v[174:177], v[150:153], v[18:33]
	v_mfma_f32_32x32x16_bf16 v[50:65], v[178:181], v[138:141], v[50:65]
	v_mfma_f32_32x32x16_bf16 v[18:33], v[178:181], v[156:159], v[18:33]
	v_mfma_f32_32x32x16_bf16 v[50:65], v[186:189], v[142:145], v[50:65]
	v_mfma_f32_32x32x16_bf16 v[18:33], v[186:189], v[160:163], v[18:33]
	s_barrier
	v_add_u32_e32 v246, s10, v164
	v_add_u32_e32 v247, s10, v165
	v_add_u32_e32 v248, s10, v202
	v_add_u32_e32 v249, s10, v203
	ds_read_b128 v[170:173], v246 offset:32768
	ds_read_b128 v[174:177], v247 offset:32768
	ds_read_b128 v[178:181], v248 offset:32768
	ds_read_b128 v[186:189], v249 offset:32768
	s_add_u32 m0, s100, 0xc000
	s_nop 0
	global_load_lds_dwordx4 v237, s[8:9]
	v_add_u32_e32 v237, 0x80, v237
	s_add_u32 m0, s100, 0xe000
	s_nop 0
	global_load_lds_dwordx4 v239, s[8:9]
	v_add_u32_e32 v239, 0x80, v239
	s_waitcnt vmcnt(6)
	s_barrier
	s_waitcnt lgkmcnt(0)
	v_mfma_f32_32x32x16_bf16 v[34:49], v[190:193], v[130:133], v[34:49]
	v_mfma_f32_32x32x16_bf16 v[2:17], v[190:193], v[146:149], v[2:17]
	v_mfma_f32_32x32x16_bf16 v[34:49], v[194:197], v[134:137], v[34:49]
	v_mfma_f32_32x32x16_bf16 v[2:17], v[194:197], v[150:153], v[2:17]
	v_mfma_f32_32x32x16_bf16 v[34:49], v[198:201], v[138:141], v[34:49]
	v_mfma_f32_32x32x16_bf16 v[2:17], v[198:201], v[156:159], v[2:17]
	v_mfma_f32_32x32x16_bf16 v[34:49], v[228:231], v[142:145], v[34:49]
	v_mfma_f32_32x32x16_bf16 v[2:17], v[228:231], v[160:163], v[2:17]
	s_barrier
	v_add_u32_e32 v246, s10, v240
	v_add_u32_e32 v247, s10, v241
	v_add_u32_e32 v248, s10, v242
	v_add_u32_e32 v249, s10, v243
	ds_read_b128 v[130:133], v246
	ds_read_b128 v[134:137], v247
	ds_read_b128 v[138:141], v248
	ds_read_b128 v[142:145], v249
	ds_read_b128 v[146:149], v246 offset:4096
	ds_read_b128 v[150:153], v247 offset:4096
	ds_read_b128 v[156:159], v248 offset:4096
	ds_read_b128 v[160:163], v249 offset:4096
	s_add_u32 m0, s100, 0x4000
	s_nop 0
	global_load_lds_dwordx4 v233, s[6:7]
	v_add_u32_e32 v233, 0x80, v233
	s_add_u32 m0, s100, 0x6000
	s_nop 0
	global_load_lds_dwordx4 v235, s[6:7]
	v_add_u32_e32 v235, 0x80, v235
	s_barrier
	s_waitcnt lgkmcnt(0)
	v_mfma_f32_32x32x16_bf16 v[114:129], v[170:173], v[130:133], v[114:129]
	v_mfma_f32_32x32x16_bf16 v[82:97], v[170:173], v[146:149], v[82:97]
	v_mfma_f32_32x32x16_bf16 v[114:129], v[174:177], v[134:137], v[114:129]
	v_mfma_f32_32x32x16_bf16 v[82:97], v[174:177], v[150:153], v[82:97]
	v_mfma_f32_32x32x16_bf16 v[114:129], v[178:181], v[138:141], v[114:129]
	v_mfma_f32_32x32x16_bf16 v[82:97], v[178:181], v[156:159], v[82:97]
	v_mfma_f32_32x32x16_bf16 v[114:129], v[186:189], v[142:145], v[114:129]
	v_mfma_f32_32x32x16_bf16 v[82:97], v[186:189], v[160:163], v[82:97]
	s_barrier
; #define MFMA(a, b, c) __builtin_amdgcn_mfma_f32_32x32x16_bf16((a), (b), (c), 0, 0, 0)
; template <bool SWAP>
; DI void gemm_mainloop(f32x16 (&acc)[4][2], const u16* __restrict__ A, int lda, int rlo, int rhi,
;                       const u16* __restrict__ B, int ldb, int K, char* lds, const u16* zero_line) {
;     ...
;   auto ldfrag = [&](const char* st, int ks, int buf) {
;     const int co = ((2 * ks + h) ^ sw) << 4;
; #pragma unroll
;     for (int mi = 0; mi < 4; ++mi) fa[buf][mi] = *(const bf16x8*)(st + arow_off + mi * 4096 + co);
; #pragma unroll
;     for (int ni = 0; ni < 2; ++ni) fb[buf][ni] = *(const bf16x8*)(st + brow_off + ni * 4096 + co);
;   };
;   auto mma = [&](int buf) {
; #pragma unroll
;     for (int mi = 0; mi < 4; ++mi)
; #pragma unroll
;       for (int ni = 0; ni < 2; ++ni)
;         acc[mi][ni] = SWAP ? MFMA(fb[buf][ni], fa[buf][mi], acc[mi][ni]) : MFMA(fa[buf][mi], fb[buf][ni], acc[mi][ni]);
;   };
;   auto pat_rd = [&]() {
; #pragma unroll
;     for (int g = 0; g < 6; ++g) {
;       __builtin_amdgcn_sched_group_barrier(0x100, 1, 0);
;       __builtin_amdgcn_sched_group_barrier(0x008, 1, 0);
;     }
;     __builtin_amdgcn_sched_group_barrier(0x008, 2, 0);
;   };
; #pragma unroll 2
;   for (int kt = 0; kt < nk; ++kt) {
;     const char* st = lds + (kt & 1) * 65536;
;     ldfrag(st, 0, 0);
;     mma(1);
;     pat_rd();
;     if (kt + 1 < nk) glds(kt + 1, (kt + 1) & 1);
;     ldfrag(st, 1, 1);
;     mma(0);
;     pat_rd();
;     ldfrag(st, 2, 0);
;     mma(1);
;     pat_rd();
;     ldfrag(st, 3, 1);
;     mma(0);
;     pat_rd();
;     asm volatile("s_waitcnt vmcnt(0)" ::: "memory");
;     __syncthreads();
;   }
	v_add_u32_e32 v246, s10, v164
	v_add_u32_e32 v247, s10, v165
	v_add_u32_e32 v248, s10, v202
	v_add_u32_e32 v249, s10, v203
	ds_read_b128 v[190:193], v246 offset:49152
	ds_read_b128 v[194:197], v247 offset:49152
	ds_read_b128 v[198:201], v248 offset:49152
	ds_read_b128 v[228:231], v249 offset:49152
	s_add_u32 m0, s100, 0x18000
	s_nop 0
	global_load_lds_dwordx4 v236, s[8:9]
	v_add_u32_e32 v236, 0x80, v236
	s_add_u32 m0, s100, 0x1a000
	s_nop 0
	global_load_lds_dwordx4 v238, s[8:9]
	v_add_u32_e32 v238, 0x80, v238
	s_barrier
	s_waitcnt lgkmcnt(0)
	v_mfma_f32_32x32x16_bf16 v[98:113], v[190:193], v[130:133], v[98:113]
	v_mfma_f32_32x32x16_bf16 v[66:81], v[190:193], v[146:149], v[66:81]
	v_mfma_f32_32x32x16_bf16 v[98:113], v[194:197], v[134:137], v[98:113]
	v_mfma_f32_32x32x16_bf16 v[66:81], v[194:197], v[150:153], v[66:81]
	v_mfma_f32_32x32x16_bf16 v[98:113], v[198:201], v[138:141], v[98:113]
	v_mfma_f32_32x32x16_bf16 v[66:81], v[198:201], v[156:159], v[66:81]
	v_mfma_f32_32x32x16_bf16 v[98:113], v[228:231], v[142:145], v[98:113]
	v_mfma_f32_32x32x16_bf16 v[66:81], v[228:231], v[160:163], v[66:81]
	s_barrier
	v_add_u32_e32 v246, s10, v240
	v_add_u32_e32 v247, s10, v241
	v_add_u32_e32 v248, s10, v242
	v_add_u32_e32 v249, s10, v243
	ds_read_b128 v[130:133], v246 offset:16384
	ds_read_b128 v[134:137], v247 offset:16384
	ds_read_b128 v[138:141], v248 offset:16384
	ds_read_b128 v[142:145], v249 offset:16384
	ds_read_b128 v[146:149], v246 offset:20480
	ds_read_b128 v[150:153], v247 offset:20480
	ds_read_b128 v[156:159], v248 offset:20480
	ds_read_b128 v[160:163], v249 offset:20480
	s_add_u32 m0, s100, 0x10000
	s_nop 0
	global_load_lds_dwordx4 v232, s[6:7]
	v_add_u32_e32 v232, 0x80, v232
	s_add_u32 m0, s100, 0x12000
	s_nop 0
	global_load_lds_dwordx4 v234, s[6:7]
	v_add_u32_e32 v234, 0x80, v234
	s_waitcnt vmcnt(10)
	s_barrier
	s_waitcnt lgkmcnt(0)
	v_mfma_f32_32x32x16_bf16 v[50:65], v[170:173], v[130:133], v[50:65]
	v_mfma_f32_32x32x16_bf16 v[18:33], v[170:173], v[146:149], v[18:33]
	v_mfma_f32_32x32x16_bf16 v[50:65], v[174:177], v[134:137], v[50:65]
	v_mfma_f32_32x32x16_bf16 v[18:33], v[174:177], v[150:153], v[18:33]
	v_mfma_f32_32x32x16_bf16 v[50:65], v[178:181], v[138:141], v[50:65]
	v_mfma_f32_32x32x16_bf16 v[18:33], v[178:181], v[156:159], v[18:33]
	v_mfma_f32_32x32x16_bf16 v[50:65], v[186:189], v[142:145], v[50:65]
	v_mfma_f32_32x32x16_bf16 v[18:33], v[186:189], v[160:163], v[18:33]
	s_barrier
	ds_read_b128 v[170:173], v164 offset:32768
	ds_read_b128 v[174:177], v165 offset:32768
	ds_read_b128 v[178:181], v202 offset:32768
	ds_read_b128 v[186:189], v203 offset:32768
	s_add_u32 m0, s100, 0x1c000
	s_nop 0
	global_load_lds_dwordx4 v237, s[8:9]
	v_add_u32_e32 v237, 0x80, v237
	s_add_u32 m0, s100, 0x1e000
	s_nop 0
	global_load_lds_dwordx4 v239, s[8:9]
	v_add_u32_e32 v239, 0x80, v239
	s_waitcnt vmcnt(6)
	s_barrier
	s_waitcnt lgkmcnt(0)
	v_mfma_f32_32x32x16_bf16 v[34:49], v[190:193], v[130:133], v[34:49]
	v_mfma_f32_32x32x16_bf16 v[2:17], v[190:193], v[146:149], v[2:17]
	v_mfma_f32_32x32x16_bf16 v[34:49], v[194:197], v[134:137], v[34:49]
	v_mfma_f32_32x32x16_bf16 v[2:17], v[194:197], v[150:153], v[2:17]
	v_mfma_f32_32x32x16_bf16 v[34:49], v[198:201], v[138:141], v[34:49]
	v_mfma_f32_32x32x16_bf16 v[2:17], v[198:201], v[156:159], v[2:17]
	v_mfma_f32_32x32x16_bf16 v[34:49], v[228:231], v[142:145], v[34:49]
	v_mfma_f32_32x32x16_bf16 v[2:17], v[228:231], v[160:163], v[2:17]
	s_barrier
	s_add_i32 s11, s11, 2
	s_cmp_lt_u32 s11, 14
	s_cbranch_scc1 .Lg8_qb
	ds_read_b128 v[130:133], v240
	ds_read_b128 v[134:137], v241
	ds_read_b128 v[138:141], v242
	ds_read_b128 v[142:145], v243
	ds_read_b128 v[146:149], v240 offset:4096
	ds_read_b128 v[150:153], v241 offset:4096
	ds_read_b128 v[156:159], v242 offset:4096
	ds_read_b128 v[160:163], v243 offset:4096
	s_add_u32 m0, s100, 0x14000
	s_nop 0
	global_load_lds_dwordx4 v233, s[6:7]
	v_add_u32_e32 v233, 0x80, v233
	s_add_u32 m0, s100, 0x16000
	s_nop 0
	global_load_lds_dwordx4 v235, s[6:7]
	v_add_u32_e32 v235, 0x80, v235
	s_barrier
	s_waitcnt lgkmcnt(0)
	v_mfma_f32_32x32x16_bf16 v[114:129], v[170:173], v[130:133], v[114:129]
	v_mfma_f32_32x32x16_bf16 v[82:97], v[170:173], v[146:149], v[82:97]
	v_mfma_f32_32x32x16_bf16 v[114:129], v[174:177], v[134:137], v[114:129]
	v_mfma_f32_32x32x16_bf16 v[82:97], v[174:177], v[150:153], v[82:97]
	v_mfma_f32_32x32x16_bf16 v[114:129], v[178:181], v[138:141], v[114:129]
	v_mfma_f32_32x32x16_bf16 v[82:97], v[178:181], v[156:159], v[82:97]
	v_mfma_f32_32x32x16_bf16 v[114:129], v[186:189], v[142:145], v[114:129]
	v_mfma_f32_32x32x16_bf16 v[82:97], v[186:189], v[160:163], v[82:97]
	s_barrier
	ds_read_b128 v[190:193], v164 offset:49152
	ds_read_b128 v[194:197], v165 offset:49152
	ds_read_b128 v[198:201], v202 offset:49152
	ds_read_b128 v[228:231], v203 offset:49152
	s_barrier
	s_waitcnt lgkmcnt(0)
	v_mfma_f32_32x32x16_bf16 v[98:113], v[190:193], v[130:133], v[98:113]
	v_mfma_f32_32x32x16_bf16 v[66:81], v[190:193], v[146:149], v[66:81]
	v_mfma_f32_32x32x16_bf16 v[98:113], v[194:197], v[134:137], v[98:113]
	v_mfma_f32_32x32x16_bf16 v[66:81], v[194:197], v[150:153], v[66:81]
	v_mfma_f32_32x32x16_bf16 v[98:113], v[198:201], v[138:141], v[98:113]
	v_mfma_f32_32x32x16_bf16 v[66:81], v[198:201], v[156:159], v[66:81]
	v_mfma_f32_32x32x16_bf16 v[98:113], v[228:231], v[142:145], v[98:113]
	v_mfma_f32_32x32x16_bf16 v[66:81], v[228:231], v[160:163], v[66:81]
	s_barrier
; template <bool SWAP>
; DI void gemm_mainloop(f32x16 (&acc)[4][2], const u16* __restrict__ A, int lda, int rlo, int rhi,
;                       const u16* __restrict__ B, int ldb, int K, char* lds, const u16* zero_line) {
;     ...
; #pragma unroll 2
;   for (int kt = 0; kt < nk; ++kt) {
;     const char* st = lds + (kt & 1) * 65536;
;     ldfrag(st, 0, 0);
;     mma(1);
;     pat_rd();
;     if (kt + 1 < nk) glds(kt + 1, (kt + 1) & 1);
;     ldfrag(st, 1, 1);
;     mma(0);
;     pat_rd();
;     ldfrag(st, 2, 0);
;     mma(1);
;     pat_rd();
;     ldfrag(st, 3, 1);
;     mma(0);
;     pat_rd();
;     asm volatile("s_waitcnt vmcnt(0)" ::: "memory");
;     __syncthreads();
;   }
;   mma(1);
	ds_read_b128 v[130:133], v240 offset:16384
	ds_read_b128 v[134:137], v241 offset:16384
	ds_read_b128 v[138:141], v242 offset:16384
	ds_read_b128 v[142:145], v243 offset:16384
	ds_read_b128 v[146:149], v240 offset:20480
	ds_read_b128 v[150:153], v241 offset:20480
	ds_read_b128 v[156:159], v242 offset:20480
	ds_read_b128 v[160:163], v243 offset:20480
	s_waitcnt vmcnt(4)
	s_barrier
	s_waitcnt lgkmcnt(0)
	v_mfma_f32_32x32x16_bf16 v[50:65], v[170:173], v[130:133], v[50:65]
	v_mfma_f32_32x32x16_bf16 v[18:33], v[170:173], v[146:149], v[18:33]
	v_mfma_f32_32x32x16_bf16 v[50:65], v[174:177], v[134:137], v[50:65]
	v_mfma_f32_32x32x16_bf16 v[18:33], v[174:177], v[150:153], v[18:33]
	v_mfma_f32_32x32x16_bf16 v[50:65], v[178:181], v[138:141], v[50:65]
	v_mfma_f32_32x32x16_bf16 v[18:33], v[178:181], v[156:159], v[18:33]
	v_mfma_f32_32x32x16_bf16 v[50:65], v[186:189], v[142:145], v[50:65]
	v_mfma_f32_32x32x16_bf16 v[18:33], v[186:189], v[160:163], v[18:33]
	v_mfma_f32_32x32x16_bf16 v[34:49], v[190:193], v[130:133], v[34:49]
	v_mfma_f32_32x32x16_bf16 v[2:17], v[190:193], v[146:149], v[2:17]
	v_mfma_f32_32x32x16_bf16 v[34:49], v[194:197], v[134:137], v[34:49]
	v_mfma_f32_32x32x16_bf16 v[2:17], v[194:197], v[150:153], v[2:17]
	v_mfma_f32_32x32x16_bf16 v[34:49], v[198:201], v[138:141], v[34:49]
	v_mfma_f32_32x32x16_bf16 v[2:17], v[198:201], v[156:159], v[2:17]
	v_mfma_f32_32x32x16_bf16 v[34:49], v[228:231], v[142:145], v[34:49]
	v_mfma_f32_32x32x16_bf16 v[2:17], v[228:231], v[160:163], v[2:17]
	s_barrier
	v_add_u32_e32 v246, s10, v164
	v_add_u32_e32 v247, s10, v165
	v_add_u32_e32 v248, s10, v202
	v_add_u32_e32 v249, s10, v203
	ds_read_b128 v[170:173], v246 offset:32768
	ds_read_b128 v[174:177], v247 offset:32768
	ds_read_b128 v[178:181], v248 offset:32768
	ds_read_b128 v[186:189], v249 offset:32768
	v_add_u32_e32 v246, s10, v240
	v_add_u32_e32 v247, s10, v241
	v_add_u32_e32 v248, s10, v242
	v_add_u32_e32 v249, s10, v243
	ds_read_b128 v[130:133], v246
	ds_read_b128 v[134:137], v247
	ds_read_b128 v[138:141], v248
	ds_read_b128 v[142:145], v249
	ds_read_b128 v[146:149], v246 offset:4096
	ds_read_b128 v[150:153], v247 offset:4096
	ds_read_b128 v[156:159], v248 offset:4096
	ds_read_b128 v[160:163], v249 offset:4096
	s_waitcnt vmcnt(2)
	s_barrier
	s_waitcnt lgkmcnt(0)
	v_mfma_f32_32x32x16_bf16 v[114:129], v[170:173], v[130:133], v[114:129]
	v_mfma_f32_32x32x16_bf16 v[82:97], v[170:173], v[146:149], v[82:97]
	v_mfma_f32_32x32x16_bf16 v[114:129], v[174:177], v[134:137], v[114:129]
	v_mfma_f32_32x32x16_bf16 v[82:97], v[174:177], v[150:153], v[82:97]
	v_mfma_f32_32x32x16_bf16 v[114:129], v[178:181], v[138:141], v[114:129]
	v_mfma_f32_32x32x16_bf16 v[82:97], v[178:181], v[156:159], v[82:97]
	v_mfma_f32_32x32x16_bf16 v[114:129], v[186:189], v[142:145], v[114:129]
	v_mfma_f32_32x32x16_bf16 v[82:97], v[186:189], v[160:163], v[82:97]
	s_barrier
	v_add_u32_e32 v246, s10, v164
	v_add_u32_e32 v247, s10, v165
	v_add_u32_e32 v248, s10, v202
	v_add_u32_e32 v249, s10, v203
	ds_read_b128 v[190:193], v246 offset:49152
	ds_read_b128 v[194:197], v247 offset:49152
	ds_read_b128 v[198:201], v248 offset:49152
	ds_read_b128 v[228:231], v249 offset:49152
	s_waitcnt vmcnt(0)
	s_barrier
	s_waitcnt lgkmcnt(0)
	v_mfma_f32_32x32x16_bf16 v[98:113], v[190:193], v[130:133], v[98:113]
	v_mfma_f32_32x32x16_bf16 v[66:81], v[190:193], v[146:149], v[66:81]
	v_mfma_f32_32x32x16_bf16 v[98:113], v[194:197], v[134:137], v[98:113]
	v_mfma_f32_32x32x16_bf16 v[66:81], v[194:197], v[150:153], v[66:81]
	v_mfma_f32_32x32x16_bf16 v[98:113], v[198:201], v[138:141], v[98:113]
	v_mfma_f32_32x32x16_bf16 v[66:81], v[198:201], v[156:159], v[66:81]
	v_mfma_f32_32x32x16_bf16 v[98:113], v[228:231], v[142:145], v[98:113]
	v_mfma_f32_32x32x16_bf16 v[66:81], v[228:231], v[160:163], v[66:81]
	s_barrier
	v_add_u32_e32 v246, s10, v240
	v_add_u32_e32 v247, s10, v241
	v_add_u32_e32 v248, s10, v242
	v_add_u32_e32 v249, s10, v243
	ds_read_b128 v[130:133], v246 offset:16384
	ds_read_b128 v[134:137], v247 offset:16384
	ds_read_b128 v[138:141], v248 offset:16384
	ds_read_b128 v[142:145], v249 offset:16384
	ds_read_b128 v[146:149], v246 offset:20480
	ds_read_b128 v[150:153], v247 offset:20480
	ds_read_b128 v[156:159], v248 offset:20480
	ds_read_b128 v[160:163], v249 offset:20480
	s_barrier
	s_waitcnt lgkmcnt(0)
	v_mfma_f32_32x32x16_bf16 v[50:65], v[170:173], v[130:133], v[50:65]
	v_mfma_f32_32x32x16_bf16 v[18:33], v[170:173], v[146:149], v[18:33]
	v_mfma_f32_32x32x16_bf16 v[50:65], v[174:177], v[134:137], v[50:65]
	v_mfma_f32_32x32x16_bf16 v[18:33], v[174:177], v[150:153], v[18:33]
	v_mfma_f32_32x32x16_bf16 v[50:65], v[178:181], v[138:141], v[50:65]
	v_mfma_f32_32x32x16_bf16 v[18:33], v[178:181], v[156:159], v[18:33]
	v_mfma_f32_32x32x16_bf16 v[50:65], v[186:189], v[142:145], v[50:65]
	v_mfma_f32_32x32x16_bf16 v[18:33], v[186:189], v[160:163], v[18:33]
	v_mfma_f32_32x32x16_bf16 v[34:49], v[190:193], v[130:133], v[34:49]
	v_mfma_f32_32x32x16_bf16 v[2:17], v[190:193], v[146:149], v[2:17]
	v_mfma_f32_32x32x16_bf16 v[34:49], v[194:197], v[134:137], v[34:49]
	v_mfma_f32_32x32x16_bf16 v[2:17], v[194:197], v[150:153], v[2:17]
	v_mfma_f32_32x32x16_bf16 v[34:49], v[198:201], v[138:141], v[34:49]
	v_mfma_f32_32x32x16_bf16 v[2:17], v[198:201], v[156:159], v[2:17]
	v_mfma_f32_32x32x16_bf16 v[34:49], v[228:231], v[142:145], v[34:49]
	v_mfma_f32_32x32x16_bf16 v[2:17], v[228:231], v[160:163], v[2:17]
	s_barrier
	s_cmp_eq_u32 s101, 0
	s_cbranch_scc0 .Lg8_qb_p1
	s_barrier

; template <bool SWAP>
; DI void gemm_mainloop(f32x16 (&acc)[4][2], const u16* __restrict__ A, int lda, int rlo, int rhi,
;                       const u16* __restrict__ B, int ldb, int K, char* lds, const u16* zero_line) {
;     ...
;   const int gch = (lc ^ ((lr >> 1) & 7)) * 8;
;   const u16* ap = A + (ptrdiff_t)lr * lda + gch;
;   const u16* bp = B + (ptrdiff_t)lr * ldb + gch;
;   const int nk = K >> 6;
;   typedef __attribute__((address_space(3))) unsigned lds_u32;
;   auto glds = [&](int kt, int st) {
;     char* as_ = lds + st * 65536 + tid * 16;
; #pragma unroll
;     for (int i = 0; i < 4; ++i) {
;       const int rr = lr + 64 * i;
;       const u16* srca = (rr >= rlo && rr < rhi) ? (ap + (ptrdiff_t)(64 * i) * lda + kt * 64) : (zero_line + lc * 8);
;       __builtin_amdgcn_global_load_lds((const unsigned*)srca, (lds_u32*)(as_ + i * 8192), 16, 0, 0);
;       __builtin_amdgcn_global_load_lds((const unsigned*)(bp + (ptrdiff_t)(64 * i) * ldb + kt * 64), (lds_u32*)(as_ + 32768 + i * 8192), 16, 0, 0);
;     }
;   };
; template <int EPI>
; DI void phase_gemm(const Params& p, const GemmArgs& ga, char* lds) {
;     ...
;   for (int it = 0; it * (int)gridDim.x < total; ++it) {
;     const int lt = logical_index(it);
;     if (lt >= total) continue;
;     int mt, nt;
;     tile_mn(lt, Mt, ga.Nt, mt, nt);
;     int bb, tokbase, S, pos0, rlo = 0, rhi = 256;
;     if (EPI == EPI_UP) {
;       bb = 0; tokbase = 0; S = NTOK;
;       pos0 = 254 * mt - 1;
;       rlo = (mt == 0) ? 1 : 0;
;       rhi = NTOK - pos0; if (rhi > 256) rhi = 256;
;     } else {
;       seq_of_token(mt * 256, bb, tokbase, S);
;       pos0 = mt * 256 - tokbase;
;     }
;     const u16* A = ga.A + (ptrdiff_t)(tokbase + pos0) * ga.lda;
;     const u16* B = ga.Bt + (size_t)(nt * 256) * ga.K;
;     f32x16 acc[4][2];
;     bool swap;
;     if (EPI == EPI_M) swap = true;
;     else if (EPI == EPI_UP) swap = true;
;     else if (EPI == EPI_QKV1) swap = (nt < 8);
;     else swap = !(nt == 4 || nt == 5);
;     if (swap) gemm_mainloop<true>(acc, A, ga.lda, rlo, rhi, B, ga.K, ga.K, lds, (const u16*)(p.ws + OFF_ZERO));
;     else gemm_mainloop<false>(acc, A, ga.lda, rlo, rhi, B, ga.K, ga.K, lds, (const u16*)(p.ws + OFF_ZERO));
.LBB0_244:
	s_add_i32 s6, s6, s27
	s_cmpk_gt_i32 s6, 0x2ff
	s_cbranch_scc1 .LBB0_243
	s_ashr_i32 s7, s6, 31
	s_lshr_b32 s7, s7, 27
	s_add_i32 s7, s6, s7
	s_ashr_i32 s35, s7, 5
	s_andn2_b32 s7, s7, 31
	s_sub_i32 s6, s6, s7
	s_ashr_i32 s7, s6, 31
	s_lshr_b32 s7, s7, 29
	s_add_i32 s7, s6, s7
	s_ashr_i32 s7, s7, 3
	s_lshl_b32 s8, s35, 11
	s_lshl_b32 s6, s6, 8
	s_lshl_b32 s24, s7, 8
	s_add_i32 s6, s6, s8
	s_lshl_b32 s36, s7, 11
	s_ashr_i32 s25, s24, 31
	s_sub_i32 s34, s6, s36
	s_mul_i32 s6, s25, s98
	s_mul_hi_u32 s7, s24, s98
	s_add_i32 s7, s7, s6
	s_mul_i32 s6, s24, s98
	s_lshl_b64 s[6:7], s[6:7], 1
	s_add_u32 s6, s16, s6
	v_mov_b32_e32 v10, v204
	s_addc_u32 s7, s17, s7
	s_ashr_i32 s8, s34, 31
	s_mul_i32 s8, s8, s98
	v_ashrrev_i32_e32 v2, 3, v10
	s_mul_hi_u32 s9, s34, s98
	v_mad_u64_u32 v[4:5], s[10:11], v2, s98, 0
	s_add_i32 s9, s9, s8
	s_mul_i32 s8, s34, s98
	v_ashrrev_i32_e32 v3, 31, v2
	v_mov_b32_e32 v0, v5
	s_lshl_b64 s[8:9], s[8:9], 1
	v_lshrrev_b32_e32 v12, 1, v2
	v_mad_u64_u32 v[6:7], s[10:11], v3, s98, v[0:1]
	s_add_u32 s8, s12, s8
	v_xor_b32_e32 v9, v12, v10
	v_mov_b32_e32 v5, v6
	s_addc_u32 s9, s13, s9
	v_lshlrev_b64 v[4:5], 1, v[4:5]
	v_lshlrev_b32_e32 v0, 4, v9
	v_and_b32_e32 v8, 31, v10
	v_lshl_add_u64 v[6:7], s[8:9], 0, v[4:5]
	v_and_b32_e32 v0, 0x70, v0
	v_lshl_add_u64 v[4:5], s[6:7], 0, v[4:5]
	v_lshrrev_b32_e32 v13, 1, v10
	v_lshl_add_u64 v[6:7], v[6:7], 0, v[0:1]
	v_lshl_add_u64 v[4:5], v[4:5], 0, v[0:1]
	v_and_or_b32 v0, v13, s51, v8
	v_lshlrev_b32_e32 v203, 7, v0
	v_lshlrev_b32_e32 v0, 7, v10
	v_lshlrev_b32_e32 v226, 4, v10
	v_and_b32_e32 v202, 0x6f80, v0
	v_and_b32_e32 v0, 0x70, v226
	v_add_u32_e32 v15, 0x8000, v226
	v_lshl_add_u64 v[180:181], s[80:81], 0, v[0:1]
	v_cmp_gt_u32_e32 vcc, s50, v2
	v_readfirstlane_b32 s6, v226
	s_mov_b32 m0, s6
	v_cndmask_b32_e32 v9, v181, v7, vcc
	v_cndmask_b32_e32 v8, v180, v6, vcc
	v_readfirstlane_b32 s6, v15
	v_add_u32_e32 v0, 64, v2
	s_barrier
	s_mov_b32 m0, s6
	v_cmp_gt_u32_e64 s[6:7], s50, v0
	v_add_u32_e32 v0, 0x2000, v226
	v_lshl_add_u64 v[6:7], v[6:7], 0, s[18:19]
	v_readfirstlane_b32 s8, v0
	v_add_u32_e32 v0, 0xa000, v226
	v_cndmask_b32_e64 v9, v181, v7, s[6:7]
	v_cndmask_b32_e64 v8, v180, v6, s[6:7]
	s_mov_b32 m0, s8
	v_readfirstlane_b32 s8, v0
	v_add_u32_e32 v0, 0x80, v2
	s_mov_b32 m0, s8
	v_cmp_gt_u32_e64 s[8:9], s50, v0
	v_add_u32_e32 v0, 0x4000, v226
	v_lshl_add_u64 v[4:5], v[4:5], 0, s[18:19]
	v_lshl_add_u64 v[6:7], v[6:7], 0, s[18:19]
	v_readfirstlane_b32 s10, v0
	v_add_u32_e32 v0, 0xc000, v226
	v_cndmask_b32_e64 v9, v181, v7, s[8:9]
	v_cndmask_b32_e64 v8, v180, v6, s[8:9]
	s_mov_b32 m0, s10
	v_readfirstlane_b32 s10, v0
	v_add_u32_e32 v0, 0xc0, v2
	s_mov_b32 m0, s10
	v_cmp_gt_u32_e64 s[10:11], s50, v0
	v_add_u32_e32 v0, 0x6000, v226
	v_lshl_add_u64 v[4:5], v[4:5], 0, s[18:19]
	v_lshl_add_u64 v[6:7], v[6:7], 0, s[18:19]
	v_readfirstlane_b32 s37, v0
	v_add_u32_e32 v0, 0xe000, v226
	v_cndmask_b32_e64 v7, v181, v7, s[10:11]
	v_cndmask_b32_e64 v6, v180, v6, s[10:11]
	s_mov_b32 m0, s37
	v_readfirstlane_b32 s37, v0
	v_lshl_add_u64 v[4:5], v[4:5], 0, s[18:19]
	s_mov_b32 m0, s37
	s_sub_i32 s36, s29, s36
	s_mulk_i32 s35, 0x1800
	s_sub_i32 s36, s36, s35
	s_ashr_i32 s37, s36, 31
	v_lshlrev_b64 v[2:3], 1, v[2:3]
	s_lshl_b64 s[36:37], s[36:37], 1
	v_lshl_add_u64 v[4:5], v[2:3], 0, s[36:37]
	v_mov_b64_e32 v[6:7], s[20:21]
	v_mad_u64_u32 v[182:183], s[38:39], s98, v4, v[6:7]
	v_mov_b32_e32 v4, v183
	v_mad_u64_u32 v[4:5], s[38:39], s98, v5, v[4:5]
	s_lshl_b64 s[38:39], s[24:25], 1
	v_bfe_u32 v11, v10, 5, 1
	v_mov_b32_e32 v183, v4
	v_lshl_add_u64 v[4:5], v[2:3], 0, s[38:39]
	v_mov_b64_e32 v[8:9], s[22:23]
	v_bfe_u32 v14, v10, 1, 3
	v_bitop3_b32 v0, v13, v11, 7 bitop3:0x6c
	v_mad_u64_u32 v[186:187], s[40:41], s98, v4, v[8:9]
	v_lshlrev_b32_e32 v228, 4, v0
	v_bitop3_b32 v0, v11, v14, 2 bitop3:0x36
	v_mov_b32_e32 v4, v187
	v_lshlrev_b32_e32 v227, 4, v0
	v_bitop3_b32 v0, v11, v14, 4 bitop3:0x36
	v_mad_u64_u32 v[4:5], s[40:41], s98, v5, v[4:5]
	v_lshlrev_b32_e32 v201, 4, v0
	v_bitop3_b32 v0, v11, v14, 6 bitop3:0x36
	v_mov_b32_e32 v187, v4
	v_lshl_add_u64 v[4:5], v[2:3], 0, s[4:5]
	v_lshlrev_b32_e32 v179, 4, v0
	v_bitop3_b32 v0, v12, 7, v10 bitop3:0x48
	v_lshl_add_u64 v[10:11], v[4:5], 0, s[36:37]
	v_lshl_add_u64 v[4:5], v[4:5], 0, s[38:39]
	v_mad_u64_u32 v[188:189], s[40:41], s98, v10, v[6:7]
	v_mad_u64_u32 v[190:191], s[40:41], s98, v4, v[8:9]
	v_mov_b32_e32 v10, v189
	v_mov_b32_e32 v4, v191
	v_mad_u64_u32 v[10:11], s[40:41], s98, v11, v[10:11]
	v_mad_u64_u32 v[4:5], s[40:41], s98, v5, v[4:5]
	s_mov_b64 s[40:41], 0x100
	v_mov_b32_e32 v191, v4
	v_lshl_add_u64 v[4:5], v[2:3], 0, s[40:41]
	v_mov_b32_e32 v189, v10
	v_lshl_add_u64 v[10:11], v[4:5], 0, s[36:37]
	v_lshl_add_u64 v[4:5], v[4:5], 0, s[38:39]
	v_mad_u64_u32 v[192:193], s[40:41], s98, v10, v[6:7]
	v_mad_u64_u32 v[194:195], s[40:41], s98, v4, v[8:9]
	v_mov_b32_e32 v10, v193
	v_mov_b32_e32 v4, v195
	v_mad_u64_u32 v[10:11], s[40:41], s98, v11, v[10:11]
	v_mad_u64_u32 v[4:5], s[40:41], s98, v5, v[4:5]
	s_mov_b64 s[40:41], 0x180
	s_nop 0
	v_lshl_add_u64 v[2:3], v[2:3], 0, s[40:41]
	v_mov_b32_e32 v195, v4
	v_lshl_add_u64 v[4:5], v[2:3], 0, s[36:37]
	v_lshl_add_u64 v[2:3], v[2:3], 0, s[38:39]
	v_mad_u64_u32 v[198:199], s[36:37], s98, v2, v[8:9]
	v_mad_u64_u32 v[196:197], s[36:37], s98, v4, v[6:7]
	v_mov_b32_e32 v2, v199
	s_waitcnt vmcnt(0)
; template <bool SWAP>
; DI void gemm_mainloop(f32x16 (&acc)[4][2], const u16* __restrict__ A, int lda, int rlo, int rhi,
;                       const u16* __restrict__ B, int ldb, int K, char* lds, const u16* zero_line) {
;     ...
; #pragma unroll
;   for (int mi = 0; mi < 4; ++mi)
; #pragma unroll
;     for (int ni = 0; ni < 2; ++ni)
; #pragma unroll
;       for (int i = 0; i < 16; ++i) acc[mi][ni][i] = 0.f;
;   const int gch = (lc ^ ((lr >> 1) & 7)) * 8;
;   const u16* ap = A + (ptrdiff_t)lr * lda + gch;
;   const u16* bp = B + (ptrdiff_t)lr * ldb + gch;
;   const int nk = K >> 6;
;   typedef __attribute__((address_space(3))) unsigned lds_u32;
;   auto glds = [&](int kt, int st) {
;     char* as_ = lds + st * 65536 + tid * 16;
; #pragma unroll
;     for (int i = 0; i < 4; ++i) {
;       const int rr = lr + 64 * i;
;       const u16* srca = (rr >= rlo && rr < rhi) ? (ap + (ptrdiff_t)(64 * i) * lda + kt * 64) : (zero_line + lc * 8);
;       __builtin_amdgcn_global_load_lds((const unsigned*)srca, (lds_u32*)(as_ + i * 8192), 16, 0, 0);
;       __builtin_amdgcn_global_load_lds((const unsigned*)(bp + (ptrdiff_t)(64 * i) * ldb + kt * 64), (lds_u32*)(as_ + 32768 + i * 8192), 16, 0, 0);
;     }
;   };
;   const int sw = (r >> 1) & 7;
;   const int arow_off = (wm * 128 + r) * 128;
;   const int brow_off = 32768 + (wn * 64 + r) * 128;
;   __syncthreads();
;   glds(0, 0);
;   asm volatile("s_waitcnt vmcnt(0)" ::: "memory");
;   __syncthreads();
;   bf16x8 fa[2][4], fb[2][2];
; #pragma unroll
;   for (int mi = 0; mi < 4; ++mi)
; #pragma unroll
;     for (int e = 0; e < 8; ++e) fa[1][mi][e] = 0;
; #pragma unroll
;   for (int ni = 0; ni < 2; ++ni)
; #pragma unroll
;     for (int e = 0; e < 8; ++e) fb[1][ni][e] = 0;
;   auto ldfrag = [&](const char* st, int ks, int buf) {
;     const int co = ((2 * ks + h) ^ sw) << 4;
; #pragma unroll
;     for (int mi = 0; mi < 4; ++mi) fa[buf][mi] = *(const bf16x8*)(st + arow_off + mi * 4096 + co);
; #pragma unroll
;     for (int ni = 0; ni < 2; ++ni) fb[buf][ni] = *(const bf16x8*)(st + brow_off + ni * 4096 + co);
;   };
	v_mov_b32_e32 v4, v197
	v_mad_u64_u32 v[2:3], s[36:37], s98, v3, v[2:3]
	v_mad_u64_u32 v[4:5], s[36:37], s98, v5, v[4:5]
	v_mov_b32_e32 v199, v2
	v_mov_b32_e32 v130, 0
	v_mov_b32_e32 v2, 0
	v_lshlrev_b32_e32 v0, 4, v0
	v_mov_b32_e32 v193, v10
	v_mov_b32_e32 v197, v4
	s_mov_b32 s25, 0x10000
	v_mov_b32_e32 v3, v2
	v_mov_b32_e32 v4, v2
	v_mov_b32_e32 v5, v2
	v_mov_b32_e32 v6, v2
	v_mov_b32_e32 v7, v2
	v_mov_b32_e32 v8, v2
	v_mov_b32_e32 v9, v2
	v_mov_b32_e32 v10, v2
	v_mov_b32_e32 v11, v2
	v_mov_b32_e32 v12, v2
	v_mov_b32_e32 v13, v2
	v_mov_b32_e32 v14, v2
	v_mov_b32_e32 v15, v2
	v_mov_b32_e32 v16, v2
	v_mov_b32_e32 v17, v2
	v_mov_b32_e32 v18, v2
	v_mov_b32_e32 v19, v2
	v_mov_b32_e32 v20, v2
	v_mov_b32_e32 v21, v2
	v_mov_b32_e32 v22, v2
	v_mov_b32_e32 v23, v2
	v_mov_b32_e32 v24, v2
	v_mov_b32_e32 v25, v2
	v_mov_b32_e32 v26, v2
	v_mov_b32_e32 v27, v2
	v_mov_b32_e32 v28, v2
	v_mov_b32_e32 v29, v2
	v_mov_b32_e32 v30, v2
	v_mov_b32_e32 v31, v2
	v_mov_b32_e32 v32, v2
	v_mov_b32_e32 v33, v2
	v_mov_b32_e32 v34, v2
	v_mov_b32_e32 v35, v2
	v_mov_b32_e32 v36, v2
	v_mov_b32_e32 v37, v2
	v_mov_b32_e32 v38, v2
	v_mov_b32_e32 v39, v2
	v_mov_b32_e32 v40, v2
	v_mov_b32_e32 v41, v2
	v_mov_b32_e32 v42, v2
	v_mov_b32_e32 v43, v2
	v_mov_b32_e32 v44, v2
	v_mov_b32_e32 v45, v2
	v_mov_b32_e32 v46, v2
	v_mov_b32_e32 v47, v2
	v_mov_b32_e32 v48, v2
	v_mov_b32_e32 v49, v2
	v_mov_b32_e32 v50, v2
	v_mov_b32_e32 v51, v2
	v_mov_b32_e32 v52, v2
	v_mov_b32_e32 v53, v2
	v_mov_b32_e32 v54, v2
	v_mov_b32_e32 v55, v2
	v_mov_b32_e32 v56, v2
	v_mov_b32_e32 v57, v2
	v_mov_b32_e32 v58, v2
	v_mov_b32_e32 v59, v2
	v_mov_b32_e32 v60, v2
	v_mov_b32_e32 v61, v2
	v_mov_b32_e32 v62, v2
	v_mov_b32_e32 v63, v2
	v_mov_b32_e32 v64, v2
	v_mov_b32_e32 v65, v2
	v_mov_b32_e32 v66, v2
	v_mov_b32_e32 v67, v2
	v_mov_b32_e32 v68, v2
	v_mov_b32_e32 v69, v2
	v_mov_b32_e32 v70, v2
	v_mov_b32_e32 v71, v2
	v_mov_b32_e32 v72, v2
	v_mov_b32_e32 v73, v2
	v_mov_b32_e32 v74, v2
	v_mov_b32_e32 v75, v2
	v_mov_b32_e32 v76, v2
	v_mov_b32_e32 v77, v2
	v_mov_b32_e32 v78, v2
	v_mov_b32_e32 v79, v2
	v_mov_b32_e32 v80, v2
	v_mov_b32_e32 v81, v2
	v_mov_b32_e32 v82, v2
	v_mov_b32_e32 v83, v2
	v_mov_b32_e32 v84, v2
	v_mov_b32_e32 v85, v2
	v_mov_b32_e32 v86, v2
	v_mov_b32_e32 v87, v2
	v_mov_b32_e32 v88, v2
	v_mov_b32_e32 v89, v2
	v_mov_b32_e32 v90, v2
	v_mov_b32_e32 v91, v2
	v_mov_b32_e32 v92, v2
	v_mov_b32_e32 v93, v2
	v_mov_b32_e32 v94, v2
	v_mov_b32_e32 v95, v2
	v_mov_b32_e32 v96, v2
	v_mov_b32_e32 v97, v2
	v_mov_b32_e32 v98, v2
	v_mov_b32_e32 v99, v2
	v_mov_b32_e32 v100, v2
	v_mov_b32_e32 v101, v2
	v_mov_b32_e32 v102, v2
	v_mov_b32_e32 v103, v2
	v_mov_b32_e32 v104, v2
	v_mov_b32_e32 v105, v2
	v_mov_b32_e32 v106, v2
	v_mov_b32_e32 v107, v2
	v_mov_b32_e32 v108, v2
	v_mov_b32_e32 v109, v2
	v_mov_b32_e32 v110, v2
	v_mov_b32_e32 v111, v2
	v_mov_b32_e32 v112, v2
	v_mov_b32_e32 v113, v2
	v_mov_b32_e32 v114, v2
	v_mov_b32_e32 v115, v2
	v_mov_b32_e32 v116, v2
	v_mov_b32_e32 v117, v2
	v_mov_b32_e32 v118, v2
	v_mov_b32_e32 v119, v2
	v_mov_b32_e32 v120, v2
	v_mov_b32_e32 v121, v2
	v_mov_b32_e32 v122, v2
	v_mov_b32_e32 v123, v2
	v_mov_b32_e32 v124, v2
	v_mov_b32_e32 v125, v2
	v_mov_b32_e32 v126, v2
	v_mov_b32_e32 v127, v2
	v_mov_b32_e32 v128, v2
	v_mov_b32_e32 v129, v2
	v_mov_b32_e32 v131, v130
	v_mov_b32_e32 v132, v130
	v_mov_b32_e32 v133, v130
	v_mov_b32_e32 v134, v130
	v_mov_b32_e32 v135, v130
	v_mov_b32_e32 v136, v130
	v_mov_b32_e32 v137, v130
	v_mov_b32_e32 v142, v130
	v_mov_b32_e32 v143, v130
	v_mov_b32_e32 v144, v130
	v_mov_b32_e32 v145, v130
	v_mov_b32_e32 v150, v130
	v_mov_b32_e32 v151, v130
	v_mov_b32_e32 v152, v130
	v_mov_b32_e32 v153, v130
	v_mov_b32_e32 v138, v130
	v_mov_b32_e32 v139, v130
	v_mov_b32_e32 v140, v130
	v_mov_b32_e32 v141, v130
	v_mov_b32_e32 v146, v130
	v_mov_b32_e32 v147, v130
	v_mov_b32_e32 v148, v130
	v_mov_b32_e32 v149, v130
	s_waitcnt vmcnt(0) lgkmcnt(0)
	s_barrier
	s_mul_i32 s6, s34, s98
	s_mul_hi_u32 s7, s34, s98
	s_lshl_b64 s[6:7], s[6:7], 1
	s_add_u32 s6, s12, s6
	s_addc_u32 s7, s13, s7
	s_mul_i32 s8, s24, s98
	s_mul_hi_u32 s9, s24, s98
	s_lshl_b64 s[8:9], s[8:9], 1
	s_add_u32 s8, s16, s8
	s_addc_u32 s9, s17, s9
	v_and_b32_e32 v130, 63, v204
	v_lshrrev_b32_e32 v131, 6, v204
	v_lshrrev_b32_e32 v132, 3, v204
	v_lshrrev_b32_e32 v0, 4, v130
	v_lshl_add_u32 v0, v131, 2, v0
	v_xor_b32_e32 v0, v0, v130
	v_and_b32_e32 v0, 7, v0
	v_lshlrev_b32_e32 v133, 4, v0
	v_mul_lo_u32 v0, v132, s98
	v_lshl_add_u32 v232, v0, 1, v133
	s_lshl_b32 s28, s98, 7
	v_add_u32_e32 v233, s28, v232
	v_add_u32_e32 v234, s28, v233
	v_add_u32_e32 v235, s28, v234
	v_and_b32_e32 v0, 31, v132
	v_lshrrev_b32_e32 v130, 5, v132
	v_lshl_add_u32 v0, v130, 6, v0
	v_mul_lo_u32 v0, v0, s98
	v_lshl_add_u32 v236, v0, 1, v133
	s_lshl_b32 s28, s98, 6
	v_add_u32_e32 v237, s28, v236
	s_lshl_b32 s28, s98, 8
	v_add_u32_e32 v238, s28, v236
	v_add_u32_e32 v239, s28, v237
	s_lshr_b32 s25, s98, 6
	s_add_i32 s25, s25, -2
	v_and_b32_e32 v132, 31, v204
	v_lshrrev_b32_e32 v0, 2, v131
	v_lshl_add_u32 v0, v0, 6, v132
	v_lshlrev_b32_e32 v244, 7, v0
	v_and_b32_e32 v0, 3, v131
	v_lshl_add_u32 v0, v0, 5, v132
	v_lshlrev_b32_e32 v245, 7, v0
	v_bfe_u32 v0, v204, 5, 1
	v_bfe_u32 v130, v132, 1, 3
	v_or_b32_e32 v133, 0, v0
	v_xor_b32_e32 v133, v133, v130
	v_lshlrev_b32_e32 v240, 4, v133
	v_or_b32_e32 v133, 2, v0
	v_xor_b32_e32 v133, v133, v130
	v_lshlrev_b32_e32 v241, 4, v133
	v_or_b32_e32 v133, 4, v0
	v_xor_b32_e32 v133, v133, v130
	v_lshlrev_b32_e32 v242, 4, v133
	v_or_b32_e32 v133, 6, v0
	v_xor_b32_e32 v133, v133, v130
	v_lshlrev_b32_e32 v243, 4, v133
	v_add_u32_e32 v246, v245, v240
	v_add_u32_e32 v247, v245, v241
	v_add_u32_e32 v248, v245, v242
	v_add_u32_e32 v249, v245, v243
	v_add_u32_e32 v240, v244, v240
	v_add_u32_e32 v241, v244, v241
	v_add_u32_e32 v242, v244, v242
	v_add_u32_e32 v243, v244, v243
	v_lshlrev_b32_e32 v131, 10, v131
	s_nop 0
	v_readfirstlane_b32 s100, v131
	v_mov_b32_e32 v146, 0
	v_mov_b32_e32 v147, 0
	v_mov_b32_e32 v148, 0
	v_mov_b32_e32 v149, 0
	v_lshlrev_b32_e32 v130, 4, v204
	v_add_u32_e32 v132, 0x10000, v130
	s_mov_b64 exec, -1
	s_mov_b32 s11, 0
	s_mov_b32 s10, 0x10000
	s_waitcnt lgkmcnt(0)
	s_add_u32 m0, s100, 0x8000
	s_nop 0
	global_load_lds_dwordx4 v236, s[8:9]
	v_add_u32_e32 v236, 0x80, v236
	s_add_u32 m0, s100, 0xa000
	s_nop 0
	global_load_lds_dwordx4 v238, s[8:9]
	v_add_u32_e32 v238, 0x80, v238
	s_add_u32 m0, s100, 0x0
	s_nop 0
	global_load_lds_dwordx4 v232, s[6:7]
	v_add_u32_e32 v232, 0x80, v232
	s_add_u32 m0, s100, 0x2000
	s_nop 0
	global_load_lds_dwordx4 v234, s[6:7]
	v_add_u32_e32 v234, 0x80, v234
	s_add_u32 m0, s100, 0xc000
	s_nop 0
	global_load_lds_dwordx4 v237, s[8:9]
	v_add_u32_e32 v237, 0x80, v237
	s_add_u32 m0, s100, 0xe000
	s_nop 0
	global_load_lds_dwordx4 v239, s[8:9]
	v_add_u32_e32 v239, 0x80, v239
	s_add_u32 m0, s100, 0x4000
	s_nop 0
	global_load_lds_dwordx4 v233, s[6:7]
	v_add_u32_e32 v233, 0x80, v233
	s_add_u32 m0, s100, 0x6000
	s_nop 0
	global_load_lds_dwordx4 v235, s[6:7]
	v_add_u32_e32 v235, 0x80, v235
	s_cmp_eq_u32 s101, 1
	s_cbranch_scc0 .Lg8_m246_p0
	s_barrier
; #define MFMA(a, b, c) __builtin_amdgcn_mfma_f32_32x32x16_bf16((a), (b), (c), 0, 0, 0)
; template <bool SWAP>
; DI void gemm_mainloop(f32x16 (&acc)[4][2], const u16* __restrict__ A, int lda, int rlo, int rhi,
;                       const u16* __restrict__ B, int ldb, int K, char* lds, const u16* zero_line) {
;     ...
;   auto ldfrag = [&](const char* st, int ks, int buf) {
;     const int co = ((2 * ks + h) ^ sw) << 4;
; #pragma unroll
;     for (int mi = 0; mi < 4; ++mi) fa[buf][mi] = *(const bf16x8*)(st + arow_off + mi * 4096 + co);
; #pragma unroll
;     for (int ni = 0; ni < 2; ++ni) fb[buf][ni] = *(const bf16x8*)(st + brow_off + ni * 4096 + co);
;   };
;   auto mma = [&](int buf) {
; #pragma unroll
;     for (int mi = 0; mi < 4; ++mi)
; #pragma unroll
;       for (int ni = 0; ni < 2; ++ni)
;         acc[mi][ni] = SWAP ? MFMA(fb[buf][ni], fa[buf][mi], acc[mi][ni]) : MFMA(fa[buf][mi], fb[buf][ni], acc[mi][ni]);
;   };
;   auto pat_rd = [&]() {
; #pragma unroll
;     for (int g = 0; g < 6; ++g) {
;       __builtin_amdgcn_sched_group_barrier(0x100, 1, 0);
;       __builtin_amdgcn_sched_group_barrier(0x008, 1, 0);
;     }
;     __builtin_amdgcn_sched_group_barrier(0x008, 2, 0);
;   };
; #pragma unroll 2
;   for (int kt = 0; kt < nk; ++kt) {
;     const char* st = lds + (kt & 1) * 65536;
;     ldfrag(st, 0, 0);
;     mma(1);
;     pat_rd();
;     if (kt + 1 < nk) glds(kt + 1, (kt + 1) & 1);
;     ldfrag(st, 1, 1);
;     mma(0);
;     pat_rd();
;     ldfrag(st, 2, 0);
;     mma(1);
;     pat_rd();
;     ldfrag(st, 3, 1);
;     mma(0);
;     pat_rd();
;     asm volatile("s_waitcnt vmcnt(0)" ::: "memory");
;     __syncthreads();
;   }
.Lg8_m246_p0:
	s_waitcnt vmcnt(4)
	s_barrier
	s_add_u32 m0, s100, 0x18000
	s_nop 0
	global_load_lds_dwordx4 v236, s[8:9]
	v_add_u32_e32 v236, 0x80, v236
	s_add_u32 m0, s100, 0x1a000
	s_nop 0
	global_load_lds_dwordx4 v238, s[8:9]
	v_add_u32_e32 v238, 0x80, v238
	s_add_u32 m0, s100, 0x10000
	s_nop 0
	global_load_lds_dwordx4 v232, s[6:7]
	v_add_u32_e32 v232, 0x80, v232
	s_add_u32 m0, s100, 0x12000
	s_nop 0
	global_load_lds_dwordx4 v234, s[6:7]
	v_add_u32_e32 v234, 0x80, v234
	s_add_u32 m0, s100, 0x1c000
	s_nop 0
	global_load_lds_dwordx4 v237, s[8:9]
	v_add_u32_e32 v237, 0x80, v237
	s_add_u32 m0, s100, 0x1e000
	s_nop 0
	global_load_lds_dwordx4 v239, s[8:9]
	v_add_u32_e32 v239, 0x80, v239
	s_waitcnt vmcnt(6)
	s_barrier
	ds_read_b128 v[162:165], v246 offset:32768
	ds_read_b128 v[166:169], v247 offset:32768
	ds_read_b128 v[170:173], v248 offset:32768
	ds_read_b128 v[174:177], v249 offset:32768
.Lg8_m246:
	ds_read_b128 v[130:133], v240
	ds_read_b128 v[134:137], v241
	ds_read_b128 v[138:141], v242
	ds_read_b128 v[142:145], v243
	ds_read_b128 v[146:149], v240 offset:4096
	ds_read_b128 v[150:153], v241 offset:4096
	ds_read_b128 v[154:157], v242 offset:4096
	ds_read_b128 v[158:161], v243 offset:4096
	s_add_u32 m0, s100, 0x14000
	s_nop 0
	global_load_lds_dwordx4 v233, s[6:7]
	v_add_u32_e32 v233, 0x80, v233
	s_add_u32 m0, s100, 0x16000
	s_nop 0
	global_load_lds_dwordx4 v235, s[6:7]
	v_add_u32_e32 v235, 0x80, v235
	s_barrier
	s_waitcnt lgkmcnt(0)
	v_mfma_f32_32x32x16_bf16 v[114:129], v[162:165], v[130:133], v[114:129]
	v_mfma_f32_32x32x16_bf16 v[82:97], v[162:165], v[146:149], v[82:97]
	v_mfma_f32_32x32x16_bf16 v[114:129], v[166:169], v[134:137], v[114:129]
	v_mfma_f32_32x32x16_bf16 v[82:97], v[166:169], v[150:153], v[82:97]
	v_mfma_f32_32x32x16_bf16 v[114:129], v[170:173], v[138:141], v[114:129]
	v_mfma_f32_32x32x16_bf16 v[82:97], v[170:173], v[154:157], v[82:97]
	v_mfma_f32_32x32x16_bf16 v[114:129], v[174:177], v[142:145], v[114:129]
	v_mfma_f32_32x32x16_bf16 v[82:97], v[174:177], v[158:161], v[82:97]
	s_barrier
	ds_read_b128 v[180:183], v246 offset:49152
	ds_read_b128 v[186:189], v247 offset:49152
	ds_read_b128 v[190:193], v248 offset:49152
	ds_read_b128 v[194:197], v249 offset:49152
	s_add_u32 m0, s100, 0x8000
	s_nop 0
	global_load_lds_dwordx4 v236, s[8:9]
	v_add_u32_e32 v236, 0x80, v236
	s_add_u32 m0, s100, 0xa000
	s_nop 0
	global_load_lds_dwordx4 v238, s[8:9]
	v_add_u32_e32 v238, 0x80, v238
	s_barrier
	s_waitcnt lgkmcnt(0)
	v_mfma_f32_32x32x16_bf16 v[98:113], v[180:183], v[130:133], v[98:113]
	v_mfma_f32_32x32x16_bf16 v[66:81], v[180:183], v[146:149], v[66:81]
	v_mfma_f32_32x32x16_bf16 v[98:113], v[186:189], v[134:137], v[98:113]
	v_mfma_f32_32x32x16_bf16 v[66:81], v[186:189], v[150:153], v[66:81]
	v_mfma_f32_32x32x16_bf16 v[98:113], v[190:193], v[138:141], v[98:113]
	v_mfma_f32_32x32x16_bf16 v[66:81], v[190:193], v[154:157], v[66:81]
	v_mfma_f32_32x32x16_bf16 v[98:113], v[194:197], v[142:145], v[98:113]
	v_mfma_f32_32x32x16_bf16 v[66:81], v[194:197], v[158:161], v[66:81]
	s_barrier
	ds_read_b128 v[130:133], v240 offset:16384
	ds_read_b128 v[134:137], v241 offset:16384
	ds_read_b128 v[138:141], v242 offset:16384
	ds_read_b128 v[142:145], v243 offset:16384
	ds_read_b128 v[146:149], v240 offset:20480
	ds_read_b128 v[150:153], v241 offset:20480
	ds_read_b128 v[154:157], v242 offset:20480
	ds_read_b128 v[158:161], v243 offset:20480
	s_add_u32 m0, s100, 0x0
	s_nop 0
	global_load_lds_dwordx4 v232, s[6:7]
	v_add_u32_e32 v232, 0x80, v232
	s_add_u32 m0, s100, 0x2000
	s_nop 0
	global_load_lds_dwordx4 v234, s[6:7]
	v_add_u32_e32 v234, 0x80, v234
	s_waitcnt vmcnt(10)
	s_barrier
	s_waitcnt lgkmcnt(0)
	v_mfma_f32_32x32x16_bf16 v[50:65], v[162:165], v[130:133], v[50:65]
	v_mfma_f32_32x32x16_bf16 v[18:33], v[162:165], v[146:149], v[18:33]
	v_mfma_f32_32x32x16_bf16 v[50:65], v[166:169], v[134:137], v[50:65]
	v_mfma_f32_32x32x16_bf16 v[18:33], v[166:169], v[150:153], v[18:33]
	v_mfma_f32_32x32x16_bf16 v[50:65], v[170:173], v[138:141], v[50:65]
	v_mfma_f32_32x32x16_bf16 v[18:33], v[170:173], v[154:157], v[18:33]
	v_mfma_f32_32x32x16_bf16 v[50:65], v[174:177], v[142:145], v[50:65]
	v_mfma_f32_32x32x16_bf16 v[18:33], v[174:177], v[158:161], v[18:33]
	s_barrier
	v_add_u32_e32 v244, s10, v246
	v_add_u32_e32 v245, s10, v247
	ds_read_b128 v[162:165], v244 offset:32768
	ds_read_b128 v[166:169], v245 offset:32768
	v_add_u32_e32 v244, s10, v248
	v_add_u32_e32 v245, s10, v249
	ds_read_b128 v[170:173], v244 offset:32768
	ds_read_b128 v[174:177], v245 offset:32768
	s_add_u32 m0, s100, 0xc000
	s_nop 0
	global_load_lds_dwordx4 v237, s[8:9]
	v_add_u32_e32 v237, 0x80, v237
	s_add_u32 m0, s100, 0xe000
	s_nop 0
	global_load_lds_dwordx4 v239, s[8:9]
	v_add_u32_e32 v239, 0x80, v239
	s_waitcnt vmcnt(6)
	s_barrier
	s_waitcnt lgkmcnt(0)
	v_mfma_f32_32x32x16_bf16 v[34:49], v[180:183], v[130:133], v[34:49]
	v_mfma_f32_32x32x16_bf16 v[2:17], v[180:183], v[146:149], v[2:17]
	v_mfma_f32_32x32x16_bf16 v[34:49], v[186:189], v[134:137], v[34:49]
	v_mfma_f32_32x32x16_bf16 v[2:17], v[186:189], v[150:153], v[2:17]
	v_mfma_f32_32x32x16_bf16 v[34:49], v[190:193], v[138:141], v[34:49]
	v_mfma_f32_32x32x16_bf16 v[2:17], v[190:193], v[154:157], v[2:17]
	v_mfma_f32_32x32x16_bf16 v[34:49], v[194:197], v[142:145], v[34:49]
	v_mfma_f32_32x32x16_bf16 v[2:17], v[194:197], v[158:161], v[2:17]
	s_barrier
; #define MFMA(a, b, c) __builtin_amdgcn_mfma_f32_32x32x16_bf16((a), (b), (c), 0, 0, 0)
; template <bool SWAP>
; DI void gemm_mainloop(f32x16 (&acc)[4][2], const u16* __restrict__ A, int lda, int rlo, int rhi,
;                       const u16* __restrict__ B, int ldb, int K, char* lds, const u16* zero_line) {
;     ...
;   auto ldfrag = [&](const char* st, int ks, int buf) {
;     const int co = ((2 * ks + h) ^ sw) << 4;
; #pragma unroll
;     for (int mi = 0; mi < 4; ++mi) fa[buf][mi] = *(const bf16x8*)(st + arow_off + mi * 4096 + co);
; #pragma unroll
;     for (int ni = 0; ni < 2; ++ni) fb[buf][ni] = *(const bf16x8*)(st + brow_off + ni * 4096 + co);
;   };
;   auto mma = [&](int buf) {
; #pragma unroll
;     for (int mi = 0; mi < 4; ++mi)
; #pragma unroll
;       for (int ni = 0; ni < 2; ++ni)
;         acc[mi][ni] = SWAP ? MFMA(fb[buf][ni], fa[buf][mi], acc[mi][ni]) : MFMA(fa[buf][mi], fb[buf][ni], acc[mi][ni]);
;   };
;   auto pat_rd = [&]() {
; #pragma unroll
;     for (int g = 0; g < 6; ++g) {
;       __builtin_amdgcn_sched_group_barrier(0x100, 1, 0);
;       __builtin_amdgcn_sched_group_barrier(0x008, 1, 0);
;     }
;     __builtin_amdgcn_sched_group_barrier(0x008, 2, 0);
;   };
; #pragma unroll 2
;   for (int kt = 0; kt < nk; ++kt) {
;     const char* st = lds + (kt & 1) * 65536;
;     ldfrag(st, 0, 0);
;     mma(1);
;     pat_rd();
;     if (kt + 1 < nk) glds(kt + 1, (kt + 1) & 1);
;     ldfrag(st, 1, 1);
;     mma(0);
;     pat_rd();
;     ldfrag(st, 2, 0);
;     mma(1);
;     pat_rd();
;     ldfrag(st, 3, 1);
;     mma(0);
;     pat_rd();
;     asm volatile("s_waitcnt vmcnt(0)" ::: "memory");
;     __syncthreads();
;   }
	v_add_u32_e32 v244, s10, v240
	v_add_u32_e32 v245, s10, v241
	ds_read_b128 v[130:133], v244
	ds_read_b128 v[134:137], v245
	ds_read_b128 v[146:149], v244 offset:4096
	ds_read_b128 v[150:153], v245 offset:4096
	v_add_u32_e32 v244, s10, v242
	v_add_u32_e32 v245, s10, v243
	ds_read_b128 v[138:141], v244
	ds_read_b128 v[142:145], v245
	ds_read_b128 v[154:157], v244 offset:4096
	ds_read_b128 v[158:161], v245 offset:4096
	s_add_u32 m0, s100, 0x4000
	s_nop 0
	global_load_lds_dwordx4 v233, s[6:7]
	v_add_u32_e32 v233, 0x80, v233
	s_add_u32 m0, s100, 0x6000
	s_nop 0
	global_load_lds_dwordx4 v235, s[6:7]
	v_add_u32_e32 v235, 0x80, v235
	s_barrier
	s_waitcnt lgkmcnt(0)
	v_mfma_f32_32x32x16_bf16 v[114:129], v[162:165], v[130:133], v[114:129]
	v_mfma_f32_32x32x16_bf16 v[82:97], v[162:165], v[146:149], v[82:97]
	v_mfma_f32_32x32x16_bf16 v[114:129], v[166:169], v[134:137], v[114:129]
	v_mfma_f32_32x32x16_bf16 v[82:97], v[166:169], v[150:153], v[82:97]
	v_mfma_f32_32x32x16_bf16 v[114:129], v[170:173], v[138:141], v[114:129]
	v_mfma_f32_32x32x16_bf16 v[82:97], v[170:173], v[154:157], v[82:97]
	v_mfma_f32_32x32x16_bf16 v[114:129], v[174:177], v[142:145], v[114:129]
	v_mfma_f32_32x32x16_bf16 v[82:97], v[174:177], v[158:161], v[82:97]
	s_barrier
	v_add_u32_e32 v244, s10, v246
	v_add_u32_e32 v245, s10, v247
	ds_read_b128 v[180:183], v244 offset:49152
	ds_read_b128 v[186:189], v245 offset:49152
	v_add_u32_e32 v244, s10, v248
	v_add_u32_e32 v245, s10, v249
	ds_read_b128 v[190:193], v244 offset:49152
	ds_read_b128 v[194:197], v245 offset:49152
	s_add_u32 m0, s100, 0x18000
	s_nop 0
	global_load_lds_dwordx4 v236, s[8:9]
	v_add_u32_e32 v236, 0x80, v236
	s_add_u32 m0, s100, 0x1a000
	s_nop 0
	global_load_lds_dwordx4 v238, s[8:9]
	v_add_u32_e32 v238, 0x80, v238
	s_barrier
	s_waitcnt lgkmcnt(0)
	v_mfma_f32_32x32x16_bf16 v[98:113], v[180:183], v[130:133], v[98:113]
	v_mfma_f32_32x32x16_bf16 v[66:81], v[180:183], v[146:149], v[66:81]
	v_mfma_f32_32x32x16_bf16 v[98:113], v[186:189], v[134:137], v[98:113]
	v_mfma_f32_32x32x16_bf16 v[66:81], v[186:189], v[150:153], v[66:81]
	v_mfma_f32_32x32x16_bf16 v[98:113], v[190:193], v[138:141], v[98:113]
	v_mfma_f32_32x32x16_bf16 v[66:81], v[190:193], v[154:157], v[66:81]
	v_mfma_f32_32x32x16_bf16 v[98:113], v[194:197], v[142:145], v[98:113]
	v_mfma_f32_32x32x16_bf16 v[66:81], v[194:197], v[158:161], v[66:81]
	s_barrier
	v_add_u32_e32 v244, s10, v240
	v_add_u32_e32 v245, s10, v241
	ds_read_b128 v[130:133], v244 offset:16384
	ds_read_b128 v[134:137], v245 offset:16384
	ds_read_b128 v[146:149], v244 offset:20480
	ds_read_b128 v[150:153], v245 offset:20480
	v_add_u32_e32 v244, s10, v242
	v_add_u32_e32 v245, s10, v243
	ds_read_b128 v[138:141], v244 offset:16384
	ds_read_b128 v[142:145], v245 offset:16384
	ds_read_b128 v[154:157], v244 offset:20480
	ds_read_b128 v[158:161], v245 offset:20480
	s_add_u32 m0, s100, 0x10000
	s_nop 0
	global_load_lds_dwordx4 v232, s[6:7]
	v_add_u32_e32 v232, 0x80, v232
	s_add_u32 m0, s100, 0x12000
	s_nop 0
	global_load_lds_dwordx4 v234, s[6:7]
	v_add_u32_e32 v234, 0x80, v234
	s_waitcnt vmcnt(10)
	s_barrier
	s_waitcnt lgkmcnt(0)
	v_mfma_f32_32x32x16_bf16 v[50:65], v[162:165], v[130:133], v[50:65]
	v_mfma_f32_32x32x16_bf16 v[18:33], v[162:165], v[146:149], v[18:33]
	v_mfma_f32_32x32x16_bf16 v[50:65], v[166:169], v[134:137], v[50:65]
	v_mfma_f32_32x32x16_bf16 v[18:33], v[166:169], v[150:153], v[18:33]
	v_mfma_f32_32x32x16_bf16 v[50:65], v[170:173], v[138:141], v[50:65]
	v_mfma_f32_32x32x16_bf16 v[18:33], v[170:173], v[154:157], v[18:33]
	v_mfma_f32_32x32x16_bf16 v[50:65], v[174:177], v[142:145], v[50:65]
	v_mfma_f32_32x32x16_bf16 v[18:33], v[174:177], v[158:161], v[18:33]
	s_barrier
	ds_read_b128 v[162:165], v246 offset:32768
	ds_read_b128 v[166:169], v247 offset:32768
	ds_read_b128 v[170:173], v248 offset:32768
	ds_read_b128 v[174:177], v249 offset:32768
	s_add_u32 m0, s100, 0x1c000
	s_nop 0
	global_load_lds_dwordx4 v237, s[8:9]
	v_add_u32_e32 v237, 0x80, v237
	s_add_u32 m0, s100, 0x1e000
	s_nop 0
	global_load_lds_dwordx4 v239, s[8:9]
	v_add_u32_e32 v239, 0x80, v239
	s_waitcnt vmcnt(6)
	s_barrier
	s_waitcnt lgkmcnt(0)
	v_mfma_f32_32x32x16_bf16 v[34:49], v[180:183], v[130:133], v[34:49]
	v_mfma_f32_32x32x16_bf16 v[2:17], v[180:183], v[146:149], v[2:17]
	v_mfma_f32_32x32x16_bf16 v[34:49], v[186:189], v[134:137], v[34:49]
	v_mfma_f32_32x32x16_bf16 v[2:17], v[186:189], v[150:153], v[2:17]
	v_mfma_f32_32x32x16_bf16 v[34:49], v[190:193], v[138:141], v[34:49]
	v_mfma_f32_32x32x16_bf16 v[2:17], v[190:193], v[154:157], v[2:17]
	v_mfma_f32_32x32x16_bf16 v[34:49], v[194:197], v[142:145], v[34:49]
	v_mfma_f32_32x32x16_bf16 v[2:17], v[194:197], v[158:161], v[2:17]
	s_barrier
	s_add_i32 s11, s11, 2
	s_cmp_lt_u32 s11, s25
	s_cbranch_scc1 .Lg8_m246
	ds_read_b128 v[130:133], v240
	ds_read_b128 v[134:137], v241
	ds_read_b128 v[138:141], v242
	ds_read_b128 v[142:145], v243
	ds_read_b128 v[146:149], v240 offset:4096
	ds_read_b128 v[150:153], v241 offset:4096
	ds_read_b128 v[154:157], v242 offset:4096
	ds_read_b128 v[158:161], v243 offset:4096
	s_add_u32 m0, s100, 0x14000
	s_nop 0
	global_load_lds_dwordx4 v233, s[6:7]
	v_add_u32_e32 v233, 0x80, v233
	s_add_u32 m0, s100, 0x16000
	s_nop 0
	global_load_lds_dwordx4 v235, s[6:7]
	v_add_u32_e32 v235, 0x80, v235
	s_barrier
	s_waitcnt lgkmcnt(0)
	v_mfma_f32_32x32x16_bf16 v[114:129], v[162:165], v[130:133], v[114:129]
	v_mfma_f32_32x32x16_bf16 v[82:97], v[162:165], v[146:149], v[82:97]
	v_mfma_f32_32x32x16_bf16 v[114:129], v[166:169], v[134:137], v[114:129]
	v_mfma_f32_32x32x16_bf16 v[82:97], v[166:169], v[150:153], v[82:97]
	v_mfma_f32_32x32x16_bf16 v[114:129], v[170:173], v[138:141], v[114:129]
	v_mfma_f32_32x32x16_bf16 v[82:97], v[170:173], v[154:157], v[82:97]
	v_mfma_f32_32x32x16_bf16 v[114:129], v[174:177], v[142:145], v[114:129]
	v_mfma_f32_32x32x16_bf16 v[82:97], v[174:177], v[158:161], v[82:97]
	s_barrier
; template <bool SWAP>
; DI void gemm_mainloop(f32x16 (&acc)[4][2], const u16* __restrict__ A, int lda, int rlo, int rhi,
;                       const u16* __restrict__ B, int ldb, int K, char* lds, const u16* zero_line) {
;     ...
; #pragma unroll 2
;   for (int kt = 0; kt < nk; ++kt) {
;     const char* st = lds + (kt & 1) * 65536;
;     ldfrag(st, 0, 0);
;     mma(1);
;     pat_rd();
;     if (kt + 1 < nk) glds(kt + 1, (kt + 1) & 1);
;     ldfrag(st, 1, 1);
;     mma(0);
;     pat_rd();
;     ldfrag(st, 2, 0);
;     mma(1);
;     pat_rd();
;     ldfrag(st, 3, 1);
;     mma(0);
;     pat_rd();
;     asm volatile("s_waitcnt vmcnt(0)" ::: "memory");
;     __syncthreads();
;   }
;   mma(1);
	ds_read_b128 v[180:183], v246 offset:49152
	ds_read_b128 v[186:189], v247 offset:49152
	ds_read_b128 v[190:193], v248 offset:49152
	ds_read_b128 v[194:197], v249 offset:49152
	s_barrier
	s_waitcnt lgkmcnt(0)
	v_mfma_f32_32x32x16_bf16 v[98:113], v[180:183], v[130:133], v[98:113]
	v_mfma_f32_32x32x16_bf16 v[66:81], v[180:183], v[146:149], v[66:81]
	v_mfma_f32_32x32x16_bf16 v[98:113], v[186:189], v[134:137], v[98:113]
	v_mfma_f32_32x32x16_bf16 v[66:81], v[186:189], v[150:153], v[66:81]
	v_mfma_f32_32x32x16_bf16 v[98:113], v[190:193], v[138:141], v[98:113]
	v_mfma_f32_32x32x16_bf16 v[66:81], v[190:193], v[154:157], v[66:81]
	v_mfma_f32_32x32x16_bf16 v[98:113], v[194:197], v[142:145], v[98:113]
	v_mfma_f32_32x32x16_bf16 v[66:81], v[194:197], v[158:161], v[66:81]
	s_barrier
	ds_read_b128 v[130:133], v240 offset:16384
	ds_read_b128 v[134:137], v241 offset:16384
	ds_read_b128 v[138:141], v242 offset:16384
	ds_read_b128 v[142:145], v243 offset:16384
	ds_read_b128 v[146:149], v240 offset:20480
	ds_read_b128 v[150:153], v241 offset:20480
	ds_read_b128 v[154:157], v242 offset:20480
	ds_read_b128 v[158:161], v243 offset:20480
	s_waitcnt vmcnt(4)
	s_barrier
	s_waitcnt lgkmcnt(0)
	v_mfma_f32_32x32x16_bf16 v[50:65], v[162:165], v[130:133], v[50:65]
	v_mfma_f32_32x32x16_bf16 v[18:33], v[162:165], v[146:149], v[18:33]
	v_mfma_f32_32x32x16_bf16 v[50:65], v[166:169], v[134:137], v[50:65]
	v_mfma_f32_32x32x16_bf16 v[18:33], v[166:169], v[150:153], v[18:33]
	v_mfma_f32_32x32x16_bf16 v[50:65], v[170:173], v[138:141], v[50:65]
	v_mfma_f32_32x32x16_bf16 v[18:33], v[170:173], v[154:157], v[18:33]
	v_mfma_f32_32x32x16_bf16 v[50:65], v[174:177], v[142:145], v[50:65]
	v_mfma_f32_32x32x16_bf16 v[18:33], v[174:177], v[158:161], v[18:33]
	v_mfma_f32_32x32x16_bf16 v[34:49], v[180:183], v[130:133], v[34:49]
	v_mfma_f32_32x32x16_bf16 v[2:17], v[180:183], v[146:149], v[2:17]
	v_mfma_f32_32x32x16_bf16 v[34:49], v[186:189], v[134:137], v[34:49]
	v_mfma_f32_32x32x16_bf16 v[2:17], v[186:189], v[150:153], v[2:17]
	v_mfma_f32_32x32x16_bf16 v[34:49], v[190:193], v[138:141], v[34:49]
	v_mfma_f32_32x32x16_bf16 v[2:17], v[190:193], v[154:157], v[2:17]
	v_mfma_f32_32x32x16_bf16 v[34:49], v[194:197], v[142:145], v[34:49]
	v_mfma_f32_32x32x16_bf16 v[2:17], v[194:197], v[158:161], v[2:17]
	s_barrier
	v_add_u32_e32 v244, s10, v246
	v_add_u32_e32 v245, s10, v247
	ds_read_b128 v[162:165], v244 offset:32768
	ds_read_b128 v[166:169], v245 offset:32768
	v_add_u32_e32 v244, s10, v248
	v_add_u32_e32 v245, s10, v249
	ds_read_b128 v[170:173], v244 offset:32768
	ds_read_b128 v[174:177], v245 offset:32768
	v_add_u32_e32 v244, s10, v240
	v_add_u32_e32 v245, s10, v241
	ds_read_b128 v[130:133], v244
	ds_read_b128 v[134:137], v245
	ds_read_b128 v[146:149], v244 offset:4096
	ds_read_b128 v[150:153], v245 offset:4096
	v_add_u32_e32 v244, s10, v242
	v_add_u32_e32 v245, s10, v243
	ds_read_b128 v[138:141], v244
	ds_read_b128 v[142:145], v245
	ds_read_b128 v[154:157], v244 offset:4096
	ds_read_b128 v[158:161], v245 offset:4096
	s_waitcnt vmcnt(2)
	s_barrier
	s_waitcnt lgkmcnt(0)
	v_mfma_f32_32x32x16_bf16 v[114:129], v[162:165], v[130:133], v[114:129]
	v_mfma_f32_32x32x16_bf16 v[82:97], v[162:165], v[146:149], v[82:97]
	v_mfma_f32_32x32x16_bf16 v[114:129], v[166:169], v[134:137], v[114:129]
	v_mfma_f32_32x32x16_bf16 v[82:97], v[166:169], v[150:153], v[82:97]
	v_mfma_f32_32x32x16_bf16 v[114:129], v[170:173], v[138:141], v[114:129]
	v_mfma_f32_32x32x16_bf16 v[82:97], v[170:173], v[154:157], v[82:97]
	v_mfma_f32_32x32x16_bf16 v[114:129], v[174:177], v[142:145], v[114:129]
	v_mfma_f32_32x32x16_bf16 v[82:97], v[174:177], v[158:161], v[82:97]
	s_barrier
	v_add_u32_e32 v244, s10, v246
	v_add_u32_e32 v245, s10, v247
	ds_read_b128 v[180:183], v244 offset:49152
	ds_read_b128 v[186:189], v245 offset:49152
	v_add_u32_e32 v244, s10, v248
	v_add_u32_e32 v245, s10, v249
	ds_read_b128 v[190:193], v244 offset:49152
	ds_read_b128 v[194:197], v245 offset:49152
	s_waitcnt vmcnt(0)
	s_barrier
	s_waitcnt lgkmcnt(0)
	v_mfma_f32_32x32x16_bf16 v[98:113], v[180:183], v[130:133], v[98:113]
	v_mfma_f32_32x32x16_bf16 v[66:81], v[180:183], v[146:149], v[66:81]
	v_mfma_f32_32x32x16_bf16 v[98:113], v[186:189], v[134:137], v[98:113]
	v_mfma_f32_32x32x16_bf16 v[66:81], v[186:189], v[150:153], v[66:81]
	v_mfma_f32_32x32x16_bf16 v[98:113], v[190:193], v[138:141], v[98:113]
	v_mfma_f32_32x32x16_bf16 v[66:81], v[190:193], v[154:157], v[66:81]
	v_mfma_f32_32x32x16_bf16 v[98:113], v[194:197], v[142:145], v[98:113]
	v_mfma_f32_32x32x16_bf16 v[66:81], v[194:197], v[158:161], v[66:81]
	s_barrier
	v_add_u32_e32 v244, s10, v240
	v_add_u32_e32 v245, s10, v241
	ds_read_b128 v[130:133], v244 offset:16384
	ds_read_b128 v[134:137], v245 offset:16384
	ds_read_b128 v[146:149], v244 offset:20480
	ds_read_b128 v[150:153], v245 offset:20480
	v_add_u32_e32 v244, s10, v242
	v_add_u32_e32 v245, s10, v243
	ds_read_b128 v[138:141], v244 offset:16384
	ds_read_b128 v[142:145], v245 offset:16384
	ds_read_b128 v[154:157], v244 offset:20480
	ds_read_b128 v[158:161], v245 offset:20480
	s_barrier
	s_waitcnt lgkmcnt(0)
	v_mfma_f32_32x32x16_bf16 v[50:65], v[162:165], v[130:133], v[50:65]
	v_mfma_f32_32x32x16_bf16 v[18:33], v[162:165], v[146:149], v[18:33]
	v_mfma_f32_32x32x16_bf16 v[50:65], v[166:169], v[134:137], v[50:65]
	v_mfma_f32_32x32x16_bf16 v[18:33], v[166:169], v[150:153], v[18:33]
	v_mfma_f32_32x32x16_bf16 v[50:65], v[170:173], v[138:141], v[50:65]
	v_mfma_f32_32x32x16_bf16 v[18:33], v[170:173], v[154:157], v[18:33]
	v_mfma_f32_32x32x16_bf16 v[50:65], v[174:177], v[142:145], v[50:65]
	v_mfma_f32_32x32x16_bf16 v[18:33], v[174:177], v[158:161], v[18:33]
	v_mfma_f32_32x32x16_bf16 v[34:49], v[180:183], v[130:133], v[34:49]
	v_mfma_f32_32x32x16_bf16 v[2:17], v[180:183], v[146:149], v[2:17]
	v_mfma_f32_32x32x16_bf16 v[34:49], v[186:189], v[134:137], v[34:49]
	v_mfma_f32_32x32x16_bf16 v[2:17], v[186:189], v[150:153], v[2:17]
	v_mfma_f32_32x32x16_bf16 v[34:49], v[190:193], v[138:141], v[34:49]
	v_mfma_f32_32x32x16_bf16 v[2:17], v[190:193], v[154:157], v[2:17]
	v_mfma_f32_32x32x16_bf16 v[34:49], v[194:197], v[142:145], v[34:49]
	v_mfma_f32_32x32x16_bf16 v[2:17], v[194:197], v[158:161], v[2:17]
	s_barrier
	s_cmp_eq_u32 s101, 0
	s_cbranch_scc0 .Lg8_m246_p1
	s_barrier

; template <bool SWAP>
; DI void gemm_mainloop(f32x16 (&acc)[4][2], const u16* __restrict__ A, int lda, int rlo, int rhi,
;                       const u16* __restrict__ B, int ldb, int K, char* lds, const u16* zero_line) {
;     ...
;   const int gch = (lc ^ ((lr >> 1) & 7)) * 8;
;   const u16* ap = A + (ptrdiff_t)lr * lda + gch;
;   const u16* bp = B + (ptrdiff_t)lr * ldb + gch;
;   const int nk = K >> 6;
;   typedef __attribute__((address_space(3))) unsigned lds_u32;
;   auto glds = [&](int kt, int st) {
;     char* as_ = lds + st * 65536 + tid * 16;
; #pragma unroll
;     for (int i = 0; i < 4; ++i) {
;       const int rr = lr + 64 * i;
;       const u16* srca = (rr >= rlo && rr < rhi) ? (ap + (ptrdiff_t)(64 * i) * lda + kt * 64) : (zero_line + lc * 8);
;       __builtin_amdgcn_global_load_lds((const unsigned*)srca, (lds_u32*)(as_ + i * 8192), 16, 0, 0);
;       __builtin_amdgcn_global_load_lds((const unsigned*)(bp + (ptrdiff_t)(64 * i) * ldb + kt * 64), (lds_u32*)(as_ + 32768 + i * 8192), 16, 0, 0);
;     }
;   };
; template <int EPI>
; DI void phase_gemm(const Params& p, const GemmArgs& ga, char* lds) {
;     ...
;   for (int it = 0; it * (int)gridDim.x < total; ++it) {
;     const int lt = logical_index(it);
;     if (lt >= total) continue;
;     int mt, nt;
;     tile_mn(lt, Mt, ga.Nt, mt, nt);
;     int bb, tokbase, S, pos0, rlo = 0, rhi = 256;
;     if (EPI == EPI_UP) {
;       bb = 0; tokbase = 0; S = NTOK;
;       pos0 = 254 * mt - 1;
;       rlo = (mt == 0) ? 1 : 0;
;       rhi = NTOK - pos0; if (rhi > 256) rhi = 256;
;     } else {
;       seq_of_token(mt * 256, bb, tokbase, S);
;       pos0 = mt * 256 - tokbase;
;     }
;     const u16* A = ga.A + (ptrdiff_t)(tokbase + pos0) * ga.lda;
;     const u16* B = ga.Bt + (size_t)(nt * 256) * ga.K;
;     f32x16 acc[4][2];
;     bool swap;
;     if (EPI == EPI_M) swap = true;
;     else if (EPI == EPI_UP) swap = true;
;     else if (EPI == EPI_QKV1) swap = (nt < 8);
;     else swap = !(nt == 4 || nt == 5);
;     if (swap) gemm_mainloop<true>(acc, A, ga.lda, rlo, rhi, B, ga.K, ga.K, lds, (const u16*)(p.ws + OFF_ZERO));
;     else gemm_mainloop<false>(acc, A, ga.lda, rlo, rhi, B, ga.K, ga.K, lds, (const u16*)(p.ws + OFF_ZERO));
.LBB0_315:
	s_add_i32 s6, s6, s25
	s_cmpk_gt_i32 s6, 0x6bf
	s_cbranch_scc1 .LBB0_314
	s_mul_hi_i32 s7, s6, 0x38e38e39
	s_lshr_b32 s8, s7, 31
	s_ashr_i32 s29, s7, 4
	s_add_i32 s29, s29, s8
	s_mul_i32 s7, s29, 0xffffffb8
	s_add_i32 s6, s7, s6
	s_ashr_i32 s8, s6, 31
	s_lshr_b32 s8, s8, 29
	s_lshl_b32 s7, s29, 3
	s_add_i32 s8, s6, s8
	s_add_i32 s6, s6, s7
	s_and_b32 s30, s8, -8
	s_sub_i32 s28, s6, s30
	s_lshl_b32 s12, s28, 8
	s_ashr_i32 s13, s12, 31
	s_ashr_i32 s9, s8, 3
	s_lshl_b64 s[6:7], s[12:13], 11
	s_add_u32 s14, s90, s6
	s_addc_u32 s15, s91, s7
	s_lshl_b32 s16, s9, 8
	s_ashr_i32 s17, s16, 31
	s_lshl_b64 s[6:7], s[16:17], 11
	s_add_u32 s20, s70, s6
	s_addc_u32 s21, s71, s7
	s_and_b32 s6, s9, -2
	s_cmp_lg_u32 s6, 4
	s_cselect_b64 s[18:19], -1, 0
	s_cmp_eq_u32 s6, 4
	s_mov_b64 s[6:7], -1
	s_cbranch_scc1 .LBB0_322
	s_waitcnt vmcnt(5)
	v_mov_b32_e32 v10, v204
	s_nop 0
	v_ashrrev_i32_e32 v2, 3, v10
	v_lshrrev_b32_e32 v13, 1, v2
	v_xor_b32_e32 v0, v13, v10
	v_ashrrev_i32_e32 v3, 31, v2
	v_lshlrev_b64 v[4:5], 11, v[2:3]
	v_lshlrev_b32_e32 v0, 4, v0
	v_and_b32_e32 v12, 31, v10
	v_lshl_add_u64 v[6:7], s[14:15], 0, v[4:5]
	v_and_b32_e32 v0, 0x70, v0
	v_lshl_add_u64 v[8:9], s[20:21], 0, v[4:5]
	s_waitcnt vmcnt(4)
	v_lshrrev_b32_e32 v14, 1, v10
	v_lshl_add_u64 v[6:7], v[6:7], 0, v[0:1]
	v_lshl_add_u64 v[164:165], v[8:9], 0, v[0:1]
	v_and_or_b32 v0, v14, s51, v12
	v_lshlrev_b32_e32 v161, 7, v0
	v_lshlrev_b32_e32 v0, 7, v10
	v_lshlrev_b32_e32 v174, 4, v10
	v_and_b32_e32 v163, 0x6f80, v0
	v_and_b32_e32 v0, 0x70, v174
	v_add_u32_e32 v175, 0x8000, v174
	v_lshl_add_u64 v[166:167], s[80:81], 0, v[0:1]
	v_cmp_gt_u32_e32 vcc, s50, v2
	v_readfirstlane_b32 s6, v174
	s_mov_b32 m0, s6
	v_cndmask_b32_e32 v9, v167, v7, vcc
	v_cndmask_b32_e32 v8, v166, v6, vcc
	v_readfirstlane_b32 s6, v175
	v_add_u32_e32 v0, 64, v2
	s_barrier
	s_mov_b32 m0, s6
	s_mov_b64 s[10:11], 0x20000
	v_cmp_gt_u32_e64 s[6:7], s50, v0
	v_add_u32_e32 v0, 0x2000, v174
	v_lshl_add_u64 v[8:9], v[6:7], 0, s[10:11]
	v_readfirstlane_b32 s8, v0
	v_add_u32_e32 v176, 0xa000, v174
	v_cndmask_b32_e64 v9, v167, v9, s[6:7]
	v_cndmask_b32_e64 v8, v166, v8, s[6:7]
	s_mov_b32 m0, s8
	v_readfirstlane_b32 s8, v176
	v_lshl_add_u64 v[8:9], v[164:165], 0, s[10:11]
	s_mov_b32 m0, s8
	v_add_u32_e32 v3, 0x80, v2
	s_mov_b64 s[22:23], 0x40000
	v_add_u32_e32 v177, 0x4000, v174
	v_lshl_add_u64 v[8:9], v[6:7], 0, s[22:23]
	v_cmp_gt_u32_e64 s[8:9], s50, v3
	v_readfirstlane_b32 s10, v177
	v_add_u32_e32 v178, 0xc000, v174
	v_cndmask_b32_e64 v9, v167, v9, s[8:9]
	v_cndmask_b32_e64 v8, v166, v8, s[8:9]
	s_mov_b32 m0, s10
	v_readfirstlane_b32 s10, v178
	v_lshl_add_u64 v[8:9], v[164:165], 0, s[22:23]
	s_mov_b32 m0, s10
	s_mov_b64 s[22:23], 0x60000
	v_add_u32_e32 v8, 0xc0, v2
	v_add_u32_e32 v179, 0x6000, v174
	v_lshl_add_u64 v[2:3], v[6:7], 0, s[22:23]
	v_cmp_gt_u32_e64 s[10:11], s50, v8
	v_readfirstlane_b32 s17, v179
	v_add_u32_e32 v180, 0xe000, v174
	v_cndmask_b32_e64 v3, v167, v3, s[10:11]
	v_cndmask_b32_e64 v2, v166, v2, s[10:11]
	s_mov_b32 m0, s17
	v_readfirstlane_b32 s17, v180
	v_lshl_add_u64 v[2:3], v[164:165], 0, s[22:23]
	s_mov_b32 m0, s17
	v_bfe_u32 v11, v10, 5, 1
	s_sub_i32 s17, s26, s30
	s_lshl_b32 s22, s29, 6
	v_bfe_u32 v15, v10, 1, 3
	v_bitop3_b32 v2, v14, v11, 7 bitop3:0x6c
	s_sub_i32 s17, s17, s22
	v_lshlrev_b32_e32 v181, 4, v2
	v_bitop3_b32 v2, v11, v15, 2 bitop3:0x36
	s_lshl_b32 s22, s17, 8
	v_lshlrev_b32_e32 v182, 4, v2
	v_bitop3_b32 v2, v11, v15, 4 bitop3:0x36
	s_ashr_i32 s23, s22, 31
	v_lshlrev_b32_e32 v183, 4, v2
	v_bitop3_b32 v2, v11, v15, 6 bitop3:0x36
	s_lshl_b64 s[22:23], s[22:23], 11
	v_lshlrev_b32_e32 v186, 4, v2
	v_lshl_add_u64 v[2:3], v[4:5], 0, s[22:23]
	v_bitop3_b32 v4, v13, 7, v10 bitop3:0x48
	s_waitcnt vmcnt(0)
	v_lshl_or_b32 v2, v4, 4, v2
	v_lshl_add_u64 v[168:169], s[70:71], 0, v[2:3]
	v_mov_b32_e32 v130, 0
	v_mov_b32_e32 v2, 0
	s_mov_b32 s13, 1
	v_add_u32_e32 v187, 0x10000, v174
	v_add_u32_e32 v192, 0x18000, v174
	v_add_u32_e32 v193, 0x12000, v174
	v_add_u32_e32 v194, 0x1a000, v174
	v_add_u32_e32 v195, 0x14000, v174
	v_add_u32_e32 v196, 0x1c000, v174
	v_add_u32_e32 v197, 0x16000, v174
	v_add_u32_e32 v198, 0x1e000, v174
	v_add_u32_e32 v199, 0x10000, v161
	v_or_b32_e32 v200, 0x10000, v163
	s_mov_b64 s[22:23], 0
	v_mov_b32_e32 v3, v2
	v_mov_b32_e32 v4, v2
	v_mov_b32_e32 v5, v2
	v_mov_b32_e32 v6, v2
	v_mov_b32_e32 v7, v2
	v_mov_b32_e32 v8, v2
	v_mov_b32_e32 v9, v2
	v_mov_b32_e32 v10, v2
	v_mov_b32_e32 v11, v2
	v_mov_b32_e32 v12, v2
	v_mov_b32_e32 v13, v2
	v_mov_b32_e32 v14, v2
	v_mov_b32_e32 v15, v2
	v_mov_b32_e32 v16, v2
	v_mov_b32_e32 v17, v2
	v_mov_b32_e32 v34, v2
	v_mov_b32_e32 v35, v2
	v_mov_b32_e32 v36, v2
	v_mov_b32_e32 v37, v2
	v_mov_b32_e32 v38, v2
	v_mov_b32_e32 v39, v2
	v_mov_b32_e32 v40, v2
	v_mov_b32_e32 v41, v2
	v_mov_b32_e32 v42, v2
	v_mov_b32_e32 v43, v2
	v_mov_b32_e32 v44, v2
	v_mov_b32_e32 v45, v2
	v_mov_b32_e32 v46, v2
	v_mov_b32_e32 v47, v2
	v_mov_b32_e32 v48, v2
	v_mov_b32_e32 v49, v2
	s_waitcnt vmcnt(0)
; template <bool SWAP>
; DI void gemm_mainloop(f32x16 (&acc)[4][2], const u16* __restrict__ A, int lda, int rlo, int rhi,
;                       const u16* __restrict__ B, int ldb, int K, char* lds, const u16* zero_line) {
;     ...
; #pragma unroll
;   for (int mi = 0; mi < 4; ++mi)
; #pragma unroll
;     for (int ni = 0; ni < 2; ++ni)
; #pragma unroll
;       for (int i = 0; i < 16; ++i) acc[mi][ni][i] = 0.f;
;   const int gch = (lc ^ ((lr >> 1) & 7)) * 8;
;   const u16* ap = A + (ptrdiff_t)lr * lda + gch;
;   const u16* bp = B + (ptrdiff_t)lr * ldb + gch;
;   const int nk = K >> 6;
;   typedef __attribute__((address_space(3))) unsigned lds_u32;
;   auto glds = [&](int kt, int st) {
;     char* as_ = lds + st * 65536 + tid * 16;
; #pragma unroll
;     for (int i = 0; i < 4; ++i) {
;       const int rr = lr + 64 * i;
;       const u16* srca = (rr >= rlo && rr < rhi) ? (ap + (ptrdiff_t)(64 * i) * lda + kt * 64) : (zero_line + lc * 8);
;       __builtin_amdgcn_global_load_lds((const unsigned*)srca, (lds_u32*)(as_ + i * 8192), 16, 0, 0);
;       __builtin_amdgcn_global_load_lds((const unsigned*)(bp + (ptrdiff_t)(64 * i) * ldb + kt * 64), (lds_u32*)(as_ + 32768 + i * 8192), 16, 0, 0);
;     }
;   };
;   const int sw = (r >> 1) & 7;
;   const int arow_off = (wm * 128 + r) * 128;
;   const int brow_off = 32768 + (wn * 64 + r) * 128;
;   __syncthreads();
;   glds(0, 0);
;   asm volatile("s_waitcnt vmcnt(0)" ::: "memory");
;   __syncthreads();
;   bf16x8 fa[2][4], fb[2][2];
; #pragma unroll
;   for (int mi = 0; mi < 4; ++mi)
; #pragma unroll
;     for (int e = 0; e < 8; ++e) fa[1][mi][e] = 0;
; #pragma unroll
;   for (int ni = 0; ni < 2; ++ni)
; #pragma unroll
;     for (int e = 0; e < 8; ++e) fb[1][ni][e] = 0;
;   auto ldfrag = [&](const char* st, int ks, int buf) {
;     const int co = ((2 * ks + h) ^ sw) << 4;
; #pragma unroll
;     for (int mi = 0; mi < 4; ++mi) fa[buf][mi] = *(const bf16x8*)(st + arow_off + mi * 4096 + co);
; #pragma unroll
;     for (int ni = 0; ni < 2; ++ni) fb[buf][ni] = *(const bf16x8*)(st + brow_off + ni * 4096 + co);
;   };
	v_mov_b32_e32 v18, v2
	v_mov_b32_e32 v19, v2
	v_mov_b32_e32 v20, v2
	v_mov_b32_e32 v21, v2
	v_mov_b32_e32 v22, v2
	v_mov_b32_e32 v23, v2
	v_mov_b32_e32 v24, v2
	v_mov_b32_e32 v25, v2
	v_mov_b32_e32 v26, v2
	v_mov_b32_e32 v27, v2
	v_mov_b32_e32 v28, v2
	v_mov_b32_e32 v29, v2
	v_mov_b32_e32 v30, v2
	v_mov_b32_e32 v31, v2
	v_mov_b32_e32 v32, v2
	v_mov_b32_e32 v33, v2
	v_mov_b32_e32 v66, v2
	v_mov_b32_e32 v67, v2
	v_mov_b32_e32 v68, v2
	v_mov_b32_e32 v69, v2
	v_mov_b32_e32 v70, v2
	v_mov_b32_e32 v71, v2
	v_mov_b32_e32 v72, v2
	v_mov_b32_e32 v73, v2
	v_mov_b32_e32 v74, v2
	v_mov_b32_e32 v75, v2
	v_mov_b32_e32 v76, v2
	v_mov_b32_e32 v77, v2
	v_mov_b32_e32 v78, v2
	v_mov_b32_e32 v79, v2
	v_mov_b32_e32 v80, v2
	v_mov_b32_e32 v81, v2
	v_mov_b32_e32 v50, v2
	v_mov_b32_e32 v51, v2
	v_mov_b32_e32 v52, v2
	v_mov_b32_e32 v53, v2
	v_mov_b32_e32 v54, v2
	v_mov_b32_e32 v55, v2
	v_mov_b32_e32 v56, v2
	v_mov_b32_e32 v57, v2
	v_mov_b32_e32 v58, v2
	v_mov_b32_e32 v59, v2
	v_mov_b32_e32 v60, v2
	v_mov_b32_e32 v61, v2
	v_mov_b32_e32 v62, v2
	v_mov_b32_e32 v63, v2
	v_mov_b32_e32 v64, v2
	v_mov_b32_e32 v65, v2
	v_mov_b32_e32 v98, v2
	v_mov_b32_e32 v99, v2
	v_mov_b32_e32 v100, v2
	v_mov_b32_e32 v101, v2
	v_mov_b32_e32 v102, v2
	v_mov_b32_e32 v103, v2
	v_mov_b32_e32 v104, v2
	v_mov_b32_e32 v105, v2
	v_mov_b32_e32 v106, v2
	v_mov_b32_e32 v107, v2
	v_mov_b32_e32 v108, v2
	v_mov_b32_e32 v109, v2
	v_mov_b32_e32 v110, v2
	v_mov_b32_e32 v111, v2
	v_mov_b32_e32 v112, v2
	v_mov_b32_e32 v113, v2
	v_mov_b32_e32 v82, v2
	v_mov_b32_e32 v83, v2
	v_mov_b32_e32 v84, v2
	v_mov_b32_e32 v85, v2
	v_mov_b32_e32 v86, v2
	v_mov_b32_e32 v87, v2
	v_mov_b32_e32 v88, v2
	v_mov_b32_e32 v89, v2
	v_mov_b32_e32 v90, v2
	v_mov_b32_e32 v91, v2
	v_mov_b32_e32 v92, v2
	v_mov_b32_e32 v93, v2
	v_mov_b32_e32 v94, v2
	v_mov_b32_e32 v95, v2
	v_mov_b32_e32 v96, v2
	v_mov_b32_e32 v97, v2
	v_mov_b32_e32 v114, v2
	v_mov_b32_e32 v115, v2
	v_mov_b32_e32 v116, v2
	v_mov_b32_e32 v117, v2
	v_mov_b32_e32 v118, v2
	v_mov_b32_e32 v119, v2
	v_mov_b32_e32 v120, v2
	v_mov_b32_e32 v121, v2
	v_mov_b32_e32 v122, v2
	v_mov_b32_e32 v123, v2
	v_mov_b32_e32 v124, v2
	v_mov_b32_e32 v125, v2
	v_mov_b32_e32 v126, v2
	v_mov_b32_e32 v127, v2
	v_mov_b32_e32 v128, v2
	v_mov_b32_e32 v129, v2
	v_mov_b32_e32 v131, v130
	v_mov_b32_e32 v132, v130
	v_mov_b32_e32 v133, v130
	v_mov_b32_e32 v134, v130
	v_mov_b32_e32 v135, v130
	v_mov_b32_e32 v136, v130
	v_mov_b32_e32 v137, v130
	v_mov_b32_e32 v138, v130
	v_mov_b32_e32 v139, v130
	v_mov_b32_e32 v140, v130
	v_mov_b32_e32 v141, v130
	v_mov_b32_e32 v146, v130
	v_mov_b32_e32 v147, v130
	v_mov_b32_e32 v148, v130
	v_mov_b32_e32 v149, v130
	v_mov_b32_e32 v142, v130
	v_mov_b32_e32 v143, v130
	v_mov_b32_e32 v144, v130
	v_mov_b32_e32 v145, v130
	v_mov_b32_e32 v150, v130
	v_mov_b32_e32 v151, v130
	v_mov_b32_e32 v152, v130
	v_mov_b32_e32 v153, v130
	s_waitcnt lgkmcnt(0)
	s_barrier
	s_ashr_i32 s7, s12, 31
	s_mov_b32 s6, s12
	s_lshl_b64 s[6:7], s[6:7], 11
	s_add_u32 s6, s90, s6
	s_addc_u32 s7, s91, s7
	s_ashr_i32 s9, s16, 31
	s_mov_b32 s8, s16
	s_lshl_b64 s[8:9], s[8:9], 11
	s_add_u32 s8, s70, s8
	s_addc_u32 s9, s71, s9
	v_and_b32_e32 v130, 63, v204
	v_lshrrev_b32_e32 v131, 6, v204
	v_lshrrev_b32_e32 v132, 3, v204
	v_lshrrev_b32_e32 v0, 4, v130
	v_lshl_add_u32 v0, v131, 2, v0
	v_xor_b32_e32 v0, v0, v130
	v_and_b32_e32 v0, 7, v0
	v_lshlrev_b32_e32 v133, 4, v0
	v_lshl_add_u32 v240, v132, 11, v133
	v_add_u32_e32 v241, 0x20000, v240
	v_add_u32_e32 v242, 0x40000, v240
	v_add_u32_e32 v243, 0x60000, v240
	v_and_b32_e32 v0, 31, v132
	v_lshrrev_b32_e32 v130, 5, v132
	v_lshl_add_u32 v0, v130, 6, v0
	v_lshl_add_u32 v244, v0, 11, v133
	v_add_u32_e32 v245, 0x10000, v244
	v_add_u32_e32 v246, 0x40000, v244
	v_add_u32_e32 v247, 0x50000, v244
	v_and_b32_e32 v132, 31, v204
	v_lshrrev_b32_e32 v0, 2, v131
	v_lshl_add_u32 v0, v0, 6, v132
	v_lshlrev_b32_e32 v166, 7, v0
	v_and_b32_e32 v0, 3, v131
	v_lshl_add_u32 v0, v0, 5, v132
	v_lshlrev_b32_e32 v249, 7, v0
	v_bfe_u32 v0, v204, 5, 1
	v_bfe_u32 v130, v132, 1, 3
	v_or_b32_e32 v133, 0, v0
	v_xor_b32_e32 v133, v133, v130
	v_lshlrev_b32_e32 v161, 4, v133
	v_or_b32_e32 v133, 2, v0
	v_xor_b32_e32 v133, v133, v130
	v_lshlrev_b32_e32 v163, 4, v133
	v_or_b32_e32 v133, 4, v0
	v_xor_b32_e32 v133, v133, v130
	v_lshlrev_b32_e32 v164, 4, v133
	v_or_b32_e32 v133, 6, v0
	v_xor_b32_e32 v133, v133, v130
	v_lshlrev_b32_e32 v165, 4, v133
	v_add_u32_e32 v248, v249, v161
	v_add_u32_e32 v186, v249, v163
	v_add_u32_e32 v187, v249, v164
	v_add_u32_e32 v249, v249, v165
	v_add_u32_e32 v161, v166, v161
	v_add_u32_e32 v163, v166, v163
	v_add_u32_e32 v164, v166, v164
	v_add_u32_e32 v165, v166, v165
	v_lshlrev_b32_e32 v131, 10, v131
	s_nop 0
	v_readfirstlane_b32 s100, v131
	v_mov_b32_e32 v146, 0
	v_mov_b32_e32 v147, 0
	v_mov_b32_e32 v148, 0
	v_mov_b32_e32 v149, 0
	v_lshlrev_b32_e32 v130, 4, v204
	v_add_u32_e32 v132, 0x10000, v130
	s_mov_b64 exec, -1
	s_mov_b32 s11, 0
	s_mov_b32 s10, 0x10000
	s_waitcnt lgkmcnt(0)
	s_add_u32 m0, s100, 0x8000
	s_nop 0
	global_load_lds_dwordx4 v244, s[8:9]
	v_add_u32_e32 v244, 0x80, v244
	s_add_u32 m0, s100, 0xa000
	s_nop 0
	global_load_lds_dwordx4 v246, s[8:9]
	v_add_u32_e32 v246, 0x80, v246
	s_add_u32 m0, s100, 0x0
	s_nop 0
	global_load_lds_dwordx4 v240, s[6:7]
	v_add_u32_e32 v240, 0x80, v240
	s_add_u32 m0, s100, 0x2000
	s_nop 0
	global_load_lds_dwordx4 v242, s[6:7]
	v_add_u32_e32 v242, 0x80, v242
	s_add_u32 m0, s100, 0xc000
	s_nop 0
	global_load_lds_dwordx4 v245, s[8:9]
	v_add_u32_e32 v245, 0x80, v245
	s_add_u32 m0, s100, 0xe000
	s_nop 0
	global_load_lds_dwordx4 v247, s[8:9]
	v_add_u32_e32 v247, 0x80, v247
	s_add_u32 m0, s100, 0x4000
	s_nop 0
	global_load_lds_dwordx4 v241, s[6:7]
	v_add_u32_e32 v241, 0x80, v241
	s_add_u32 m0, s100, 0x6000
	s_nop 0
	global_load_lds_dwordx4 v243, s[6:7]
	v_add_u32_e32 v243, 0x80, v243
	s_cmp_eq_u32 s101, 1
	s_cbranch_scc0 .Lg8_ia_p0
	s_barrier
; #define MFMA(a, b, c) __builtin_amdgcn_mfma_f32_32x32x16_bf16((a), (b), (c), 0, 0, 0)
; template <bool SWAP>
; DI void gemm_mainloop(f32x16 (&acc)[4][2], const u16* __restrict__ A, int lda, int rlo, int rhi,
;                       const u16* __restrict__ B, int ldb, int K, char* lds, const u16* zero_line) {
;     ...
;   auto ldfrag = [&](const char* st, int ks, int buf) {
;     const int co = ((2 * ks + h) ^ sw) << 4;
; #pragma unroll
;     for (int mi = 0; mi < 4; ++mi) fa[buf][mi] = *(const bf16x8*)(st + arow_off + mi * 4096 + co);
; #pragma unroll
;     for (int ni = 0; ni < 2; ++ni) fb[buf][ni] = *(const bf16x8*)(st + brow_off + ni * 4096 + co);
;   };
;   auto mma = [&](int buf) {
; #pragma unroll
;     for (int mi = 0; mi < 4; ++mi)
; #pragma unroll
;       for (int ni = 0; ni < 2; ++ni)
;         acc[mi][ni] = SWAP ? MFMA(fb[buf][ni], fa[buf][mi], acc[mi][ni]) : MFMA(fa[buf][mi], fb[buf][ni], acc[mi][ni]);
;   };
;   auto pat_rd = [&]() {
; #pragma unroll
;     for (int g = 0; g < 6; ++g) {
;       __builtin_amdgcn_sched_group_barrier(0x100, 1, 0);
;       __builtin_amdgcn_sched_group_barrier(0x008, 1, 0);
;     }
;     __builtin_amdgcn_sched_group_barrier(0x008, 2, 0);
;   };
; #pragma unroll 2
;   for (int kt = 0; kt < nk; ++kt) {
;     const char* st = lds + (kt & 1) * 65536;
;     ldfrag(st, 0, 0);
;     mma(1);
;     pat_rd();
;     if (kt + 1 < nk) glds(kt + 1, (kt + 1) & 1);
;     ldfrag(st, 1, 1);
;     mma(0);
;     pat_rd();
;     ldfrag(st, 2, 0);
;     mma(1);
;     pat_rd();
;     ldfrag(st, 3, 1);
;     mma(0);
;     pat_rd();
;     asm volatile("s_waitcnt vmcnt(0)" ::: "memory");
;     __syncthreads();
;   }
.Lg8_ia_p0:
	s_waitcnt vmcnt(4)
	s_barrier
	s_add_u32 m0, s100, 0x18000
	s_nop 0
	global_load_lds_dwordx4 v244, s[8:9]
	v_add_u32_e32 v244, 0x80, v244
	s_add_u32 m0, s100, 0x1a000
	s_nop 0
	global_load_lds_dwordx4 v246, s[8:9]
	v_add_u32_e32 v246, 0x80, v246
	s_add_u32 m0, s100, 0x10000
	s_nop 0
	global_load_lds_dwordx4 v240, s[6:7]
	v_add_u32_e32 v240, 0x80, v240
	s_add_u32 m0, s100, 0x12000
	s_nop 0
	global_load_lds_dwordx4 v242, s[6:7]
	v_add_u32_e32 v242, 0x80, v242
	s_add_u32 m0, s100, 0x1c000
	s_nop 0
	global_load_lds_dwordx4 v245, s[8:9]
	v_add_u32_e32 v245, 0x80, v245
	s_add_u32 m0, s100, 0x1e000
	s_nop 0
	global_load_lds_dwordx4 v247, s[8:9]
	v_add_u32_e32 v247, 0x80, v247
	s_waitcnt vmcnt(6)
	s_barrier
	ds_read_b128 v[176:179], v248 offset:32768
	ds_read_b128 v[180:183], v186 offset:32768
	ds_read_b128 v[192:195], v187 offset:32768
	ds_read_b128 v[196:199], v249 offset:32768
.Lg8_ia:
	ds_read_b128 v[130:133], v161
	ds_read_b128 v[134:137], v163
	ds_read_b128 v[138:141], v164
	ds_read_b128 v[142:145], v165
	ds_read_b128 v[146:149], v161 offset:4096
	ds_read_b128 v[150:153], v163 offset:4096
	ds_read_b128 v[168:171], v164 offset:4096
	ds_read_b128 v[172:175], v165 offset:4096
	s_add_u32 m0, s100, 0x14000
	s_nop 0
	global_load_lds_dwordx4 v241, s[6:7]
	v_add_u32_e32 v241, 0x80, v241
	s_add_u32 m0, s100, 0x16000
	s_nop 0
	global_load_lds_dwordx4 v243, s[6:7]
	v_add_u32_e32 v243, 0x80, v243
	s_barrier
	s_waitcnt lgkmcnt(0)
	v_mfma_f32_32x32x16_bf16 v[114:129], v[176:179], v[130:133], v[114:129]
	v_mfma_f32_32x32x16_bf16 v[98:113], v[176:179], v[146:149], v[98:113]
	v_mfma_f32_32x32x16_bf16 v[114:129], v[180:183], v[134:137], v[114:129]
	v_mfma_f32_32x32x16_bf16 v[98:113], v[180:183], v[150:153], v[98:113]
	v_mfma_f32_32x32x16_bf16 v[114:129], v[192:195], v[138:141], v[114:129]
	v_mfma_f32_32x32x16_bf16 v[98:113], v[192:195], v[168:171], v[98:113]
	v_mfma_f32_32x32x16_bf16 v[114:129], v[196:199], v[142:145], v[114:129]
	v_mfma_f32_32x32x16_bf16 v[98:113], v[196:199], v[172:175], v[98:113]
	s_barrier
	ds_read_b128 v[200:203], v248 offset:49152
	ds_read_b128 v[228:231], v186 offset:49152
	ds_read_b128 v[232:235], v187 offset:49152
	ds_read_b128 v[236:239], v249 offset:49152
	s_add_u32 m0, s100, 0x8000
	s_nop 0
	global_load_lds_dwordx4 v244, s[8:9]
	v_add_u32_e32 v244, 0x80, v244
	s_add_u32 m0, s100, 0xa000
	s_nop 0
	global_load_lds_dwordx4 v246, s[8:9]
	v_add_u32_e32 v246, 0x80, v246
	s_barrier
	s_waitcnt lgkmcnt(0)
	v_mfma_f32_32x32x16_bf16 v[82:97], v[200:203], v[130:133], v[82:97]
	v_mfma_f32_32x32x16_bf16 v[50:65], v[200:203], v[146:149], v[50:65]
	v_mfma_f32_32x32x16_bf16 v[82:97], v[228:231], v[134:137], v[82:97]
	v_mfma_f32_32x32x16_bf16 v[50:65], v[228:231], v[150:153], v[50:65]
	v_mfma_f32_32x32x16_bf16 v[82:97], v[232:235], v[138:141], v[82:97]
	v_mfma_f32_32x32x16_bf16 v[50:65], v[232:235], v[168:171], v[50:65]
	v_mfma_f32_32x32x16_bf16 v[82:97], v[236:239], v[142:145], v[82:97]
	v_mfma_f32_32x32x16_bf16 v[50:65], v[236:239], v[172:175], v[50:65]
	s_barrier
	ds_read_b128 v[130:133], v161 offset:16384
	ds_read_b128 v[134:137], v163 offset:16384
	ds_read_b128 v[138:141], v164 offset:16384
	ds_read_b128 v[142:145], v165 offset:16384
	ds_read_b128 v[146:149], v161 offset:20480
	ds_read_b128 v[150:153], v163 offset:20480
	ds_read_b128 v[168:171], v164 offset:20480
	ds_read_b128 v[172:175], v165 offset:20480
	s_add_u32 m0, s100, 0x0
	s_nop 0
	global_load_lds_dwordx4 v240, s[6:7]
	v_add_u32_e32 v240, 0x80, v240
	s_add_u32 m0, s100, 0x2000
	s_nop 0
	global_load_lds_dwordx4 v242, s[6:7]
	v_add_u32_e32 v242, 0x80, v242
	s_waitcnt vmcnt(10)
	s_barrier
	s_waitcnt lgkmcnt(0)
	v_mfma_f32_32x32x16_bf16 v[66:81], v[176:179], v[130:133], v[66:81]
	v_mfma_f32_32x32x16_bf16 v[34:49], v[176:179], v[146:149], v[34:49]
	v_mfma_f32_32x32x16_bf16 v[66:81], v[180:183], v[134:137], v[66:81]
	v_mfma_f32_32x32x16_bf16 v[34:49], v[180:183], v[150:153], v[34:49]
	v_mfma_f32_32x32x16_bf16 v[66:81], v[192:195], v[138:141], v[66:81]
	v_mfma_f32_32x32x16_bf16 v[34:49], v[192:195], v[168:171], v[34:49]
	v_mfma_f32_32x32x16_bf16 v[66:81], v[196:199], v[142:145], v[66:81]
	v_mfma_f32_32x32x16_bf16 v[34:49], v[196:199], v[172:175], v[34:49]
	s_barrier
	v_add_u32_e32 v166, s10, v248
	ds_read_b128 v[176:179], v166 offset:32768
	v_add_u32_e32 v166, s10, v186
	ds_read_b128 v[180:183], v166 offset:32768
	v_add_u32_e32 v166, s10, v187
	ds_read_b128 v[192:195], v166 offset:32768
	v_add_u32_e32 v166, s10, v249
	ds_read_b128 v[196:199], v166 offset:32768
	s_add_u32 m0, s100, 0xc000
	s_nop 0
	global_load_lds_dwordx4 v245, s[8:9]
	v_add_u32_e32 v245, 0x80, v245
	s_add_u32 m0, s100, 0xe000
	s_nop 0
	global_load_lds_dwordx4 v247, s[8:9]
	v_add_u32_e32 v247, 0x80, v247
	s_waitcnt vmcnt(6)
	s_barrier
	s_waitcnt lgkmcnt(0)
	v_mfma_f32_32x32x16_bf16 v[18:33], v[200:203], v[130:133], v[18:33]
	v_mfma_f32_32x32x16_bf16 v[2:17], v[200:203], v[146:149], v[2:17]
	v_mfma_f32_32x32x16_bf16 v[18:33], v[228:231], v[134:137], v[18:33]
	v_mfma_f32_32x32x16_bf16 v[2:17], v[228:231], v[150:153], v[2:17]
	v_mfma_f32_32x32x16_bf16 v[18:33], v[232:235], v[138:141], v[18:33]
	v_mfma_f32_32x32x16_bf16 v[2:17], v[232:235], v[168:171], v[2:17]
	v_mfma_f32_32x32x16_bf16 v[18:33], v[236:239], v[142:145], v[18:33]
	v_mfma_f32_32x32x16_bf16 v[2:17], v[236:239], v[172:175], v[2:17]
	s_barrier
; #define MFMA(a, b, c) __builtin_amdgcn_mfma_f32_32x32x16_bf16((a), (b), (c), 0, 0, 0)
; template <bool SWAP>
; DI void gemm_mainloop(f32x16 (&acc)[4][2], const u16* __restrict__ A, int lda, int rlo, int rhi,
;                       const u16* __restrict__ B, int ldb, int K, char* lds, const u16* zero_line) {
;     ...
;   auto ldfrag = [&](const char* st, int ks, int buf) {
;     const int co = ((2 * ks + h) ^ sw) << 4;
; #pragma unroll
;     for (int mi = 0; mi < 4; ++mi) fa[buf][mi] = *(const bf16x8*)(st + arow_off + mi * 4096 + co);
; #pragma unroll
;     for (int ni = 0; ni < 2; ++ni) fb[buf][ni] = *(const bf16x8*)(st + brow_off + ni * 4096 + co);
;   };
;   auto mma = [&](int buf) {
; #pragma unroll
;     for (int mi = 0; mi < 4; ++mi)
; #pragma unroll
;       for (int ni = 0; ni < 2; ++ni)
;         acc[mi][ni] = SWAP ? MFMA(fb[buf][ni], fa[buf][mi], acc[mi][ni]) : MFMA(fa[buf][mi], fb[buf][ni], acc[mi][ni]);
;   };
;   auto pat_rd = [&]() {
; #pragma unroll
;     for (int g = 0; g < 6; ++g) {
;       __builtin_amdgcn_sched_group_barrier(0x100, 1, 0);
;       __builtin_amdgcn_sched_group_barrier(0x008, 1, 0);
;     }
;     __builtin_amdgcn_sched_group_barrier(0x008, 2, 0);
;   };
; #pragma unroll 2
;   for (int kt = 0; kt < nk; ++kt) {
;     const char* st = lds + (kt & 1) * 65536;
;     ldfrag(st, 0, 0);
;     mma(1);
;     pat_rd();
;     if (kt + 1 < nk) glds(kt + 1, (kt + 1) & 1);
;     ldfrag(st, 1, 1);
;     mma(0);
;     pat_rd();
;     ldfrag(st, 2, 0);
;     mma(1);
;     pat_rd();
;     ldfrag(st, 3, 1);
;     mma(0);
;     pat_rd();
;     asm volatile("s_waitcnt vmcnt(0)" ::: "memory");
;     __syncthreads();
;   }
	v_add_u32_e32 v166, s10, v161
	ds_read_b128 v[130:133], v166
	ds_read_b128 v[146:149], v166 offset:4096
	v_add_u32_e32 v166, s10, v163
	ds_read_b128 v[134:137], v166
	ds_read_b128 v[150:153], v166 offset:4096
	v_add_u32_e32 v166, s10, v164
	ds_read_b128 v[138:141], v166
	ds_read_b128 v[168:171], v166 offset:4096
	v_add_u32_e32 v166, s10, v165
	ds_read_b128 v[142:145], v166
	ds_read_b128 v[172:175], v166 offset:4096
	s_add_u32 m0, s100, 0x4000
	s_nop 0
	global_load_lds_dwordx4 v241, s[6:7]
	v_add_u32_e32 v241, 0x80, v241
	s_add_u32 m0, s100, 0x6000
	s_nop 0
	global_load_lds_dwordx4 v243, s[6:7]
	v_add_u32_e32 v243, 0x80, v243
	s_barrier
	s_waitcnt lgkmcnt(0)
	v_mfma_f32_32x32x16_bf16 v[114:129], v[176:179], v[130:133], v[114:129]
	v_mfma_f32_32x32x16_bf16 v[98:113], v[176:179], v[146:149], v[98:113]
	v_mfma_f32_32x32x16_bf16 v[114:129], v[180:183], v[134:137], v[114:129]
	v_mfma_f32_32x32x16_bf16 v[98:113], v[180:183], v[150:153], v[98:113]
	v_mfma_f32_32x32x16_bf16 v[114:129], v[192:195], v[138:141], v[114:129]
	v_mfma_f32_32x32x16_bf16 v[98:113], v[192:195], v[168:171], v[98:113]
	v_mfma_f32_32x32x16_bf16 v[114:129], v[196:199], v[142:145], v[114:129]
	v_mfma_f32_32x32x16_bf16 v[98:113], v[196:199], v[172:175], v[98:113]
	s_barrier
	v_add_u32_e32 v166, s10, v248
	ds_read_b128 v[200:203], v166 offset:49152
	v_add_u32_e32 v166, s10, v186
	ds_read_b128 v[228:231], v166 offset:49152
	v_add_u32_e32 v166, s10, v187
	ds_read_b128 v[232:235], v166 offset:49152
	v_add_u32_e32 v166, s10, v249
	ds_read_b128 v[236:239], v166 offset:49152
	s_add_u32 m0, s100, 0x18000
	s_nop 0
	global_load_lds_dwordx4 v244, s[8:9]
	v_add_u32_e32 v244, 0x80, v244
	s_add_u32 m0, s100, 0x1a000
	s_nop 0
	global_load_lds_dwordx4 v246, s[8:9]
	v_add_u32_e32 v246, 0x80, v246
	s_barrier
	s_waitcnt lgkmcnt(0)
	v_mfma_f32_32x32x16_bf16 v[82:97], v[200:203], v[130:133], v[82:97]
	v_mfma_f32_32x32x16_bf16 v[50:65], v[200:203], v[146:149], v[50:65]
	v_mfma_f32_32x32x16_bf16 v[82:97], v[228:231], v[134:137], v[82:97]
	v_mfma_f32_32x32x16_bf16 v[50:65], v[228:231], v[150:153], v[50:65]
	v_mfma_f32_32x32x16_bf16 v[82:97], v[232:235], v[138:141], v[82:97]
	v_mfma_f32_32x32x16_bf16 v[50:65], v[232:235], v[168:171], v[50:65]
	v_mfma_f32_32x32x16_bf16 v[82:97], v[236:239], v[142:145], v[82:97]
	v_mfma_f32_32x32x16_bf16 v[50:65], v[236:239], v[172:175], v[50:65]
	s_barrier
	v_add_u32_e32 v166, s10, v161
	ds_read_b128 v[130:133], v166 offset:16384
	ds_read_b128 v[146:149], v166 offset:20480
	v_add_u32_e32 v166, s10, v163
	ds_read_b128 v[134:137], v166 offset:16384
	ds_read_b128 v[150:153], v166 offset:20480
	v_add_u32_e32 v166, s10, v164
	ds_read_b128 v[138:141], v166 offset:16384
	ds_read_b128 v[168:171], v166 offset:20480
	v_add_u32_e32 v166, s10, v165
	ds_read_b128 v[142:145], v166 offset:16384
	ds_read_b128 v[172:175], v166 offset:20480
	s_add_u32 m0, s100, 0x10000
	s_nop 0
	global_load_lds_dwordx4 v240, s[6:7]
	v_add_u32_e32 v240, 0x80, v240
	s_add_u32 m0, s100, 0x12000
	s_nop 0
	global_load_lds_dwordx4 v242, s[6:7]
	v_add_u32_e32 v242, 0x80, v242
	s_waitcnt vmcnt(10)
	s_barrier
	s_waitcnt lgkmcnt(0)
	v_mfma_f32_32x32x16_bf16 v[66:81], v[176:179], v[130:133], v[66:81]
	v_mfma_f32_32x32x16_bf16 v[34:49], v[176:179], v[146:149], v[34:49]
	v_mfma_f32_32x32x16_bf16 v[66:81], v[180:183], v[134:137], v[66:81]
	v_mfma_f32_32x32x16_bf16 v[34:49], v[180:183], v[150:153], v[34:49]
	v_mfma_f32_32x32x16_bf16 v[66:81], v[192:195], v[138:141], v[66:81]
	v_mfma_f32_32x32x16_bf16 v[34:49], v[192:195], v[168:171], v[34:49]
	v_mfma_f32_32x32x16_bf16 v[66:81], v[196:199], v[142:145], v[66:81]
	v_mfma_f32_32x32x16_bf16 v[34:49], v[196:199], v[172:175], v[34:49]
	s_barrier
	ds_read_b128 v[176:179], v248 offset:32768
	ds_read_b128 v[180:183], v186 offset:32768
	ds_read_b128 v[192:195], v187 offset:32768
	ds_read_b128 v[196:199], v249 offset:32768
	s_add_u32 m0, s100, 0x1c000
	s_nop 0
	global_load_lds_dwordx4 v245, s[8:9]
	v_add_u32_e32 v245, 0x80, v245
	s_add_u32 m0, s100, 0x1e000
	s_nop 0
	global_load_lds_dwordx4 v247, s[8:9]
	v_add_u32_e32 v247, 0x80, v247
	s_waitcnt vmcnt(6)
	s_barrier
	s_waitcnt lgkmcnt(0)
	v_mfma_f32_32x32x16_bf16 v[18:33], v[200:203], v[130:133], v[18:33]
	v_mfma_f32_32x32x16_bf16 v[2:17], v[200:203], v[146:149], v[2:17]
	v_mfma_f32_32x32x16_bf16 v[18:33], v[228:231], v[134:137], v[18:33]
	v_mfma_f32_32x32x16_bf16 v[2:17], v[228:231], v[150:153], v[2:17]
	v_mfma_f32_32x32x16_bf16 v[18:33], v[232:235], v[138:141], v[18:33]
	v_mfma_f32_32x32x16_bf16 v[2:17], v[232:235], v[168:171], v[2:17]
	v_mfma_f32_32x32x16_bf16 v[18:33], v[236:239], v[142:145], v[18:33]
	v_mfma_f32_32x32x16_bf16 v[2:17], v[236:239], v[172:175], v[2:17]
	s_barrier
	s_add_i32 s11, s11, 2
	s_cmp_lt_u32 s11, 14
	s_cbranch_scc1 .Lg8_ia
	ds_read_b128 v[130:133], v161
	ds_read_b128 v[134:137], v163
	ds_read_b128 v[138:141], v164
	ds_read_b128 v[142:145], v165
	ds_read_b128 v[146:149], v161 offset:4096
	ds_read_b128 v[150:153], v163 offset:4096
	ds_read_b128 v[168:171], v164 offset:4096
	ds_read_b128 v[172:175], v165 offset:4096
	s_add_u32 m0, s100, 0x14000
	s_nop 0
	global_load_lds_dwordx4 v241, s[6:7]
	v_add_u32_e32 v241, 0x80, v241
	s_add_u32 m0, s100, 0x16000
	s_nop 0
	global_load_lds_dwordx4 v243, s[6:7]
	v_add_u32_e32 v243, 0x80, v243
	s_barrier
	s_waitcnt lgkmcnt(0)
	v_mfma_f32_32x32x16_bf16 v[114:129], v[176:179], v[130:133], v[114:129]
	v_mfma_f32_32x32x16_bf16 v[98:113], v[176:179], v[146:149], v[98:113]
	v_mfma_f32_32x32x16_bf16 v[114:129], v[180:183], v[134:137], v[114:129]
	v_mfma_f32_32x32x16_bf16 v[98:113], v[180:183], v[150:153], v[98:113]
	v_mfma_f32_32x32x16_bf16 v[114:129], v[192:195], v[138:141], v[114:129]
	v_mfma_f32_32x32x16_bf16 v[98:113], v[192:195], v[168:171], v[98:113]
	v_mfma_f32_32x32x16_bf16 v[114:129], v[196:199], v[142:145], v[114:129]
	v_mfma_f32_32x32x16_bf16 v[98:113], v[196:199], v[172:175], v[98:113]
	s_barrier
; template <bool SWAP>
; DI void gemm_mainloop(f32x16 (&acc)[4][2], const u16* __restrict__ A, int lda, int rlo, int rhi,
;                       const u16* __restrict__ B, int ldb, int K, char* lds, const u16* zero_line) {
;     ...
; #pragma unroll 2
;   for (int kt = 0; kt < nk; ++kt) {
;     const char* st = lds + (kt & 1) * 65536;
;     ldfrag(st, 0, 0);
;     mma(1);
;     pat_rd();
;     if (kt + 1 < nk) glds(kt + 1, (kt + 1) & 1);
;     ldfrag(st, 1, 1);
;     mma(0);
;     pat_rd();
;     ldfrag(st, 2, 0);
;     mma(1);
;     pat_rd();
;     ldfrag(st, 3, 1);
;     mma(0);
;     pat_rd();
;     asm volatile("s_waitcnt vmcnt(0)" ::: "memory");
;     __syncthreads();
;   }
;   mma(1);
	ds_read_b128 v[200:203], v248 offset:49152
	ds_read_b128 v[228:231], v186 offset:49152
	ds_read_b128 v[232:235], v187 offset:49152
	ds_read_b128 v[236:239], v249 offset:49152
	s_barrier
	s_waitcnt lgkmcnt(0)
	v_mfma_f32_32x32x16_bf16 v[82:97], v[200:203], v[130:133], v[82:97]
	v_mfma_f32_32x32x16_bf16 v[50:65], v[200:203], v[146:149], v[50:65]
	v_mfma_f32_32x32x16_bf16 v[82:97], v[228:231], v[134:137], v[82:97]
	v_mfma_f32_32x32x16_bf16 v[50:65], v[228:231], v[150:153], v[50:65]
	v_mfma_f32_32x32x16_bf16 v[82:97], v[232:235], v[138:141], v[82:97]
	v_mfma_f32_32x32x16_bf16 v[50:65], v[232:235], v[168:171], v[50:65]
	v_mfma_f32_32x32x16_bf16 v[82:97], v[236:239], v[142:145], v[82:97]
	v_mfma_f32_32x32x16_bf16 v[50:65], v[236:239], v[172:175], v[50:65]
	s_barrier
	ds_read_b128 v[130:133], v161 offset:16384
	ds_read_b128 v[134:137], v163 offset:16384
	ds_read_b128 v[138:141], v164 offset:16384
	ds_read_b128 v[142:145], v165 offset:16384
	ds_read_b128 v[146:149], v161 offset:20480
	ds_read_b128 v[150:153], v163 offset:20480
	ds_read_b128 v[168:171], v164 offset:20480
	ds_read_b128 v[172:175], v165 offset:20480
	s_waitcnt vmcnt(4)
	s_barrier
	s_waitcnt lgkmcnt(0)
	v_mfma_f32_32x32x16_bf16 v[66:81], v[176:179], v[130:133], v[66:81]
	v_mfma_f32_32x32x16_bf16 v[34:49], v[176:179], v[146:149], v[34:49]
	v_mfma_f32_32x32x16_bf16 v[66:81], v[180:183], v[134:137], v[66:81]
	v_mfma_f32_32x32x16_bf16 v[34:49], v[180:183], v[150:153], v[34:49]
	v_mfma_f32_32x32x16_bf16 v[66:81], v[192:195], v[138:141], v[66:81]
	v_mfma_f32_32x32x16_bf16 v[34:49], v[192:195], v[168:171], v[34:49]
	v_mfma_f32_32x32x16_bf16 v[66:81], v[196:199], v[142:145], v[66:81]
	v_mfma_f32_32x32x16_bf16 v[34:49], v[196:199], v[172:175], v[34:49]
	v_mfma_f32_32x32x16_bf16 v[18:33], v[200:203], v[130:133], v[18:33]
	v_mfma_f32_32x32x16_bf16 v[2:17], v[200:203], v[146:149], v[2:17]
	v_mfma_f32_32x32x16_bf16 v[18:33], v[228:231], v[134:137], v[18:33]
	v_mfma_f32_32x32x16_bf16 v[2:17], v[228:231], v[150:153], v[2:17]
	v_mfma_f32_32x32x16_bf16 v[18:33], v[232:235], v[138:141], v[18:33]
	v_mfma_f32_32x32x16_bf16 v[2:17], v[232:235], v[168:171], v[2:17]
	v_mfma_f32_32x32x16_bf16 v[18:33], v[236:239], v[142:145], v[18:33]
	v_mfma_f32_32x32x16_bf16 v[2:17], v[236:239], v[172:175], v[2:17]
	s_barrier
	v_add_u32_e32 v166, s10, v248
	ds_read_b128 v[176:179], v166 offset:32768
	v_add_u32_e32 v166, s10, v186
	ds_read_b128 v[180:183], v166 offset:32768
	v_add_u32_e32 v166, s10, v187
	ds_read_b128 v[192:195], v166 offset:32768
	v_add_u32_e32 v166, s10, v249
	ds_read_b128 v[196:199], v166 offset:32768
	v_add_u32_e32 v166, s10, v161
	ds_read_b128 v[130:133], v166
	ds_read_b128 v[146:149], v166 offset:4096
	v_add_u32_e32 v166, s10, v163
	ds_read_b128 v[134:137], v166
	ds_read_b128 v[150:153], v166 offset:4096
	v_add_u32_e32 v166, s10, v164
	ds_read_b128 v[138:141], v166
	ds_read_b128 v[168:171], v166 offset:4096
	v_add_u32_e32 v166, s10, v165
	ds_read_b128 v[142:145], v166
	ds_read_b128 v[172:175], v166 offset:4096
	s_waitcnt vmcnt(2)
	s_barrier
	s_waitcnt lgkmcnt(0)
	v_mfma_f32_32x32x16_bf16 v[114:129], v[176:179], v[130:133], v[114:129]
	v_mfma_f32_32x32x16_bf16 v[98:113], v[176:179], v[146:149], v[98:113]
	v_mfma_f32_32x32x16_bf16 v[114:129], v[180:183], v[134:137], v[114:129]
	v_mfma_f32_32x32x16_bf16 v[98:113], v[180:183], v[150:153], v[98:113]
	v_mfma_f32_32x32x16_bf16 v[114:129], v[192:195], v[138:141], v[114:129]
	v_mfma_f32_32x32x16_bf16 v[98:113], v[192:195], v[168:171], v[98:113]
	v_mfma_f32_32x32x16_bf16 v[114:129], v[196:199], v[142:145], v[114:129]
	v_mfma_f32_32x32x16_bf16 v[98:113], v[196:199], v[172:175], v[98:113]
	s_barrier
	v_add_u32_e32 v166, s10, v248
	ds_read_b128 v[200:203], v166 offset:49152
	v_add_u32_e32 v166, s10, v186
	ds_read_b128 v[228:231], v166 offset:49152
	v_add_u32_e32 v166, s10, v187
	ds_read_b128 v[232:235], v166 offset:49152
	v_add_u32_e32 v166, s10, v249
	ds_read_b128 v[236:239], v166 offset:49152
	s_waitcnt vmcnt(0)
	s_barrier
	s_waitcnt lgkmcnt(0)
	v_mfma_f32_32x32x16_bf16 v[82:97], v[200:203], v[130:133], v[82:97]
	v_mfma_f32_32x32x16_bf16 v[50:65], v[200:203], v[146:149], v[50:65]
	v_mfma_f32_32x32x16_bf16 v[82:97], v[228:231], v[134:137], v[82:97]
	v_mfma_f32_32x32x16_bf16 v[50:65], v[228:231], v[150:153], v[50:65]
	v_mfma_f32_32x32x16_bf16 v[82:97], v[232:235], v[138:141], v[82:97]
	v_mfma_f32_32x32x16_bf16 v[50:65], v[232:235], v[168:171], v[50:65]
	v_mfma_f32_32x32x16_bf16 v[82:97], v[236:239], v[142:145], v[82:97]
	v_mfma_f32_32x32x16_bf16 v[50:65], v[236:239], v[172:175], v[50:65]
	s_barrier
	v_add_u32_e32 v166, s10, v161
	ds_read_b128 v[130:133], v166 offset:16384
	ds_read_b128 v[146:149], v166 offset:20480
	v_add_u32_e32 v166, s10, v163
	ds_read_b128 v[134:137], v166 offset:16384
	ds_read_b128 v[150:153], v166 offset:20480
	v_add_u32_e32 v166, s10, v164
	ds_read_b128 v[138:141], v166 offset:16384
	ds_read_b128 v[168:171], v166 offset:20480
	v_add_u32_e32 v166, s10, v165
	ds_read_b128 v[142:145], v166 offset:16384
	ds_read_b128 v[172:175], v166 offset:20480
	s_barrier
	s_waitcnt lgkmcnt(0)
	v_mfma_f32_32x32x16_bf16 v[66:81], v[176:179], v[130:133], v[66:81]
	v_mfma_f32_32x32x16_bf16 v[34:49], v[176:179], v[146:149], v[34:49]
	v_mfma_f32_32x32x16_bf16 v[66:81], v[180:183], v[134:137], v[66:81]
	v_mfma_f32_32x32x16_bf16 v[34:49], v[180:183], v[150:153], v[34:49]
	v_mfma_f32_32x32x16_bf16 v[66:81], v[192:195], v[138:141], v[66:81]
	v_mfma_f32_32x32x16_bf16 v[34:49], v[192:195], v[168:171], v[34:49]
	v_mfma_f32_32x32x16_bf16 v[66:81], v[196:199], v[142:145], v[66:81]
	v_mfma_f32_32x32x16_bf16 v[34:49], v[196:199], v[172:175], v[34:49]
	v_mfma_f32_32x32x16_bf16 v[18:33], v[200:203], v[130:133], v[18:33]
	v_mfma_f32_32x32x16_bf16 v[2:17], v[200:203], v[146:149], v[2:17]
	v_mfma_f32_32x32x16_bf16 v[18:33], v[228:231], v[134:137], v[18:33]
	v_mfma_f32_32x32x16_bf16 v[2:17], v[228:231], v[150:153], v[2:17]
	v_mfma_f32_32x32x16_bf16 v[18:33], v[232:235], v[138:141], v[18:33]
	v_mfma_f32_32x32x16_bf16 v[2:17], v[232:235], v[168:171], v[2:17]
	v_mfma_f32_32x32x16_bf16 v[18:33], v[236:239], v[142:145], v[18:33]
	v_mfma_f32_32x32x16_bf16 v[2:17], v[236:239], v[172:175], v[2:17]
	s_barrier
	s_cmp_eq_u32 s101, 0
	s_cbranch_scc0 .Lg8_ia_p1
	s_barrier

; template <bool SWAP>
; DI void gemm_mainloop(f32x16 (&acc)[4][2], const u16* __restrict__ A, int lda, int rlo, int rhi,
;                       const u16* __restrict__ B, int ldb, int K, char* lds, const u16* zero_line) {
;     ...
;   const int gch = (lc ^ ((lr >> 1) & 7)) * 8;
;   const u16* ap = A + (ptrdiff_t)lr * lda + gch;
;   const u16* bp = B + (ptrdiff_t)lr * ldb + gch;
;   const int nk = K >> 6;
;   typedef __attribute__((address_space(3))) unsigned lds_u32;
;   auto glds = [&](int kt, int st) {
;     char* as_ = lds + st * 65536 + tid * 16;
; #pragma unroll
;     for (int i = 0; i < 4; ++i) {
;       const int rr = lr + 64 * i;
;       const u16* srca = (rr >= rlo && rr < rhi) ? (ap + (ptrdiff_t)(64 * i) * lda + kt * 64) : (zero_line + lc * 8);
;       __builtin_amdgcn_global_load_lds((const unsigned*)srca, (lds_u32*)(as_ + i * 8192), 16, 0, 0);
;       __builtin_amdgcn_global_load_lds((const unsigned*)(bp + (ptrdiff_t)(64 * i) * ldb + kt * 64), (lds_u32*)(as_ + 32768 + i * 8192), 16, 0, 0);
;     }
;   };
;   const int sw = (r >> 1) & 7;
;   const int arow_off = (wm * 128 + r) * 128;
;   const int brow_off = 32768 + (wn * 64 + r) * 128;
;   __syncthreads();
;   glds(0, 0);
;   asm volatile("s_waitcnt vmcnt(0)" ::: "memory");
;   __syncthreads();
.LBB0_322:
	s_and_b64 vcc, exec, s[6:7]
	s_cbranch_vccz .LBB0_328
	s_waitcnt vmcnt(5)
	s_nop 8
	v_mov_b32_e32 v10, v204
	s_nop 0
	v_ashrrev_i32_e32 v2, 3, v10
	v_lshrrev_b32_e32 v13, 1, v2
	v_xor_b32_e32 v0, v13, v10
	v_ashrrev_i32_e32 v3, 31, v2
	v_lshlrev_b64 v[4:5], 11, v[2:3]
	v_lshlrev_b32_e32 v0, 4, v0
	v_and_b32_e32 v12, 31, v10
	v_lshl_add_u64 v[6:7], s[14:15], 0, v[4:5]
	v_and_b32_e32 v0, 0x70, v0
	v_lshl_add_u64 v[8:9], s[20:21], 0, v[4:5]
	s_waitcnt vmcnt(4)
	v_lshrrev_b32_e32 v14, 1, v10
	v_lshl_add_u64 v[6:7], v[6:7], 0, v[0:1]
	v_lshl_add_u64 v[164:165], v[8:9], 0, v[0:1]
	v_and_or_b32 v0, v14, s51, v12
	v_lshlrev_b32_e32 v161, 7, v0
	v_lshlrev_b32_e32 v0, 7, v10
	v_lshlrev_b32_e32 v174, 4, v10
	v_and_b32_e32 v163, 0x6f80, v0
	v_and_b32_e32 v0, 0x70, v174
	v_add_u32_e32 v175, 0x8000, v174
	v_lshl_add_u64 v[166:167], s[80:81], 0, v[0:1]
	v_cmp_gt_u32_e32 vcc, s50, v2
	v_readfirstlane_b32 s6, v174
	s_mov_b32 m0, s6
	v_cndmask_b32_e32 v9, v167, v7, vcc
	v_cndmask_b32_e32 v8, v166, v6, vcc
	v_readfirstlane_b32 s6, v175
	v_add_u32_e32 v0, 64, v2
	s_barrier
	s_mov_b32 m0, s6
	s_mov_b64 s[10:11], 0x20000
	v_cmp_gt_u32_e64 s[6:7], s50, v0
	v_add_u32_e32 v0, 0x2000, v174
	v_lshl_add_u64 v[8:9], v[6:7], 0, s[10:11]
	v_readfirstlane_b32 s8, v0
	v_add_u32_e32 v176, 0xa000, v174
	v_cndmask_b32_e64 v9, v167, v9, s[6:7]
	v_cndmask_b32_e64 v8, v166, v8, s[6:7]
	s_mov_b32 m0, s8
	v_readfirstlane_b32 s8, v176
	v_lshl_add_u64 v[8:9], v[164:165], 0, s[10:11]
	s_mov_b32 m0, s8
	v_add_u32_e32 v3, 0x80, v2
	s_mov_b64 s[14:15], 0x40000
	v_add_u32_e32 v177, 0x4000, v174
	v_lshl_add_u64 v[8:9], v[6:7], 0, s[14:15]
	v_cmp_gt_u32_e64 s[8:9], s50, v3
	v_readfirstlane_b32 s10, v177
	v_add_u32_e32 v178, 0xc000, v174
	v_cndmask_b32_e64 v9, v167, v9, s[8:9]
	v_cndmask_b32_e64 v8, v166, v8, s[8:9]
	s_mov_b32 m0, s10
	v_readfirstlane_b32 s10, v178
	v_lshl_add_u64 v[8:9], v[164:165], 0, s[14:15]
	s_mov_b32 m0, s10
	s_mov_b64 s[20:21], 0x60000
	v_add_u32_e32 v8, 0xc0, v2
	v_add_u32_e32 v179, 0x6000, v174
	v_lshl_add_u64 v[2:3], v[6:7], 0, s[20:21]
	v_cmp_gt_u32_e64 s[10:11], s50, v8
	v_readfirstlane_b32 s14, v179
	v_add_u32_e32 v180, 0xe000, v174
	v_cndmask_b32_e64 v3, v167, v3, s[10:11]
	v_cndmask_b32_e64 v2, v166, v2, s[10:11]
	s_mov_b32 m0, s14
	v_readfirstlane_b32 s14, v180
	v_lshl_add_u64 v[2:3], v[164:165], 0, s[20:21]
	s_mov_b32 m0, s14
	v_bfe_u32 v11, v10, 5, 1
	s_sub_i32 s14, s26, s30
	s_lshl_b32 s15, s29, 6
	v_bfe_u32 v15, v10, 1, 3
	v_bitop3_b32 v2, v14, v11, 7 bitop3:0x6c
	s_sub_i32 s14, s14, s15
	v_lshlrev_b32_e32 v181, 4, v2
	v_bitop3_b32 v2, v11, v15, 2 bitop3:0x36
	s_lshl_b32 s14, s14, 8
	v_lshlrev_b32_e32 v182, 4, v2
	v_bitop3_b32 v2, v11, v15, 4 bitop3:0x36
	s_ashr_i32 s15, s14, 31
	v_lshlrev_b32_e32 v183, 4, v2
	v_bitop3_b32 v2, v11, v15, 6 bitop3:0x36
	s_lshl_b64 s[14:15], s[14:15], 11
	v_lshlrev_b32_e32 v186, 4, v2
	v_lshl_add_u64 v[2:3], v[4:5], 0, s[14:15]
	v_bitop3_b32 v4, v13, 7, v10 bitop3:0x48
	s_waitcnt vmcnt(0)
	v_lshl_or_b32 v2, v4, 4, v2
	v_lshl_add_u64 v[168:169], s[70:71], 0, v[2:3]
	v_mov_b32_e32 v130, 0
	v_mov_b32_e32 v2, 0
	s_mov_b32 s13, 1
	v_add_u32_e32 v187, 0x10000, v174
	v_add_u32_e32 v192, 0x18000, v174
	v_add_u32_e32 v193, 0x12000, v174
	v_add_u32_e32 v194, 0x1a000, v174
	v_add_u32_e32 v195, 0x14000, v174
	v_add_u32_e32 v196, 0x1c000, v174
	v_add_u32_e32 v197, 0x16000, v174
	v_add_u32_e32 v198, 0x1e000, v174
	v_add_u32_e32 v199, 0x10000, v161
	v_or_b32_e32 v200, 0x10000, v163
	s_mov_b64 s[14:15], 0
	v_mov_b32_e32 v3, v2
	v_mov_b32_e32 v4, v2
	v_mov_b32_e32 v5, v2
	v_mov_b32_e32 v6, v2
	v_mov_b32_e32 v7, v2
	v_mov_b32_e32 v8, v2
	v_mov_b32_e32 v9, v2
	v_mov_b32_e32 v10, v2
	v_mov_b32_e32 v11, v2
	v_mov_b32_e32 v12, v2
	v_mov_b32_e32 v13, v2
	v_mov_b32_e32 v14, v2
	v_mov_b32_e32 v15, v2
	v_mov_b32_e32 v16, v2
	v_mov_b32_e32 v17, v2
	v_mov_b32_e32 v34, v2
	v_mov_b32_e32 v35, v2
	v_mov_b32_e32 v36, v2
	v_mov_b32_e32 v37, v2
	v_mov_b32_e32 v38, v2
	v_mov_b32_e32 v39, v2
	v_mov_b32_e32 v40, v2
	v_mov_b32_e32 v41, v2
	v_mov_b32_e32 v42, v2
	v_mov_b32_e32 v43, v2
	v_mov_b32_e32 v44, v2
	v_mov_b32_e32 v45, v2
	v_mov_b32_e32 v46, v2
	v_mov_b32_e32 v47, v2
	v_mov_b32_e32 v48, v2
	v_mov_b32_e32 v49, v2
	s_waitcnt vmcnt(0)
; template <bool SWAP>
; DI void gemm_mainloop(f32x16 (&acc)[4][2], const u16* __restrict__ A, int lda, int rlo, int rhi,
;                       const u16* __restrict__ B, int ldb, int K, char* lds, const u16* zero_line) {
;     ...
; #pragma unroll
;   for (int mi = 0; mi < 4; ++mi)
; #pragma unroll
;     for (int ni = 0; ni < 2; ++ni)
; #pragma unroll
;       for (int i = 0; i < 16; ++i) acc[mi][ni][i] = 0.f;
;   const int gch = (lc ^ ((lr >> 1) & 7)) * 8;
;   const u16* ap = A + (ptrdiff_t)lr * lda + gch;
;   const u16* bp = B + (ptrdiff_t)lr * ldb + gch;
;   const int nk = K >> 6;
;   typedef __attribute__((address_space(3))) unsigned lds_u32;
;   auto glds = [&](int kt, int st) {
;     char* as_ = lds + st * 65536 + tid * 16;
; #pragma unroll
;     for (int i = 0; i < 4; ++i) {
;       const int rr = lr + 64 * i;
;       const u16* srca = (rr >= rlo && rr < rhi) ? (ap + (ptrdiff_t)(64 * i) * lda + kt * 64) : (zero_line + lc * 8);
;       __builtin_amdgcn_global_load_lds((const unsigned*)srca, (lds_u32*)(as_ + i * 8192), 16, 0, 0);
;       __builtin_amdgcn_global_load_lds((const unsigned*)(bp + (ptrdiff_t)(64 * i) * ldb + kt * 64), (lds_u32*)(as_ + 32768 + i * 8192), 16, 0, 0);
;     }
;   };
;   const int sw = (r >> 1) & 7;
;   const int arow_off = (wm * 128 + r) * 128;
;   const int brow_off = 32768 + (wn * 64 + r) * 128;
;   __syncthreads();
;   glds(0, 0);
;   asm volatile("s_waitcnt vmcnt(0)" ::: "memory");
;   __syncthreads();
;   bf16x8 fa[2][4], fb[2][2];
; #pragma unroll
;   for (int mi = 0; mi < 4; ++mi)
; #pragma unroll
;     for (int e = 0; e < 8; ++e) fa[1][mi][e] = 0;
; #pragma unroll
;   for (int ni = 0; ni < 2; ++ni)
; #pragma unroll
;     for (int e = 0; e < 8; ++e) fb[1][ni][e] = 0;
;   auto ldfrag = [&](const char* st, int ks, int buf) {
;     const int co = ((2 * ks + h) ^ sw) << 4;
; #pragma unroll
;     for (int mi = 0; mi < 4; ++mi) fa[buf][mi] = *(const bf16x8*)(st + arow_off + mi * 4096 + co);
; #pragma unroll
;     for (int ni = 0; ni < 2; ++ni) fb[buf][ni] = *(const bf16x8*)(st + brow_off + ni * 4096 + co);
;   };
	v_mov_b32_e32 v18, v2
	v_mov_b32_e32 v19, v2
	v_mov_b32_e32 v20, v2
	v_mov_b32_e32 v21, v2
	v_mov_b32_e32 v22, v2
	v_mov_b32_e32 v23, v2
	v_mov_b32_e32 v24, v2
	v_mov_b32_e32 v25, v2
	v_mov_b32_e32 v26, v2
	v_mov_b32_e32 v27, v2
	v_mov_b32_e32 v28, v2
	v_mov_b32_e32 v29, v2
	v_mov_b32_e32 v30, v2
	v_mov_b32_e32 v31, v2
	v_mov_b32_e32 v32, v2
	v_mov_b32_e32 v33, v2
	v_mov_b32_e32 v66, v2
	v_mov_b32_e32 v67, v2
	v_mov_b32_e32 v68, v2
	v_mov_b32_e32 v69, v2
	v_mov_b32_e32 v70, v2
	v_mov_b32_e32 v71, v2
	v_mov_b32_e32 v72, v2
	v_mov_b32_e32 v73, v2
	v_mov_b32_e32 v74, v2
	v_mov_b32_e32 v75, v2
	v_mov_b32_e32 v76, v2
	v_mov_b32_e32 v77, v2
	v_mov_b32_e32 v78, v2
	v_mov_b32_e32 v79, v2
	v_mov_b32_e32 v80, v2
	v_mov_b32_e32 v81, v2
	v_mov_b32_e32 v50, v2
	v_mov_b32_e32 v51, v2
	v_mov_b32_e32 v52, v2
	v_mov_b32_e32 v53, v2
	v_mov_b32_e32 v54, v2
	v_mov_b32_e32 v55, v2
	v_mov_b32_e32 v56, v2
	v_mov_b32_e32 v57, v2
	v_mov_b32_e32 v58, v2
	v_mov_b32_e32 v59, v2
	v_mov_b32_e32 v60, v2
	v_mov_b32_e32 v61, v2
	v_mov_b32_e32 v62, v2
	v_mov_b32_e32 v63, v2
	v_mov_b32_e32 v64, v2
	v_mov_b32_e32 v65, v2
	v_mov_b32_e32 v98, v2
	v_mov_b32_e32 v99, v2
	v_mov_b32_e32 v100, v2
	v_mov_b32_e32 v101, v2
	v_mov_b32_e32 v102, v2
	v_mov_b32_e32 v103, v2
	v_mov_b32_e32 v104, v2
	v_mov_b32_e32 v105, v2
	v_mov_b32_e32 v106, v2
	v_mov_b32_e32 v107, v2
	v_mov_b32_e32 v108, v2
	v_mov_b32_e32 v109, v2
	v_mov_b32_e32 v110, v2
	v_mov_b32_e32 v111, v2
	v_mov_b32_e32 v112, v2
	v_mov_b32_e32 v113, v2
	v_mov_b32_e32 v82, v2
	v_mov_b32_e32 v83, v2
	v_mov_b32_e32 v84, v2
	v_mov_b32_e32 v85, v2
	v_mov_b32_e32 v86, v2
	v_mov_b32_e32 v87, v2
	v_mov_b32_e32 v88, v2
	v_mov_b32_e32 v89, v2
	v_mov_b32_e32 v90, v2
	v_mov_b32_e32 v91, v2
	v_mov_b32_e32 v92, v2
	v_mov_b32_e32 v93, v2
	v_mov_b32_e32 v94, v2
	v_mov_b32_e32 v95, v2
	v_mov_b32_e32 v96, v2
	v_mov_b32_e32 v97, v2
	v_mov_b32_e32 v114, v2
	v_mov_b32_e32 v115, v2
	v_mov_b32_e32 v116, v2
	v_mov_b32_e32 v117, v2
	v_mov_b32_e32 v118, v2
	v_mov_b32_e32 v119, v2
	v_mov_b32_e32 v120, v2
	v_mov_b32_e32 v121, v2
	v_mov_b32_e32 v122, v2
	v_mov_b32_e32 v123, v2
	v_mov_b32_e32 v124, v2
	v_mov_b32_e32 v125, v2
	v_mov_b32_e32 v126, v2
	v_mov_b32_e32 v127, v2
	v_mov_b32_e32 v128, v2
	v_mov_b32_e32 v129, v2
	v_mov_b32_e32 v131, v130
	v_mov_b32_e32 v132, v130
	v_mov_b32_e32 v133, v130
	v_mov_b32_e32 v134, v130
	v_mov_b32_e32 v135, v130
	v_mov_b32_e32 v136, v130
	v_mov_b32_e32 v137, v130
	v_mov_b32_e32 v138, v130
	v_mov_b32_e32 v139, v130
	v_mov_b32_e32 v140, v130
	v_mov_b32_e32 v141, v130
	v_mov_b32_e32 v146, v130
	v_mov_b32_e32 v147, v130
	v_mov_b32_e32 v148, v130
	v_mov_b32_e32 v149, v130
	v_mov_b32_e32 v142, v130
	v_mov_b32_e32 v143, v130
	v_mov_b32_e32 v144, v130
	v_mov_b32_e32 v145, v130
	v_mov_b32_e32 v150, v130
	v_mov_b32_e32 v151, v130
	v_mov_b32_e32 v152, v130
	v_mov_b32_e32 v153, v130
	s_waitcnt lgkmcnt(0)
	s_barrier
	s_ashr_i32 s7, s12, 31
	s_mov_b32 s6, s12
	s_lshl_b64 s[6:7], s[6:7], 11
	s_add_u32 s6, s90, s6
	s_addc_u32 s7, s91, s7
	s_ashr_i32 s9, s16, 31
	s_mov_b32 s8, s16
	s_lshl_b64 s[8:9], s[8:9], 11
	s_add_u32 s8, s70, s8
	s_addc_u32 s9, s71, s9
	v_and_b32_e32 v130, 63, v204
	v_lshrrev_b32_e32 v131, 6, v204
	v_lshrrev_b32_e32 v132, 3, v204
	v_lshrrev_b32_e32 v0, 4, v130
	v_lshl_add_u32 v0, v131, 2, v0
	v_xor_b32_e32 v0, v0, v130
	v_and_b32_e32 v0, 7, v0
	v_lshlrev_b32_e32 v133, 4, v0
	v_lshl_add_u32 v240, v132, 11, v133
	v_add_u32_e32 v241, 0x20000, v240
	v_add_u32_e32 v242, 0x40000, v240
	v_add_u32_e32 v243, 0x60000, v240
	v_and_b32_e32 v0, 31, v132
	v_lshrrev_b32_e32 v130, 5, v132
	v_lshl_add_u32 v0, v130, 6, v0
	v_lshl_add_u32 v244, v0, 11, v133
	v_add_u32_e32 v245, 0x10000, v244
	v_add_u32_e32 v246, 0x40000, v244
	v_add_u32_e32 v247, 0x50000, v244
	v_and_b32_e32 v132, 31, v204
	v_lshrrev_b32_e32 v0, 2, v131
	v_lshl_add_u32 v0, v0, 6, v132
	v_lshlrev_b32_e32 v166, 7, v0
	v_and_b32_e32 v0, 3, v131
	v_lshl_add_u32 v0, v0, 5, v132
	v_lshlrev_b32_e32 v249, 7, v0
	v_bfe_u32 v0, v204, 5, 1
	v_bfe_u32 v130, v132, 1, 3
	v_or_b32_e32 v133, 0, v0
	v_xor_b32_e32 v133, v133, v130
	v_lshlrev_b32_e32 v161, 4, v133
	v_or_b32_e32 v133, 2, v0
	v_xor_b32_e32 v133, v133, v130
	v_lshlrev_b32_e32 v163, 4, v133
	v_or_b32_e32 v133, 4, v0
	v_xor_b32_e32 v133, v133, v130
	v_lshlrev_b32_e32 v164, 4, v133
	v_or_b32_e32 v133, 6, v0
	v_xor_b32_e32 v133, v133, v130
	v_lshlrev_b32_e32 v165, 4, v133
	v_add_u32_e32 v248, v249, v161
	v_add_u32_e32 v186, v249, v163
	v_add_u32_e32 v187, v249, v164
	v_add_u32_e32 v249, v249, v165
	v_add_u32_e32 v161, v166, v161
	v_add_u32_e32 v163, v166, v163
	v_add_u32_e32 v164, v166, v164
	v_add_u32_e32 v165, v166, v165
	v_lshlrev_b32_e32 v131, 10, v131
	s_nop 0
	v_readfirstlane_b32 s100, v131
	v_mov_b32_e32 v146, 0
	v_mov_b32_e32 v147, 0
	v_mov_b32_e32 v148, 0
	v_mov_b32_e32 v149, 0
	v_lshlrev_b32_e32 v130, 4, v204
	v_add_u32_e32 v132, 0x10000, v130
	s_mov_b64 exec, -1
	s_mov_b32 s11, 0
	s_mov_b32 s10, 0x10000
	s_waitcnt lgkmcnt(0)
	s_add_u32 m0, s100, 0x8000
	s_nop 0
	global_load_lds_dwordx4 v244, s[8:9]
	v_add_u32_e32 v244, 0x80, v244
	s_add_u32 m0, s100, 0xa000
	s_nop 0
	global_load_lds_dwordx4 v246, s[8:9]
	v_add_u32_e32 v246, 0x80, v246
	s_add_u32 m0, s100, 0x0
	s_nop 0
	global_load_lds_dwordx4 v240, s[6:7]
	v_add_u32_e32 v240, 0x80, v240
	s_add_u32 m0, s100, 0x2000
	s_nop 0
	global_load_lds_dwordx4 v242, s[6:7]
	v_add_u32_e32 v242, 0x80, v242
	s_add_u32 m0, s100, 0xc000
	s_nop 0
	global_load_lds_dwordx4 v245, s[8:9]
	v_add_u32_e32 v245, 0x80, v245
	s_add_u32 m0, s100, 0xe000
	s_nop 0
	global_load_lds_dwordx4 v247, s[8:9]
	v_add_u32_e32 v247, 0x80, v247
	s_add_u32 m0, s100, 0x4000
	s_nop 0
	global_load_lds_dwordx4 v241, s[6:7]
	v_add_u32_e32 v241, 0x80, v241
	s_add_u32 m0, s100, 0x6000
	s_nop 0
	global_load_lds_dwordx4 v243, s[6:7]
	v_add_u32_e32 v243, 0x80, v243
	s_cmp_eq_u32 s101, 1
	s_cbranch_scc0 .Lg8_ib_p0
	s_barrier

; #define MFMA(a, b, c) __builtin_amdgcn_mfma_f32_32x32x16_bf16((a), (b), (c), 0, 0, 0)
; template <bool SWAP>
; DI void gemm_mainloop(f32x16 (&acc)[4][2], const u16* __restrict__ A, int lda, int rlo, int rhi,
;                       const u16* __restrict__ B, int ldb, int K, char* lds, const u16* zero_line) {
;     ...
;   auto ldfrag = [&](const char* st, int ks, int buf) {
;     const int co = ((2 * ks + h) ^ sw) << 4;
; #pragma unroll
;     for (int mi = 0; mi < 4; ++mi) fa[buf][mi] = *(const bf16x8*)(st + arow_off + mi * 4096 + co);
; #pragma unroll
;     for (int ni = 0; ni < 2; ++ni) fb[buf][ni] = *(const bf16x8*)(st + brow_off + ni * 4096 + co);
;   };
;   auto mma = [&](int buf) {
; #pragma unroll
;     for (int mi = 0; mi < 4; ++mi)
; #pragma unroll
;       for (int ni = 0; ni < 2; ++ni)
;         acc[mi][ni] = SWAP ? MFMA(fb[buf][ni], fa[buf][mi], acc[mi][ni]) : MFMA(fa[buf][mi], fb[buf][ni], acc[mi][ni]);
;   };
;   auto pat_rd = [&]() {
; #pragma unroll
;     for (int g = 0; g < 6; ++g) {
;       __builtin_amdgcn_sched_group_barrier(0x100, 1, 0);
;       __builtin_amdgcn_sched_group_barrier(0x008, 1, 0);
;     }
;     __builtin_amdgcn_sched_group_barrier(0x008, 2, 0);
;   };
; #pragma unroll 2
;   for (int kt = 0; kt < nk; ++kt) {
;     const char* st = lds + (kt & 1) * 65536;
;     ldfrag(st, 0, 0);
;     mma(1);
;     pat_rd();
;     if (kt + 1 < nk) glds(kt + 1, (kt + 1) & 1);
;     ldfrag(st, 1, 1);
;     mma(0);
;     pat_rd();
;     ldfrag(st, 2, 0);
;     mma(1);
;     pat_rd();
;     ldfrag(st, 3, 1);
;     mma(0);
;     pat_rd();
;     asm volatile("s_waitcnt vmcnt(0)" ::: "memory");
;     __syncthreads();
;   }
.Lg8_ib:
	ds_read_b128 v[130:133], v161
	ds_read_b128 v[134:137], v163
	ds_read_b128 v[138:141], v164
	ds_read_b128 v[142:145], v165
	ds_read_b128 v[146:149], v161 offset:4096
	ds_read_b128 v[150:153], v163 offset:4096
	ds_read_b128 v[168:171], v164 offset:4096
	ds_read_b128 v[172:175], v165 offset:4096
	s_add_u32 m0, s100, 0x14000
	s_nop 0
	global_load_lds_dwordx4 v241, s[6:7]
	v_add_u32_e32 v241, 0x80, v241
	s_add_u32 m0, s100, 0x16000
	s_nop 0
	global_load_lds_dwordx4 v243, s[6:7]
	v_add_u32_e32 v243, 0x80, v243
	s_barrier
	s_waitcnt lgkmcnt(0)
	v_mfma_f32_32x32x16_bf16 v[114:129], v[130:133], v[176:179], v[114:129]
	v_mfma_f32_32x32x16_bf16 v[98:113], v[146:149], v[176:179], v[98:113]
	v_mfma_f32_32x32x16_bf16 v[114:129], v[134:137], v[180:183], v[114:129]
	v_mfma_f32_32x32x16_bf16 v[98:113], v[150:153], v[180:183], v[98:113]
	v_mfma_f32_32x32x16_bf16 v[114:129], v[138:141], v[192:195], v[114:129]
	v_mfma_f32_32x32x16_bf16 v[98:113], v[168:171], v[192:195], v[98:113]
	v_mfma_f32_32x32x16_bf16 v[114:129], v[142:145], v[196:199], v[114:129]
	v_mfma_f32_32x32x16_bf16 v[98:113], v[172:175], v[196:199], v[98:113]
	s_barrier
	ds_read_b128 v[200:203], v248 offset:49152
	ds_read_b128 v[228:231], v186 offset:49152
	ds_read_b128 v[232:235], v187 offset:49152
	ds_read_b128 v[236:239], v249 offset:49152
	s_add_u32 m0, s100, 0x8000
	s_nop 0
	global_load_lds_dwordx4 v244, s[8:9]
	v_add_u32_e32 v244, 0x80, v244
	s_add_u32 m0, s100, 0xa000
	s_nop 0
	global_load_lds_dwordx4 v246, s[8:9]
	v_add_u32_e32 v246, 0x80, v246
	s_barrier
	s_waitcnt lgkmcnt(0)
	v_mfma_f32_32x32x16_bf16 v[82:97], v[130:133], v[200:203], v[82:97]
	v_mfma_f32_32x32x16_bf16 v[50:65], v[146:149], v[200:203], v[50:65]
	v_mfma_f32_32x32x16_bf16 v[82:97], v[134:137], v[228:231], v[82:97]
	v_mfma_f32_32x32x16_bf16 v[50:65], v[150:153], v[228:231], v[50:65]
	v_mfma_f32_32x32x16_bf16 v[82:97], v[138:141], v[232:235], v[82:97]
	v_mfma_f32_32x32x16_bf16 v[50:65], v[168:171], v[232:235], v[50:65]
	v_mfma_f32_32x32x16_bf16 v[82:97], v[142:145], v[236:239], v[82:97]
	v_mfma_f32_32x32x16_bf16 v[50:65], v[172:175], v[236:239], v[50:65]
	s_barrier
	ds_read_b128 v[130:133], v161 offset:16384
	ds_read_b128 v[134:137], v163 offset:16384
	ds_read_b128 v[138:141], v164 offset:16384
	ds_read_b128 v[142:145], v165 offset:16384
	ds_read_b128 v[146:149], v161 offset:20480
	ds_read_b128 v[150:153], v163 offset:20480
	ds_read_b128 v[168:171], v164 offset:20480
	ds_read_b128 v[172:175], v165 offset:20480
	s_add_u32 m0, s100, 0x0
	s_nop 0
	global_load_lds_dwordx4 v240, s[6:7]
	v_add_u32_e32 v240, 0x80, v240
	s_add_u32 m0, s100, 0x2000
	s_nop 0
	global_load_lds_dwordx4 v242, s[6:7]
	v_add_u32_e32 v242, 0x80, v242
	s_waitcnt vmcnt(10)
	s_barrier
	s_waitcnt lgkmcnt(0)
	v_mfma_f32_32x32x16_bf16 v[66:81], v[130:133], v[176:179], v[66:81]
	v_mfma_f32_32x32x16_bf16 v[34:49], v[146:149], v[176:179], v[34:49]
	v_mfma_f32_32x32x16_bf16 v[66:81], v[134:137], v[180:183], v[66:81]
	v_mfma_f32_32x32x16_bf16 v[34:49], v[150:153], v[180:183], v[34:49]
	v_mfma_f32_32x32x16_bf16 v[66:81], v[138:141], v[192:195], v[66:81]
	v_mfma_f32_32x32x16_bf16 v[34:49], v[168:171], v[192:195], v[34:49]
	v_mfma_f32_32x32x16_bf16 v[66:81], v[142:145], v[196:199], v[66:81]
	v_mfma_f32_32x32x16_bf16 v[34:49], v[172:175], v[196:199], v[34:49]
	s_barrier
	v_add_u32_e32 v166, s10, v248
	ds_read_b128 v[176:179], v166 offset:32768
	v_add_u32_e32 v166, s10, v186
	ds_read_b128 v[180:183], v166 offset:32768
	v_add_u32_e32 v166, s10, v187
	ds_read_b128 v[192:195], v166 offset:32768
	v_add_u32_e32 v166, s10, v249
	ds_read_b128 v[196:199], v166 offset:32768
	s_add_u32 m0, s100, 0xc000
	s_nop 0
	global_load_lds_dwordx4 v245, s[8:9]
	v_add_u32_e32 v245, 0x80, v245
	s_add_u32 m0, s100, 0xe000
	s_nop 0
	global_load_lds_dwordx4 v247, s[8:9]
	v_add_u32_e32 v247, 0x80, v247
	s_waitcnt vmcnt(6)
	s_barrier
	s_waitcnt lgkmcnt(0)
	v_mfma_f32_32x32x16_bf16 v[18:33], v[130:133], v[200:203], v[18:33]
	v_mfma_f32_32x32x16_bf16 v[2:17], v[146:149], v[200:203], v[2:17]
	v_mfma_f32_32x32x16_bf16 v[18:33], v[134:137], v[228:231], v[18:33]
	v_mfma_f32_32x32x16_bf16 v[2:17], v[150:153], v[228:231], v[2:17]
	v_mfma_f32_32x32x16_bf16 v[18:33], v[138:141], v[232:235], v[18:33]
	v_mfma_f32_32x32x16_bf16 v[2:17], v[168:171], v[232:235], v[2:17]
	v_mfma_f32_32x32x16_bf16 v[18:33], v[142:145], v[236:239], v[18:33]
	v_mfma_f32_32x32x16_bf16 v[2:17], v[172:175], v[236:239], v[2:17]
	s_barrier
	v_add_u32_e32 v166, s10, v161
	ds_read_b128 v[130:133], v166
	ds_read_b128 v[146:149], v166 offset:4096
	v_add_u32_e32 v166, s10, v163
	ds_read_b128 v[134:137], v166
	ds_read_b128 v[150:153], v166 offset:4096
	v_add_u32_e32 v166, s10, v164
	ds_read_b128 v[138:141], v166
	ds_read_b128 v[168:171], v166 offset:4096
	v_add_u32_e32 v166, s10, v165
	ds_read_b128 v[142:145], v166
	ds_read_b128 v[172:175], v166 offset:4096
	s_add_u32 m0, s100, 0x4000
	s_nop 0
	global_load_lds_dwordx4 v241, s[6:7]
	v_add_u32_e32 v241, 0x80, v241
	s_add_u32 m0, s100, 0x6000
	s_nop 0
	global_load_lds_dwordx4 v243, s[6:7]
	v_add_u32_e32 v243, 0x80, v243
	s_barrier
	s_waitcnt lgkmcnt(0)
	v_mfma_f32_32x32x16_bf16 v[114:129], v[130:133], v[176:179], v[114:129]
	v_mfma_f32_32x32x16_bf16 v[98:113], v[146:149], v[176:179], v[98:113]
	v_mfma_f32_32x32x16_bf16 v[114:129], v[134:137], v[180:183], v[114:129]
	v_mfma_f32_32x32x16_bf16 v[98:113], v[150:153], v[180:183], v[98:113]
	v_mfma_f32_32x32x16_bf16 v[114:129], v[138:141], v[192:195], v[114:129]
	v_mfma_f32_32x32x16_bf16 v[98:113], v[168:171], v[192:195], v[98:113]
	v_mfma_f32_32x32x16_bf16 v[114:129], v[142:145], v[196:199], v[114:129]
	v_mfma_f32_32x32x16_bf16 v[98:113], v[172:175], v[196:199], v[98:113]
	s_barrier
; template <bool SWAP>
; DI void gemm_mainloop(f32x16 (&acc)[4][2], const u16* __restrict__ A, int lda, int rlo, int rhi,
;                       const u16* __restrict__ B, int ldb, int K, char* lds, const u16* zero_line) {
;     ...
; #pragma unroll 2
;   for (int kt = 0; kt < nk; ++kt) {
;     const char* st = lds + (kt & 1) * 65536;
;     ldfrag(st, 0, 0);
;     mma(1);
;     pat_rd();
;     if (kt + 1 < nk) glds(kt + 1, (kt + 1) & 1);
;     ldfrag(st, 1, 1);
;     mma(0);
;     pat_rd();
;     ldfrag(st, 2, 0);
;     mma(1);
;     pat_rd();
;     ldfrag(st, 3, 1);
;     mma(0);
;     pat_rd();
;     asm volatile("s_waitcnt vmcnt(0)" ::: "memory");
;     __syncthreads();
;   }
;   mma(1);
	v_add_u32_e32 v166, s10, v248
	ds_read_b128 v[200:203], v166 offset:49152
	v_add_u32_e32 v166, s10, v186
	ds_read_b128 v[228:231], v166 offset:49152
	v_add_u32_e32 v166, s10, v187
	ds_read_b128 v[232:235], v166 offset:49152
	v_add_u32_e32 v166, s10, v249
	ds_read_b128 v[236:239], v166 offset:49152
	s_add_u32 m0, s100, 0x18000
	s_nop 0
	global_load_lds_dwordx4 v244, s[8:9]
	v_add_u32_e32 v244, 0x80, v244
	s_add_u32 m0, s100, 0x1a000
	s_nop 0
	global_load_lds_dwordx4 v246, s[8:9]
	v_add_u32_e32 v246, 0x80, v246
	s_barrier
	s_waitcnt lgkmcnt(0)
	v_mfma_f32_32x32x16_bf16 v[82:97], v[130:133], v[200:203], v[82:97]
	v_mfma_f32_32x32x16_bf16 v[50:65], v[146:149], v[200:203], v[50:65]
	v_mfma_f32_32x32x16_bf16 v[82:97], v[134:137], v[228:231], v[82:97]
	v_mfma_f32_32x32x16_bf16 v[50:65], v[150:153], v[228:231], v[50:65]
	v_mfma_f32_32x32x16_bf16 v[82:97], v[138:141], v[232:235], v[82:97]
	v_mfma_f32_32x32x16_bf16 v[50:65], v[168:171], v[232:235], v[50:65]
	v_mfma_f32_32x32x16_bf16 v[82:97], v[142:145], v[236:239], v[82:97]
	v_mfma_f32_32x32x16_bf16 v[50:65], v[172:175], v[236:239], v[50:65]
	s_barrier
	v_add_u32_e32 v166, s10, v161
	ds_read_b128 v[130:133], v166 offset:16384
	ds_read_b128 v[146:149], v166 offset:20480
	v_add_u32_e32 v166, s10, v163
	ds_read_b128 v[134:137], v166 offset:16384
	ds_read_b128 v[150:153], v166 offset:20480
	v_add_u32_e32 v166, s10, v164
	ds_read_b128 v[138:141], v166 offset:16384
	ds_read_b128 v[168:171], v166 offset:20480
	v_add_u32_e32 v166, s10, v165
	ds_read_b128 v[142:145], v166 offset:16384
	ds_read_b128 v[172:175], v166 offset:20480
	s_add_u32 m0, s100, 0x10000
	s_nop 0
	global_load_lds_dwordx4 v240, s[6:7]
	v_add_u32_e32 v240, 0x80, v240
	s_add_u32 m0, s100, 0x12000
	s_nop 0
	global_load_lds_dwordx4 v242, s[6:7]
	v_add_u32_e32 v242, 0x80, v242
	s_waitcnt vmcnt(10)
	s_barrier
	s_waitcnt lgkmcnt(0)
	v_mfma_f32_32x32x16_bf16 v[66:81], v[130:133], v[176:179], v[66:81]
	v_mfma_f32_32x32x16_bf16 v[34:49], v[146:149], v[176:179], v[34:49]
	v_mfma_f32_32x32x16_bf16 v[66:81], v[134:137], v[180:183], v[66:81]
	v_mfma_f32_32x32x16_bf16 v[34:49], v[150:153], v[180:183], v[34:49]
	v_mfma_f32_32x32x16_bf16 v[66:81], v[138:141], v[192:195], v[66:81]
	v_mfma_f32_32x32x16_bf16 v[34:49], v[168:171], v[192:195], v[34:49]
	v_mfma_f32_32x32x16_bf16 v[66:81], v[142:145], v[196:199], v[66:81]
	v_mfma_f32_32x32x16_bf16 v[34:49], v[172:175], v[196:199], v[34:49]
	s_barrier
	ds_read_b128 v[176:179], v248 offset:32768
	ds_read_b128 v[180:183], v186 offset:32768
	ds_read_b128 v[192:195], v187 offset:32768
	ds_read_b128 v[196:199], v249 offset:32768
	s_add_u32 m0, s100, 0x1c000
	s_nop 0
	global_load_lds_dwordx4 v245, s[8:9]
	v_add_u32_e32 v245, 0x80, v245
	s_add_u32 m0, s100, 0x1e000
	s_nop 0
	global_load_lds_dwordx4 v247, s[8:9]
	v_add_u32_e32 v247, 0x80, v247
	s_waitcnt vmcnt(6)
	s_barrier
	s_waitcnt lgkmcnt(0)
	v_mfma_f32_32x32x16_bf16 v[18:33], v[130:133], v[200:203], v[18:33]
	v_mfma_f32_32x32x16_bf16 v[2:17], v[146:149], v[200:203], v[2:17]
	v_mfma_f32_32x32x16_bf16 v[18:33], v[134:137], v[228:231], v[18:33]
	v_mfma_f32_32x32x16_bf16 v[2:17], v[150:153], v[228:231], v[2:17]
	v_mfma_f32_32x32x16_bf16 v[18:33], v[138:141], v[232:235], v[18:33]
	v_mfma_f32_32x32x16_bf16 v[2:17], v[168:171], v[232:235], v[2:17]
	v_mfma_f32_32x32x16_bf16 v[18:33], v[142:145], v[236:239], v[18:33]
	v_mfma_f32_32x32x16_bf16 v[2:17], v[172:175], v[236:239], v[2:17]
	s_barrier
	s_add_i32 s11, s11, 2
	s_cmp_lt_u32 s11, 14
	s_cbranch_scc1 .Lg8_ib
	ds_read_b128 v[130:133], v161
	ds_read_b128 v[134:137], v163
	ds_read_b128 v[138:141], v164
	ds_read_b128 v[142:145], v165
	ds_read_b128 v[146:149], v161 offset:4096
	ds_read_b128 v[150:153], v163 offset:4096
	ds_read_b128 v[168:171], v164 offset:4096
	ds_read_b128 v[172:175], v165 offset:4096
	s_add_u32 m0, s100, 0x14000
	s_nop 0
	global_load_lds_dwordx4 v241, s[6:7]
	v_add_u32_e32 v241, 0x80, v241
	s_add_u32 m0, s100, 0x16000
	s_nop 0
	global_load_lds_dwordx4 v243, s[6:7]
	v_add_u32_e32 v243, 0x80, v243
	s_barrier
	s_waitcnt lgkmcnt(0)
	v_mfma_f32_32x32x16_bf16 v[114:129], v[130:133], v[176:179], v[114:129]
	v_mfma_f32_32x32x16_bf16 v[98:113], v[146:149], v[176:179], v[98:113]
	v_mfma_f32_32x32x16_bf16 v[114:129], v[134:137], v[180:183], v[114:129]
	v_mfma_f32_32x32x16_bf16 v[98:113], v[150:153], v[180:183], v[98:113]
	v_mfma_f32_32x32x16_bf16 v[114:129], v[138:141], v[192:195], v[114:129]
	v_mfma_f32_32x32x16_bf16 v[98:113], v[168:171], v[192:195], v[98:113]
	v_mfma_f32_32x32x16_bf16 v[114:129], v[142:145], v[196:199], v[114:129]
	v_mfma_f32_32x32x16_bf16 v[98:113], v[172:175], v[196:199], v[98:113]
	s_barrier
	ds_read_b128 v[200:203], v248 offset:49152
	ds_read_b128 v[228:231], v186 offset:49152
	ds_read_b128 v[232:235], v187 offset:49152
	ds_read_b128 v[236:239], v249 offset:49152
	s_barrier
	s_waitcnt lgkmcnt(0)
	v_mfma_f32_32x32x16_bf16 v[82:97], v[130:133], v[200:203], v[82:97]
	v_mfma_f32_32x32x16_bf16 v[50:65], v[146:149], v[200:203], v[50:65]
	v_mfma_f32_32x32x16_bf16 v[82:97], v[134:137], v[228:231], v[82:97]
	v_mfma_f32_32x32x16_bf16 v[50:65], v[150:153], v[228:231], v[50:65]
	v_mfma_f32_32x32x16_bf16 v[82:97], v[138:141], v[232:235], v[82:97]
	v_mfma_f32_32x32x16_bf16 v[50:65], v[168:171], v[232:235], v[50:65]
	v_mfma_f32_32x32x16_bf16 v[82:97], v[142:145], v[236:239], v[82:97]
	v_mfma_f32_32x32x16_bf16 v[50:65], v[172:175], v[236:239], v[50:65]
	s_barrier
; template <bool SWAP>
; DI void gemm_mainloop(f32x16 (&acc)[4][2], const u16* __restrict__ A, int lda, int rlo, int rhi,
;                       const u16* __restrict__ B, int ldb, int K, char* lds, const u16* zero_line) {
;     ...
; #pragma unroll 2
;   for (int kt = 0; kt < nk; ++kt) {
;     const char* st = lds + (kt & 1) * 65536;
;     ldfrag(st, 0, 0);
;     mma(1);
;     pat_rd();
;     if (kt + 1 < nk) glds(kt + 1, (kt + 1) & 1);
;     ldfrag(st, 1, 1);
;     mma(0);
;     pat_rd();
;     ldfrag(st, 2, 0);
;     mma(1);
;     pat_rd();
;     ldfrag(st, 3, 1);
;     mma(0);
;     pat_rd();
;     asm volatile("s_waitcnt vmcnt(0)" ::: "memory");
;     __syncthreads();
;   }
;   mma(1);
	ds_read_b128 v[130:133], v161 offset:16384
	ds_read_b128 v[134:137], v163 offset:16384
	ds_read_b128 v[138:141], v164 offset:16384
	ds_read_b128 v[142:145], v165 offset:16384
	ds_read_b128 v[146:149], v161 offset:20480
	ds_read_b128 v[150:153], v163 offset:20480
	ds_read_b128 v[168:171], v164 offset:20480
	ds_read_b128 v[172:175], v165 offset:20480
	s_waitcnt vmcnt(4)
	s_barrier
	s_waitcnt lgkmcnt(0)
	v_mfma_f32_32x32x16_bf16 v[66:81], v[130:133], v[176:179], v[66:81]
	v_mfma_f32_32x32x16_bf16 v[34:49], v[146:149], v[176:179], v[34:49]
	v_mfma_f32_32x32x16_bf16 v[66:81], v[134:137], v[180:183], v[66:81]
	v_mfma_f32_32x32x16_bf16 v[34:49], v[150:153], v[180:183], v[34:49]
	v_mfma_f32_32x32x16_bf16 v[66:81], v[138:141], v[192:195], v[66:81]
	v_mfma_f32_32x32x16_bf16 v[34:49], v[168:171], v[192:195], v[34:49]
	v_mfma_f32_32x32x16_bf16 v[66:81], v[142:145], v[196:199], v[66:81]
	v_mfma_f32_32x32x16_bf16 v[34:49], v[172:175], v[196:199], v[34:49]
	v_mfma_f32_32x32x16_bf16 v[18:33], v[130:133], v[200:203], v[18:33]
	v_mfma_f32_32x32x16_bf16 v[2:17], v[146:149], v[200:203], v[2:17]
	v_mfma_f32_32x32x16_bf16 v[18:33], v[134:137], v[228:231], v[18:33]
	v_mfma_f32_32x32x16_bf16 v[2:17], v[150:153], v[228:231], v[2:17]
	v_mfma_f32_32x32x16_bf16 v[18:33], v[138:141], v[232:235], v[18:33]
	v_mfma_f32_32x32x16_bf16 v[2:17], v[168:171], v[232:235], v[2:17]
	v_mfma_f32_32x32x16_bf16 v[18:33], v[142:145], v[236:239], v[18:33]
	v_mfma_f32_32x32x16_bf16 v[2:17], v[172:175], v[236:239], v[2:17]
	s_barrier
	v_add_u32_e32 v166, s10, v248
	ds_read_b128 v[176:179], v166 offset:32768
	v_add_u32_e32 v166, s10, v186
	ds_read_b128 v[180:183], v166 offset:32768
	v_add_u32_e32 v166, s10, v187
	ds_read_b128 v[192:195], v166 offset:32768
	v_add_u32_e32 v166, s10, v249
	ds_read_b128 v[196:199], v166 offset:32768
	v_add_u32_e32 v166, s10, v161
	ds_read_b128 v[130:133], v166
	ds_read_b128 v[146:149], v166 offset:4096
	v_add_u32_e32 v166, s10, v163
	ds_read_b128 v[134:137], v166
	ds_read_b128 v[150:153], v166 offset:4096
	v_add_u32_e32 v166, s10, v164
	ds_read_b128 v[138:141], v166
	ds_read_b128 v[168:171], v166 offset:4096
	v_add_u32_e32 v166, s10, v165
	ds_read_b128 v[142:145], v166
	ds_read_b128 v[172:175], v166 offset:4096
	s_waitcnt vmcnt(2)
	s_barrier
	s_waitcnt lgkmcnt(0)
	v_mfma_f32_32x32x16_bf16 v[114:129], v[130:133], v[176:179], v[114:129]
	v_mfma_f32_32x32x16_bf16 v[98:113], v[146:149], v[176:179], v[98:113]
	v_mfma_f32_32x32x16_bf16 v[114:129], v[134:137], v[180:183], v[114:129]
	v_mfma_f32_32x32x16_bf16 v[98:113], v[150:153], v[180:183], v[98:113]
	v_mfma_f32_32x32x16_bf16 v[114:129], v[138:141], v[192:195], v[114:129]
	v_mfma_f32_32x32x16_bf16 v[98:113], v[168:171], v[192:195], v[98:113]
	v_mfma_f32_32x32x16_bf16 v[114:129], v[142:145], v[196:199], v[114:129]
	v_mfma_f32_32x32x16_bf16 v[98:113], v[172:175], v[196:199], v[98:113]
	s_barrier
	v_add_u32_e32 v166, s10, v248
	ds_read_b128 v[200:203], v166 offset:49152
	v_add_u32_e32 v166, s10, v186
	ds_read_b128 v[228:231], v166 offset:49152
	v_add_u32_e32 v166, s10, v187
	ds_read_b128 v[232:235], v166 offset:49152
	v_add_u32_e32 v166, s10, v249
	ds_read_b128 v[236:239], v166 offset:49152
	s_waitcnt vmcnt(0)
	s_barrier
	s_waitcnt lgkmcnt(0)
	v_mfma_f32_32x32x16_bf16 v[82:97], v[130:133], v[200:203], v[82:97]
	v_mfma_f32_32x32x16_bf16 v[50:65], v[146:149], v[200:203], v[50:65]
	v_mfma_f32_32x32x16_bf16 v[82:97], v[134:137], v[228:231], v[82:97]
	v_mfma_f32_32x32x16_bf16 v[50:65], v[150:153], v[228:231], v[50:65]
	v_mfma_f32_32x32x16_bf16 v[82:97], v[138:141], v[232:235], v[82:97]
	v_mfma_f32_32x32x16_bf16 v[50:65], v[168:171], v[232:235], v[50:65]
	v_mfma_f32_32x32x16_bf16 v[82:97], v[142:145], v[236:239], v[82:97]
	v_mfma_f32_32x32x16_bf16 v[50:65], v[172:175], v[236:239], v[50:65]
	s_barrier
	v_add_u32_e32 v166, s10, v161
	ds_read_b128 v[130:133], v166 offset:16384
	ds_read_b128 v[146:149], v166 offset:20480
	v_add_u32_e32 v166, s10, v163
	ds_read_b128 v[134:137], v166 offset:16384
	ds_read_b128 v[150:153], v166 offset:20480
	v_add_u32_e32 v166, s10, v164
	ds_read_b128 v[138:141], v166 offset:16384
	ds_read_b128 v[168:171], v166 offset:20480
	v_add_u32_e32 v166, s10, v165
	ds_read_b128 v[142:145], v166 offset:16384
	ds_read_b128 v[172:175], v166 offset:20480
	s_barrier
	s_waitcnt lgkmcnt(0)
	v_mfma_f32_32x32x16_bf16 v[66:81], v[130:133], v[176:179], v[66:81]
	v_mfma_f32_32x32x16_bf16 v[34:49], v[146:149], v[176:179], v[34:49]
	v_mfma_f32_32x32x16_bf16 v[66:81], v[134:137], v[180:183], v[66:81]
	v_mfma_f32_32x32x16_bf16 v[34:49], v[150:153], v[180:183], v[34:49]
	v_mfma_f32_32x32x16_bf16 v[66:81], v[138:141], v[192:195], v[66:81]
	v_mfma_f32_32x32x16_bf16 v[34:49], v[168:171], v[192:195], v[34:49]
	v_mfma_f32_32x32x16_bf16 v[66:81], v[142:145], v[196:199], v[66:81]
	v_mfma_f32_32x32x16_bf16 v[34:49], v[172:175], v[196:199], v[34:49]
	v_mfma_f32_32x32x16_bf16 v[18:33], v[130:133], v[200:203], v[18:33]
	v_mfma_f32_32x32x16_bf16 v[2:17], v[146:149], v[200:203], v[2:17]
	v_mfma_f32_32x32x16_bf16 v[18:33], v[134:137], v[228:231], v[18:33]
	v_mfma_f32_32x32x16_bf16 v[2:17], v[150:153], v[228:231], v[2:17]
	v_mfma_f32_32x32x16_bf16 v[18:33], v[138:141], v[232:235], v[18:33]
	v_mfma_f32_32x32x16_bf16 v[2:17], v[168:171], v[232:235], v[2:17]
	v_mfma_f32_32x32x16_bf16 v[18:33], v[142:145], v[236:239], v[18:33]
	v_mfma_f32_32x32x16_bf16 v[2:17], v[172:175], v[236:239], v[2:17]
	s_barrier
	s_cmp_eq_u32 s101, 0
	s_cbranch_scc0 .Lg8_ib_p1
	s_barrier
